# v082 + GEMM unit boundaries: the trailing wave half takes its offset-restoring barrier after its next-tile decode and accumulator zeroing (just before the k-loop) instead of right after the epilogue,
# speedup vs baseline: 1.0035x; 1.0035x over previous
.LBB0_284:
	s_or_b64 exec, exec, s[0:1]
	s_ashr_i32 s1, s92, 31
	s_lshr_b32 s1, s1, 29
	s_add_i32 s1, s92, s1
	s_ashr_i32 s3, s1, 3
	s_and_b32 s1, s1, -8
	s_ashr_i32 s0, s14, 3
	s_sub_i32 s1, s92, s1
	s_mul_i32 s0, s0, s1
	s_add_i32 s3, s0, s3
	s_ashr_i32 s13, s14, 31
	s_lshl_b32 s50, s14, 1
	s_add_u32 s0, s6, 0x3c58a200
	s_addc_u32 s1, s7, 0
	v_writelane_b32 v254, s0, 4
	v_add_u32_e32 v0, 64, v149
	v_cmp_lt_i32_e32 vcc, v151, v0
	v_writelane_b32 v254, s1, 5
	s_add_u32 s0, s6, 0x3c58a400
	s_addc_u32 s1, s7, 0
	v_writelane_b32 v254, s0, 6
	v_cndmask_b32_e32 v1, v144, v151, vcc
	v_cmp_lt_i32_e32 vcc, v150, v0
	v_writelane_b32 v254, s1, 7
	s_add_u32 s0, s6, 0x3c58a500
	s_addc_u32 s1, s7, 0
	v_writelane_b32 v254, s0, 8
	v_lshlrev_b32_e32 v229, 2, v1
	v_cndmask_b32_e32 v1, v144, v150, vcc
	v_writelane_b32 v254, s1, 9
	s_add_u32 s0, s6, 0x3c58a600
	s_addc_u32 s1, s7, 0
	v_writelane_b32 v254, s0, 10
	v_cmp_lt_i32_e32 vcc, v148, v0
	v_lshlrev_b32_e32 v230, 2, v1
	v_writelane_b32 v254, s1, 11
	s_add_u32 s0, s6, 0x3c58a700
	s_addc_u32 s1, s7, 0
	v_writelane_b32 v254, s0, 12
	v_cndmask_b32_e32 v1, v144, v148, vcc
	v_cmp_lt_i32_e32 vcc, v147, v0
	v_writelane_b32 v254, s1, 13
	s_add_u32 s0, s6, 0x3c58a800
	s_addc_u32 s1, s7, 0
	v_writelane_b32 v254, s0, 14
	v_lshlrev_b32_e32 v231, 2, v1
	v_cndmask_b32_e32 v1, v144, v147, vcc
	v_writelane_b32 v254, s1, 15
	s_add_u32 s0, s6, 0x3c58a900
	s_addc_u32 s1, s7, 0
	v_writelane_b32 v254, s0, 16
	v_lshlrev_b32_e32 v232, 2, v1
	v_cmp_lt_i32_e32 vcc, v146, v0
	v_writelane_b32 v254, s1, 17
	s_add_u32 s0, s6, 0x3c58aa00
	s_addc_u32 s1, s7, 0
	v_writelane_b32 v254, s0, 18
	v_cndmask_b32_e32 v2, v144, v146, vcc
	v_cmp_lt_i32_e32 vcc, v145, v0
	v_writelane_b32 v254, s1, 19
	s_add_u32 s0, s6, 0x3c58ab00
	s_addc_u32 s1, s7, 0
	v_writelane_b32 v254, s0, 20
	v_cndmask_b32_e32 v0, v144, v145, vcc
	v_lshlrev_b32_e32 v234, 2, v0
	v_writelane_b32 v254, s1, 21
	s_add_u32 s0, s6, 0x3c58ac00
	s_addc_u32 s1, s7, 0
	v_writelane_b32 v254, s0, 22
	s_mul_i32 s2, s15, s14
	v_lshlrev_b32_e32 v233, 2, v2
	v_writelane_b32 v254, s1, 23
	s_add_u32 s0, s6, 0x3c58ad00
	s_addc_u32 s1, s7, 0
	v_writelane_b32 v254, s0, 24
	s_mov_b32 s65, 0
	s_movk_i32 s60, 0x100
	v_writelane_b32 v254, s1, 25
	s_add_u32 s0, s6, 0x3c58ae00
	s_addc_u32 s1, s7, 0
	v_writelane_b32 v254, s0, 26
	s_movk_i32 s77, 0x90
	s_movk_i32 s78, 0xffe0
	v_writelane_b32 v254, s1, 27
	s_add_u32 s0, s6, 0x3c58af00
	s_addc_u32 s1, s7, 0
	v_writelane_b32 v254, s0, 28
	v_mov_b32_e32 v235, 0x358637bd
	s_movk_i32 s79, 0x1600
	v_writelane_b32 v254, s1, 29
	s_add_u32 s0, s6, 0x3c58b000
	s_addc_u32 s1, s7, 0
	v_writelane_b32 v254, s0, 30
	s_mov_b32 s22, 0xf800000
	v_mov_b32_e32 v238, 0x260
	v_writelane_b32 v254, s1, 31
	s_add_u32 s0, s6, 0x3c58b100
	s_addc_u32 s1, s7, 0
	v_writelane_b32 v254, s0, 32
	s_movk_i32 s62, 0x110
	v_mov_b32_e32 v241, 0x2000
	v_writelane_b32 v254, s1, 33
	s_add_u32 s0, s6, 0x3c58b200
	s_addc_u32 s1, s7, 0
	v_writelane_b32 v254, s0, 34
	v_mov_b64_e32 v[196:197], 0x200
	v_mov_b64_e32 v[198:199], 0x1ff
	v_writelane_b32 v254, s1, 35
	s_add_u32 s0, s6, 0x3c58b300
	s_addc_u32 s1, s7, 0
	v_writelane_b32 v254, s0, 36
	v_mov_b64_e32 v[250:251], 0xb00
	v_mov_b64_e32 v[202:203], 0xaff
	v_writelane_b32 v254, s1, 37
	s_add_u32 s0, s6, 0x3c58d400
	s_addc_u32 s1, s7, 0
	v_writelane_b32 v254, s0, 38
	v_mov_b32_e32 v239, 0xa0000
	s_mov_b32 s25, 0
	v_writelane_b32 v254, s1, 39
	s_add_u32 s0, s6, 0x3c58d500
	s_addc_u32 s1, s7, 0
	v_writelane_b32 v254, s0, 40
	s_mov_b64 s[68:69], 0x80
	s_mov_b64 s[80:81], 0x20000
	v_writelane_b32 v254, s1, 41
	s_and_b64 s[0:1], s[8:9], exec
	s_cselect_b32 s3, s3, s92
	s_lshl_b32 s0, s3, 3
	s_cmpk_lt_i32 s3, 0x400
	v_writelane_b32 v254, s0, 42
	s_cselect_b64 s[0:1], -1, 0
	v_writelane_b32 v254, s0, 43
	s_cmpk_lt_i32 s3, 0x200
	s_mov_b64 s[82:83], 0x1000
	v_writelane_b32 v254, s1, 44
	s_cselect_b64 s[0:1], -1, 0
	v_writelane_b32 v254, s0, 45
	s_waitcnt lgkmcnt(0)
	s_barrier
; #define INP(i) ldsptr(lds, (i))
; #define XIN() (INP(prompt ? I_XP : I_XS) + (size_t)(prompt ? c : c - NCH_P) * CH * DM)
; __global__ void __launch_bounds__(512, 2) mega_fwd(Args a) {
;     ...
;             const int S_ = prompt ? 8192 : 2048, nseq = CH / S_, NQB = S_ / 256;
;             const int memseq0 = prompt ? (CH / 8192) * c : 8 + (CH / 2048) * (c - NCH_P);
;             gfloat* const ssq1 = ssq; gfloat* const ssq2 = ssq + CH * 4; gfloat* const ssq3 = ssq + 2 * CH * 4;
;             if (PH_EN(3) && k == 0) {
;                 const gfloat* gain = INP(I_NFF1);
;                 const gfloat* xin_ = XIN();
;                 if (xl_good && (CH / 8) % (2 * G) == 0) {
;                     const int m0 = (CH / 8) * xl_x + xl_r * 8 + wave;
;                     for (int i0 = 0; i0 < CH / 8; i0 += 2 * G) { const size_t ra = (size_t)(m0 + i0) * DM, rb = (size_t)(m0 + i0 + G) * DM; rms_row2_bf16(xin_ + ra, xin_ + rb, gain, xn + ra, xn + rb, lane); }
	v_writelane_b32 v254, s1, 46
	s_abs_i32 s0, s50
	v_cvt_f32_u32_e32 v1, s0
	s_mul_i32 s1, s2, s33
	v_writelane_b32 v254, s1, 47
	s_sub_i32 s1, 0, s0
	v_rcp_iflag_f32_e32 v1, v1
	s_movk_i32 s33, 0x2800
	v_mul_f32_e32 v0, 0x4f7ffffe, v1
	v_cvt_u32_f32_e32 v0, v0
	v_mov_b32_e32 v1, 0
	v_readfirstlane_b32 s2, v0
	s_mul_i32 s1, s1, s2
	s_mul_hi_u32 s1, s2, s1
	s_add_i32 s2, s2, s1
	s_lshr_b32 s1, s2, 20
	s_mul_i32 s1, s1, s0
	s_sub_i32 s1, 0x1000, s1
	s_sub_i32 s2, s1, s0
	s_cmp_ge_u32 s1, s0
	s_cselect_b32 s1, s2, s1
	s_sub_i32 s2, s1, s0
	s_cmp_ge_u32 s1, s0
	s_cselect_b32 s0, s2, s1
	s_cmp_lg_u32 s0, 0
	s_cselect_b64 s[0:1], -1, 0
	v_writelane_b32 v254, s0, 48
	s_lshl_b32 s12, s14, 4
	s_add_i32 s61, 0, 0x21460
	v_writelane_b32 v254, s1, 49
	s_lshl_b32 s0, s3, 6
	v_writelane_b32 v254, s0, 50
	s_lshl_b32 s0, s14, 6
	v_writelane_b32 v254, s0, 51
	v_writelane_b32 v254, s3, 52
	s_lshl_b32 s0, s3, 7
	v_writelane_b32 v254, s0, 53
	s_add_i32 s0, 0, 0x214b8
	v_writelane_b32 v254, s0, 54
	s_add_i32 s0, 0, 0x21510
	v_writelane_b32 v254, s0, 55
	s_add_i32 s0, 0, 0x21508
	v_writelane_b32 v254, s0, 56
	s_add_i32 s0, 0, 0x2150c
	v_writelane_b32 v254, s0, 57
	s_add_i32 s0, 0, 0x214b0
	v_writelane_b32 v254, s0, 58
	s_add_i32 s0, 0, 0x20000
	v_writelane_b32 v254, s0, 59
	s_add_i32 s0, 0, 0x21450
	v_writelane_b32 v254, s0, 60
	s_add_i32 s0, 0, 0x1b600
	v_writelane_b32 v254, s0, 61
	s_add_i32 s0, 0, 0x21458
	v_writelane_b32 v254, s0, 62
	s_add_i32 s0, 0, 0x21428
	v_writelane_b32 v254, s0, 63
	s_add_i32 s0, 0, 0x21500
	v_writelane_b32 v255, s0, 0
	s_add_i32 s0, 0, 0x21504
	v_writelane_b32 v255, s0, 1
	v_writelane_b32 v255, s92, 2
	v_writelane_b32 v255, s12, 3
	v_writelane_b32 v255, s61, 4
	s_lshl_b32 s19, s14, 7
	s_add_i32 s76, 0, 0x21000
	v_writelane_b32 v255, s50, 5
	v_mov_b32_e32 v246, 0x21450
	ds_read_b128 v[246:249], v246
	v_and_b32_e32 v252, 63, v228
	v_lshlrev_b32_e32 v252, 2, v252
	v_mov_b32_e32 v253, 0
	s_waitcnt lgkmcnt(0)
	v_lshl_add_u64 v[246:247], v[246:247], 0, v[252:253]
	v_lshl_add_u64 v[248:249], v[248:249], 0, v[252:253]
	global_load_dword v246, v[246:247], off
	global_load_dword v248, v[248:249], off
	s_waitcnt vmcnt(0)
	v_and_b32_e32 v246, 0x7fffffff, v246
	v_and_b32_e32 v248, 0x7fffffff, v248
	v_xor_b32_e32 v253, 4, v252
	ds_bpermute_b32 v247, v253, v246
	ds_bpermute_b32 v249, v253, v248
	s_waitcnt lgkmcnt(0)
	v_max_f32_e32 v246, v246, v247
	v_max_f32_e32 v248, v248, v249
	v_xor_b32_e32 v253, 8, v252
	ds_bpermute_b32 v247, v253, v246
	ds_bpermute_b32 v249, v253, v248
	s_waitcnt lgkmcnt(0)
	v_max_f32_e32 v246, v246, v247
	v_max_f32_e32 v248, v248, v249
	v_xor_b32_e32 v253, 16, v252
	ds_bpermute_b32 v247, v253, v246
	ds_bpermute_b32 v249, v253, v248
	s_waitcnt lgkmcnt(0)
	v_max_f32_e32 v246, v246, v247
	v_max_f32_e32 v248, v248, v249
	v_xor_b32_e32 v253, 32, v252
	ds_bpermute_b32 v247, v253, v246
	ds_bpermute_b32 v249, v253, v248
	s_waitcnt lgkmcnt(0)
	v_max_f32_e32 v246, v246, v247
	v_max_f32_e32 v248, v248, v249
	v_xor_b32_e32 v253, 64, v252
	ds_bpermute_b32 v247, v253, v246
	ds_bpermute_b32 v249, v253, v248
	s_waitcnt lgkmcnt(0)
	v_max_f32_e32 v246, v246, v247
	v_max_f32_e32 v248, v248, v249
	v_xor_b32_e32 v253, 128, v252
	ds_bpermute_b32 v247, v253, v246
	ds_bpermute_b32 v249, v253, v248
	s_waitcnt lgkmcnt(0)
	v_max_f32_e32 v246, v246, v247
	v_max_f32_e32 v248, v248, v249
	v_mul_f32_e32 v246, v246, v248
	v_mul_f32_e32 v246, 0x414fbf83, v246
	s_nop 1
	v_readfirstlane_b32 s0, v246
	s_nop 3
	v_writelane_b32 v255, s0, 20
	s_mov_b32 s0, 0
	s_nop 0
	v_writelane_b32 v255, s0, 21
	s_branch .LBB0_289

;     __device__ bool next(int i, Unit& u) const { if (!b.next(i / 3, u)) return false; u.pz = i % 3; return true; }
; #define PG8_STAGE(bufoff, gbase, voff) do { _Pragma("unroll") for (int _i = 0; _i < 2; ++_i) \
;         __builtin_amdgcn_global_load_lds((const gunsigned*)((const gchar*)(gbase) + (voff)[_i]), (LAS unsigned*)(lds + (bufoff) + ldsw + _i * 8192), 16, 0, 0); } while (0)
; #define PG8_LDA(dst, b, h) do { _Pragma("unroll") for (int m = 0; m < 4; ++m) _Pragma("unroll") for (int k = 0; k < 2; ++k) dst[m][k] = *(const LAS bf16x8*)(lds + PG8_SA(b, h) + aoff + m * 2048 + k * 1024); } while (0)
; #define PG8_LDB(dst, b, h) do { _Pragma("unroll") for (int n = 0; n < 2; ++n) _Pragma("unroll") for (int k = 0; k < 2; ++k) dst[n][k] = *(const LAS bf16x8*)(lds + PG8_SB(b, h) + boff + n * 2048 + k * 1024); } while (0)
; #define PG8_MMA(ai, bj, At, Bt) do { __builtin_amdgcn_s_setprio(1); _Pragma("unroll") for (int m = 0; m < 4; ++m) _Pragma("unroll") for (int n = 0; n < 2; ++n) _Pragma("unroll") for (int k = 0; k < 2; ++k) \
;         acc[ai][bj][m][n] = __builtin_amdgcn_mfma_f32_16x16x32_bf16(Bt[n][k], At[m][k], acc[ai][bj][m][n], 0, 0, 0); __builtin_amdgcn_s_setprio(0); } while (0)
; #define PG8_BAR __builtin_amdgcn_s_barrier()
; template <class Epi, class Sched>
; __device__ __forceinline__ void gemm_phase(LAS unsigned char* lds, const int tid, const Gemm g, const Sched& S, const Epi& E) {
;     ...
;     for (;;) {
;         const bool has_next = S.next(ui + 1, nxt);
;         const gchar* nA = has_next ? (const gchar*)g.A + (size_t)nxt.pm * tstep + (size_t)nxt.pz * g.zA : cA;
;         const gchar* nB = has_next ? (const gchar*)g.Bt + (size_t)nxt.pn * tstep + (size_t)nxt.pz * g.zB : cB;
;         for (int t = 0; t < nt; t += 2) {
;             const bool last = (t == nt - 2);
;             const gchar* a1 = cA + (size_t)(t + 1) * kstep;
;             const gchar* a2 = last ? nA : cA + (size_t)(t + 2) * kstep; const gchar* b2 = last ? nB : cB + (size_t)(t + 2) * kstep;
;             const gchar* a3 = a2 + kstep; const gchar* b3 = b2 + kstep;
;             PG8_LDB(B0, 0, 0); PG8_LDB(B1, 0, 1); PG8_SCHED; PG8_LDA(At, 0, 0); PG8_STAGE(PG8_SA(1, 1), a1 + hstep, voffA);
;             PG8_WAIT_V(8); PG8_WAIT_L(0); PG8_BAR; PG8_MMA(0, 0, At, B0); PG8_MMA(0, 1, At, B1); PG8_BAR; PG8_SCHED;
;     ...
;         cur = nxt; cA = nA; cB = nB; ++ui;
;         if (wr == 1) PG8_BAR;
.LBB0_318:
	s_add_u32 s31, s72, 0x100
	v_mov_b32_e32 v2, 0
	s_addc_u32 s93, s73, 0
	s_mov_b32 s29, -2
	v_mov_b32_e32 v3, v2
	v_mov_b32_e32 v4, v2
	v_mov_b32_e32 v5, v2
	v_mov_b32_e32 v6, v2
	v_mov_b32_e32 v7, v2
	v_mov_b32_e32 v8, v2
	v_mov_b32_e32 v9, v2
	v_mov_b32_e32 v18, v2
	v_mov_b32_e32 v19, v2
	v_mov_b32_e32 v20, v2
	v_mov_b32_e32 v21, v2
	v_mov_b32_e32 v22, v2
	v_mov_b32_e32 v23, v2
	v_mov_b32_e32 v24, v2
	v_mov_b32_e32 v25, v2
	v_mov_b32_e32 v34, v2
	v_mov_b32_e32 v35, v2
	v_mov_b32_e32 v36, v2
	v_mov_b32_e32 v37, v2
	v_mov_b32_e32 v38, v2
	v_mov_b32_e32 v39, v2
	v_mov_b32_e32 v40, v2
	v_mov_b32_e32 v41, v2
	v_mov_b32_e32 v50, v2
	v_mov_b32_e32 v51, v2
	v_mov_b32_e32 v52, v2
	v_mov_b32_e32 v53, v2
	v_mov_b32_e32 v54, v2
	v_mov_b32_e32 v55, v2
	v_mov_b32_e32 v56, v2
	v_mov_b32_e32 v57, v2
	v_mov_b32_e32 v10, v2
	v_mov_b32_e32 v11, v2
	v_mov_b32_e32 v12, v2
	v_mov_b32_e32 v13, v2
	v_mov_b32_e32 v14, v2
	v_mov_b32_e32 v15, v2
	v_mov_b32_e32 v16, v2
	v_mov_b32_e32 v17, v2
	v_mov_b32_e32 v26, v2
	v_mov_b32_e32 v27, v2
	v_mov_b32_e32 v28, v2
	v_mov_b32_e32 v29, v2
	v_mov_b32_e32 v30, v2
	v_mov_b32_e32 v31, v2
	v_mov_b32_e32 v32, v2
	v_mov_b32_e32 v33, v2
	v_mov_b32_e32 v42, v2
	v_mov_b32_e32 v43, v2
	v_mov_b32_e32 v44, v2
	v_mov_b32_e32 v45, v2
	v_mov_b32_e32 v46, v2
	v_mov_b32_e32 v47, v2
	v_mov_b32_e32 v48, v2
	v_mov_b32_e32 v49, v2
	v_mov_b32_e32 v58, v2
	v_mov_b32_e32 v59, v2
	v_mov_b32_e32 v60, v2
	v_mov_b32_e32 v61, v2
	v_mov_b32_e32 v62, v2
	v_mov_b32_e32 v63, v2
	v_mov_b32_e32 v64, v2
	v_mov_b32_e32 v65, v2
	v_mov_b32_e32 v66, v2
	v_mov_b32_e32 v67, v2
	v_mov_b32_e32 v68, v2
	v_mov_b32_e32 v69, v2
	v_mov_b32_e32 v70, v2
	v_mov_b32_e32 v71, v2
	v_mov_b32_e32 v72, v2
	v_mov_b32_e32 v73, v2
	s_waitcnt vmcnt(0)
	v_mov_b32_e32 v82, v2
	v_mov_b32_e32 v83, v2
	v_mov_b32_e32 v84, v2
	v_mov_b32_e32 v85, v2
	v_mov_b32_e32 v86, v2
	v_mov_b32_e32 v87, v2
	v_mov_b32_e32 v88, v2
	v_mov_b32_e32 v89, v2
	v_mov_b32_e32 v98, v2
	v_mov_b32_e32 v99, v2
	v_mov_b32_e32 v100, v2
	v_mov_b32_e32 v101, v2
	v_mov_b32_e32 v102, v2
	v_mov_b32_e32 v103, v2
	v_mov_b32_e32 v104, v2
	v_mov_b32_e32 v105, v2
	v_mov_b32_e32 v114, v2
	v_mov_b32_e32 v115, v2
	v_mov_b32_e32 v116, v2
	v_mov_b32_e32 v117, v2
	v_mov_b32_e32 v118, v2
	v_mov_b32_e32 v119, v2
	v_mov_b32_e32 v120, v2
	v_mov_b32_e32 v121, v2
	v_mov_b32_e32 v74, v2
	v_mov_b32_e32 v75, v2
	v_mov_b32_e32 v76, v2
	v_mov_b32_e32 v77, v2
	v_mov_b32_e32 v78, v2
	v_mov_b32_e32 v79, v2
	v_mov_b32_e32 v80, v2
	v_mov_b32_e32 v81, v2
	v_mov_b32_e32 v90, v2
	v_mov_b32_e32 v91, v2
	v_mov_b32_e32 v92, v2
	v_mov_b32_e32 v93, v2
	v_mov_b32_e32 v94, v2
	v_mov_b32_e32 v95, v2
	v_mov_b32_e32 v96, v2
	v_mov_b32_e32 v97, v2
	v_mov_b32_e32 v106, v2
	v_mov_b32_e32 v107, v2
	v_mov_b32_e32 v108, v2
	v_mov_b32_e32 v109, v2
	v_mov_b32_e32 v110, v2
	v_mov_b32_e32 v111, v2
	v_mov_b32_e32 v112, v2
	v_mov_b32_e32 v113, v2
	v_mov_b32_e32 v122, v2
	v_mov_b32_e32 v123, v2
	v_mov_b32_e32 v124, v2
	v_mov_b32_e32 v125, v2
	v_mov_b32_e32 v126, v2
	v_mov_b32_e32 v127, v2
	v_mov_b32_e32 v128, v2
	v_mov_b32_e32 v129, v2
	v_add_u32_e32 v201, 0x80, v0
	v_add_u32_e32 v247, 0x80, v158
	v_add_u32_e32 v249, 0x80, v154
	v_add_u32_e32 v251, 0x80, v156
	v_readlane_b32 vcc_lo, v255, 21
	s_nop 3
	s_cmp_eq_u32 vcc_lo, 1
	s_cbranch_scc0 .Lnb_319
	s_barrier
	s_mov_b32 vcc_lo, 0
	s_nop 0
	v_writelane_b32 v255, vcc_lo, 21
.Lnb_319:
.LBB0_319:
	s_add_u32 vcc_lo, s10, 0x100
	s_addc_u32 vcc_hi, s11, 0
	s_add_i32 s39, 0, 0x10000
	s_cmp_eq_u32 s29, 40
	s_cselect_b32 s75, s21, vcc_hi
	s_cselect_b32 s74, s20, vcc_lo
	s_cselect_b32 s73, s1, s93
	s_cselect_b32 s72, s0, s31
	s_add_i32 s30, 0, 0x14000
	v_add_u32_e32 v142, s39, v174
	v_add_u32_e32 v168, s30, v174
	ds_read_b128 v[130:133], v142
	ds_read_b128 v[134:137], v142 offset:1024
	ds_read_b128 v[138:141], v142 offset:2048
	ds_read_b128 v[142:145], v142 offset:3072
	ds_read_b128 v[146:149], v168
	ds_read_b128 v[150:153], v168 offset:1024
	ds_read_b128 v[164:167], v168 offset:2048
	ds_read_b128 v[168:171], v168 offset:3072
	s_add_i32 m0, s46, 0xc000
	ds_read_b128 v[192:195], v190
	ds_read_b128 v[204:207], v190 offset:1024
	ds_read_b128 v[208:211], v190 offset:2048
	ds_read_b128 v[212:215], v190 offset:3072
	ds_read_b128 v[216:219], v190 offset:4096
	ds_read_b128 v[220:223], v190 offset:5120
	ds_read_b128 v[224:227], v190 offset:6144
	ds_read_b128 v[242:245], v190 offset:7168
	global_load_lds_dwordx4 v162, s[10:11]
	s_add_i32 m0, s46, 0xe000
	s_nop 0
	global_load_lds_dwordx4 v160, s[10:11]
	s_waitcnt vmcnt(8)
	s_waitcnt lgkmcnt(0)
	s_setprio 1
	s_barrier
; #define PG8_STAGE(bufoff, gbase, voff) do { _Pragma("unroll") for (int _i = 0; _i < 2; ++_i) \
;         __builtin_amdgcn_global_load_lds((const gunsigned*)((const gchar*)(gbase) + (voff)[_i]), (LAS unsigned*)(lds + (bufoff) + ldsw + _i * 8192), 16, 0, 0); } while (0)
; #define PG8_LDA(dst, b, h) do { _Pragma("unroll") for (int m = 0; m < 4; ++m) _Pragma("unroll") for (int k = 0; k < 2; ++k) dst[m][k] = *(const LAS bf16x8*)(lds + PG8_SA(b, h) + aoff + m * 2048 + k * 1024); } while (0)
; #define PG8_LDB(dst, b, h) do { _Pragma("unroll") for (int n = 0; n < 2; ++n) _Pragma("unroll") for (int k = 0; k < 2; ++k) dst[n][k] = *(const LAS bf16x8*)(lds + PG8_SB(b, h) + boff + n * 2048 + k * 1024); } while (0)
; #define PG8_MMA(ai, bj, At, Bt) do { __builtin_amdgcn_s_setprio(1); _Pragma("unroll") for (int m = 0; m < 4; ++m) _Pragma("unroll") for (int n = 0; n < 2; ++n) _Pragma("unroll") for (int k = 0; k < 2; ++k) \
;         acc[ai][bj][m][n] = __builtin_amdgcn_mfma_f32_16x16x32_bf16(Bt[n][k], At[m][k], acc[ai][bj][m][n], 0, 0, 0); __builtin_amdgcn_s_setprio(0); } while (0)
; #define PG8_WAIT_V(n) asm volatile("s_waitcnt vmcnt(" #n ")" ::: "memory")
; #define PG8_WAIT_L(n) asm volatile("s_waitcnt lgkmcnt(" #n ")" ::: "memory")
; #define PG8_BAR __builtin_amdgcn_s_barrier()
; #define PG8_SCHED __builtin_amdgcn_sched_barrier(0)
; template <class Epi, class Sched>
; __device__ __forceinline__ void gemm_phase(LAS unsigned char* lds, const int tid, const Gemm g, const Sched& S, const Epi& E) {
;     ...
;             PG8_WAIT_V(8); PG8_WAIT_L(0); PG8_BAR; PG8_MMA(0, 0, At, B0); PG8_MMA(0, 1, At, B1); PG8_BAR; PG8_SCHED;
;             PG8_LDA(At, 0, 1); PG8_STAGE(PG8_SB(0, 0), b2, voffB); PG8_STAGE(PG8_SB(0, 1), b2 + hstep, voffB); PG8_STAGE(PG8_SA(0, 0), a2, voffA);
;             PG8_WAIT_V(8); PG8_WAIT_L(0); PG8_BAR; PG8_MMA(1, 0, At, B0); PG8_MMA(1, 1, At, B1); PG8_BAR; PG8_SCHED;
;             PG8_LDB(B0, 1, 0); PG8_LDB(B1, 1, 1); PG8_SCHED; PG8_LDA(At, 1, 0); PG8_STAGE(PG8_SA(0, 1), a2 + hstep, voffA);
;             PG8_WAIT_V(8); PG8_WAIT_L(0); PG8_BAR; PG8_MMA(0, 0, At, B0); PG8_MMA(0, 1, At, B1); PG8_BAR; PG8_SCHED;
	v_mfma_f32_16x16x32_bf16 v[126:129], v[130:133], v[192:195], v[126:129]
	v_mfma_f32_16x16x32_bf16 v[122:125], v[138:141], v[192:195], v[122:125]
	v_mfma_f32_16x16x32_bf16 v[110:113], v[130:133], v[208:211], v[110:113]
	v_mfma_f32_16x16x32_bf16 v[106:109], v[138:141], v[208:211], v[106:109]
	v_mfma_f32_16x16x32_bf16 v[94:97], v[130:133], v[216:219], v[94:97]
	v_mfma_f32_16x16x32_bf16 v[90:93], v[138:141], v[216:219], v[90:93]
	v_mfma_f32_16x16x32_bf16 v[78:81], v[130:133], v[224:227], v[78:81]
	v_mfma_f32_16x16x32_bf16 v[74:77], v[138:141], v[224:227], v[74:77]
	v_mfma_f32_16x16x32_bf16 v[126:129], v[134:137], v[204:207], v[126:129]
	v_mfma_f32_16x16x32_bf16 v[122:125], v[142:145], v[204:207], v[122:125]
	v_mfma_f32_16x16x32_bf16 v[110:113], v[134:137], v[212:215], v[110:113]
	v_mfma_f32_16x16x32_bf16 v[106:109], v[142:145], v[212:215], v[106:109]
	v_mfma_f32_16x16x32_bf16 v[94:97], v[134:137], v[220:223], v[94:97]
	v_mfma_f32_16x16x32_bf16 v[90:93], v[142:145], v[220:223], v[90:93]
	v_mfma_f32_16x16x32_bf16 v[78:81], v[134:137], v[242:245], v[78:81]
	v_mfma_f32_16x16x32_bf16 v[74:77], v[142:145], v[242:245], v[74:77]
	s_setprio 0
	s_setprio 1
	v_mfma_f32_16x16x32_bf16 v[118:121], v[146:149], v[192:195], v[118:121]
	v_mfma_f32_16x16x32_bf16 v[114:117], v[164:167], v[192:195], v[114:117]
	v_mfma_f32_16x16x32_bf16 v[102:105], v[146:149], v[208:211], v[102:105]
	v_mfma_f32_16x16x32_bf16 v[98:101], v[164:167], v[208:211], v[98:101]
	v_mfma_f32_16x16x32_bf16 v[86:89], v[146:149], v[216:219], v[86:89]
	v_mfma_f32_16x16x32_bf16 v[82:85], v[164:167], v[216:219], v[82:85]
	v_mfma_f32_16x16x32_bf16 v[70:73], v[146:149], v[224:227], v[70:73]
	v_mfma_f32_16x16x32_bf16 v[66:69], v[164:167], v[224:227], v[66:69]
	v_mfma_f32_16x16x32_bf16 v[118:121], v[150:153], v[204:207], v[118:121]
	v_mfma_f32_16x16x32_bf16 v[114:117], v[168:171], v[204:207], v[114:117]
	v_mfma_f32_16x16x32_bf16 v[102:105], v[150:153], v[212:215], v[102:105]
	v_mfma_f32_16x16x32_bf16 v[98:101], v[168:171], v[212:215], v[98:101]
	v_mfma_f32_16x16x32_bf16 v[86:89], v[150:153], v[220:223], v[86:89]
	v_mfma_f32_16x16x32_bf16 v[82:85], v[168:171], v[220:223], v[82:85]
	v_mfma_f32_16x16x32_bf16 v[70:73], v[150:153], v[242:245], v[70:73]
	v_mfma_f32_16x16x32_bf16 v[66:69], v[168:171], v[242:245], v[66:69]
	s_barrier
	s_setprio 0
	s_add_i32 s10, s39, s43
	s_mov_b32 m0, s10
	ds_read_b128 v[192:195], v190 offset:16384
	ds_read_b128 v[204:207], v190 offset:17408
	ds_read_b128 v[208:211], v190 offset:18432
	ds_read_b128 v[212:215], v190 offset:19456
	ds_read_b128 v[216:219], v190 offset:20480
	ds_read_b128 v[220:223], v190 offset:21504
	ds_read_b128 v[224:227], v190 offset:22528
	ds_read_b128 v[242:245], v190 offset:23552
	global_load_lds_dwordx4 v0, s[72:73]
	s_add_i32 m0, s10, 0x2000
	s_add_u32 s10, s72, 0xb0000
	s_addc_u32 s11, s73, 0
	s_add_i32 s30, s30, s43
	global_load_lds_dwordx4 v158, s[72:73]
	s_mov_b32 m0, s30
	s_nop 0
	global_load_lds_dwordx4 v0, s[10:11]
	s_add_i32 m0, s30, 0x2000
	s_nop 0
	global_load_lds_dwordx4 v158, s[10:11]
	s_mov_b32 m0, s46
	s_nop 0
	global_load_lds_dwordx4 v154, s[74:75]
	s_mov_b32 m0, s47
	s_nop 0
	global_load_lds_dwordx4 v156, s[74:75]
	s_waitcnt vmcnt(8)
	s_waitcnt lgkmcnt(0)
	s_setprio 1
	s_barrier
	v_mfma_f32_16x16x32_bf16 v[62:65], v[130:133], v[192:195], v[62:65]
	v_mfma_f32_16x16x32_bf16 v[58:61], v[138:141], v[192:195], v[58:61]
	v_mfma_f32_16x16x32_bf16 v[46:49], v[130:133], v[208:211], v[46:49]
	v_mfma_f32_16x16x32_bf16 v[42:45], v[138:141], v[208:211], v[42:45]
	v_mfma_f32_16x16x32_bf16 v[30:33], v[130:133], v[216:219], v[30:33]
	v_mfma_f32_16x16x32_bf16 v[26:29], v[138:141], v[216:219], v[26:29]
	v_mfma_f32_16x16x32_bf16 v[14:17], v[130:133], v[224:227], v[14:17]
	v_mfma_f32_16x16x32_bf16 v[10:13], v[138:141], v[224:227], v[10:13]
	v_mfma_f32_16x16x32_bf16 v[62:65], v[134:137], v[204:207], v[62:65]
	v_mfma_f32_16x16x32_bf16 v[58:61], v[142:145], v[204:207], v[58:61]
	v_mfma_f32_16x16x32_bf16 v[46:49], v[134:137], v[212:215], v[46:49]
	v_mfma_f32_16x16x32_bf16 v[42:45], v[142:145], v[212:215], v[42:45]
	v_mfma_f32_16x16x32_bf16 v[30:33], v[134:137], v[220:223], v[30:33]
	v_mfma_f32_16x16x32_bf16 v[26:29], v[142:145], v[220:223], v[26:29]
	v_mfma_f32_16x16x32_bf16 v[14:17], v[134:137], v[242:245], v[14:17]
	v_mfma_f32_16x16x32_bf16 v[10:13], v[142:145], v[242:245], v[10:13]
	s_setprio 0
	s_setprio 1
	v_mfma_f32_16x16x32_bf16 v[54:57], v[146:149], v[192:195], v[54:57]
	v_mfma_f32_16x16x32_bf16 v[50:53], v[164:167], v[192:195], v[50:53]
	v_mfma_f32_16x16x32_bf16 v[38:41], v[146:149], v[208:211], v[38:41]
	v_mfma_f32_16x16x32_bf16 v[34:37], v[164:167], v[208:211], v[34:37]
	v_mfma_f32_16x16x32_bf16 v[22:25], v[146:149], v[216:219], v[22:25]
	v_mfma_f32_16x16x32_bf16 v[18:21], v[164:167], v[216:219], v[18:21]
	v_mfma_f32_16x16x32_bf16 v[6:9], v[146:149], v[224:227], v[6:9]
	v_mfma_f32_16x16x32_bf16 v[2:5], v[164:167], v[224:227], v[2:5]
	v_mfma_f32_16x16x32_bf16 v[54:57], v[150:153], v[204:207], v[54:57]
	v_mfma_f32_16x16x32_bf16 v[50:53], v[168:171], v[204:207], v[50:53]
	v_mfma_f32_16x16x32_bf16 v[38:41], v[150:153], v[212:215], v[38:41]
	v_mfma_f32_16x16x32_bf16 v[34:37], v[168:171], v[212:215], v[34:37]
	v_mfma_f32_16x16x32_bf16 v[22:25], v[150:153], v[220:223], v[22:25]
	v_mfma_f32_16x16x32_bf16 v[18:21], v[168:171], v[220:223], v[18:21]
	v_mfma_f32_16x16x32_bf16 v[6:9], v[150:153], v[242:245], v[6:9]
	v_mfma_f32_16x16x32_bf16 v[2:5], v[168:171], v[242:245], v[2:5]
	s_barrier
; #define PG8_STAGE(bufoff, gbase, voff) do { _Pragma("unroll") for (int _i = 0; _i < 2; ++_i) \
;         __builtin_amdgcn_global_load_lds((const gunsigned*)((const gchar*)(gbase) + (voff)[_i]), (LAS unsigned*)(lds + (bufoff) + ldsw + _i * 8192), 16, 0, 0); } while (0)
; #define PG8_LDA(dst, b, h) do { _Pragma("unroll") for (int m = 0; m < 4; ++m) _Pragma("unroll") for (int k = 0; k < 2; ++k) dst[m][k] = *(const LAS bf16x8*)(lds + PG8_SA(b, h) + aoff + m * 2048 + k * 1024); } while (0)
; #define PG8_MMA(ai, bj, At, Bt) do { __builtin_amdgcn_s_setprio(1); _Pragma("unroll") for (int m = 0; m < 4; ++m) _Pragma("unroll") for (int n = 0; n < 2; ++n) _Pragma("unroll") for (int k = 0; k < 2; ++k) \
;         acc[ai][bj][m][n] = __builtin_amdgcn_mfma_f32_16x16x32_bf16(Bt[n][k], At[m][k], acc[ai][bj][m][n], 0, 0, 0); __builtin_amdgcn_s_setprio(0); } while (0)
; #define PG8_WAIT_V(n) asm volatile("s_waitcnt vmcnt(" #n ")" ::: "memory")
; #define PG8_WAIT_L(n) asm volatile("s_waitcnt lgkmcnt(" #n ")" ::: "memory")
; #define PG8_BAR __builtin_amdgcn_s_barrier()
; #define PG8_SCHED __builtin_amdgcn_sched_barrier(0)
; template <class Epi, class Sched>
; __device__ __forceinline__ void gemm_phase(LAS unsigned char* lds, const int tid, const Gemm g, const Sched& S, const Epi& E) {
;     ...
;             PG8_WAIT_V(8); PG8_WAIT_L(0); PG8_BAR; PG8_MMA(0, 0, At, B0); PG8_MMA(0, 1, At, B1); PG8_BAR; PG8_SCHED;
;             PG8_LDA(At, 1, 1); PG8_STAGE(PG8_SB(1, 0), b3, voffB); PG8_STAGE(PG8_SB(1, 1), b3 + hstep, voffB); PG8_STAGE(PG8_SA(1, 0), a3, voffA);
;             PG8_WAIT_V(8); PG8_WAIT_L(0); PG8_BAR; PG8_MMA(1, 0, At, B0); PG8_MMA(1, 1, At, B1); PG8_BAR; PG8_SCHED;
;         }
;         if (wr == 0) PG8_BAR;
	s_setprio 0
	s_add_i32 s30, 0, 0x18000
	s_add_i32 s39, 0, 0x1c000
	v_add_u32_e32 v142, s30, v174
	v_add_u32_e32 v168, s39, v174
	ds_read_b128 v[130:133], v142
	ds_read_b128 v[134:137], v142 offset:1024
	ds_read_b128 v[138:141], v142 offset:2048
	ds_read_b128 v[142:145], v142 offset:3072
	ds_read_b128 v[146:149], v168
	ds_read_b128 v[150:153], v168 offset:1024
	ds_read_b128 v[164:167], v168 offset:2048
	ds_read_b128 v[168:171], v168 offset:3072
	s_add_u32 s10, s74, 0xb0000
	s_addc_u32 s11, s75, 0
	s_mov_b32 m0, s48
	ds_read_b128 v[192:195], v190 offset:32768
	ds_read_b128 v[204:207], v190 offset:33792
	ds_read_b128 v[208:211], v190 offset:34816
	ds_read_b128 v[212:215], v190 offset:35840
	ds_read_b128 v[216:219], v190 offset:36864
	ds_read_b128 v[220:223], v190 offset:37888
	ds_read_b128 v[224:227], v190 offset:38912
	ds_read_b128 v[242:245], v190 offset:39936
	global_load_lds_dwordx4 v154, s[10:11]
	s_mov_b32 m0, s49
	s_nop 0
	global_load_lds_dwordx4 v156, s[10:11]
	s_waitcnt vmcnt(8)
	s_waitcnt lgkmcnt(0)
	s_setprio 1
	s_barrier
	v_mfma_f32_16x16x32_bf16 v[126:129], v[130:133], v[192:195], v[126:129]
	v_mfma_f32_16x16x32_bf16 v[122:125], v[138:141], v[192:195], v[122:125]
	v_mfma_f32_16x16x32_bf16 v[110:113], v[130:133], v[208:211], v[110:113]
	v_mfma_f32_16x16x32_bf16 v[106:109], v[138:141], v[208:211], v[106:109]
	v_mfma_f32_16x16x32_bf16 v[94:97], v[130:133], v[216:219], v[94:97]
	v_mfma_f32_16x16x32_bf16 v[90:93], v[138:141], v[216:219], v[90:93]
	v_mfma_f32_16x16x32_bf16 v[78:81], v[130:133], v[224:227], v[78:81]
	v_mfma_f32_16x16x32_bf16 v[74:77], v[138:141], v[224:227], v[74:77]
	v_mfma_f32_16x16x32_bf16 v[126:129], v[134:137], v[204:207], v[126:129]
	v_mfma_f32_16x16x32_bf16 v[122:125], v[142:145], v[204:207], v[122:125]
	v_mfma_f32_16x16x32_bf16 v[110:113], v[134:137], v[212:215], v[110:113]
	v_mfma_f32_16x16x32_bf16 v[106:109], v[142:145], v[212:215], v[106:109]
	v_mfma_f32_16x16x32_bf16 v[94:97], v[134:137], v[220:223], v[94:97]
	v_mfma_f32_16x16x32_bf16 v[90:93], v[142:145], v[220:223], v[90:93]
	v_mfma_f32_16x16x32_bf16 v[78:81], v[134:137], v[242:245], v[78:81]
	v_mfma_f32_16x16x32_bf16 v[74:77], v[142:145], v[242:245], v[74:77]
	s_setprio 0
	s_setprio 1
	v_mfma_f32_16x16x32_bf16 v[118:121], v[146:149], v[192:195], v[118:121]
	v_mfma_f32_16x16x32_bf16 v[114:117], v[164:167], v[192:195], v[114:117]
	v_mfma_f32_16x16x32_bf16 v[102:105], v[146:149], v[208:211], v[102:105]
	v_mfma_f32_16x16x32_bf16 v[98:101], v[164:167], v[208:211], v[98:101]
	v_mfma_f32_16x16x32_bf16 v[86:89], v[146:149], v[216:219], v[86:89]
	v_mfma_f32_16x16x32_bf16 v[82:85], v[164:167], v[216:219], v[82:85]
	v_mfma_f32_16x16x32_bf16 v[70:73], v[146:149], v[224:227], v[70:73]
	v_mfma_f32_16x16x32_bf16 v[66:69], v[164:167], v[224:227], v[66:69]
	v_mfma_f32_16x16x32_bf16 v[118:121], v[150:153], v[204:207], v[118:121]
	v_mfma_f32_16x16x32_bf16 v[114:117], v[168:171], v[204:207], v[114:117]
	v_mfma_f32_16x16x32_bf16 v[102:105], v[150:153], v[212:215], v[102:105]
	v_mfma_f32_16x16x32_bf16 v[98:101], v[168:171], v[212:215], v[98:101]
	v_mfma_f32_16x16x32_bf16 v[86:89], v[150:153], v[220:223], v[86:89]
	v_mfma_f32_16x16x32_bf16 v[82:85], v[168:171], v[220:223], v[82:85]
	v_mfma_f32_16x16x32_bf16 v[70:73], v[150:153], v[242:245], v[70:73]
	v_mfma_f32_16x16x32_bf16 v[66:69], v[168:171], v[242:245], v[66:69]
	s_barrier
	s_setprio 0
	s_add_i32 s10, s30, s43
	s_mov_b32 m0, s10
	ds_read_b128 v[192:195], v190 offset:49152
	ds_read_b128 v[204:207], v190 offset:50176
	ds_read_b128 v[208:211], v190 offset:51200
	ds_read_b128 v[212:215], v190 offset:52224
	ds_read_b128 v[216:219], v190 offset:53248
	ds_read_b128 v[220:223], v190 offset:54272
	ds_read_b128 v[224:227], v190 offset:55296
	ds_read_b128 v[242:245], v190 offset:56320
	global_load_lds_dwordx4 v201, s[72:73]
	s_add_i32 m0, s10, 0x2000
	s_add_u32 s10, s72, 0xb0080
	s_addc_u32 s11, s73, 0
	s_add_i32 s30, s39, s43
	global_load_lds_dwordx4 v247, s[72:73]
	s_mov_b32 m0, s30
	s_nop 0
	global_load_lds_dwordx4 v0, s[10:11]
	s_add_i32 m0, s30, 0x2000
	s_nop 0
	global_load_lds_dwordx4 v158, s[10:11]
	s_mov_b32 m0, s53
	s_nop 0
	global_load_lds_dwordx4 v249, s[74:75]
	s_mov_b32 m0, s54
	s_nop 0
	global_load_lds_dwordx4 v251, s[74:75]
	s_waitcnt vmcnt(8)
	s_waitcnt lgkmcnt(0)
	s_setprio 1
	s_barrier
	v_mfma_f32_16x16x32_bf16 v[62:65], v[130:133], v[192:195], v[62:65]
	v_mfma_f32_16x16x32_bf16 v[58:61], v[138:141], v[192:195], v[58:61]
	v_mfma_f32_16x16x32_bf16 v[46:49], v[130:133], v[208:211], v[46:49]
	v_mfma_f32_16x16x32_bf16 v[42:45], v[138:141], v[208:211], v[42:45]
	v_mfma_f32_16x16x32_bf16 v[30:33], v[130:133], v[216:219], v[30:33]
	v_mfma_f32_16x16x32_bf16 v[26:29], v[138:141], v[216:219], v[26:29]
	v_mfma_f32_16x16x32_bf16 v[14:17], v[130:133], v[224:227], v[14:17]
	v_mfma_f32_16x16x32_bf16 v[10:13], v[138:141], v[224:227], v[10:13]
	v_mfma_f32_16x16x32_bf16 v[62:65], v[134:137], v[204:207], v[62:65]
	v_mfma_f32_16x16x32_bf16 v[58:61], v[142:145], v[204:207], v[58:61]
	v_mfma_f32_16x16x32_bf16 v[46:49], v[134:137], v[212:215], v[46:49]
	v_mfma_f32_16x16x32_bf16 v[42:45], v[142:145], v[212:215], v[42:45]
	v_mfma_f32_16x16x32_bf16 v[30:33], v[134:137], v[220:223], v[30:33]
	v_mfma_f32_16x16x32_bf16 v[26:29], v[142:145], v[220:223], v[26:29]
	v_mfma_f32_16x16x32_bf16 v[14:17], v[134:137], v[242:245], v[14:17]
	v_mfma_f32_16x16x32_bf16 v[10:13], v[142:145], v[242:245], v[10:13]
	s_setprio 0
	s_setprio 1
	v_mfma_f32_16x16x32_bf16 v[54:57], v[146:149], v[192:195], v[54:57]
	v_mfma_f32_16x16x32_bf16 v[50:53], v[164:167], v[192:195], v[50:53]
	v_mfma_f32_16x16x32_bf16 v[38:41], v[146:149], v[208:211], v[38:41]
	v_mfma_f32_16x16x32_bf16 v[34:37], v[164:167], v[208:211], v[34:37]
	v_mfma_f32_16x16x32_bf16 v[22:25], v[146:149], v[216:219], v[22:25]
	v_mfma_f32_16x16x32_bf16 v[18:21], v[164:167], v[216:219], v[18:21]
	v_mfma_f32_16x16x32_bf16 v[6:9], v[146:149], v[224:227], v[6:9]
	v_mfma_f32_16x16x32_bf16 v[2:5], v[164:167], v[224:227], v[2:5]
	v_mfma_f32_16x16x32_bf16 v[54:57], v[150:153], v[204:207], v[54:57]
	v_mfma_f32_16x16x32_bf16 v[50:53], v[168:171], v[204:207], v[50:53]
	v_mfma_f32_16x16x32_bf16 v[38:41], v[150:153], v[212:215], v[38:41]
	v_mfma_f32_16x16x32_bf16 v[34:37], v[168:171], v[212:215], v[34:37]
	v_mfma_f32_16x16x32_bf16 v[22:25], v[150:153], v[220:223], v[22:25]
	v_mfma_f32_16x16x32_bf16 v[18:21], v[168:171], v[220:223], v[18:21]
	v_mfma_f32_16x16x32_bf16 v[6:9], v[150:153], v[242:245], v[6:9]
	v_mfma_f32_16x16x32_bf16 v[2:5], v[168:171], v[242:245], v[2:5]
	s_barrier
	s_setprio 0
	s_add_i32 s29, s29, 2
	s_add_u32 s31, s31, 0x100
	s_addc_u32 s93, s93, 0
	s_cmp_gt_u32 s29, 41
	s_mov_b64 s[10:11], vcc
	s_cbranch_scc0 .LBB0_319
	s_and_b64 vcc, exec, s[16:17]
	s_cbranch_vccz .LBB0_322
	s_barrier

;     __device__ __forceinline__ void operator()(f32x4 (&acc)[2][2][4][2], const Unit& u, int wr, int wc, int fr, int fq, LAS unsigned char* lds, int tid) const {
;     ...
;         asm volatile("s_waitcnt vmcnt(0) lgkmcnt(0)" ::: "memory"); __builtin_amdgcn_s_barrier(); asm volatile("" ::: "memory");
;         if (tid < 256) { const gfloat* p = ssq + (size_t)(u.pm * BM + tid) * 4; f32x4 pv4;
;             asm volatile("global_load_dwordx4 %0, %1, off sc0 sc1\n\ts_waitcnt vmcnt(0)" : "=v"(pv4) : "v"(p) : "memory");
;             rsl[tid] = __builtin_amdgcn_rsqf(((pv4.x + pv4.y) + (pv4.z + pv4.w)) * (1.0f / DM) + EPS); }
;         asm volatile("s_waitcnt vmcnt(0) lgkmcnt(0)" ::: "memory"); __builtin_amdgcn_s_barrier(); asm volatile("" ::: "memory");
;         f32x4 gv[2][2];
; #pragma unroll
;         for (int bj = 0; bj < 2; ++bj)
; #pragma unroll
;             for (int n = 0; n < 2; ++n) gv[bj][n] = *(const gf32x4*)(gain + col0 + bj * HALF + n * 4);
; #pragma unroll
;         for (int ai = 0; ai < 2; ++ai)
; #pragma unroll
;             for (int m = 0; m < 4; ++m) { const int rl = ai * HALF + wr * 64 + m * 16 + fr; const float rs = rsl[rl]; const size_t off = (size_t)(u.pm * BM + rl) * DM + col0;
; #pragma unroll
;                 for (int bj = 0; bj < 2; ++bj)
; #pragma unroll
;                     for (int n = 0; n < 2; ++n) *(gf32x4*)(out + off + bj * HALF + n * 4) = acc[ai][bj][m][n] * rs * gv[bj][n]; }
.LBB0_354:
	s_or_b64 exec, exec, s[10:11]
	v_lshlrev_b64 v[82:83], 2, v[166:167]
	s_waitcnt vmcnt(0) lgkmcnt(0)
	s_barrier
	v_lshl_add_u64 v[2:3], s[60:61], 0, v[82:83]
	global_load_dwordx4 v[14:17], v[2:3], off
	global_load_dwordx4 v[10:13], v[2:3], off offset:16
	global_load_dwordx4 v[6:9], v[2:3], off offset:512
	s_nop 0
	global_load_dwordx4 v[2:5], v[2:3], off offset:528
	v_lshlrev_b64 v[86:87], 12, v[164:165]
	v_lshl_add_u64 v[170:171], s[56:57], 0, v[86:87]
	v_lshl_add_u32 v86, v179, 2, s76
	ds_read_b32 v166, v178
	ds_read_b32 v164, v86
	v_lshl_add_u32 v86, v180, 2, s76
	ds_read_b32 v86, v86
	v_add_u32_e32 v84, s31, v179
	v_add_u32_e32 v168, s31, v180
	v_ashrrev_i32_e32 v85, 31, v84
	v_ashrrev_i32_e32 v169, 31, v168
	v_lshlrev_b64 v[84:85], 12, v[84:85]
	v_lshl_add_u32 v87, v181, 2, s76
	v_lshlrev_b64 v[168:169], 12, v[168:169]
	v_lshl_add_u64 v[84:85], s[56:57], 0, v[84:85]
	s_waitcnt lgkmcnt(2)
	v_pk_mul_f32 v[128:129], v[128:129], v[166:167] op_sel_hi:[1,0]
	v_pk_mul_f32 v[126:127], v[126:127], v[166:167] op_sel_hi:[1,0]
	v_lshl_add_u64 v[170:171], v[170:171], 0, v[82:83]
	v_lshl_add_u64 v[168:169], s[56:57], 0, v[168:169]
	v_lshl_add_u64 v[84:85], v[84:85], 0, v[82:83]
	v_pk_mul_f32 v[124:125], v[124:125], v[166:167] op_sel_hi:[1,0]
	v_pk_mul_f32 v[122:123], v[122:123], v[166:167] op_sel_hi:[1,0]
	v_pk_mul_f32 v[120:121], v[120:121], v[166:167] op_sel_hi:[1,0]
	v_pk_mul_f32 v[118:119], v[118:119], v[166:167] op_sel_hi:[1,0]
	v_pk_mul_f32 v[116:117], v[116:117], v[166:167] op_sel_hi:[1,0]
	v_pk_mul_f32 v[114:115], v[114:115], v[166:167] op_sel_hi:[1,0]
	s_waitcnt lgkmcnt(1)
	v_pk_mul_f32 v[112:113], v[112:113], v[164:165] op_sel_hi:[1,0]
	v_pk_mul_f32 v[110:111], v[110:111], v[164:165] op_sel_hi:[1,0]
	v_pk_mul_f32 v[166:167], v[108:109], v[164:165] op_sel_hi:[1,0]
	v_pk_mul_f32 v[204:205], v[106:107], v[164:165] op_sel_hi:[1,0]
	v_pk_mul_f32 v[206:207], v[104:105], v[164:165] op_sel_hi:[1,0]
	v_pk_mul_f32 v[208:209], v[102:103], v[164:165] op_sel_hi:[1,0]
	v_pk_mul_f32 v[210:211], v[100:101], v[164:165] op_sel_hi:[1,0]
	v_pk_mul_f32 v[164:165], v[98:99], v[164:165] op_sel_hi:[1,0]
	s_waitcnt lgkmcnt(0)
	v_pk_mul_f32 v[212:213], v[96:97], v[86:87] op_sel_hi:[1,0]
	v_pk_mul_f32 v[214:215], v[94:95], v[86:87] op_sel_hi:[1,0]
	v_pk_mul_f32 v[138:139], v[138:139], v[86:87] op_sel_hi:[1,0]
	v_pk_mul_f32 v[216:217], v[140:141], v[86:87] op_sel_hi:[1,0]
	v_pk_mul_f32 v[142:143], v[142:143], v[86:87] op_sel_hi:[1,0]
	v_pk_mul_f32 v[218:219], v[144:145], v[86:87] op_sel_hi:[1,0]
	ds_read_b32 v88, v87
	ds_read_b32 v172, v183
	ds_read_b32 v192, v185
	ds_read_b32 v194, v187
	ds_read_b32 v200, v189
	v_lshl_add_u64 v[168:169], v[168:169], 0, v[82:83]
	s_waitcnt lgkmcnt(3)
	v_pk_mul_f32 v[52:53], v[52:53], v[172:173] op_sel_hi:[1,0]
	v_pk_mul_f32 v[50:51], v[50:51], v[172:173] op_sel_hi:[1,0]
	s_waitcnt lgkmcnt(2)
	v_pk_mul_f32 v[36:37], v[36:37], v[192:193] op_sel_hi:[1,0]
	v_pk_mul_f32 v[34:35], v[34:35], v[192:193] op_sel_hi:[1,0]
	s_waitcnt lgkmcnt(1)
	v_pk_mul_f32 v[20:21], v[20:21], v[194:195] op_sel_hi:[1,0]
	v_pk_mul_f32 v[18:19], v[18:19], v[194:195] op_sel_hi:[1,0]
	v_pk_mul_f32 v[24:25], v[24:25], v[194:195] op_sel_hi:[1,0]
	v_pk_mul_f32 v[22:23], v[22:23], v[194:195] op_sel_hi:[1,0]
	v_pk_mul_f32 v[64:65], v[64:65], v[172:173] op_sel_hi:[1,0]
	v_pk_mul_f32 v[62:63], v[62:63], v[172:173] op_sel_hi:[1,0]
	v_pk_mul_f32 v[48:49], v[48:49], v[192:193] op_sel_hi:[1,0]
	v_pk_mul_f32 v[46:47], v[46:47], v[192:193] op_sel_hi:[1,0]
	v_pk_mul_f32 v[32:33], v[32:33], v[194:195] op_sel_hi:[1,0]
	v_pk_mul_f32 v[30:31], v[30:31], v[194:195] op_sel_hi:[1,0]
	v_pk_mul_f32 v[60:61], v[60:61], v[172:173] op_sel_hi:[1,0]
	v_pk_mul_f32 v[58:59], v[58:59], v[172:173] op_sel_hi:[1,0]
	v_pk_mul_f32 v[44:45], v[44:45], v[192:193] op_sel_hi:[1,0]
	v_pk_mul_f32 v[42:43], v[42:43], v[192:193] op_sel_hi:[1,0]
	v_pk_mul_f32 v[28:29], v[28:29], v[194:195] op_sel_hi:[1,0]
	v_pk_mul_f32 v[26:27], v[26:27], v[194:195] op_sel_hi:[1,0]
	v_pk_mul_f32 v[56:57], v[56:57], v[172:173] op_sel_hi:[1,0]
	v_pk_mul_f32 v[54:55], v[54:55], v[172:173] op_sel_hi:[1,0]
	v_pk_mul_f32 v[40:41], v[40:41], v[192:193] op_sel_hi:[1,0]
	v_pk_mul_f32 v[38:39], v[38:39], v[192:193] op_sel_hi:[1,0]
	s_and_b64 vcc, exec, s[8:9]
	s_mov_b64 s[8:9], -1
	s_waitcnt vmcnt(3)
	v_pk_mul_f32 v[96:97], v[16:17], v[128:129]
	v_pk_mul_f32 v[94:95], v[14:15], v[126:127]
	s_waitcnt vmcnt(2)
	v_pk_mul_f32 v[100:101], v[12:13], v[124:125]
	v_pk_mul_f32 v[98:99], v[10:11], v[122:123]
	s_waitcnt vmcnt(1)
	v_pk_mul_f32 v[104:105], v[8:9], v[120:121]
	v_pk_mul_f32 v[102:103], v[6:7], v[118:119]
	s_waitcnt vmcnt(0)
; #define PG8_BAR __builtin_amdgcn_s_barrier()
;     __device__ __forceinline__ void operator()(f32x4 (&acc)[2][2][4][2], const Unit& u, int wr, int wc, int fr, int fq, LAS unsigned char* lds, int tid) const {
;     ...
; #pragma unroll
;         for (int ai = 0; ai < 2; ++ai)
; #pragma unroll
;             for (int m = 0; m < 4; ++m) { const int rl = ai * HALF + wr * 64 + m * 16 + fr; const float rs = rsl[rl]; const size_t off = (size_t)(u.pm * BM + rl) * DM + col0;
; #pragma unroll
;                 for (int bj = 0; bj < 2; ++bj)
; #pragma unroll
;                     for (int n = 0; n < 2; ++n) *(gf32x4*)(out + off + bj * HALF + n * 4) = acc[ai][bj][m][n] * rs * gv[bj][n]; }
; template <class Epi, class Sched>
; __device__ __forceinline__ void gemm_phase(LAS unsigned char* lds, const int tid, const Gemm g, const Sched& S, const Epi& E) {
;     ...
;         if (!has_next) break;
; #pragma unroll
;         for (int a = 0; a < 2; ++a)
; #pragma unroll
;             for (int b = 0; b < 2; ++b)
; #pragma unroll
;                 for (int m = 0; m < 4; ++m)
; #pragma unroll
;                     for (int n = 0; n < 2; ++n) acc[a][b][m][n] = (f32x4){0.f, 0.f, 0.f, 0.f};
;         cur = nxt; cA = nA; cB = nB; ++ui;
;         if (wr == 1) PG8_BAR;
	v_pk_mul_f32 v[108:109], v[4:5], v[116:117]
	v_pk_mul_f32 v[106:107], v[2:3], v[114:115]
	v_pk_mul_f32 v[112:113], v[16:17], v[112:113]
	v_pk_mul_f32 v[110:111], v[14:15], v[110:111]
	v_pk_mul_f32 v[116:117], v[12:13], v[166:167]
	v_pk_mul_f32 v[114:115], v[10:11], v[204:205]
	v_pk_mul_f32 v[120:121], v[8:9], v[206:207]
	v_pk_mul_f32 v[118:119], v[6:7], v[208:209]
	v_pk_mul_f32 v[124:125], v[4:5], v[210:211]
	v_pk_mul_f32 v[122:123], v[2:3], v[164:165]
	v_pk_mul_f32 v[128:129], v[16:17], v[212:213]
	v_pk_mul_f32 v[126:127], v[14:15], v[214:215]
	v_pk_mul_f32 v[140:141], v[12:13], v[138:139]
	v_pk_mul_f32 v[138:139], v[10:11], v[216:217]
	v_pk_mul_f32 v[144:145], v[8:9], v[142:143]
	v_pk_mul_f32 v[142:143], v[6:7], v[218:219]
	global_store_dwordx4 v[170:171], v[94:97], off
	global_store_dwordx4 v[170:171], v[98:101], off offset:16
	global_store_dwordx4 v[170:171], v[102:105], off offset:512
	global_store_dwordx4 v[170:171], v[106:109], off offset:528
	global_store_dwordx4 v[84:85], v[110:113], off
	global_store_dwordx4 v[84:85], v[114:117], off offset:16
	global_store_dwordx4 v[84:85], v[118:121], off offset:512
	global_store_dwordx4 v[84:85], v[122:125], off offset:528
	global_store_dwordx4 v[168:169], v[126:129], off
	global_store_dwordx4 v[168:169], v[138:141], off offset:16
	global_store_dwordx4 v[168:169], v[142:145], off offset:512
	v_pk_mul_f32 v[84:85], v[90:91], v[86:87] op_sel_hi:[1,0]
	v_pk_mul_f32 v[90:91], v[92:93], v[86:87] op_sel_hi:[1,0]
	v_pk_mul_f32 v[86:87], v[4:5], v[84:85]
	v_pk_mul_f32 v[84:85], v[2:3], v[90:91]
	global_store_dwordx4 v[168:169], v[84:87], off offset:528
	v_pk_mul_f32 v[92:93], v[132:133], v[88:89] op_sel_hi:[1,0]
	v_pk_mul_f32 v[52:53], v[4:5], v[52:53]
	v_add_u32_e32 v84, s31, v181
	v_ashrrev_i32_e32 v85, 31, v84
	v_lshlrev_b64 v[90:91], 12, v[84:85]
	v_pk_mul_f32 v[84:85], v[130:131], v[88:89] op_sel_hi:[1,0]
	v_lshl_add_u64 v[90:91], s[56:57], 0, v[90:91]
	v_pk_mul_f32 v[86:87], v[16:17], v[84:85]
	v_pk_mul_f32 v[84:85], v[14:15], v[92:93]
	v_lshl_add_u64 v[90:91], v[90:91], 0, v[82:83]
	global_store_dwordx4 v[90:91], v[84:87], off
	v_pk_mul_f32 v[92:93], v[136:137], v[88:89] op_sel_hi:[1,0]
	v_pk_mul_f32 v[50:51], v[2:3], v[50:51]
	v_pk_mul_f32 v[84:85], v[134:135], v[88:89] op_sel_hi:[1,0]
	v_pk_mul_f32 v[36:37], v[4:5], v[36:37]
	v_pk_mul_f32 v[86:87], v[12:13], v[84:85]
	v_pk_mul_f32 v[84:85], v[10:11], v[92:93]
	global_store_dwordx4 v[90:91], v[84:87], off offset:16
	v_pk_mul_f32 v[92:93], v[148:149], v[88:89] op_sel_hi:[1,0]
	v_pk_mul_f32 v[34:35], v[2:3], v[34:35]
	v_pk_mul_f32 v[84:85], v[146:147], v[88:89] op_sel_hi:[1,0]
	v_pk_mul_f32 v[20:21], v[4:5], v[20:21]
	v_pk_mul_f32 v[86:87], v[8:9], v[84:85]
	v_pk_mul_f32 v[84:85], v[6:7], v[92:93]
	global_store_dwordx4 v[90:91], v[84:87], off offset:512
	v_pk_mul_f32 v[18:19], v[2:3], v[18:19]
	v_pk_mul_f32 v[24:25], v[8:9], v[24:25]
	v_pk_mul_f32 v[84:85], v[150:151], v[88:89] op_sel_hi:[1,0]
	v_pk_mul_f32 v[88:89], v[152:153], v[88:89] op_sel_hi:[1,0]
	v_pk_mul_f32 v[86:87], v[4:5], v[84:85]
	v_pk_mul_f32 v[84:85], v[2:3], v[88:89]
	global_store_dwordx4 v[90:91], v[84:87], off offset:528
	v_pk_mul_f32 v[22:23], v[6:7], v[22:23]
	v_pk_mul_f32 v[64:65], v[16:17], v[64:65]
	v_add_u32_e32 v84, s31, v182
	v_ashrrev_i32_e32 v85, 31, v84
	v_lshlrev_b64 v[84:85], 12, v[84:85]
	v_lshl_add_u64 v[84:85], s[56:57], 0, v[84:85]
	v_lshl_add_u64 v[84:85], v[84:85], 0, v[82:83]
	global_store_dwordx4 v[84:85], v[50:53], off offset:528
	v_pk_mul_f32 v[62:63], v[14:15], v[62:63]
	v_pk_mul_f32 v[48:49], v[16:17], v[48:49]
	v_add_u32_e32 v50, s31, v184
	v_ashrrev_i32_e32 v51, 31, v50
	v_lshlrev_b64 v[50:51], 12, v[50:51]
	v_lshl_add_u64 v[50:51], s[56:57], 0, v[50:51]
	v_lshl_add_u64 v[50:51], v[50:51], 0, v[82:83]
	global_store_dwordx4 v[50:51], v[34:37], off offset:528
	v_pk_mul_f32 v[46:47], v[14:15], v[46:47]
	v_pk_mul_f32 v[32:33], v[16:17], v[32:33]
	v_add_u32_e32 v34, s31, v186
	v_ashrrev_i32_e32 v35, 31, v34
	v_lshlrev_b64 v[34:35], 12, v[34:35]
	v_lshl_add_u64 v[34:35], s[56:57], 0, v[34:35]
	v_lshl_add_u64 v[34:35], v[34:35], 0, v[82:83]
	global_store_dwordx4 v[34:35], v[18:21], off offset:528
	global_store_dwordx4 v[34:35], v[22:25], off offset:512
	v_pk_mul_f32 v[30:31], v[14:15], v[30:31]
	v_add_u32_e32 v18, s31, v188
	v_ashrrev_i32_e32 v19, 31, v18
	v_lshlrev_b64 v[18:19], 12, v[18:19]
	s_waitcnt lgkmcnt(0)
	v_pk_mul_f32 v[20:21], v[66:67], v[200:201] op_sel_hi:[1,0]
	v_pk_mul_f32 v[22:23], v[70:71], v[200:201] op_sel_hi:[1,0]
	v_lshl_add_u64 v[18:19], s[56:57], 0, v[18:19]
	v_pk_mul_f32 v[16:17], v[16:17], v[20:21]
	v_pk_mul_f32 v[14:15], v[14:15], v[22:23]
	v_lshl_add_u64 v[18:19], v[18:19], 0, v[82:83]
	global_store_dwordx4 v[18:19], v[14:17], off
	v_pk_mul_f32 v[60:61], v[12:13], v[60:61]
	v_pk_mul_f32 v[58:59], v[10:11], v[58:59]
	v_pk_mul_f32 v[14:15], v[68:69], v[200:201] op_sel_hi:[1,0]
	v_pk_mul_f32 v[16:17], v[72:73], v[200:201] op_sel_hi:[1,0]
	v_pk_mul_f32 v[44:45], v[12:13], v[44:45]
	v_pk_mul_f32 v[42:43], v[10:11], v[42:43]
	v_pk_mul_f32 v[28:29], v[12:13], v[28:29]
	v_pk_mul_f32 v[26:27], v[10:11], v[26:27]
	v_pk_mul_f32 v[12:13], v[12:13], v[14:15]
	v_pk_mul_f32 v[10:11], v[10:11], v[16:17]
	global_store_dwordx4 v[18:19], v[10:13], off offset:16
	v_pk_mul_f32 v[56:57], v[8:9], v[56:57]
	v_pk_mul_f32 v[54:55], v[6:7], v[54:55]
	v_pk_mul_f32 v[10:11], v[74:75], v[200:201] op_sel_hi:[1,0]
	v_pk_mul_f32 v[12:13], v[76:77], v[200:201] op_sel_hi:[1,0]
	v_pk_mul_f32 v[40:41], v[8:9], v[40:41]
	v_pk_mul_f32 v[38:39], v[6:7], v[38:39]
	v_pk_mul_f32 v[8:9], v[8:9], v[10:11]
	v_pk_mul_f32 v[6:7], v[6:7], v[12:13]
	global_store_dwordx4 v[18:19], v[6:9], off offset:512
	global_store_dwordx4 v[84:85], v[62:65], off
	global_store_dwordx4 v[84:85], v[58:61], off offset:16
	v_pk_mul_f32 v[6:7], v[78:79], v[200:201] op_sel_hi:[1,0]
	v_pk_mul_f32 v[8:9], v[80:81], v[200:201] op_sel_hi:[1,0]
	v_pk_mul_f32 v[4:5], v[4:5], v[6:7]
	v_pk_mul_f32 v[2:3], v[2:3], v[8:9]
	global_store_dwordx4 v[84:85], v[54:57], off offset:512
	global_store_dwordx4 v[50:51], v[46:49], off
	global_store_dwordx4 v[50:51], v[42:45], off offset:16
	global_store_dwordx4 v[50:51], v[38:41], off offset:512
	global_store_dwordx4 v[34:35], v[30:33], off
	global_store_dwordx4 v[34:35], v[26:29], off offset:16
	global_store_dwordx4 v[18:19], v[2:5], off offset:528
	s_cbranch_vccnz .LBB0_307
	s_andn2_b64 vcc, exec, s[62:63]
	s_cbranch_vccnz .LBB0_306
	s_mov_b32 vcc_lo, 1
	s_nop 0
	v_writelane_b32 v255, vcc_lo, 21
	s_branch .LBB0_306

;     __device__ bool next(int i, Unit& u) const { if (!b.next(i / 3, u)) return false; u.pz = i % 3; return true; }
; #define PG8_STAGE(bufoff, gbase, voff) do { _Pragma("unroll") for (int _i = 0; _i < 2; ++_i) \
;         __builtin_amdgcn_global_load_lds((const gunsigned*)((const gchar*)(gbase) + (voff)[_i]), (LAS unsigned*)(lds + (bufoff) + ldsw + _i * 8192), 16, 0, 0); } while (0)
; #define PG8_LDA(dst, b, h) do { _Pragma("unroll") for (int m = 0; m < 4; ++m) _Pragma("unroll") for (int k = 0; k < 2; ++k) dst[m][k] = *(const LAS bf16x8*)(lds + PG8_SA(b, h) + aoff + m * 2048 + k * 1024); } while (0)
; #define PG8_LDB(dst, b, h) do { _Pragma("unroll") for (int n = 0; n < 2; ++n) _Pragma("unroll") for (int k = 0; k < 2; ++k) dst[n][k] = *(const LAS bf16x8*)(lds + PG8_SB(b, h) + boff + n * 2048 + k * 1024); } while (0)
; #define PG8_WAIT_V(n) asm volatile("s_waitcnt vmcnt(" #n ")" ::: "memory")
; #define PG8_BAR __builtin_amdgcn_s_barrier()
; template <class Epi, class Sched>
; __device__ __forceinline__ void gemm_phase(LAS unsigned char* lds, const int tid, const Gemm g, const Sched& S, const Epi& E) {
;     ...
;         const bool has_next = S.next(ui + 1, nxt);
;         const gchar* nA = has_next ? (const gchar*)g.A + (size_t)nxt.pm * tstep + (size_t)nxt.pz * g.zA : cA;
;         const gchar* nB = has_next ? (const gchar*)g.Bt + (size_t)nxt.pn * tstep + (size_t)nxt.pz * g.zB : cB;
;         for (int t = 0; t < nt; t += 2) {
;             const bool last = (t == nt - 2);
;             const gchar* a1 = cA + (size_t)(t + 1) * kstep;
;             const gchar* a2 = last ? nA : cA + (size_t)(t + 2) * kstep; const gchar* b2 = last ? nB : cB + (size_t)(t + 2) * kstep;
;             const gchar* a3 = a2 + kstep; const gchar* b3 = b2 + kstep;
;             PG8_LDB(B0, 0, 0); PG8_LDB(B1, 0, 1); PG8_SCHED; PG8_LDA(At, 0, 0); PG8_STAGE(PG8_SA(1, 1), a1 + hstep, voffA);
;             PG8_WAIT_V(8); PG8_WAIT_L(0); PG8_BAR; PG8_MMA(0, 0, At, B0); PG8_MMA(0, 1, At, B1); PG8_BAR; PG8_SCHED;
;     ...
; #pragma unroll
;         for (int a = 0; a < 2; ++a)
; #pragma unroll
;             for (int b = 0; b < 2; ++b)
; #pragma unroll
;                 for (int m = 0; m < 4; ++m)
; #pragma unroll
;                     for (int n = 0; n < 2; ++n) acc[a][b][m][n] = (f32x4){0.f, 0.f, 0.f, 0.f};
;         cur = nxt; cA = nA; cB = nB; ++ui;
;         if (wr == 1) PG8_BAR;
.LBB0_368:
	s_ashr_i32 s11, s10, 31
	s_lshl_b64 s[46:47], s[10:11], 19
	s_add_u32 s60, s86, s46
	s_addc_u32 s61, s87, s47
	s_and_b64 s[46:47], s[2:3], exec
	s_cselect_b32 s11, s61, s21
	s_cselect_b32 s12, s60, s20
	s_ashr_i32 s9, s8, 31
	s_lshl_b64 s[46:47], s[8:9], 19
	s_add_u32 s62, s58, s46
	s_addc_u32 s63, s59, s47
	s_and_b64 s[46:47], s[2:3], exec
	s_cselect_b32 s9, s63, s17
	s_cselect_b32 s15, s62, s16
	s_add_u32 s23, s16, 0x100
	s_addc_u32 s24, s17, 0
	s_add_u32 s16, s20, 0x40080
	v_mov_b32_e32 v2, 0
	s_addc_u32 s17, s21, 0
	s_mov_b32 s31, -2
	v_mov_b32_e32 v3, v2
	v_mov_b32_e32 v4, v2
	v_mov_b32_e32 v5, v2
	v_mov_b32_e32 v10, v2
	v_mov_b32_e32 v11, v2
	v_mov_b32_e32 v12, v2
	v_mov_b32_e32 v13, v2
	v_mov_b32_e32 v18, v2
	v_mov_b32_e32 v19, v2
	v_mov_b32_e32 v20, v2
	v_mov_b32_e32 v21, v2
	v_mov_b32_e32 v26, v2
	v_mov_b32_e32 v27, v2
	v_mov_b32_e32 v28, v2
	v_mov_b32_e32 v29, v2
	v_mov_b32_e32 v34, v2
	v_mov_b32_e32 v35, v2
	v_mov_b32_e32 v36, v2
	v_mov_b32_e32 v37, v2
	v_mov_b32_e32 v42, v2
	v_mov_b32_e32 v43, v2
	v_mov_b32_e32 v44, v2
	v_mov_b32_e32 v45, v2
	v_mov_b32_e32 v50, v2
	v_mov_b32_e32 v51, v2
	v_mov_b32_e32 v52, v2
	v_mov_b32_e32 v53, v2
	v_mov_b32_e32 v58, v2
	v_mov_b32_e32 v59, v2
	v_mov_b32_e32 v60, v2
	v_mov_b32_e32 v61, v2
	v_mov_b32_e32 v6, v2
	v_mov_b32_e32 v7, v2
	v_mov_b32_e32 v8, v2
	v_mov_b32_e32 v9, v2
	v_mov_b32_e32 v14, v2
	v_mov_b32_e32 v15, v2
	v_mov_b32_e32 v16, v2
	v_mov_b32_e32 v17, v2
	v_mov_b32_e32 v22, v2
	v_mov_b32_e32 v23, v2
	v_mov_b32_e32 v24, v2
	v_mov_b32_e32 v25, v2
	v_mov_b32_e32 v30, v2
	v_mov_b32_e32 v31, v2
	v_mov_b32_e32 v32, v2
	v_mov_b32_e32 v33, v2
	v_mov_b32_e32 v38, v2
	v_mov_b32_e32 v39, v2
	v_mov_b32_e32 v40, v2
	v_mov_b32_e32 v41, v2
	v_mov_b32_e32 v46, v2
	v_mov_b32_e32 v47, v2
	v_mov_b32_e32 v48, v2
	v_mov_b32_e32 v49, v2
	v_mov_b32_e32 v54, v2
	v_mov_b32_e32 v55, v2
	v_mov_b32_e32 v56, v2
	v_mov_b32_e32 v57, v2
	v_mov_b32_e32 v62, v2
	v_mov_b32_e32 v63, v2
	v_mov_b32_e32 v64, v2
	v_mov_b32_e32 v65, v2
	v_mov_b32_e32 v66, v2
	v_mov_b32_e32 v67, v2
	v_mov_b32_e32 v68, v2
	v_mov_b32_e32 v69, v2
	v_mov_b32_e32 v74, v2
	v_mov_b32_e32 v75, v2
	v_mov_b32_e32 v76, v2
	v_mov_b32_e32 v77, v2
	s_waitcnt vmcnt(0)
	v_mov_b32_e32 v82, v2
	v_mov_b32_e32 v83, v2
	v_mov_b32_e32 v84, v2
	v_mov_b32_e32 v85, v2
	v_mov_b32_e32 v90, v2
	v_mov_b32_e32 v91, v2
	v_mov_b32_e32 v92, v2
	v_mov_b32_e32 v93, v2
	v_mov_b32_e32 v98, v2
	v_mov_b32_e32 v99, v2
	v_mov_b32_e32 v100, v2
	v_mov_b32_e32 v101, v2
	v_mov_b32_e32 v106, v2
	v_mov_b32_e32 v107, v2
	v_mov_b32_e32 v108, v2
	v_mov_b32_e32 v109, v2
	v_mov_b32_e32 v114, v2
	v_mov_b32_e32 v115, v2
	v_mov_b32_e32 v116, v2
	v_mov_b32_e32 v117, v2
	v_mov_b32_e32 v122, v2
	v_mov_b32_e32 v123, v2
	v_mov_b32_e32 v124, v2
	v_mov_b32_e32 v125, v2
	v_mov_b32_e32 v70, v2
	v_mov_b32_e32 v71, v2
	v_mov_b32_e32 v72, v2
	v_mov_b32_e32 v73, v2
	v_mov_b32_e32 v78, v2
	v_mov_b32_e32 v79, v2
	v_mov_b32_e32 v80, v2
	v_mov_b32_e32 v81, v2
	v_mov_b32_e32 v86, v2
	v_mov_b32_e32 v87, v2
	v_mov_b32_e32 v88, v2
	v_mov_b32_e32 v89, v2
	v_mov_b32_e32 v94, v2
	v_mov_b32_e32 v95, v2
	v_mov_b32_e32 v96, v2
	v_mov_b32_e32 v97, v2
	v_mov_b32_e32 v102, v2
	v_mov_b32_e32 v103, v2
	v_mov_b32_e32 v104, v2
	v_mov_b32_e32 v105, v2
	v_mov_b32_e32 v110, v2
	v_mov_b32_e32 v111, v2
	v_mov_b32_e32 v112, v2
	v_mov_b32_e32 v113, v2
	v_mov_b32_e32 v118, v2
	v_mov_b32_e32 v119, v2
	v_mov_b32_e32 v120, v2
	v_mov_b32_e32 v121, v2
	v_mov_b32_e32 v126, v2
	v_mov_b32_e32 v127, v2
	v_mov_b32_e32 v128, v2
	v_mov_b32_e32 v129, v2
	v_add_u32_e32 v141, 0x80, v0
	v_add_u32_e32 v153, 0x80, v130
	v_add_u32_e32 v201, 0x80, v134
	v_add_u32_e32 v225, 0x80, v132
	v_readlane_b32 vcc_lo, v255, 21
	s_nop 3
	s_cmp_eq_u32 vcc_lo, 1
	s_cbranch_scc0 .Lnb_369
	s_barrier
	s_mov_b32 vcc_lo, 0
	s_nop 0
	v_writelane_b32 v255, vcc_lo, 21
.Lnb_369:
.LBB0_369:
	s_add_u32 s20, s16, 0xfffc0080
	s_addc_u32 s21, s17, -1
	s_add_i32 s29, 0, 0x10000
	s_cmp_eq_u32 s31, 12
	s_cselect_b32 s57, s11, s21
	s_cselect_b32 s56, s12, s20
	v_add_u32_e32 v140, s29, v145
	s_cselect_b32 s21, s9, s24
	s_cselect_b32 s20, s15, s23
	s_add_i32 s30, 0, 0x14000
	ds_read_b128 v[146:149], v140
	ds_read_b128 v[156:159], v140 offset:1024
	ds_read_b128 v[160:163], v140 offset:2048
	ds_read_b128 v[164:167], v140 offset:3072
	v_add_u32_e32 v140, s30, v145
	ds_read_b128 v[168:171], v140
	ds_read_b128 v[172:175], v140 offset:1024
	ds_read_b128 v[176:179], v140 offset:2048
	ds_read_b128 v[180:183], v140 offset:3072
	s_add_i32 m0, s73, 0xc000
	ds_read_b128 v[184:187], v155
	ds_read_b128 v[188:191], v155 offset:1024
	ds_read_b128 v[192:195], v155 offset:2048
	ds_read_b128 v[204:207], v155 offset:3072
	ds_read_b128 v[208:211], v155 offset:4096
	ds_read_b128 v[212:215], v155 offset:5120
	ds_read_b128 v[216:219], v155 offset:6144
	ds_read_b128 v[220:223], v155 offset:7168
	global_load_lds_dwordx4 v138, s[16:17]
	s_add_i32 m0, s73, 0xe000
	s_nop 0
	global_load_lds_dwordx4 v136, s[16:17]
	s_waitcnt vmcnt(8)
	s_waitcnt lgkmcnt(0)
	s_setprio 1
	s_barrier
; #define PG8_STAGE(bufoff, gbase, voff) do { _Pragma("unroll") for (int _i = 0; _i < 2; ++_i) \
;         __builtin_amdgcn_global_load_lds((const gunsigned*)((const gchar*)(gbase) + (voff)[_i]), (LAS unsigned*)(lds + (bufoff) + ldsw + _i * 8192), 16, 0, 0); } while (0)
; #define PG8_LDA(dst, b, h) do { _Pragma("unroll") for (int m = 0; m < 4; ++m) _Pragma("unroll") for (int k = 0; k < 2; ++k) dst[m][k] = *(const LAS bf16x8*)(lds + PG8_SA(b, h) + aoff + m * 2048 + k * 1024); } while (0)
; #define PG8_LDB(dst, b, h) do { _Pragma("unroll") for (int n = 0; n < 2; ++n) _Pragma("unroll") for (int k = 0; k < 2; ++k) dst[n][k] = *(const LAS bf16x8*)(lds + PG8_SB(b, h) + boff + n * 2048 + k * 1024); } while (0)
; #define PG8_MMA(ai, bj, At, Bt) do { __builtin_amdgcn_s_setprio(1); _Pragma("unroll") for (int m = 0; m < 4; ++m) _Pragma("unroll") for (int n = 0; n < 2; ++n) _Pragma("unroll") for (int k = 0; k < 2; ++k) \
;         acc[ai][bj][m][n] = __builtin_amdgcn_mfma_f32_16x16x32_bf16(Bt[n][k], At[m][k], acc[ai][bj][m][n], 0, 0, 0); __builtin_amdgcn_s_setprio(0); } while (0)
; #define PG8_WAIT_V(n) asm volatile("s_waitcnt vmcnt(" #n ")" ::: "memory")
; #define PG8_WAIT_L(n) asm volatile("s_waitcnt lgkmcnt(" #n ")" ::: "memory")
; #define PG8_BAR __builtin_amdgcn_s_barrier()
; #define PG8_SCHED __builtin_amdgcn_sched_barrier(0)
; template <class Epi, class Sched>
; __device__ __forceinline__ void gemm_phase(LAS unsigned char* lds, const int tid, const Gemm g, const Sched& S, const Epi& E) {
;     ...
;             PG8_WAIT_V(8); PG8_WAIT_L(0); PG8_BAR; PG8_MMA(0, 0, At, B0); PG8_MMA(0, 1, At, B1); PG8_BAR; PG8_SCHED;
;             PG8_LDA(At, 0, 1); PG8_STAGE(PG8_SB(0, 0), b2, voffB); PG8_STAGE(PG8_SB(0, 1), b2 + hstep, voffB); PG8_STAGE(PG8_SA(0, 0), a2, voffA);
;             PG8_WAIT_V(8); PG8_WAIT_L(0); PG8_BAR; PG8_MMA(1, 0, At, B0); PG8_MMA(1, 1, At, B1); PG8_BAR; PG8_SCHED;
;             PG8_LDB(B0, 1, 0); PG8_LDB(B1, 1, 1); PG8_SCHED; PG8_LDA(At, 1, 0); PG8_STAGE(PG8_SA(0, 1), a2 + hstep, voffA);
;             PG8_WAIT_V(8); PG8_WAIT_L(0); PG8_BAR; PG8_MMA(0, 0, At, B0); PG8_MMA(0, 1, At, B1); PG8_BAR; PG8_SCHED;
	v_mfma_f32_16x16x32_bf16 v[126:129], v[146:149], v[184:187], v[126:129]
	v_mfma_f32_16x16x32_bf16 v[118:121], v[160:163], v[184:187], v[118:121]
	v_mfma_f32_16x16x32_bf16 v[110:113], v[146:149], v[192:195], v[110:113]
	v_mfma_f32_16x16x32_bf16 v[102:105], v[160:163], v[192:195], v[102:105]
	v_mfma_f32_16x16x32_bf16 v[94:97], v[146:149], v[208:211], v[94:97]
	v_mfma_f32_16x16x32_bf16 v[86:89], v[160:163], v[208:211], v[86:89]
	v_mfma_f32_16x16x32_bf16 v[78:81], v[146:149], v[216:219], v[78:81]
	v_mfma_f32_16x16x32_bf16 v[70:73], v[160:163], v[216:219], v[70:73]
	v_mfma_f32_16x16x32_bf16 v[126:129], v[156:159], v[188:191], v[126:129]
	v_mfma_f32_16x16x32_bf16 v[118:121], v[164:167], v[188:191], v[118:121]
	v_mfma_f32_16x16x32_bf16 v[110:113], v[156:159], v[204:207], v[110:113]
	v_mfma_f32_16x16x32_bf16 v[102:105], v[164:167], v[204:207], v[102:105]
	v_mfma_f32_16x16x32_bf16 v[94:97], v[156:159], v[212:215], v[94:97]
	v_mfma_f32_16x16x32_bf16 v[86:89], v[164:167], v[212:215], v[86:89]
	v_mfma_f32_16x16x32_bf16 v[78:81], v[156:159], v[220:223], v[78:81]
	v_mfma_f32_16x16x32_bf16 v[70:73], v[164:167], v[220:223], v[70:73]
	s_setprio 0
	s_setprio 1
	v_mfma_f32_16x16x32_bf16 v[122:125], v[168:171], v[184:187], v[122:125]
	v_mfma_f32_16x16x32_bf16 v[114:117], v[176:179], v[184:187], v[114:117]
	v_mfma_f32_16x16x32_bf16 v[106:109], v[168:171], v[192:195], v[106:109]
	v_mfma_f32_16x16x32_bf16 v[98:101], v[176:179], v[192:195], v[98:101]
	v_mfma_f32_16x16x32_bf16 v[90:93], v[168:171], v[208:211], v[90:93]
	v_mfma_f32_16x16x32_bf16 v[82:85], v[176:179], v[208:211], v[82:85]
	v_mfma_f32_16x16x32_bf16 v[74:77], v[168:171], v[216:219], v[74:77]
	v_mfma_f32_16x16x32_bf16 v[66:69], v[176:179], v[216:219], v[66:69]
	v_mfma_f32_16x16x32_bf16 v[122:125], v[172:175], v[188:191], v[122:125]
	v_mfma_f32_16x16x32_bf16 v[114:117], v[180:183], v[188:191], v[114:117]
	v_mfma_f32_16x16x32_bf16 v[106:109], v[172:175], v[204:207], v[106:109]
	v_mfma_f32_16x16x32_bf16 v[98:101], v[180:183], v[204:207], v[98:101]
	v_mfma_f32_16x16x32_bf16 v[90:93], v[172:175], v[212:215], v[90:93]
	v_mfma_f32_16x16x32_bf16 v[82:85], v[180:183], v[212:215], v[82:85]
	v_mfma_f32_16x16x32_bf16 v[74:77], v[172:175], v[220:223], v[74:77]
	v_mfma_f32_16x16x32_bf16 v[66:69], v[180:183], v[220:223], v[66:69]
	s_barrier
	s_setprio 0
	s_add_i32 s29, s29, s43
	s_mov_b32 m0, s29
	ds_read_b128 v[184:187], v155 offset:16384
	ds_read_b128 v[188:191], v155 offset:17408
	ds_read_b128 v[192:195], v155 offset:18432
	ds_read_b128 v[204:207], v155 offset:19456
	ds_read_b128 v[208:211], v155 offset:20480
	ds_read_b128 v[212:215], v155 offset:21504
	ds_read_b128 v[216:219], v155 offset:22528
	ds_read_b128 v[220:223], v155 offset:23552
	global_load_lds_dwordx4 v0, s[20:21]
	s_add_i32 m0, s29, 0x2000
	s_add_u32 s46, s20, 0x40000
	s_addc_u32 s47, s21, 0
	s_add_i32 s29, s30, s43
	global_load_lds_dwordx4 v130, s[20:21]
	s_mov_b32 m0, s29
	s_nop 0
	global_load_lds_dwordx4 v0, s[46:47]
	s_add_i32 m0, s29, 0x2000
	s_nop 0
	global_load_lds_dwordx4 v130, s[46:47]
	s_mov_b32 m0, s73
	s_nop 0
	global_load_lds_dwordx4 v134, s[56:57]
	s_mov_b32 m0, s74
	s_nop 0
	global_load_lds_dwordx4 v132, s[56:57]
	s_waitcnt vmcnt(8)
	s_waitcnt lgkmcnt(0)
	s_setprio 1
	s_barrier
	v_mfma_f32_16x16x32_bf16 v[62:65], v[146:149], v[184:187], v[62:65]
	v_mfma_f32_16x16x32_bf16 v[54:57], v[160:163], v[184:187], v[54:57]
	v_mfma_f32_16x16x32_bf16 v[46:49], v[146:149], v[192:195], v[46:49]
	v_mfma_f32_16x16x32_bf16 v[38:41], v[160:163], v[192:195], v[38:41]
	v_mfma_f32_16x16x32_bf16 v[30:33], v[146:149], v[208:211], v[30:33]
	v_mfma_f32_16x16x32_bf16 v[22:25], v[160:163], v[208:211], v[22:25]
	v_mfma_f32_16x16x32_bf16 v[14:17], v[146:149], v[216:219], v[14:17]
	v_mfma_f32_16x16x32_bf16 v[6:9], v[160:163], v[216:219], v[6:9]
	v_mfma_f32_16x16x32_bf16 v[62:65], v[156:159], v[188:191], v[62:65]
	v_mfma_f32_16x16x32_bf16 v[54:57], v[164:167], v[188:191], v[54:57]
	v_mfma_f32_16x16x32_bf16 v[46:49], v[156:159], v[204:207], v[46:49]
	v_mfma_f32_16x16x32_bf16 v[38:41], v[164:167], v[204:207], v[38:41]
	v_mfma_f32_16x16x32_bf16 v[30:33], v[156:159], v[212:215], v[30:33]
	v_mfma_f32_16x16x32_bf16 v[22:25], v[164:167], v[212:215], v[22:25]
	v_mfma_f32_16x16x32_bf16 v[14:17], v[156:159], v[220:223], v[14:17]
	v_mfma_f32_16x16x32_bf16 v[6:9], v[164:167], v[220:223], v[6:9]
	s_setprio 0
	s_setprio 1
	v_mfma_f32_16x16x32_bf16 v[58:61], v[168:171], v[184:187], v[58:61]
	v_mfma_f32_16x16x32_bf16 v[50:53], v[176:179], v[184:187], v[50:53]
	v_mfma_f32_16x16x32_bf16 v[42:45], v[168:171], v[192:195], v[42:45]
	v_mfma_f32_16x16x32_bf16 v[34:37], v[176:179], v[192:195], v[34:37]
	v_mfma_f32_16x16x32_bf16 v[26:29], v[168:171], v[208:211], v[26:29]
	v_mfma_f32_16x16x32_bf16 v[18:21], v[176:179], v[208:211], v[18:21]
	v_mfma_f32_16x16x32_bf16 v[10:13], v[168:171], v[216:219], v[10:13]
	v_mfma_f32_16x16x32_bf16 v[2:5], v[176:179], v[216:219], v[2:5]
	v_mfma_f32_16x16x32_bf16 v[58:61], v[172:175], v[188:191], v[58:61]
	v_mfma_f32_16x16x32_bf16 v[50:53], v[180:183], v[188:191], v[50:53]
	v_mfma_f32_16x16x32_bf16 v[42:45], v[172:175], v[204:207], v[42:45]
	v_mfma_f32_16x16x32_bf16 v[34:37], v[180:183], v[204:207], v[34:37]
	v_mfma_f32_16x16x32_bf16 v[26:29], v[172:175], v[212:215], v[26:29]
	v_mfma_f32_16x16x32_bf16 v[18:21], v[180:183], v[212:215], v[18:21]
	v_mfma_f32_16x16x32_bf16 v[10:13], v[172:175], v[220:223], v[10:13]
	v_mfma_f32_16x16x32_bf16 v[2:5], v[180:183], v[220:223], v[2:5]
	s_barrier
; #define PG8_STAGE(bufoff, gbase, voff) do { _Pragma("unroll") for (int _i = 0; _i < 2; ++_i) \
;         __builtin_amdgcn_global_load_lds((const gunsigned*)((const gchar*)(gbase) + (voff)[_i]), (LAS unsigned*)(lds + (bufoff) + ldsw + _i * 8192), 16, 0, 0); } while (0)
; #define PG8_LDA(dst, b, h) do { _Pragma("unroll") for (int m = 0; m < 4; ++m) _Pragma("unroll") for (int k = 0; k < 2; ++k) dst[m][k] = *(const LAS bf16x8*)(lds + PG8_SA(b, h) + aoff + m * 2048 + k * 1024); } while (0)
; #define PG8_MMA(ai, bj, At, Bt) do { __builtin_amdgcn_s_setprio(1); _Pragma("unroll") for (int m = 0; m < 4; ++m) _Pragma("unroll") for (int n = 0; n < 2; ++n) _Pragma("unroll") for (int k = 0; k < 2; ++k) \
;         acc[ai][bj][m][n] = __builtin_amdgcn_mfma_f32_16x16x32_bf16(Bt[n][k], At[m][k], acc[ai][bj][m][n], 0, 0, 0); __builtin_amdgcn_s_setprio(0); } while (0)
; #define PG8_WAIT_V(n) asm volatile("s_waitcnt vmcnt(" #n ")" ::: "memory")
; #define PG8_WAIT_L(n) asm volatile("s_waitcnt lgkmcnt(" #n ")" ::: "memory")
; #define PG8_BAR __builtin_amdgcn_s_barrier()
; #define PG8_SCHED __builtin_amdgcn_sched_barrier(0)
; template <class Epi, class Sched>
; __device__ __forceinline__ void gemm_phase(LAS unsigned char* lds, const int tid, const Gemm g, const Sched& S, const Epi& E) {
;     ...
;             PG8_WAIT_V(8); PG8_WAIT_L(0); PG8_BAR; PG8_MMA(0, 0, At, B0); PG8_MMA(0, 1, At, B1); PG8_BAR; PG8_SCHED;
;             PG8_LDA(At, 1, 1); PG8_STAGE(PG8_SB(1, 0), b3, voffB); PG8_STAGE(PG8_SB(1, 1), b3 + hstep, voffB); PG8_STAGE(PG8_SA(1, 0), a3, voffA);
;             PG8_WAIT_V(8); PG8_WAIT_L(0); PG8_BAR; PG8_MMA(1, 0, At, B0); PG8_MMA(1, 1, At, B1); PG8_BAR; PG8_SCHED;
;         }
;         if (wr == 0) PG8_BAR;
	s_setprio 0
	s_add_i32 s29, 0, 0x18000
	v_add_u32_e32 v142, s29, v145
	s_add_i32 s30, 0, 0x1c000
	ds_read_b128 v[146:149], v142
	ds_read_b128 v[156:159], v142 offset:1024
	ds_read_b128 v[160:163], v142 offset:2048
	ds_read_b128 v[164:167], v142 offset:3072
	v_add_u32_e32 v142, s30, v145
	ds_read_b128 v[168:171], v142
	ds_read_b128 v[172:175], v142 offset:1024
	ds_read_b128 v[176:179], v142 offset:2048
	ds_read_b128 v[180:183], v142 offset:3072
	s_add_u32 s46, s56, 0x40000
	s_addc_u32 s47, s57, 0
	s_mov_b32 m0, s75
	ds_read_b128 v[184:187], v155 offset:32768
	ds_read_b128 v[188:191], v155 offset:33792
	ds_read_b128 v[192:195], v155 offset:34816
	ds_read_b128 v[204:207], v155 offset:35840
	ds_read_b128 v[208:211], v155 offset:36864
	ds_read_b128 v[212:215], v155 offset:37888
	ds_read_b128 v[216:219], v155 offset:38912
	ds_read_b128 v[220:223], v155 offset:39936
	global_load_lds_dwordx4 v134, s[46:47]
	s_mov_b32 m0, s92
	s_nop 0
	global_load_lds_dwordx4 v132, s[46:47]
	s_waitcnt vmcnt(8)
	s_waitcnt lgkmcnt(0)
	s_setprio 1
	s_barrier
	v_mfma_f32_16x16x32_bf16 v[126:129], v[146:149], v[184:187], v[126:129]
	v_mfma_f32_16x16x32_bf16 v[118:121], v[160:163], v[184:187], v[118:121]
	v_mfma_f32_16x16x32_bf16 v[110:113], v[146:149], v[192:195], v[110:113]
	v_mfma_f32_16x16x32_bf16 v[102:105], v[160:163], v[192:195], v[102:105]
	v_mfma_f32_16x16x32_bf16 v[94:97], v[146:149], v[208:211], v[94:97]
	v_mfma_f32_16x16x32_bf16 v[86:89], v[160:163], v[208:211], v[86:89]
	v_mfma_f32_16x16x32_bf16 v[78:81], v[146:149], v[216:219], v[78:81]
	v_mfma_f32_16x16x32_bf16 v[70:73], v[160:163], v[216:219], v[70:73]
	v_mfma_f32_16x16x32_bf16 v[126:129], v[156:159], v[188:191], v[126:129]
	v_mfma_f32_16x16x32_bf16 v[118:121], v[164:167], v[188:191], v[118:121]
	v_mfma_f32_16x16x32_bf16 v[110:113], v[156:159], v[204:207], v[110:113]
	v_mfma_f32_16x16x32_bf16 v[102:105], v[164:167], v[204:207], v[102:105]
	v_mfma_f32_16x16x32_bf16 v[94:97], v[156:159], v[212:215], v[94:97]
	v_mfma_f32_16x16x32_bf16 v[86:89], v[164:167], v[212:215], v[86:89]
	v_mfma_f32_16x16x32_bf16 v[78:81], v[156:159], v[220:223], v[78:81]
	v_mfma_f32_16x16x32_bf16 v[70:73], v[164:167], v[220:223], v[70:73]
	s_setprio 0
	s_setprio 1
	v_mfma_f32_16x16x32_bf16 v[122:125], v[168:171], v[184:187], v[122:125]
	v_mfma_f32_16x16x32_bf16 v[114:117], v[176:179], v[184:187], v[114:117]
	v_mfma_f32_16x16x32_bf16 v[106:109], v[168:171], v[192:195], v[106:109]
	v_mfma_f32_16x16x32_bf16 v[98:101], v[176:179], v[192:195], v[98:101]
	v_mfma_f32_16x16x32_bf16 v[90:93], v[168:171], v[208:211], v[90:93]
	v_mfma_f32_16x16x32_bf16 v[82:85], v[176:179], v[208:211], v[82:85]
	v_mfma_f32_16x16x32_bf16 v[74:77], v[168:171], v[216:219], v[74:77]
	v_mfma_f32_16x16x32_bf16 v[66:69], v[176:179], v[216:219], v[66:69]
	v_mfma_f32_16x16x32_bf16 v[122:125], v[172:175], v[188:191], v[122:125]
	v_mfma_f32_16x16x32_bf16 v[114:117], v[180:183], v[188:191], v[114:117]
	v_mfma_f32_16x16x32_bf16 v[106:109], v[172:175], v[204:207], v[106:109]
	v_mfma_f32_16x16x32_bf16 v[98:101], v[180:183], v[204:207], v[98:101]
	v_mfma_f32_16x16x32_bf16 v[90:93], v[172:175], v[212:215], v[90:93]
	v_mfma_f32_16x16x32_bf16 v[82:85], v[180:183], v[212:215], v[82:85]
	v_mfma_f32_16x16x32_bf16 v[74:77], v[172:175], v[220:223], v[74:77]
	v_mfma_f32_16x16x32_bf16 v[66:69], v[180:183], v[220:223], v[66:69]
	s_barrier
	s_setprio 0
	s_add_i32 s29, s29, s43
	s_mov_b32 m0, s29
	ds_read_b128 v[184:187], v155 offset:49152
	ds_read_b128 v[188:191], v155 offset:50176
	ds_read_b128 v[192:195], v155 offset:51200
	ds_read_b128 v[204:207], v155 offset:52224
	ds_read_b128 v[208:211], v155 offset:53248
	ds_read_b128 v[212:215], v155 offset:54272
	ds_read_b128 v[216:219], v155 offset:55296
	ds_read_b128 v[220:223], v155 offset:56320
	global_load_lds_dwordx4 v141, s[20:21]
	s_add_i32 m0, s29, 0x2000
	s_add_i32 s29, s30, s43
	global_load_lds_dwordx4 v153, s[20:21]
	s_add_u32 s20, s20, 0x40080
	s_addc_u32 s21, s21, 0
	s_mov_b32 m0, s29
	s_nop 0
	global_load_lds_dwordx4 v0, s[20:21]
	s_add_i32 m0, s29, 0x2000
	s_nop 0
	global_load_lds_dwordx4 v130, s[20:21]
	s_mov_b32 m0, s93
	s_nop 0
	global_load_lds_dwordx4 v201, s[56:57]
	s_mov_b32 m0, s44
	s_nop 0
	global_load_lds_dwordx4 v225, s[56:57]
	s_waitcnt vmcnt(8)
	s_waitcnt lgkmcnt(0)
	s_setprio 1
	s_barrier
	v_mfma_f32_16x16x32_bf16 v[62:65], v[146:149], v[184:187], v[62:65]
	v_mfma_f32_16x16x32_bf16 v[54:57], v[160:163], v[184:187], v[54:57]
	v_mfma_f32_16x16x32_bf16 v[46:49], v[146:149], v[192:195], v[46:49]
	v_mfma_f32_16x16x32_bf16 v[38:41], v[160:163], v[192:195], v[38:41]
	v_mfma_f32_16x16x32_bf16 v[30:33], v[146:149], v[208:211], v[30:33]
	v_mfma_f32_16x16x32_bf16 v[22:25], v[160:163], v[208:211], v[22:25]
	v_mfma_f32_16x16x32_bf16 v[14:17], v[146:149], v[216:219], v[14:17]
	v_mfma_f32_16x16x32_bf16 v[6:9], v[160:163], v[216:219], v[6:9]
	v_mfma_f32_16x16x32_bf16 v[62:65], v[156:159], v[188:191], v[62:65]
	v_mfma_f32_16x16x32_bf16 v[54:57], v[164:167], v[188:191], v[54:57]
	v_mfma_f32_16x16x32_bf16 v[46:49], v[156:159], v[204:207], v[46:49]
	v_mfma_f32_16x16x32_bf16 v[38:41], v[164:167], v[204:207], v[38:41]
	v_mfma_f32_16x16x32_bf16 v[30:33], v[156:159], v[212:215], v[30:33]
	v_mfma_f32_16x16x32_bf16 v[22:25], v[164:167], v[212:215], v[22:25]
	v_mfma_f32_16x16x32_bf16 v[14:17], v[156:159], v[220:223], v[14:17]
	v_mfma_f32_16x16x32_bf16 v[6:9], v[164:167], v[220:223], v[6:9]
	s_setprio 0
	s_setprio 1
	v_mfma_f32_16x16x32_bf16 v[58:61], v[168:171], v[184:187], v[58:61]
	v_mfma_f32_16x16x32_bf16 v[50:53], v[176:179], v[184:187], v[50:53]
	v_mfma_f32_16x16x32_bf16 v[42:45], v[168:171], v[192:195], v[42:45]
	v_mfma_f32_16x16x32_bf16 v[34:37], v[176:179], v[192:195], v[34:37]
	v_mfma_f32_16x16x32_bf16 v[26:29], v[168:171], v[208:211], v[26:29]
	v_mfma_f32_16x16x32_bf16 v[18:21], v[176:179], v[208:211], v[18:21]
	v_mfma_f32_16x16x32_bf16 v[10:13], v[168:171], v[216:219], v[10:13]
	v_mfma_f32_16x16x32_bf16 v[2:5], v[176:179], v[216:219], v[2:5]
	v_mfma_f32_16x16x32_bf16 v[58:61], v[172:175], v[188:191], v[58:61]
	v_mfma_f32_16x16x32_bf16 v[50:53], v[180:183], v[188:191], v[50:53]
	v_mfma_f32_16x16x32_bf16 v[42:45], v[172:175], v[204:207], v[42:45]
	v_mfma_f32_16x16x32_bf16 v[34:37], v[180:183], v[204:207], v[34:37]
	v_mfma_f32_16x16x32_bf16 v[26:29], v[172:175], v[212:215], v[26:29]
	v_mfma_f32_16x16x32_bf16 v[18:21], v[180:183], v[212:215], v[18:21]
	v_mfma_f32_16x16x32_bf16 v[10:13], v[172:175], v[220:223], v[10:13]
	v_mfma_f32_16x16x32_bf16 v[2:5], v[180:183], v[220:223], v[2:5]
	s_barrier
	s_setprio 0
	s_add_i32 s31, s31, 2
	s_add_u32 s23, s23, 0x100
	s_addc_u32 s24, s24, 0
	s_add_u32 s16, s16, 0x100
	s_addc_u32 s17, s17, 0
	s_cmp_gt_u32 s31, 13
	s_cbranch_scc0 .LBB0_369
	s_and_b64 vcc, exec, s[6:7]
	s_cbranch_vccz .LBB0_372
	s_barrier

; __device__ __forceinline__ unsigned pk2(float lo, float hi) { f32x2 v = {lo, hi}; bf16x2_t b = __builtin_convertvector(v, bf16x2_t); return __builtin_bit_cast(unsigned, b); }
; __device__ __forceinline__ float sigmoidf_(float x) { return __builtin_amdgcn_rcpf(1.0f + __builtin_amdgcn_exp2f(-x * LOG2E)); }
;     __device__ __forceinline__ void operator()(const f32x4 (&acc)[2][2][4][2], const Unit& u, int wr, int wc, int fr, int fq, LAS unsigned char* lds, int tid) const {
;     ...
;         for (int ai = 0; ai < 2; ++ai)
; #pragma unroll
;             for (int m = 0; m < 4; ++m) { const size_t row = (size_t)(row0 + ai * HALF + m * 16); const float rs = rsv[ai][m]; gbf16* rowp = O + row * FF + col0;
;                 float h[8];
; #pragma unroll
;                 for (int n = 0; n < 2; ++n)
; #pragma unroll
;                     for (int e = 0; e < 4; ++e) { const float g = acc[ai][0][m][n][e] * rs, uu = acc[ai][1][m][n][e] * rs; h[n * 4 + e] = g * sigmoidf_(g) * uu; }
;                 u32x4 w; w.x = pk2(h[0], h[1]); w.y = pk2(h[2], h[3]); w.z = pk2(h[4], h[5]); w.w = pk2(h[6], h[7]);
;                 *(gu32x4*)rowp = w; }
.Lk8_rs_hit:
	s_andn2_b64 vcc, exec, s[2:3]
	v_lshl_or_b32 v174, s1, 7, v151
	v_mov_b32_e32 v170, v226
	v_mov_b32_e32 v166, v236
	v_mov_b32_e32 v162, v237
	v_mov_b32_e32 v158, v244
	v_mov_b32_e32 v154, v245
	v_mov_b32_e32 v150, v246
	v_mov_b32_e32 v144, v247
	v_mov_b32_e32 v142, v248
	v_pk_mul_f32 v[126:127], v[126:127], v[170:171] op_sel_hi:[1,0]
	v_mul_f32_e32 v141, 0xbfb8aa3b, v126
	v_exp_f32_e32 v141, v141
	v_pk_mul_f32 v[122:123], v[122:123], v[170:171] op_sel_hi:[1,0]
	v_pk_mul_f32 v[124:125], v[124:125], v[170:171] op_sel_hi:[1,0]
	v_pk_mul_f32 v[118:119], v[118:119], v[170:171] op_sel_hi:[1,0]
	v_add_f32_e32 v141, 1.0, v141
	v_rcp_f32_e32 v176, v141
	v_mul_f32_e32 v141, 0xbfb8aa3b, v127
	v_exp_f32_e32 v141, v141
	v_pk_mul_f32 v[114:115], v[114:115], v[170:171] op_sel_hi:[1,0]
	v_ashrrev_i32_e32 v175, 31, v174
	v_mov_b64_e32 v[148:149], s[88:89]
	v_add_f32_e32 v141, 1.0, v141
	v_rcp_f32_e32 v177, v141
	v_pk_mul_f32 v[116:117], v[116:117], v[170:171] op_sel_hi:[1,0]
	v_mad_i64_i32 v[172:173], s[0:1], v172, s79, v[148:149]
	v_pk_mul_f32 v[126:127], v[126:127], v[176:177]
	v_pk_mul_f32 v[110:111], v[110:111], v[166:167] op_sel_hi:[1,0]
	v_pk_mul_f32 v[122:123], v[122:123], v[126:127]
	v_pk_mul_f32 v[126:127], v[128:129], v[170:171] op_sel_hi:[1,0]
	v_pk_mul_f32 v[106:107], v[106:107], v[166:167] op_sel_hi:[1,0]
	v_mul_f32_e32 v128, 0xbfb8aa3b, v126
	v_mul_f32_e32 v129, 0xbfb8aa3b, v127
	v_exp_f32_e32 v128, v128
	v_exp_f32_e32 v129, v129
	v_pk_mul_f32 v[108:109], v[108:109], v[166:167] op_sel_hi:[1,0]
	v_pk_mul_f32 v[102:103], v[102:103], v[166:167] op_sel_hi:[1,0]
	v_add_f32_e32 v128, 1.0, v128
	v_add_f32_e32 v129, 1.0, v129
	v_rcp_f32_e32 v128, v128
	v_rcp_f32_e32 v129, v129
	v_pk_mul_f32 v[98:99], v[98:99], v[166:167] op_sel_hi:[1,0]
	v_pk_mul_f32 v[100:101], v[100:101], v[166:167] op_sel_hi:[1,0]
	v_pk_mul_f32 v[94:95], v[94:95], v[162:163] op_sel_hi:[1,0]
	v_pk_mul_f32 v[126:127], v[126:127], v[128:129]
	v_pk_mul_f32 v[90:91], v[90:91], v[162:163] op_sel_hi:[1,0]
	v_pk_mul_f32 v[124:125], v[124:125], v[126:127]
	v_mul_f32_e32 v126, 0xbfb8aa3b, v118
	v_mul_f32_e32 v127, 0xbfb8aa3b, v119
	v_exp_f32_e32 v126, v126
	v_exp_f32_e32 v127, v127
	v_pk_mul_f32 v[92:93], v[92:93], v[162:163] op_sel_hi:[1,0]
	v_pk_mul_f32 v[86:87], v[86:87], v[162:163] op_sel_hi:[1,0]
	v_add_f32_e32 v126, 1.0, v126
	v_add_f32_e32 v127, 1.0, v127
	v_rcp_f32_e32 v126, v126
	v_rcp_f32_e32 v127, v127
	v_pk_mul_f32 v[82:83], v[82:83], v[162:163] op_sel_hi:[1,0]
	v_pk_mul_f32 v[84:85], v[84:85], v[162:163] op_sel_hi:[1,0]
	v_pk_mul_f32 v[78:79], v[78:79], v[158:159] op_sel_hi:[1,0]
	v_pk_mul_f32 v[118:119], v[118:119], v[126:127]
	v_pk_mul_f32 v[74:75], v[74:75], v[158:159] op_sel_hi:[1,0]
	v_pk_mul_f32 v[118:119], v[114:115], v[118:119]
	v_pk_mul_f32 v[114:115], v[120:121], v[170:171] op_sel_hi:[1,0]
	v_cvt_pk_bf16_f32 v118, v118, v119
	v_mul_f32_e32 v120, 0xbfb8aa3b, v114
	v_mul_f32_e32 v121, 0xbfb8aa3b, v115
	v_exp_f32_e32 v120, v120
	v_exp_f32_e32 v121, v121
	v_pk_mul_f32 v[76:77], v[76:77], v[158:159] op_sel_hi:[1,0]
	v_pk_mul_f32 v[70:71], v[70:71], v[158:159] op_sel_hi:[1,0]
	v_add_f32_e32 v120, 1.0, v120
	v_add_f32_e32 v121, 1.0, v121
	v_rcp_f32_e32 v120, v120
	v_rcp_f32_e32 v121, v121
	v_pk_mul_f32 v[66:67], v[66:67], v[158:159] op_sel_hi:[1,0]
	v_pk_mul_f32 v[68:69], v[68:69], v[158:159] op_sel_hi:[1,0]
	v_pk_mul_f32 v[62:63], v[62:63], v[154:155] op_sel_hi:[1,0]
	v_pk_mul_f32 v[114:115], v[114:115], v[120:121]
	v_pk_mul_f32 v[58:59], v[58:59], v[154:155] op_sel_hi:[1,0]
	v_pk_mul_f32 v[120:121], v[116:117], v[114:115]
	v_lshlrev_b64 v[114:115], 1, v[174:175]
	v_lshl_add_u64 v[126:127], v[172:173], 0, v[114:115]
	v_cvt_pk_bf16_f32 v116, v122, v123
	v_cvt_pk_bf16_f32 v117, v124, v125
	v_cvt_pk_bf16_f32 v119, v120, v121
	global_store_dwordx4 v[126:127], v[116:119], off
	v_pk_mul_f32 v[60:61], v[60:61], v[154:155] op_sel_hi:[1,0]
	v_pk_mul_f32 v[54:55], v[54:55], v[154:155] op_sel_hi:[1,0]
	v_mul_f32_e32 v118, 0xbfb8aa3b, v110
	v_mul_f32_e32 v119, 0xbfb8aa3b, v111
	v_exp_f32_e32 v118, v118
	v_exp_f32_e32 v119, v119
	v_mad_i64_i32 v[116:117], s[0:1], v168, s79, v[148:149]
	v_add_f32_e32 v118, 1.0, v118
	v_add_f32_e32 v119, 1.0, v119
	v_rcp_f32_e32 v118, v118
	v_rcp_f32_e32 v119, v119
	v_pk_mul_f32 v[50:51], v[50:51], v[154:155] op_sel_hi:[1,0]
	v_pk_mul_f32 v[52:53], v[52:53], v[154:155] op_sel_hi:[1,0]
	v_pk_mul_f32 v[46:47], v[46:47], v[150:151] op_sel_hi:[1,0]
	v_pk_mul_f32 v[110:111], v[110:111], v[118:119]
	v_pk_mul_f32 v[42:43], v[42:43], v[150:151] op_sel_hi:[1,0]
	v_pk_mul_f32 v[106:107], v[106:107], v[110:111]
	v_pk_mul_f32 v[110:111], v[112:113], v[166:167] op_sel_hi:[1,0]
	v_pk_mul_f32 v[44:45], v[44:45], v[150:151] op_sel_hi:[1,0]
	v_mul_f32_e32 v112, 0xbfb8aa3b, v110
	v_mul_f32_e32 v113, 0xbfb8aa3b, v111
	v_exp_f32_e32 v112, v112
	v_exp_f32_e32 v113, v113
	v_pk_mul_f32 v[38:39], v[38:39], v[150:151] op_sel_hi:[1,0]
	v_pk_mul_f32 v[34:35], v[34:35], v[150:151] op_sel_hi:[1,0]
	v_add_f32_e32 v112, 1.0, v112
	v_add_f32_e32 v113, 1.0, v113
	v_rcp_f32_e32 v112, v112
	v_rcp_f32_e32 v113, v113
	v_pk_mul_f32 v[36:37], v[36:37], v[150:151] op_sel_hi:[1,0]
	v_pk_mul_f32 v[30:31], v[30:31], v[144:145] op_sel_hi:[1,0]
	v_pk_mul_f32 v[26:27], v[26:27], v[144:145] op_sel_hi:[1,0]
	v_pk_mul_f32 v[110:111], v[110:111], v[112:113]
	v_pk_mul_f32 v[28:29], v[28:29], v[144:145] op_sel_hi:[1,0]
	v_pk_mul_f32 v[108:109], v[108:109], v[110:111]
	v_mul_f32_e32 v110, 0xbfb8aa3b, v102
	v_mul_f32_e32 v111, 0xbfb8aa3b, v103
	v_exp_f32_e32 v110, v110
	v_exp_f32_e32 v111, v111
	v_pk_mul_f32 v[22:23], v[22:23], v[144:145] op_sel_hi:[1,0]
	v_pk_mul_f32 v[18:19], v[18:19], v[144:145] op_sel_hi:[1,0]
; __device__ __forceinline__ unsigned pk2(float lo, float hi) { f32x2 v = {lo, hi}; bf16x2_t b = __builtin_convertvector(v, bf16x2_t); return __builtin_bit_cast(unsigned, b); }
; __device__ __forceinline__ float sigmoidf_(float x) { return __builtin_amdgcn_rcpf(1.0f + __builtin_amdgcn_exp2f(-x * LOG2E)); }
;     __device__ __forceinline__ void operator()(const f32x4 (&acc)[2][2][4][2], const Unit& u, int wr, int wc, int fr, int fq, LAS unsigned char* lds, int tid) const {
;     ...
;         for (int ai = 0; ai < 2; ++ai)
; #pragma unroll
;             for (int m = 0; m < 4; ++m) { const size_t row = (size_t)(row0 + ai * HALF + m * 16); const float rs = rsv[ai][m]; gbf16* rowp = O + row * FF + col0;
;                 float h[8];
; #pragma unroll
;                 for (int n = 0; n < 2; ++n)
; #pragma unroll
;                     for (int e = 0; e < 4; ++e) { const float g = acc[ai][0][m][n][e] * rs, uu = acc[ai][1][m][n][e] * rs; h[n * 4 + e] = g * sigmoidf_(g) * uu; }
;                 u32x4 w; w.x = pk2(h[0], h[1]); w.y = pk2(h[2], h[3]); w.z = pk2(h[4], h[5]); w.w = pk2(h[6], h[7]);
;                 *(gu32x4*)rowp = w; }
	v_add_f32_e32 v110, 1.0, v110
	v_add_f32_e32 v111, 1.0, v111
	v_rcp_f32_e32 v110, v110
	v_rcp_f32_e32 v111, v111
	v_pk_mul_f32 v[20:21], v[20:21], v[144:145] op_sel_hi:[1,0]
	v_pk_mul_f32 v[14:15], v[14:15], v[142:143] op_sel_hi:[1,0]
	v_pk_mul_f32 v[10:11], v[10:11], v[142:143] op_sel_hi:[1,0]
	v_pk_mul_f32 v[102:103], v[102:103], v[110:111]
	v_lshl_add_u64 v[110:111], v[116:117], 0, v[114:115]
	v_pk_mul_f32 v[102:103], v[98:99], v[102:103]
	v_pk_mul_f32 v[98:99], v[104:105], v[166:167] op_sel_hi:[1,0]
	v_pk_mul_f32 v[12:13], v[12:13], v[142:143] op_sel_hi:[1,0]
	v_mul_f32_e32 v104, 0xbfb8aa3b, v98
	v_mul_f32_e32 v105, 0xbfb8aa3b, v99
	v_exp_f32_e32 v104, v104
	v_exp_f32_e32 v105, v105
	v_pk_mul_f32 v[6:7], v[6:7], v[142:143] op_sel_hi:[1,0]
	v_pk_mul_f32 v[2:3], v[2:3], v[142:143] op_sel_hi:[1,0]
	v_add_f32_e32 v104, 1.0, v104
	v_add_f32_e32 v105, 1.0, v105
	v_rcp_f32_e32 v104, v104
	v_rcp_f32_e32 v105, v105
	v_pk_mul_f32 v[4:5], v[4:5], v[142:143] op_sel_hi:[1,0]
	v_pk_mul_f32 v[98:99], v[98:99], v[104:105]
	s_nop 0
	v_pk_mul_f32 v[104:105], v[100:101], v[98:99]
	v_cvt_pk_bf16_f32 v98, v106, v107
	v_cvt_pk_bf16_f32 v99, v108, v109
	v_cvt_pk_bf16_f32 v100, v102, v103
	v_cvt_pk_bf16_f32 v101, v104, v105
	global_store_dwordx4 v[110:111], v[98:101], off
	s_nop 1
	v_mul_f32_e32 v100, 0xbfb8aa3b, v94
	v_mul_f32_e32 v101, 0xbfb8aa3b, v95
	v_exp_f32_e32 v100, v100
	v_exp_f32_e32 v101, v101
	v_mad_i64_i32 v[98:99], s[0:1], v164, s79, v[148:149]
	v_add_f32_e32 v100, 1.0, v100
	v_add_f32_e32 v101, 1.0, v101
	v_rcp_f32_e32 v100, v100
	v_rcp_f32_e32 v101, v101
	s_nop 0
	v_pk_mul_f32 v[94:95], v[94:95], v[100:101]
	s_nop 0
	v_pk_mul_f32 v[90:91], v[90:91], v[94:95]
	v_pk_mul_f32 v[94:95], v[96:97], v[162:163] op_sel_hi:[1,0]
	s_nop 0
	v_mul_f32_e32 v96, 0xbfb8aa3b, v94
	v_mul_f32_e32 v97, 0xbfb8aa3b, v95
	v_exp_f32_e32 v96, v96
	v_exp_f32_e32 v97, v97
	v_add_f32_e32 v96, 1.0, v96
	v_add_f32_e32 v97, 1.0, v97
	v_rcp_f32_e32 v96, v96
	v_rcp_f32_e32 v97, v97
	s_nop 0
	v_pk_mul_f32 v[94:95], v[94:95], v[96:97]
	s_nop 0
	v_pk_mul_f32 v[92:93], v[92:93], v[94:95]
	v_mul_f32_e32 v94, 0xbfb8aa3b, v86
	v_mul_f32_e32 v95, 0xbfb8aa3b, v87
	v_exp_f32_e32 v94, v94
	v_exp_f32_e32 v95, v95
	v_add_f32_e32 v94, 1.0, v94
	v_add_f32_e32 v95, 1.0, v95
	v_rcp_f32_e32 v94, v94
	v_rcp_f32_e32 v95, v95
	s_nop 0
	v_pk_mul_f32 v[86:87], v[86:87], v[94:95]
	s_nop 0
	v_pk_mul_f32 v[86:87], v[82:83], v[86:87]
	v_pk_mul_f32 v[82:83], v[88:89], v[162:163] op_sel_hi:[1,0]
	v_lshl_add_u64 v[94:95], v[98:99], 0, v[114:115]
	v_mul_f32_e32 v88, 0xbfb8aa3b, v82
	v_mul_f32_e32 v89, 0xbfb8aa3b, v83
	v_exp_f32_e32 v88, v88
	v_exp_f32_e32 v89, v89
	v_add_f32_e32 v88, 1.0, v88
	v_add_f32_e32 v89, 1.0, v89
	v_rcp_f32_e32 v88, v88
	v_rcp_f32_e32 v89, v89
	s_nop 0
	v_pk_mul_f32 v[82:83], v[82:83], v[88:89]
	s_nop 0
	v_pk_mul_f32 v[88:89], v[84:85], v[82:83]
	v_cvt_pk_bf16_f32 v82, v90, v91
	v_cvt_pk_bf16_f32 v83, v92, v93
	v_cvt_pk_bf16_f32 v84, v86, v87
	v_cvt_pk_bf16_f32 v85, v88, v89
	global_store_dwordx4 v[94:95], v[82:85], off
	s_nop 1
	v_mul_f32_e32 v84, 0xbfb8aa3b, v78
	v_mul_f32_e32 v85, 0xbfb8aa3b, v79
	v_exp_f32_e32 v84, v84
	v_exp_f32_e32 v85, v85
	v_mad_i64_i32 v[82:83], s[0:1], v160, s79, v[148:149]
	v_add_f32_e32 v84, 1.0, v84
	v_add_f32_e32 v85, 1.0, v85
	v_rcp_f32_e32 v84, v84
	v_rcp_f32_e32 v85, v85
	s_nop 0
	v_pk_mul_f32 v[78:79], v[78:79], v[84:85]
	s_nop 0
	v_pk_mul_f32 v[74:75], v[74:75], v[78:79]
	v_pk_mul_f32 v[78:79], v[80:81], v[158:159] op_sel_hi:[1,0]
	s_nop 0
	v_mul_f32_e32 v80, 0xbfb8aa3b, v78
	v_mul_f32_e32 v81, 0xbfb8aa3b, v79
	v_exp_f32_e32 v80, v80
	v_exp_f32_e32 v81, v81
	v_add_f32_e32 v80, 1.0, v80
	v_add_f32_e32 v81, 1.0, v81
	v_rcp_f32_e32 v80, v80
	v_rcp_f32_e32 v81, v81
	s_nop 0
	v_pk_mul_f32 v[78:79], v[78:79], v[80:81]
	s_nop 0
	v_pk_mul_f32 v[76:77], v[76:77], v[78:79]
	v_mul_f32_e32 v78, 0xbfb8aa3b, v70
	v_mul_f32_e32 v79, 0xbfb8aa3b, v71
	v_exp_f32_e32 v78, v78
	v_exp_f32_e32 v79, v79
	v_add_f32_e32 v78, 1.0, v78
	v_add_f32_e32 v79, 1.0, v79
	v_rcp_f32_e32 v78, v78
	v_rcp_f32_e32 v79, v79
	s_nop 0
	v_pk_mul_f32 v[70:71], v[70:71], v[78:79]
	s_nop 0
	v_pk_mul_f32 v[70:71], v[66:67], v[70:71]
	v_pk_mul_f32 v[66:67], v[72:73], v[158:159] op_sel_hi:[1,0]
	v_lshl_add_u64 v[78:79], v[82:83], 0, v[114:115]
	v_mul_f32_e32 v72, 0xbfb8aa3b, v66
	v_mul_f32_e32 v73, 0xbfb8aa3b, v67
	v_exp_f32_e32 v72, v72
	v_exp_f32_e32 v73, v73
	v_add_f32_e32 v72, 1.0, v72
	v_add_f32_e32 v73, 1.0, v73
	v_rcp_f32_e32 v72, v72
	v_rcp_f32_e32 v73, v73
	s_nop 0
	v_pk_mul_f32 v[66:67], v[66:67], v[72:73]
	s_nop 0
	v_pk_mul_f32 v[72:73], v[68:69], v[66:67]
	v_cvt_pk_bf16_f32 v66, v74, v75
	v_cvt_pk_bf16_f32 v67, v76, v77
	v_cvt_pk_bf16_f32 v68, v70, v71
	v_cvt_pk_bf16_f32 v69, v72, v73
	global_store_dwordx4 v[78:79], v[66:69], off
	s_nop 1
	v_mul_f32_e32 v68, 0xbfb8aa3b, v62
	v_mul_f32_e32 v69, 0xbfb8aa3b, v63
	v_exp_f32_e32 v68, v68
	v_exp_f32_e32 v69, v69
	v_mad_i64_i32 v[66:67], s[0:1], v156, s79, v[148:149]
	v_add_f32_e32 v68, 1.0, v68
	v_add_f32_e32 v69, 1.0, v69
	v_rcp_f32_e32 v68, v68
	v_rcp_f32_e32 v69, v69
	s_nop 0
	v_pk_mul_f32 v[62:63], v[62:63], v[68:69]
	s_nop 0
	v_pk_mul_f32 v[58:59], v[58:59], v[62:63]
	v_pk_mul_f32 v[62:63], v[64:65], v[154:155] op_sel_hi:[1,0]
	s_nop 0
	v_mul_f32_e32 v64, 0xbfb8aa3b, v62
	v_mul_f32_e32 v65, 0xbfb8aa3b, v63
	v_exp_f32_e32 v64, v64
	v_exp_f32_e32 v65, v65
	v_add_f32_e32 v64, 1.0, v64
	v_add_f32_e32 v65, 1.0, v65
	v_rcp_f32_e32 v64, v64
	v_rcp_f32_e32 v65, v65
	s_nop 0
	v_pk_mul_f32 v[62:63], v[62:63], v[64:65]
	s_nop 0
	v_pk_mul_f32 v[60:61], v[60:61], v[62:63]
	v_mul_f32_e32 v62, 0xbfb8aa3b, v54
	v_mul_f32_e32 v63, 0xbfb8aa3b, v55
; __device__ __forceinline__ unsigned pk2(float lo, float hi) { f32x2 v = {lo, hi}; bf16x2_t b = __builtin_convertvector(v, bf16x2_t); return __builtin_bit_cast(unsigned, b); }
; __device__ __forceinline__ float sigmoidf_(float x) { return __builtin_amdgcn_rcpf(1.0f + __builtin_amdgcn_exp2f(-x * LOG2E)); }
; #define PG8_BAR __builtin_amdgcn_s_barrier()
;     __device__ __forceinline__ void operator()(const f32x4 (&acc)[2][2][4][2], const Unit& u, int wr, int wc, int fr, int fq, LAS unsigned char* lds, int tid) const {
;     ...
;             for (int m = 0; m < 4; ++m) { const size_t row = (size_t)(row0 + ai * HALF + m * 16); const float rs = rsv[ai][m]; gbf16* rowp = O + row * FF + col0;
;                 float h[8];
; #pragma unroll
;                 for (int n = 0; n < 2; ++n)
; #pragma unroll
;                     for (int e = 0; e < 4; ++e) { const float g = acc[ai][0][m][n][e] * rs, uu = acc[ai][1][m][n][e] * rs; h[n * 4 + e] = g * sigmoidf_(g) * uu; }
;                 u32x4 w; w.x = pk2(h[0], h[1]); w.y = pk2(h[2], h[3]); w.z = pk2(h[4], h[5]); w.w = pk2(h[6], h[7]);
;                 *(gu32x4*)rowp = w; }
; template <class Epi, class Sched>
; __device__ __forceinline__ void gemm_phase(LAS unsigned char* lds, const int tid, const Gemm g, const Sched& S, const Epi& E) {
;     ...
;         if (!has_next) break;
; #pragma unroll
;         for (int a = 0; a < 2; ++a)
; #pragma unroll
;             for (int b = 0; b < 2; ++b)
; #pragma unroll
;                 for (int m = 0; m < 4; ++m)
; #pragma unroll
;                     for (int n = 0; n < 2; ++n) acc[a][b][m][n] = (f32x4){0.f, 0.f, 0.f, 0.f};
;         cur = nxt; cA = nA; cB = nB; ++ui;
;         if (wr == 1) PG8_BAR;
	v_exp_f32_e32 v62, v62
	v_exp_f32_e32 v63, v63
	v_add_f32_e32 v62, 1.0, v62
	v_add_f32_e32 v63, 1.0, v63
	v_rcp_f32_e32 v62, v62
	v_rcp_f32_e32 v63, v63
	s_nop 0
	v_pk_mul_f32 v[54:55], v[54:55], v[62:63]
	s_nop 0
	v_pk_mul_f32 v[54:55], v[50:51], v[54:55]
	v_pk_mul_f32 v[50:51], v[56:57], v[154:155] op_sel_hi:[1,0]
	v_lshl_add_u64 v[62:63], v[66:67], 0, v[114:115]
	v_mul_f32_e32 v56, 0xbfb8aa3b, v50
	v_mul_f32_e32 v57, 0xbfb8aa3b, v51
	v_exp_f32_e32 v56, v56
	v_exp_f32_e32 v57, v57
	v_add_f32_e32 v56, 1.0, v56
	v_add_f32_e32 v57, 1.0, v57
	v_rcp_f32_e32 v56, v56
	v_rcp_f32_e32 v57, v57
	s_nop 0
	v_pk_mul_f32 v[50:51], v[50:51], v[56:57]
	s_nop 0
	v_pk_mul_f32 v[56:57], v[52:53], v[50:51]
	v_cvt_pk_bf16_f32 v50, v58, v59
	v_cvt_pk_bf16_f32 v51, v60, v61
	v_cvt_pk_bf16_f32 v52, v54, v55
	v_cvt_pk_bf16_f32 v53, v56, v57
	global_store_dwordx4 v[62:63], v[50:53], off
	s_nop 1
	v_mul_f32_e32 v52, 0xbfb8aa3b, v46
	v_mul_f32_e32 v53, 0xbfb8aa3b, v47
	v_exp_f32_e32 v52, v52
	v_exp_f32_e32 v53, v53
	v_mad_i64_i32 v[50:51], s[0:1], v152, s79, v[148:149]
	v_add_f32_e32 v52, 1.0, v52
	v_add_f32_e32 v53, 1.0, v53
	v_rcp_f32_e32 v52, v52
	v_rcp_f32_e32 v53, v53
	s_nop 0
	v_pk_mul_f32 v[46:47], v[46:47], v[52:53]
	s_nop 0
	v_pk_mul_f32 v[42:43], v[42:43], v[46:47]
	v_pk_mul_f32 v[46:47], v[48:49], v[150:151] op_sel_hi:[1,0]
	s_nop 0
	v_mul_f32_e32 v48, 0xbfb8aa3b, v46
	v_mul_f32_e32 v49, 0xbfb8aa3b, v47
	v_exp_f32_e32 v48, v48
	v_exp_f32_e32 v49, v49
	v_add_f32_e32 v48, 1.0, v48
	v_add_f32_e32 v49, 1.0, v49
	v_rcp_f32_e32 v48, v48
	v_rcp_f32_e32 v49, v49
	s_nop 0
	v_pk_mul_f32 v[46:47], v[46:47], v[48:49]
	s_nop 0
	v_pk_mul_f32 v[44:45], v[44:45], v[46:47]
	v_mul_f32_e32 v46, 0xbfb8aa3b, v38
	v_mul_f32_e32 v47, 0xbfb8aa3b, v39
	v_exp_f32_e32 v46, v46
	v_exp_f32_e32 v47, v47
	v_add_f32_e32 v46, 1.0, v46
	v_add_f32_e32 v47, 1.0, v47
	v_rcp_f32_e32 v46, v46
	v_rcp_f32_e32 v47, v47
	s_nop 0
	v_pk_mul_f32 v[38:39], v[38:39], v[46:47]
	s_nop 0
	v_pk_mul_f32 v[38:39], v[34:35], v[38:39]
	v_pk_mul_f32 v[34:35], v[40:41], v[150:151] op_sel_hi:[1,0]
	v_lshl_add_u64 v[46:47], v[50:51], 0, v[114:115]
	v_mul_f32_e32 v40, 0xbfb8aa3b, v34
	v_mul_f32_e32 v41, 0xbfb8aa3b, v35
	v_exp_f32_e32 v40, v40
	v_exp_f32_e32 v41, v41
	v_add_f32_e32 v40, 1.0, v40
	v_add_f32_e32 v41, 1.0, v41
	v_rcp_f32_e32 v40, v40
	v_rcp_f32_e32 v41, v41
	s_nop 0
	v_pk_mul_f32 v[34:35], v[34:35], v[40:41]
	s_nop 0
	v_pk_mul_f32 v[40:41], v[36:37], v[34:35]
	v_cvt_pk_bf16_f32 v34, v42, v43
	v_cvt_pk_bf16_f32 v35, v44, v45
	v_cvt_pk_bf16_f32 v36, v38, v39
	v_cvt_pk_bf16_f32 v37, v40, v41
	global_store_dwordx4 v[46:47], v[34:37], off
	s_nop 1
	v_mul_f32_e32 v36, 0xbfb8aa3b, v30
	v_mul_f32_e32 v37, 0xbfb8aa3b, v31
	v_exp_f32_e32 v36, v36
	v_exp_f32_e32 v37, v37
	v_mad_i64_i32 v[34:35], s[0:1], v146, s79, v[148:149]
	v_add_f32_e32 v36, 1.0, v36
	v_add_f32_e32 v37, 1.0, v37
	v_rcp_f32_e32 v36, v36
	v_rcp_f32_e32 v37, v37
	s_nop 0
	v_pk_mul_f32 v[30:31], v[30:31], v[36:37]
	s_nop 0
	v_pk_mul_f32 v[26:27], v[26:27], v[30:31]
	v_pk_mul_f32 v[30:31], v[32:33], v[144:145] op_sel_hi:[1,0]
	s_nop 0
	v_mul_f32_e32 v32, 0xbfb8aa3b, v30
	v_mul_f32_e32 v33, 0xbfb8aa3b, v31
	v_exp_f32_e32 v32, v32
	v_exp_f32_e32 v33, v33
	v_add_f32_e32 v32, 1.0, v32
	v_add_f32_e32 v33, 1.0, v33
	v_rcp_f32_e32 v32, v32
	v_rcp_f32_e32 v33, v33
	s_nop 0
	v_pk_mul_f32 v[30:31], v[30:31], v[32:33]
	s_nop 0
	v_pk_mul_f32 v[28:29], v[28:29], v[30:31]
	v_mul_f32_e32 v30, 0xbfb8aa3b, v22
	v_mul_f32_e32 v31, 0xbfb8aa3b, v23
	v_exp_f32_e32 v30, v30
	v_exp_f32_e32 v31, v31
	v_add_f32_e32 v30, 1.0, v30
	v_add_f32_e32 v31, 1.0, v31
	v_rcp_f32_e32 v30, v30
	v_rcp_f32_e32 v31, v31
	s_nop 0
	v_pk_mul_f32 v[22:23], v[22:23], v[30:31]
	s_nop 0
	v_pk_mul_f32 v[22:23], v[18:19], v[22:23]
	v_pk_mul_f32 v[18:19], v[24:25], v[144:145] op_sel_hi:[1,0]
	v_lshl_add_u64 v[30:31], v[34:35], 0, v[114:115]
	v_mul_f32_e32 v24, 0xbfb8aa3b, v18
	v_mul_f32_e32 v25, 0xbfb8aa3b, v19
	v_exp_f32_e32 v24, v24
	v_exp_f32_e32 v25, v25
	v_add_f32_e32 v24, 1.0, v24
	v_add_f32_e32 v25, 1.0, v25
	v_rcp_f32_e32 v24, v24
	v_rcp_f32_e32 v25, v25
	s_nop 0
	v_pk_mul_f32 v[18:19], v[18:19], v[24:25]
	s_nop 0
	v_pk_mul_f32 v[24:25], v[20:21], v[18:19]
	v_cvt_pk_bf16_f32 v18, v26, v27
	v_cvt_pk_bf16_f32 v19, v28, v29
	v_cvt_pk_bf16_f32 v20, v22, v23
	v_cvt_pk_bf16_f32 v21, v24, v25
	global_store_dwordx4 v[30:31], v[18:21], off
	s_nop 1
	v_mul_f32_e32 v20, 0xbfb8aa3b, v14
	v_mul_f32_e32 v21, 0xbfb8aa3b, v15
	v_exp_f32_e32 v20, v20
	v_exp_f32_e32 v21, v21
	v_mad_i64_i32 v[18:19], s[0:1], v140, s79, v[148:149]
	v_add_f32_e32 v20, 1.0, v20
	v_add_f32_e32 v21, 1.0, v21
	v_rcp_f32_e32 v20, v20
	v_rcp_f32_e32 v21, v21
	s_mov_b64 s[0:1], -1
	v_pk_mul_f32 v[14:15], v[14:15], v[20:21]
	s_nop 0
	v_pk_mul_f32 v[10:11], v[10:11], v[14:15]
	v_pk_mul_f32 v[14:15], v[16:17], v[142:143] op_sel_hi:[1,0]
	s_nop 0
	v_mul_f32_e32 v16, 0xbfb8aa3b, v14
	v_mul_f32_e32 v17, 0xbfb8aa3b, v15
	v_exp_f32_e32 v16, v16
	v_exp_f32_e32 v17, v17
	v_add_f32_e32 v16, 1.0, v16
	v_add_f32_e32 v17, 1.0, v17
	v_rcp_f32_e32 v16, v16
	v_rcp_f32_e32 v17, v17
	s_nop 0
	v_pk_mul_f32 v[14:15], v[14:15], v[16:17]
	s_nop 0
	v_pk_mul_f32 v[12:13], v[12:13], v[14:15]
	v_mul_f32_e32 v14, 0xbfb8aa3b, v6
	v_mul_f32_e32 v15, 0xbfb8aa3b, v7
	v_exp_f32_e32 v14, v14
	v_exp_f32_e32 v15, v15
	v_add_f32_e32 v14, 1.0, v14
	v_add_f32_e32 v15, 1.0, v15
	v_rcp_f32_e32 v14, v14
	v_rcp_f32_e32 v15, v15
	s_nop 0
	v_pk_mul_f32 v[6:7], v[6:7], v[14:15]
	s_nop 0
	v_pk_mul_f32 v[6:7], v[2:3], v[6:7]
	v_pk_mul_f32 v[2:3], v[8:9], v[142:143] op_sel_hi:[1,0]
	v_lshl_add_u64 v[14:15], v[18:19], 0, v[114:115]
	v_mul_f32_e32 v8, 0xbfb8aa3b, v2
	v_mul_f32_e32 v9, 0xbfb8aa3b, v3
	v_exp_f32_e32 v8, v8
	v_exp_f32_e32 v9, v9
	v_add_f32_e32 v8, 1.0, v8
	v_add_f32_e32 v9, 1.0, v9
	v_rcp_f32_e32 v8, v8
	v_rcp_f32_e32 v9, v9
	s_nop 0
	v_pk_mul_f32 v[2:3], v[2:3], v[8:9]
	s_nop 0
	v_pk_mul_f32 v[8:9], v[4:5], v[2:3]
	v_cvt_pk_bf16_f32 v2, v10, v11
	v_cvt_pk_bf16_f32 v3, v12, v13
	v_cvt_pk_bf16_f32 v4, v6, v7
	v_cvt_pk_bf16_f32 v5, v8, v9
	global_store_dwordx4 v[14:15], v[2:5], off
	s_cbranch_vccnz .LBB0_365
	s_andn2_b64 vcc, exec, s[4:5]
	s_cbranch_vccnz .LBB0_364
	s_mov_b32 vcc_lo, 1
	s_nop 0
	v_writelane_b32 v255, vcc_lo, 21
	s_branch .LBB0_364

; #define PG8_STAGE(bufoff, gbase, voff) do { _Pragma("unroll") for (int _i = 0; _i < 2; ++_i) \
;         __builtin_amdgcn_global_load_lds((const gunsigned*)((const gchar*)(gbase) + (voff)[_i]), (LAS unsigned*)(lds + (bufoff) + ldsw + _i * 8192), 16, 0, 0); } while (0)
; #define PG8_LDA(dst, b, h) do { _Pragma("unroll") for (int m = 0; m < 4; ++m) _Pragma("unroll") for (int k = 0; k < 2; ++k) dst[m][k] = *(const LAS bf16x8*)(lds + PG8_SA(b, h) + aoff + m * 2048 + k * 1024); } while (0)
; #define PG8_LDB(dst, b, h) do { _Pragma("unroll") for (int n = 0; n < 2; ++n) _Pragma("unroll") for (int k = 0; k < 2; ++k) dst[n][k] = *(const LAS bf16x8*)(lds + PG8_SB(b, h) + boff + n * 2048 + k * 1024); } while (0)
; #define PG8_WAIT_V(n) asm volatile("s_waitcnt vmcnt(" #n ")" ::: "memory")
; #define PG8_WAIT_L(n) asm volatile("s_waitcnt lgkmcnt(" #n ")" ::: "memory")
; #define PG8_BAR __builtin_amdgcn_s_barrier()
; #define PG8_SCHED __builtin_amdgcn_sched_barrier(0)
; template <class Epi, class Sched>
; __device__ __forceinline__ void gemm_phase(LAS unsigned char* lds, const int tid, const Gemm g, const Sched& S, const Epi& E) {
;     ...
;         const gchar* nA = has_next ? (const gchar*)g.A + (size_t)nxt.pm * tstep + (size_t)nxt.pz * g.zA : cA;
;         const gchar* nB = has_next ? (const gchar*)g.Bt + (size_t)nxt.pn * tstep + (size_t)nxt.pz * g.zB : cB;
;         for (int t = 0; t < nt; t += 2) {
;             const bool last = (t == nt - 2);
;             const gchar* a1 = cA + (size_t)(t + 1) * kstep;
;             const gchar* a2 = last ? nA : cA + (size_t)(t + 2) * kstep; const gchar* b2 = last ? nB : cB + (size_t)(t + 2) * kstep;
;             const gchar* a3 = a2 + kstep; const gchar* b3 = b2 + kstep;
;             PG8_LDB(B0, 0, 0); PG8_LDB(B1, 0, 1); PG8_SCHED; PG8_LDA(At, 0, 0); PG8_STAGE(PG8_SA(1, 1), a1 + hstep, voffA);
;             PG8_WAIT_V(8); PG8_WAIT_L(0); PG8_BAR; PG8_MMA(0, 0, At, B0); PG8_MMA(0, 1, At, B1); PG8_BAR; PG8_SCHED;
;     ...
; #pragma unroll
;         for (int a = 0; a < 2; ++a)
; #pragma unroll
;             for (int b = 0; b < 2; ++b)
; #pragma unroll
;                 for (int m = 0; m < 4; ++m)
; #pragma unroll
;                     for (int n = 0; n < 2; ++n) acc[a][b][m][n] = (f32x4){0.f, 0.f, 0.f, 0.f};
;         cur = nxt; cA = nA; cB = nB; ++ui;
;         if (wr == 1) PG8_BAR;
.LBB0_396:
	s_ashr_i32 s57, s56, 31
	s_lshl_b64 s[50:51], s[56:57], 19
	s_add_u32 s58, s64, s50
	s_addc_u32 s59, s41, s51
	s_and_b64 s[50:51], s[6:7], exec
	s_cselect_b32 s1, s59, s93
	s_cselect_b32 s31, s58, s92
	s_ashr_i32 s17, s16, 31
	s_lshl_b64 s[50:51], s[16:17], 19
	s_add_u32 s60, s23, s50
	s_addc_u32 s61, s24, s51
	s_and_b64 s[50:51], s[6:7], exec
	s_cselect_b32 s17, s61, s21
	s_cselect_b32 s50, s60, s20
	s_add_u32 s51, s20, 0x100
	s_addc_u32 s52, s21, 0
	s_add_u32 s92, s92, 0x40080
	v_mov_b32_e32 v2, 0
	s_addc_u32 s93, s93, 0
	s_mov_b32 s53, -2
	s_waitcnt lgkmcnt(0)
	v_mov_b32_e32 v3, v2
	v_mov_b32_e32 v4, v2
	v_mov_b32_e32 v5, v2
	v_mov_b32_e32 v6, v2
	v_mov_b32_e32 v7, v2
	v_mov_b32_e32 v8, v2
	v_mov_b32_e32 v9, v2
	v_mov_b32_e32 v18, v2
	v_mov_b32_e32 v19, v2
	v_mov_b32_e32 v20, v2
	v_mov_b32_e32 v21, v2
	v_mov_b32_e32 v22, v2
	v_mov_b32_e32 v23, v2
	v_mov_b32_e32 v24, v2
	v_mov_b32_e32 v25, v2
	v_mov_b32_e32 v34, v2
	v_mov_b32_e32 v35, v2
	v_mov_b32_e32 v36, v2
	v_mov_b32_e32 v37, v2
	v_mov_b32_e32 v38, v2
	v_mov_b32_e32 v39, v2
	v_mov_b32_e32 v40, v2
	v_mov_b32_e32 v41, v2
	v_mov_b32_e32 v50, v2
	v_mov_b32_e32 v51, v2
	v_mov_b32_e32 v52, v2
	v_mov_b32_e32 v53, v2
	v_mov_b32_e32 v54, v2
	v_mov_b32_e32 v55, v2
	v_mov_b32_e32 v56, v2
	v_mov_b32_e32 v57, v2
	v_mov_b32_e32 v10, v2
	v_mov_b32_e32 v11, v2
	v_mov_b32_e32 v12, v2
	v_mov_b32_e32 v13, v2
	v_mov_b32_e32 v14, v2
	v_mov_b32_e32 v15, v2
	v_mov_b32_e32 v16, v2
	v_mov_b32_e32 v17, v2
	v_mov_b32_e32 v26, v2
	v_mov_b32_e32 v27, v2
	v_mov_b32_e32 v28, v2
	v_mov_b32_e32 v29, v2
	v_mov_b32_e32 v30, v2
	v_mov_b32_e32 v31, v2
	v_mov_b32_e32 v32, v2
	v_mov_b32_e32 v33, v2
	v_mov_b32_e32 v42, v2
	v_mov_b32_e32 v43, v2
	v_mov_b32_e32 v44, v2
	v_mov_b32_e32 v45, v2
	v_mov_b32_e32 v46, v2
	v_mov_b32_e32 v47, v2
	v_mov_b32_e32 v48, v2
	v_mov_b32_e32 v49, v2
	v_mov_b32_e32 v58, v2
	v_mov_b32_e32 v59, v2
	v_mov_b32_e32 v60, v2
	v_mov_b32_e32 v61, v2
	v_mov_b32_e32 v62, v2
	v_mov_b32_e32 v63, v2
	v_mov_b32_e32 v64, v2
	v_mov_b32_e32 v65, v2
	v_mov_b32_e32 v66, v2
	v_mov_b32_e32 v67, v2
	v_mov_b32_e32 v68, v2
	v_mov_b32_e32 v69, v2
	v_mov_b32_e32 v70, v2
	v_mov_b32_e32 v71, v2
	v_mov_b32_e32 v72, v2
	v_mov_b32_e32 v73, v2
	s_waitcnt vmcnt(0)
	v_mov_b32_e32 v82, v2
	v_mov_b32_e32 v83, v2
	v_mov_b32_e32 v84, v2
	v_mov_b32_e32 v85, v2
	v_mov_b32_e32 v86, v2
	v_mov_b32_e32 v87, v2
	v_mov_b32_e32 v88, v2
	v_mov_b32_e32 v89, v2
	v_mov_b32_e32 v98, v2
	v_mov_b32_e32 v99, v2
	v_mov_b32_e32 v100, v2
	v_mov_b32_e32 v101, v2
	v_mov_b32_e32 v102, v2
	v_mov_b32_e32 v103, v2
	v_mov_b32_e32 v104, v2
	v_mov_b32_e32 v105, v2
	v_mov_b32_e32 v114, v2
	v_mov_b32_e32 v115, v2
	v_mov_b32_e32 v116, v2
	v_mov_b32_e32 v117, v2
	v_mov_b32_e32 v118, v2
	v_mov_b32_e32 v119, v2
	v_mov_b32_e32 v120, v2
	v_mov_b32_e32 v121, v2
	v_mov_b32_e32 v74, v2
	v_mov_b32_e32 v75, v2
	v_mov_b32_e32 v76, v2
	v_mov_b32_e32 v77, v2
	v_mov_b32_e32 v78, v2
	v_mov_b32_e32 v79, v2
	v_mov_b32_e32 v80, v2
	v_mov_b32_e32 v81, v2
	v_mov_b32_e32 v90, v2
	v_mov_b32_e32 v91, v2
	v_mov_b32_e32 v92, v2
	v_mov_b32_e32 v93, v2
	v_mov_b32_e32 v94, v2
	v_mov_b32_e32 v95, v2
	v_mov_b32_e32 v96, v2
	v_mov_b32_e32 v97, v2
	v_mov_b32_e32 v106, v2
	v_mov_b32_e32 v107, v2
	v_mov_b32_e32 v108, v2
	v_mov_b32_e32 v109, v2
	v_mov_b32_e32 v110, v2
	v_mov_b32_e32 v111, v2
	v_mov_b32_e32 v112, v2
	v_mov_b32_e32 v113, v2
	v_mov_b32_e32 v122, v2
	v_mov_b32_e32 v123, v2
	v_mov_b32_e32 v124, v2
	v_mov_b32_e32 v125, v2
	v_mov_b32_e32 v126, v2
	v_mov_b32_e32 v127, v2
	v_mov_b32_e32 v128, v2
	v_mov_b32_e32 v129, v2
	v_add_u32_e32 v195, 0x80, v0
	v_add_u32_e32 v201, 0x80, v158
	v_add_u32_e32 v221, 0x80, v154
	v_add_u32_e32 v223, 0x80, v156
	v_readlane_b32 vcc_lo, v255, 21
	s_nop 3
	s_cmp_eq_u32 vcc_lo, 1
	s_cbranch_scc0 .Lnb_397
	s_barrier
	s_mov_b32 vcc_lo, 0
	s_nop 0
	v_writelane_b32 v255, vcc_lo, 21
.Lnb_397:
.LBB0_397:
	s_add_u32 s20, s92, 0xfffc0080
	s_addc_u32 s21, s93, -1
	s_add_i32 s29, 0, 0x10000
	s_cmp_eq_u32 s53, 12
	s_cselect_b32 s73, s1, s21
	s_cselect_b32 s72, s31, s20
	s_cselect_b32 s21, s17, s52
	s_cselect_b32 s20, s50, s51
	s_add_i32 s30, 0, 0x14000
	v_add_u32_e32 v142, s29, v177
	v_add_u32_e32 v168, s30, v177
	ds_read_b128 v[130:133], v142
	ds_read_b128 v[134:137], v142 offset:1024
	ds_read_b128 v[138:141], v142 offset:2048
	ds_read_b128 v[142:145], v142 offset:3072
	ds_read_b128 v[146:149], v168
	ds_read_b128 v[150:153], v168 offset:1024
	ds_read_b128 v[164:167], v168 offset:2048
	ds_read_b128 v[168:171], v168 offset:3072
	s_add_i32 m0, s43, 0xc000
	ds_read_b128 v[172:175], v181
	ds_read_b128 v[182:185], v181 offset:1024
	ds_read_b128 v[186:189], v181 offset:2048
	ds_read_b128 v[190:193], v181 offset:3072
	ds_read_b128 v[204:207], v181 offset:4096
	ds_read_b128 v[208:211], v181 offset:5120
	ds_read_b128 v[212:215], v181 offset:6144
	ds_read_b128 v[216:219], v181 offset:7168
	global_load_lds_dwordx4 v162, s[92:93]
	s_add_i32 m0, s43, 0xe000
	s_nop 0
	global_load_lds_dwordx4 v160, s[92:93]
	s_waitcnt vmcnt(8)
	s_waitcnt lgkmcnt(0)
	s_setprio 1
	s_barrier
; #define PG8_STAGE(bufoff, gbase, voff) do { _Pragma("unroll") for (int _i = 0; _i < 2; ++_i) \
;         __builtin_amdgcn_global_load_lds((const gunsigned*)((const gchar*)(gbase) + (voff)[_i]), (LAS unsigned*)(lds + (bufoff) + ldsw + _i * 8192), 16, 0, 0); } while (0)
; #define PG8_LDA(dst, b, h) do { _Pragma("unroll") for (int m = 0; m < 4; ++m) _Pragma("unroll") for (int k = 0; k < 2; ++k) dst[m][k] = *(const LAS bf16x8*)(lds + PG8_SA(b, h) + aoff + m * 2048 + k * 1024); } while (0)
; #define PG8_LDB(dst, b, h) do { _Pragma("unroll") for (int n = 0; n < 2; ++n) _Pragma("unroll") for (int k = 0; k < 2; ++k) dst[n][k] = *(const LAS bf16x8*)(lds + PG8_SB(b, h) + boff + n * 2048 + k * 1024); } while (0)
; #define PG8_MMA(ai, bj, At, Bt) do { __builtin_amdgcn_s_setprio(1); _Pragma("unroll") for (int m = 0; m < 4; ++m) _Pragma("unroll") for (int n = 0; n < 2; ++n) _Pragma("unroll") for (int k = 0; k < 2; ++k) \
;         acc[ai][bj][m][n] = __builtin_amdgcn_mfma_f32_16x16x32_bf16(Bt[n][k], At[m][k], acc[ai][bj][m][n], 0, 0, 0); __builtin_amdgcn_s_setprio(0); } while (0)
; #define PG8_WAIT_V(n) asm volatile("s_waitcnt vmcnt(" #n ")" ::: "memory")
; #define PG8_WAIT_L(n) asm volatile("s_waitcnt lgkmcnt(" #n ")" ::: "memory")
; #define PG8_BAR __builtin_amdgcn_s_barrier()
; #define PG8_SCHED __builtin_amdgcn_sched_barrier(0)
; template <class Epi, class Sched>
; __device__ __forceinline__ void gemm_phase(LAS unsigned char* lds, const int tid, const Gemm g, const Sched& S, const Epi& E) {
;     ...
;             PG8_LDB(B0, 0, 0); PG8_LDB(B1, 0, 1); PG8_SCHED; PG8_LDA(At, 0, 0); PG8_STAGE(PG8_SA(1, 1), a1 + hstep, voffA);
;             PG8_WAIT_V(8); PG8_WAIT_L(0); PG8_BAR; PG8_MMA(0, 0, At, B0); PG8_MMA(0, 1, At, B1); PG8_BAR; PG8_SCHED;
;             PG8_LDA(At, 0, 1); PG8_STAGE(PG8_SB(0, 0), b2, voffB); PG8_STAGE(PG8_SB(0, 1), b2 + hstep, voffB); PG8_STAGE(PG8_SA(0, 0), a2, voffA);
;             PG8_WAIT_V(8); PG8_WAIT_L(0); PG8_BAR; PG8_MMA(1, 0, At, B0); PG8_MMA(1, 1, At, B1); PG8_BAR; PG8_SCHED;
;             PG8_LDB(B0, 1, 0); PG8_LDB(B1, 1, 1); PG8_SCHED; PG8_LDA(At, 1, 0); PG8_STAGE(PG8_SA(0, 1), a2 + hstep, voffA);
;             PG8_WAIT_V(8); PG8_WAIT_L(0); PG8_BAR; PG8_MMA(0, 0, At, B0); PG8_MMA(0, 1, At, B1); PG8_BAR; PG8_SCHED;
	v_mfma_f32_16x16x32_bf16 v[126:129], v[130:133], v[172:175], v[126:129]
	v_mfma_f32_16x16x32_bf16 v[122:125], v[138:141], v[172:175], v[122:125]
	v_mfma_f32_16x16x32_bf16 v[110:113], v[130:133], v[186:189], v[110:113]
	v_mfma_f32_16x16x32_bf16 v[106:109], v[138:141], v[186:189], v[106:109]
	v_mfma_f32_16x16x32_bf16 v[94:97], v[130:133], v[204:207], v[94:97]
	v_mfma_f32_16x16x32_bf16 v[90:93], v[138:141], v[204:207], v[90:93]
	v_mfma_f32_16x16x32_bf16 v[78:81], v[130:133], v[212:215], v[78:81]
	v_mfma_f32_16x16x32_bf16 v[74:77], v[138:141], v[212:215], v[74:77]
	v_mfma_f32_16x16x32_bf16 v[126:129], v[134:137], v[182:185], v[126:129]
	v_mfma_f32_16x16x32_bf16 v[122:125], v[142:145], v[182:185], v[122:125]
	v_mfma_f32_16x16x32_bf16 v[110:113], v[134:137], v[190:193], v[110:113]
	v_mfma_f32_16x16x32_bf16 v[106:109], v[142:145], v[190:193], v[106:109]
	v_mfma_f32_16x16x32_bf16 v[94:97], v[134:137], v[208:211], v[94:97]
	v_mfma_f32_16x16x32_bf16 v[90:93], v[142:145], v[208:211], v[90:93]
	v_mfma_f32_16x16x32_bf16 v[78:81], v[134:137], v[216:219], v[78:81]
	v_mfma_f32_16x16x32_bf16 v[74:77], v[142:145], v[216:219], v[74:77]
	s_setprio 0
	s_setprio 1
	v_mfma_f32_16x16x32_bf16 v[118:121], v[146:149], v[172:175], v[118:121]
	v_mfma_f32_16x16x32_bf16 v[114:117], v[164:167], v[172:175], v[114:117]
	v_mfma_f32_16x16x32_bf16 v[102:105], v[146:149], v[186:189], v[102:105]
	v_mfma_f32_16x16x32_bf16 v[98:101], v[164:167], v[186:189], v[98:101]
	v_mfma_f32_16x16x32_bf16 v[86:89], v[146:149], v[204:207], v[86:89]
	v_mfma_f32_16x16x32_bf16 v[82:85], v[164:167], v[204:207], v[82:85]
	v_mfma_f32_16x16x32_bf16 v[70:73], v[146:149], v[212:215], v[70:73]
	v_mfma_f32_16x16x32_bf16 v[66:69], v[164:167], v[212:215], v[66:69]
	v_mfma_f32_16x16x32_bf16 v[118:121], v[150:153], v[182:185], v[118:121]
	v_mfma_f32_16x16x32_bf16 v[114:117], v[168:171], v[182:185], v[114:117]
	v_mfma_f32_16x16x32_bf16 v[102:105], v[150:153], v[190:193], v[102:105]
	v_mfma_f32_16x16x32_bf16 v[98:101], v[168:171], v[190:193], v[98:101]
	v_mfma_f32_16x16x32_bf16 v[86:89], v[150:153], v[208:211], v[86:89]
	v_mfma_f32_16x16x32_bf16 v[82:85], v[168:171], v[208:211], v[82:85]
	v_mfma_f32_16x16x32_bf16 v[70:73], v[150:153], v[216:219], v[70:73]
	v_mfma_f32_16x16x32_bf16 v[66:69], v[168:171], v[216:219], v[66:69]
	s_barrier
	s_setprio 0
	s_add_i32 s29, s29, s15
	s_mov_b32 m0, s29
	ds_read_b128 v[172:175], v181 offset:16384
	ds_read_b128 v[182:185], v181 offset:17408
	ds_read_b128 v[186:189], v181 offset:18432
	ds_read_b128 v[190:193], v181 offset:19456
	ds_read_b128 v[204:207], v181 offset:20480
	ds_read_b128 v[208:211], v181 offset:21504
	ds_read_b128 v[212:215], v181 offset:22528
	ds_read_b128 v[216:219], v181 offset:23552
	global_load_lds_dwordx4 v0, s[20:21]
	s_add_i32 m0, s29, 0x2000
	s_add_u32 s54, s20, 0x40000
	s_addc_u32 s55, s21, 0
	s_add_i32 s29, s30, s15
	global_load_lds_dwordx4 v158, s[20:21]
	s_mov_b32 m0, s29
	s_nop 0
	global_load_lds_dwordx4 v0, s[54:55]
	s_add_i32 m0, s29, 0x2000
	s_nop 0
	global_load_lds_dwordx4 v158, s[54:55]
	s_mov_b32 m0, s43
	s_nop 0
	global_load_lds_dwordx4 v154, s[72:73]
	s_mov_b32 m0, s44
	s_nop 0
	global_load_lds_dwordx4 v156, s[72:73]
	s_waitcnt vmcnt(8)
	s_waitcnt lgkmcnt(0)
	s_setprio 1
	s_barrier
	v_mfma_f32_16x16x32_bf16 v[62:65], v[130:133], v[172:175], v[62:65]
	v_mfma_f32_16x16x32_bf16 v[58:61], v[138:141], v[172:175], v[58:61]
	v_mfma_f32_16x16x32_bf16 v[46:49], v[130:133], v[186:189], v[46:49]
	v_mfma_f32_16x16x32_bf16 v[42:45], v[138:141], v[186:189], v[42:45]
	v_mfma_f32_16x16x32_bf16 v[30:33], v[130:133], v[204:207], v[30:33]
	v_mfma_f32_16x16x32_bf16 v[26:29], v[138:141], v[204:207], v[26:29]
	v_mfma_f32_16x16x32_bf16 v[14:17], v[130:133], v[212:215], v[14:17]
	v_mfma_f32_16x16x32_bf16 v[10:13], v[138:141], v[212:215], v[10:13]
	v_mfma_f32_16x16x32_bf16 v[62:65], v[134:137], v[182:185], v[62:65]
	v_mfma_f32_16x16x32_bf16 v[58:61], v[142:145], v[182:185], v[58:61]
	v_mfma_f32_16x16x32_bf16 v[46:49], v[134:137], v[190:193], v[46:49]
	v_mfma_f32_16x16x32_bf16 v[42:45], v[142:145], v[190:193], v[42:45]
	v_mfma_f32_16x16x32_bf16 v[30:33], v[134:137], v[208:211], v[30:33]
	v_mfma_f32_16x16x32_bf16 v[26:29], v[142:145], v[208:211], v[26:29]
	v_mfma_f32_16x16x32_bf16 v[14:17], v[134:137], v[216:219], v[14:17]
	v_mfma_f32_16x16x32_bf16 v[10:13], v[142:145], v[216:219], v[10:13]
	s_setprio 0
	s_setprio 1
	v_mfma_f32_16x16x32_bf16 v[54:57], v[146:149], v[172:175], v[54:57]
	v_mfma_f32_16x16x32_bf16 v[50:53], v[164:167], v[172:175], v[50:53]
	v_mfma_f32_16x16x32_bf16 v[38:41], v[146:149], v[186:189], v[38:41]
	v_mfma_f32_16x16x32_bf16 v[34:37], v[164:167], v[186:189], v[34:37]
	v_mfma_f32_16x16x32_bf16 v[22:25], v[146:149], v[204:207], v[22:25]
	v_mfma_f32_16x16x32_bf16 v[18:21], v[164:167], v[204:207], v[18:21]
	v_mfma_f32_16x16x32_bf16 v[6:9], v[146:149], v[212:215], v[6:9]
	v_mfma_f32_16x16x32_bf16 v[2:5], v[164:167], v[212:215], v[2:5]
	v_mfma_f32_16x16x32_bf16 v[54:57], v[150:153], v[182:185], v[54:57]
	v_mfma_f32_16x16x32_bf16 v[50:53], v[168:171], v[182:185], v[50:53]
	v_mfma_f32_16x16x32_bf16 v[38:41], v[150:153], v[190:193], v[38:41]
	v_mfma_f32_16x16x32_bf16 v[34:37], v[168:171], v[190:193], v[34:37]
	v_mfma_f32_16x16x32_bf16 v[22:25], v[150:153], v[208:211], v[22:25]
	v_mfma_f32_16x16x32_bf16 v[18:21], v[168:171], v[208:211], v[18:21]
	v_mfma_f32_16x16x32_bf16 v[6:9], v[150:153], v[216:219], v[6:9]
	v_mfma_f32_16x16x32_bf16 v[2:5], v[168:171], v[216:219], v[2:5]
	s_barrier
; #define PG8_STAGE(bufoff, gbase, voff) do { _Pragma("unroll") for (int _i = 0; _i < 2; ++_i) \
;         __builtin_amdgcn_global_load_lds((const gunsigned*)((const gchar*)(gbase) + (voff)[_i]), (LAS unsigned*)(lds + (bufoff) + ldsw + _i * 8192), 16, 0, 0); } while (0)
; #define PG8_LDA(dst, b, h) do { _Pragma("unroll") for (int m = 0; m < 4; ++m) _Pragma("unroll") for (int k = 0; k < 2; ++k) dst[m][k] = *(const LAS bf16x8*)(lds + PG8_SA(b, h) + aoff + m * 2048 + k * 1024); } while (0)
; #define PG8_LDB(dst, b, h) do { _Pragma("unroll") for (int n = 0; n < 2; ++n) _Pragma("unroll") for (int k = 0; k < 2; ++k) dst[n][k] = *(const LAS bf16x8*)(lds + PG8_SB(b, h) + boff + n * 2048 + k * 1024); } while (0)
; #define PG8_MMA(ai, bj, At, Bt) do { __builtin_amdgcn_s_setprio(1); _Pragma("unroll") for (int m = 0; m < 4; ++m) _Pragma("unroll") for (int n = 0; n < 2; ++n) _Pragma("unroll") for (int k = 0; k < 2; ++k) \
;         acc[ai][bj][m][n] = __builtin_amdgcn_mfma_f32_16x16x32_bf16(Bt[n][k], At[m][k], acc[ai][bj][m][n], 0, 0, 0); __builtin_amdgcn_s_setprio(0); } while (0)
; #define PG8_WAIT_V(n) asm volatile("s_waitcnt vmcnt(" #n ")" ::: "memory")
; #define PG8_WAIT_L(n) asm volatile("s_waitcnt lgkmcnt(" #n ")" ::: "memory")
; #define PG8_BAR __builtin_amdgcn_s_barrier()
; #define PG8_SCHED __builtin_amdgcn_sched_barrier(0)
; template <class Epi, class Sched>
; __device__ __forceinline__ void gemm_phase(LAS unsigned char* lds, const int tid, const Gemm g, const Sched& S, const Epi& E) {
;     ...
;             PG8_LDB(B0, 1, 0); PG8_LDB(B1, 1, 1); PG8_SCHED; PG8_LDA(At, 1, 0); PG8_STAGE(PG8_SA(0, 1), a2 + hstep, voffA);
;             PG8_WAIT_V(8); PG8_WAIT_L(0); PG8_BAR; PG8_MMA(0, 0, At, B0); PG8_MMA(0, 1, At, B1); PG8_BAR; PG8_SCHED;
;             PG8_LDA(At, 1, 1); PG8_STAGE(PG8_SB(1, 0), b3, voffB); PG8_STAGE(PG8_SB(1, 1), b3 + hstep, voffB); PG8_STAGE(PG8_SA(1, 0), a3, voffA);
;             PG8_WAIT_V(8); PG8_WAIT_L(0); PG8_BAR; PG8_MMA(1, 0, At, B0); PG8_MMA(1, 1, At, B1); PG8_BAR; PG8_SCHED;
;         }
;         if (wr == 0) PG8_BAR;
	s_setprio 0
	s_add_i32 s29, 0, 0x18000
	s_add_i32 s30, 0, 0x1c000
	v_add_u32_e32 v142, s29, v177
	v_add_u32_e32 v168, s30, v177
	ds_read_b128 v[130:133], v142
	ds_read_b128 v[134:137], v142 offset:1024
	ds_read_b128 v[138:141], v142 offset:2048
	ds_read_b128 v[142:145], v142 offset:3072
	ds_read_b128 v[146:149], v168
	ds_read_b128 v[150:153], v168 offset:1024
	ds_read_b128 v[164:167], v168 offset:2048
	ds_read_b128 v[168:171], v168 offset:3072
	s_add_u32 s54, s72, 0x40000
	s_addc_u32 s55, s73, 0
	s_mov_b32 m0, s45
	ds_read_b128 v[172:175], v181 offset:32768
	ds_read_b128 v[182:185], v181 offset:33792
	ds_read_b128 v[186:189], v181 offset:34816
	ds_read_b128 v[190:193], v181 offset:35840
	ds_read_b128 v[204:207], v181 offset:36864
	ds_read_b128 v[208:211], v181 offset:37888
	ds_read_b128 v[212:215], v181 offset:38912
	ds_read_b128 v[216:219], v181 offset:39936
	global_load_lds_dwordx4 v154, s[54:55]
	s_mov_b32 m0, s46
	s_nop 0
	global_load_lds_dwordx4 v156, s[54:55]
	s_waitcnt vmcnt(8)
	s_waitcnt lgkmcnt(0)
	s_setprio 1
	s_barrier
	v_mfma_f32_16x16x32_bf16 v[126:129], v[130:133], v[172:175], v[126:129]
	v_mfma_f32_16x16x32_bf16 v[122:125], v[138:141], v[172:175], v[122:125]
	v_mfma_f32_16x16x32_bf16 v[110:113], v[130:133], v[186:189], v[110:113]
	v_mfma_f32_16x16x32_bf16 v[106:109], v[138:141], v[186:189], v[106:109]
	v_mfma_f32_16x16x32_bf16 v[94:97], v[130:133], v[204:207], v[94:97]
	v_mfma_f32_16x16x32_bf16 v[90:93], v[138:141], v[204:207], v[90:93]
	v_mfma_f32_16x16x32_bf16 v[78:81], v[130:133], v[212:215], v[78:81]
	v_mfma_f32_16x16x32_bf16 v[74:77], v[138:141], v[212:215], v[74:77]
	v_mfma_f32_16x16x32_bf16 v[126:129], v[134:137], v[182:185], v[126:129]
	v_mfma_f32_16x16x32_bf16 v[122:125], v[142:145], v[182:185], v[122:125]
	v_mfma_f32_16x16x32_bf16 v[110:113], v[134:137], v[190:193], v[110:113]
	v_mfma_f32_16x16x32_bf16 v[106:109], v[142:145], v[190:193], v[106:109]
	v_mfma_f32_16x16x32_bf16 v[94:97], v[134:137], v[208:211], v[94:97]
	v_mfma_f32_16x16x32_bf16 v[90:93], v[142:145], v[208:211], v[90:93]
	v_mfma_f32_16x16x32_bf16 v[78:81], v[134:137], v[216:219], v[78:81]
	v_mfma_f32_16x16x32_bf16 v[74:77], v[142:145], v[216:219], v[74:77]
	s_setprio 0
	s_setprio 1
	v_mfma_f32_16x16x32_bf16 v[118:121], v[146:149], v[172:175], v[118:121]
	v_mfma_f32_16x16x32_bf16 v[114:117], v[164:167], v[172:175], v[114:117]
	v_mfma_f32_16x16x32_bf16 v[102:105], v[146:149], v[186:189], v[102:105]
	v_mfma_f32_16x16x32_bf16 v[98:101], v[164:167], v[186:189], v[98:101]
	v_mfma_f32_16x16x32_bf16 v[86:89], v[146:149], v[204:207], v[86:89]
	v_mfma_f32_16x16x32_bf16 v[82:85], v[164:167], v[204:207], v[82:85]
	v_mfma_f32_16x16x32_bf16 v[70:73], v[146:149], v[212:215], v[70:73]
	v_mfma_f32_16x16x32_bf16 v[66:69], v[164:167], v[212:215], v[66:69]
	v_mfma_f32_16x16x32_bf16 v[118:121], v[150:153], v[182:185], v[118:121]
	v_mfma_f32_16x16x32_bf16 v[114:117], v[168:171], v[182:185], v[114:117]
	v_mfma_f32_16x16x32_bf16 v[102:105], v[150:153], v[190:193], v[102:105]
	v_mfma_f32_16x16x32_bf16 v[98:101], v[168:171], v[190:193], v[98:101]
	v_mfma_f32_16x16x32_bf16 v[86:89], v[150:153], v[208:211], v[86:89]
	v_mfma_f32_16x16x32_bf16 v[82:85], v[168:171], v[208:211], v[82:85]
	v_mfma_f32_16x16x32_bf16 v[70:73], v[150:153], v[216:219], v[70:73]
	v_mfma_f32_16x16x32_bf16 v[66:69], v[168:171], v[216:219], v[66:69]
	s_barrier
	s_setprio 0
	s_add_i32 s29, s29, s15
	s_mov_b32 m0, s29
	ds_read_b128 v[172:175], v181 offset:49152
	ds_read_b128 v[182:185], v181 offset:50176
	ds_read_b128 v[186:189], v181 offset:51200
	ds_read_b128 v[190:193], v181 offset:52224
	ds_read_b128 v[204:207], v181 offset:53248
	ds_read_b128 v[208:211], v181 offset:54272
	ds_read_b128 v[212:215], v181 offset:55296
	ds_read_b128 v[216:219], v181 offset:56320
	global_load_lds_dwordx4 v195, s[20:21]
	s_add_i32 m0, s29, 0x2000
	s_add_i32 s29, s30, s15
	global_load_lds_dwordx4 v201, s[20:21]
	s_add_u32 s20, s20, 0x40080
	s_addc_u32 s21, s21, 0
	s_mov_b32 m0, s29
	s_nop 0
	global_load_lds_dwordx4 v0, s[20:21]
	s_add_i32 m0, s29, 0x2000
	s_nop 0
	global_load_lds_dwordx4 v158, s[20:21]
	s_mov_b32 m0, s12
	s_nop 0
	global_load_lds_dwordx4 v221, s[72:73]
	s_mov_b32 m0, s47
	s_nop 0
	global_load_lds_dwordx4 v223, s[72:73]
	s_waitcnt vmcnt(8)
	s_waitcnt lgkmcnt(0)
	s_setprio 1
	s_barrier
	v_mfma_f32_16x16x32_bf16 v[62:65], v[130:133], v[172:175], v[62:65]
	v_mfma_f32_16x16x32_bf16 v[58:61], v[138:141], v[172:175], v[58:61]
	v_mfma_f32_16x16x32_bf16 v[46:49], v[130:133], v[186:189], v[46:49]
	v_mfma_f32_16x16x32_bf16 v[42:45], v[138:141], v[186:189], v[42:45]
	v_mfma_f32_16x16x32_bf16 v[30:33], v[130:133], v[204:207], v[30:33]
	v_mfma_f32_16x16x32_bf16 v[26:29], v[138:141], v[204:207], v[26:29]
	v_mfma_f32_16x16x32_bf16 v[14:17], v[130:133], v[212:215], v[14:17]
	v_mfma_f32_16x16x32_bf16 v[10:13], v[138:141], v[212:215], v[10:13]
	v_mfma_f32_16x16x32_bf16 v[62:65], v[134:137], v[182:185], v[62:65]
	v_mfma_f32_16x16x32_bf16 v[58:61], v[142:145], v[182:185], v[58:61]
	v_mfma_f32_16x16x32_bf16 v[46:49], v[134:137], v[190:193], v[46:49]
	v_mfma_f32_16x16x32_bf16 v[42:45], v[142:145], v[190:193], v[42:45]
	v_mfma_f32_16x16x32_bf16 v[30:33], v[134:137], v[208:211], v[30:33]
	v_mfma_f32_16x16x32_bf16 v[26:29], v[142:145], v[208:211], v[26:29]
	v_mfma_f32_16x16x32_bf16 v[14:17], v[134:137], v[216:219], v[14:17]
	v_mfma_f32_16x16x32_bf16 v[10:13], v[142:145], v[216:219], v[10:13]
	s_setprio 0
	s_setprio 1
	v_mfma_f32_16x16x32_bf16 v[54:57], v[146:149], v[172:175], v[54:57]
	v_mfma_f32_16x16x32_bf16 v[50:53], v[164:167], v[172:175], v[50:53]
	v_mfma_f32_16x16x32_bf16 v[38:41], v[146:149], v[186:189], v[38:41]
	v_mfma_f32_16x16x32_bf16 v[34:37], v[164:167], v[186:189], v[34:37]
	v_mfma_f32_16x16x32_bf16 v[22:25], v[146:149], v[204:207], v[22:25]
	v_mfma_f32_16x16x32_bf16 v[18:21], v[164:167], v[204:207], v[18:21]
	v_mfma_f32_16x16x32_bf16 v[6:9], v[146:149], v[212:215], v[6:9]
	v_mfma_f32_16x16x32_bf16 v[2:5], v[164:167], v[212:215], v[2:5]
	v_mfma_f32_16x16x32_bf16 v[54:57], v[150:153], v[182:185], v[54:57]
	v_mfma_f32_16x16x32_bf16 v[50:53], v[168:171], v[182:185], v[50:53]
	v_mfma_f32_16x16x32_bf16 v[38:41], v[150:153], v[190:193], v[38:41]
	v_mfma_f32_16x16x32_bf16 v[34:37], v[168:171], v[190:193], v[34:37]
	v_mfma_f32_16x16x32_bf16 v[22:25], v[150:153], v[208:211], v[22:25]
	v_mfma_f32_16x16x32_bf16 v[18:21], v[168:171], v[208:211], v[18:21]
	v_mfma_f32_16x16x32_bf16 v[6:9], v[150:153], v[216:219], v[6:9]
	v_mfma_f32_16x16x32_bf16 v[2:5], v[168:171], v[216:219], v[2:5]
	s_barrier
	s_setprio 0
	s_add_i32 s53, s53, 2
	s_add_u32 s51, s51, 0x100
	s_addc_u32 s52, s52, 0
	s_add_u32 s92, s92, 0x100
	s_addc_u32 s93, s93, 0
	s_cmp_gt_u32 s53, 13
	s_cbranch_scc0 .LBB0_397
	s_and_b64 vcc, exec, s[10:11]
	s_cbranch_vccz .LBB0_400
	s_barrier

; #define PG8_BAR __builtin_amdgcn_s_barrier()
; template <class Epi, class Sched>
; __device__ __forceinline__ void gemm_phase(LAS unsigned char* lds, const int tid, const Gemm g, const Sched& S, const Epi& E) {
;     ...
;         if (!has_next) break;
; #pragma unroll
;         for (int a = 0; a < 2; ++a)
; #pragma unroll
;             for (int b = 0; b < 2; ++b)
; #pragma unroll
;                 for (int m = 0; m < 4; ++m)
; #pragma unroll
;                     for (int n = 0; n < 2; ++n) acc[a][b][m][n] = (f32x4){0.f, 0.f, 0.f, 0.f};
;         cur = nxt; cA = nA; cB = nB; ++ui;
;         if (wr == 1) PG8_BAR;
.LBB0_418:
	s_or_b64 exec, exec, s[20:21]
	s_andn2_b64 vcc, exec, s[6:7]
	s_mov_b64 s[0:1], -1
	s_cbranch_vccnz .LBB0_389
	s_andn2_b64 vcc, exec, s[8:9]
	s_cbranch_vccnz .LBB0_388
	s_mov_b32 vcc_lo, 1
	s_nop 0
	v_writelane_b32 v255, vcc_lo, 21
	s_branch .LBB0_388

; #define PG8_STAGE(bufoff, gbase, voff) do { _Pragma("unroll") for (int _i = 0; _i < 2; ++_i) \
;         __builtin_amdgcn_global_load_lds((const gunsigned*)((const gchar*)(gbase) + (voff)[_i]), (LAS unsigned*)(lds + (bufoff) + ldsw + _i * 8192), 16, 0, 0); } while (0)
; #define PG8_LDA(dst, b, h) do { _Pragma("unroll") for (int m = 0; m < 4; ++m) _Pragma("unroll") for (int k = 0; k < 2; ++k) dst[m][k] = *(const LAS bf16x8*)(lds + PG8_SA(b, h) + aoff + m * 2048 + k * 1024); } while (0)
; #define PG8_LDB(dst, b, h) do { _Pragma("unroll") for (int n = 0; n < 2; ++n) _Pragma("unroll") for (int k = 0; k < 2; ++k) dst[n][k] = *(const LAS bf16x8*)(lds + PG8_SB(b, h) + boff + n * 2048 + k * 1024); } while (0)
; #define PG8_WAIT_V(n) asm volatile("s_waitcnt vmcnt(" #n ")" ::: "memory")
; #define PG8_WAIT_L(n) asm volatile("s_waitcnt lgkmcnt(" #n ")" ::: "memory")
; #define PG8_BAR __builtin_amdgcn_s_barrier()
; #define PG8_SCHED __builtin_amdgcn_sched_barrier(0)
; template <class Epi, class Sched>
; __device__ __forceinline__ void gemm_phase(LAS unsigned char* lds, const int tid, const Gemm g, const Sched& S, const Epi& E) {
;     ...
;         const gchar* nA = has_next ? (const gchar*)g.A + (size_t)nxt.pm * tstep + (size_t)nxt.pz * g.zA : cA;
;         const gchar* nB = has_next ? (const gchar*)g.Bt + (size_t)nxt.pn * tstep + (size_t)nxt.pz * g.zB : cB;
;         for (int t = 0; t < nt; t += 2) {
;             const bool last = (t == nt - 2);
;             const gchar* a1 = cA + (size_t)(t + 1) * kstep;
;             const gchar* a2 = last ? nA : cA + (size_t)(t + 2) * kstep; const gchar* b2 = last ? nB : cB + (size_t)(t + 2) * kstep;
;             const gchar* a3 = a2 + kstep; const gchar* b3 = b2 + kstep;
;             PG8_LDB(B0, 0, 0); PG8_LDB(B1, 0, 1); PG8_SCHED; PG8_LDA(At, 0, 0); PG8_STAGE(PG8_SA(1, 1), a1 + hstep, voffA);
;             PG8_WAIT_V(8); PG8_WAIT_L(0); PG8_BAR; PG8_MMA(0, 0, At, B0); PG8_MMA(0, 1, At, B1); PG8_BAR; PG8_SCHED;
;     ...
; #pragma unroll
;         for (int a = 0; a < 2; ++a)
; #pragma unroll
;             for (int b = 0; b < 2; ++b)
; #pragma unroll
;                 for (int m = 0; m < 4; ++m)
; #pragma unroll
;                     for (int n = 0; n < 2; ++n) acc[a][b][m][n] = (f32x4){0.f, 0.f, 0.f, 0.f};
;         cur = nxt; cA = nA; cB = nB; ++ui;
;         if (wr == 1) PG8_BAR;
.LBB0_443:
	s_ashr_i32 s71, s70, 31
	s_lshl_b64 s[52:53], s[70:71], 18
	s_add_u32 s1, s74, s52
	s_addc_u32 s5, s75, s53
	s_ashr_i32 s63, s62, 31
	s_lshl_b64 s[52:53], s[62:63], 25
	s_add_u32 s56, s1, s52
	s_addc_u32 s57, s5, s53
	s_and_b64 s[52:53], s[2:3], exec
	s_cselect_b32 s1, s57, s21
	s_cselect_b32 s5, s56, s20
	s_ashr_i32 s61, s60, 31
	s_lshl_b64 s[52:53], s[60:61], 18
	s_add_u32 s15, s43, s52
	s_addc_u32 s23, s92, s53
	s_lshl_b64 s[52:53], s[62:63], 20
	s_add_u32 s58, s15, s52
	s_addc_u32 s59, s23, s53
	s_and_b64 s[52:53], s[2:3], exec
	s_cselect_b32 s15, s59, s17
	s_cselect_b32 s23, s58, s16
	s_add_u32 s24, s16, 0x100
	s_addc_u32 s31, s17, 0
	s_add_u32 s16, s20, 0x20080
	v_mov_b32_e32 v2, 0
	s_addc_u32 s17, s21, 0
	s_mov_b32 s51, -2
	v_mov_b32_e32 v3, v2
	v_mov_b32_e32 v4, v2
	v_mov_b32_e32 v5, v2
	v_mov_b32_e32 v6, v2
	v_mov_b32_e32 v7, v2
	v_mov_b32_e32 v8, v2
	v_mov_b32_e32 v9, v2
	v_mov_b32_e32 v18, v2
	v_mov_b32_e32 v19, v2
	v_mov_b32_e32 v20, v2
	v_mov_b32_e32 v21, v2
	v_mov_b32_e32 v22, v2
	v_mov_b32_e32 v23, v2
	v_mov_b32_e32 v24, v2
	v_mov_b32_e32 v25, v2
	v_mov_b32_e32 v34, v2
	v_mov_b32_e32 v35, v2
	v_mov_b32_e32 v36, v2
	v_mov_b32_e32 v37, v2
	v_mov_b32_e32 v38, v2
	v_mov_b32_e32 v39, v2
	v_mov_b32_e32 v40, v2
	v_mov_b32_e32 v41, v2
	v_mov_b32_e32 v50, v2
	v_mov_b32_e32 v51, v2
	v_mov_b32_e32 v52, v2
	v_mov_b32_e32 v53, v2
	v_mov_b32_e32 v54, v2
	v_mov_b32_e32 v55, v2
	v_mov_b32_e32 v56, v2
	v_mov_b32_e32 v57, v2
	v_mov_b32_e32 v10, v2
	v_mov_b32_e32 v11, v2
	v_mov_b32_e32 v12, v2
	v_mov_b32_e32 v13, v2
	v_mov_b32_e32 v14, v2
	v_mov_b32_e32 v15, v2
	v_mov_b32_e32 v16, v2
	v_mov_b32_e32 v17, v2
	v_mov_b32_e32 v26, v2
	v_mov_b32_e32 v27, v2
	v_mov_b32_e32 v28, v2
	v_mov_b32_e32 v29, v2
	v_mov_b32_e32 v30, v2
	v_mov_b32_e32 v31, v2
	v_mov_b32_e32 v32, v2
	v_mov_b32_e32 v33, v2
	v_mov_b32_e32 v42, v2
	v_mov_b32_e32 v43, v2
	v_mov_b32_e32 v44, v2
	v_mov_b32_e32 v45, v2
	v_mov_b32_e32 v46, v2
	v_mov_b32_e32 v47, v2
	v_mov_b32_e32 v48, v2
	v_mov_b32_e32 v49, v2
	v_mov_b32_e32 v58, v2
	v_mov_b32_e32 v59, v2
	v_mov_b32_e32 v60, v2
	v_mov_b32_e32 v61, v2
	v_mov_b32_e32 v62, v2
	v_mov_b32_e32 v63, v2
	v_mov_b32_e32 v64, v2
	v_mov_b32_e32 v65, v2
	v_mov_b32_e32 v66, v2
	v_mov_b32_e32 v67, v2
	v_mov_b32_e32 v68, v2
	v_mov_b32_e32 v69, v2
	v_mov_b32_e32 v70, v2
	v_mov_b32_e32 v71, v2
	v_mov_b32_e32 v72, v2
	v_mov_b32_e32 v73, v2
	s_waitcnt vmcnt(0)
	v_mov_b32_e32 v82, v2
	v_mov_b32_e32 v83, v2
	v_mov_b32_e32 v84, v2
	v_mov_b32_e32 v85, v2
	v_mov_b32_e32 v86, v2
	v_mov_b32_e32 v87, v2
	v_mov_b32_e32 v88, v2
	v_mov_b32_e32 v89, v2
	v_mov_b32_e32 v98, v2
	v_mov_b32_e32 v99, v2
	v_mov_b32_e32 v100, v2
	v_mov_b32_e32 v101, v2
	v_mov_b32_e32 v102, v2
	v_mov_b32_e32 v103, v2
	v_mov_b32_e32 v104, v2
	v_mov_b32_e32 v105, v2
	v_mov_b32_e32 v114, v2
	v_mov_b32_e32 v115, v2
	v_mov_b32_e32 v116, v2
	v_mov_b32_e32 v117, v2
	v_mov_b32_e32 v118, v2
	v_mov_b32_e32 v119, v2
	v_mov_b32_e32 v120, v2
	v_mov_b32_e32 v121, v2
	v_mov_b32_e32 v74, v2
	v_mov_b32_e32 v75, v2
	v_mov_b32_e32 v76, v2
	v_mov_b32_e32 v77, v2
	v_mov_b32_e32 v78, v2
	v_mov_b32_e32 v79, v2
	v_mov_b32_e32 v80, v2
	v_mov_b32_e32 v81, v2
	v_mov_b32_e32 v90, v2
	v_mov_b32_e32 v91, v2
	v_mov_b32_e32 v92, v2
	v_mov_b32_e32 v93, v2
	v_mov_b32_e32 v94, v2
	v_mov_b32_e32 v95, v2
	v_mov_b32_e32 v96, v2
	v_mov_b32_e32 v97, v2
	v_mov_b32_e32 v106, v2
	v_mov_b32_e32 v107, v2
	v_mov_b32_e32 v108, v2
	v_mov_b32_e32 v109, v2
	v_mov_b32_e32 v110, v2
	v_mov_b32_e32 v111, v2
	v_mov_b32_e32 v112, v2
	v_mov_b32_e32 v113, v2
	v_mov_b32_e32 v124, v2
	v_mov_b32_e32 v125, v2
	v_mov_b32_e32 v126, v2
	v_mov_b32_e32 v127, v2
	v_mov_b32_e32 v128, v2
	v_mov_b32_e32 v129, v2
	v_mov_b32_e32 v130, v2
	v_mov_b32_e32 v131, v2
	v_add_u32_e32 v201, 0x80, v0
	v_add_u32_e32 v215, 0x80, v208
	v_add_u32_e32 v217, 0x80, v204
	v_add_u32_e32 v219, 0x80, v206
	v_readlane_b32 vcc_lo, v255, 21
	s_nop 3
	s_cmp_eq_u32 vcc_lo, 1
	s_cbranch_scc0 .Lnb_444
	s_barrier
	s_mov_b32 vcc_lo, 0
	s_nop 0
	v_writelane_b32 v255, vcc_lo, 21
.Lnb_444:
.LBB0_444:
	s_add_u32 s20, s16, 0xfffe0080
	s_addc_u32 s21, s17, -1
	s_add_i32 s29, 0, 0x10000
	s_cmp_eq_u32 s51, 4
	s_cselect_b32 s73, s1, s21
	s_cselect_b32 s72, s5, s20
	v_add_u32_e32 v122, s29, v242
	s_cselect_b32 s21, s15, s31
	s_cselect_b32 s20, s23, s24
	s_add_i32 s30, 0, 0x14000
	ds_read_b128 v[132:135], v122
	ds_read_b128 v[136:139], v122 offset:1024
	ds_read_b128 v[140:143], v122 offset:2048
	ds_read_b128 v[144:147], v122 offset:3072
	v_add_u32_e32 v122, s30, v242
	ds_read_b128 v[148:151], v122
	ds_read_b128 v[152:155], v122 offset:1024
	ds_read_b128 v[156:159], v122 offset:2048
	ds_read_b128 v[160:163], v122 offset:3072
	s_add_i32 m0, s93, 0xc000
	ds_read_b128 v[164:167], v244
	ds_read_b128 v[168:171], v244 offset:1024
	ds_read_b128 v[172:175], v244 offset:2048
	ds_read_b128 v[176:179], v244 offset:3072
	ds_read_b128 v[180:183], v244 offset:4096
	ds_read_b128 v[184:187], v244 offset:5120
	ds_read_b128 v[188:191], v244 offset:6144
	ds_read_b128 v[192:195], v244 offset:7168
	global_load_lds_dwordx4 v212, s[16:17]
	s_add_i32 m0, s93, 0xe000
	s_nop 0
	global_load_lds_dwordx4 v210, s[16:17]
	s_waitcnt vmcnt(8)
	s_waitcnt lgkmcnt(0)
	s_setprio 1
	s_barrier
; #define PG8_STAGE(bufoff, gbase, voff) do { _Pragma("unroll") for (int _i = 0; _i < 2; ++_i) \
;         __builtin_amdgcn_global_load_lds((const gunsigned*)((const gchar*)(gbase) + (voff)[_i]), (LAS unsigned*)(lds + (bufoff) + ldsw + _i * 8192), 16, 0, 0); } while (0)
; #define PG8_LDA(dst, b, h) do { _Pragma("unroll") for (int m = 0; m < 4; ++m) _Pragma("unroll") for (int k = 0; k < 2; ++k) dst[m][k] = *(const LAS bf16x8*)(lds + PG8_SA(b, h) + aoff + m * 2048 + k * 1024); } while (0)
; #define PG8_LDB(dst, b, h) do { _Pragma("unroll") for (int n = 0; n < 2; ++n) _Pragma("unroll") for (int k = 0; k < 2; ++k) dst[n][k] = *(const LAS bf16x8*)(lds + PG8_SB(b, h) + boff + n * 2048 + k * 1024); } while (0)
; #define PG8_MMA(ai, bj, At, Bt) do { __builtin_amdgcn_s_setprio(1); _Pragma("unroll") for (int m = 0; m < 4; ++m) _Pragma("unroll") for (int n = 0; n < 2; ++n) _Pragma("unroll") for (int k = 0; k < 2; ++k) \
;         acc[ai][bj][m][n] = __builtin_amdgcn_mfma_f32_16x16x32_bf16(Bt[n][k], At[m][k], acc[ai][bj][m][n], 0, 0, 0); __builtin_amdgcn_s_setprio(0); } while (0)
; #define PG8_WAIT_V(n) asm volatile("s_waitcnt vmcnt(" #n ")" ::: "memory")
; #define PG8_WAIT_L(n) asm volatile("s_waitcnt lgkmcnt(" #n ")" ::: "memory")
; #define PG8_BAR __builtin_amdgcn_s_barrier()
; #define PG8_SCHED __builtin_amdgcn_sched_barrier(0)
; template <class Epi, class Sched>
; __device__ __forceinline__ void gemm_phase(LAS unsigned char* lds, const int tid, const Gemm g, const Sched& S, const Epi& E) {
;     ...
;             PG8_LDB(B0, 0, 0); PG8_LDB(B1, 0, 1); PG8_SCHED; PG8_LDA(At, 0, 0); PG8_STAGE(PG8_SA(1, 1), a1 + hstep, voffA);
;             PG8_WAIT_V(8); PG8_WAIT_L(0); PG8_BAR; PG8_MMA(0, 0, At, B0); PG8_MMA(0, 1, At, B1); PG8_BAR; PG8_SCHED;
;             PG8_LDA(At, 0, 1); PG8_STAGE(PG8_SB(0, 0), b2, voffB); PG8_STAGE(PG8_SB(0, 1), b2 + hstep, voffB); PG8_STAGE(PG8_SA(0, 0), a2, voffA);
;             PG8_WAIT_V(8); PG8_WAIT_L(0); PG8_BAR; PG8_MMA(1, 0, At, B0); PG8_MMA(1, 1, At, B1); PG8_BAR; PG8_SCHED;
;             PG8_LDB(B0, 1, 0); PG8_LDB(B1, 1, 1); PG8_SCHED; PG8_LDA(At, 1, 0); PG8_STAGE(PG8_SA(0, 1), a2 + hstep, voffA);
;             PG8_WAIT_V(8); PG8_WAIT_L(0); PG8_BAR; PG8_MMA(0, 0, At, B0); PG8_MMA(0, 1, At, B1); PG8_BAR; PG8_SCHED;
	v_mfma_f32_16x16x32_bf16 v[128:131], v[132:135], v[164:167], v[128:131]
	v_mfma_f32_16x16x32_bf16 v[122:125], v[140:143], v[164:167], v[124:127]
	v_mfma_f32_16x16x32_bf16 v[110:113], v[132:135], v[172:175], v[110:113]
	v_mfma_f32_16x16x32_bf16 v[106:109], v[140:143], v[172:175], v[106:109]
	v_mfma_f32_16x16x32_bf16 v[94:97], v[132:135], v[180:183], v[94:97]
	v_mfma_f32_16x16x32_bf16 v[90:93], v[140:143], v[180:183], v[90:93]
	v_mfma_f32_16x16x32_bf16 v[78:81], v[132:135], v[188:191], v[78:81]
	v_mfma_f32_16x16x32_bf16 v[74:77], v[140:143], v[188:191], v[74:77]
	v_mfma_f32_16x16x32_bf16 v[128:131], v[136:139], v[168:171], v[128:131]
	v_mfma_f32_16x16x32_bf16 v[122:125], v[144:147], v[168:171], v[122:125]
	v_mfma_f32_16x16x32_bf16 v[110:113], v[136:139], v[176:179], v[110:113]
	v_mfma_f32_16x16x32_bf16 v[106:109], v[144:147], v[176:179], v[106:109]
	v_mfma_f32_16x16x32_bf16 v[94:97], v[136:139], v[184:187], v[94:97]
	v_mfma_f32_16x16x32_bf16 v[90:93], v[144:147], v[184:187], v[90:93]
	v_mfma_f32_16x16x32_bf16 v[78:81], v[136:139], v[192:195], v[78:81]
	v_mfma_f32_16x16x32_bf16 v[74:77], v[144:147], v[192:195], v[74:77]
	s_setprio 0
	s_setprio 1
	v_mfma_f32_16x16x32_bf16 v[118:121], v[148:151], v[164:167], v[118:121]
	v_mfma_f32_16x16x32_bf16 v[114:117], v[156:159], v[164:167], v[114:117]
	v_mfma_f32_16x16x32_bf16 v[102:105], v[148:151], v[172:175], v[102:105]
	v_mfma_f32_16x16x32_bf16 v[98:101], v[156:159], v[172:175], v[98:101]
	v_mfma_f32_16x16x32_bf16 v[86:89], v[148:151], v[180:183], v[86:89]
	v_mfma_f32_16x16x32_bf16 v[82:85], v[156:159], v[180:183], v[82:85]
	v_mfma_f32_16x16x32_bf16 v[70:73], v[148:151], v[188:191], v[70:73]
	v_mfma_f32_16x16x32_bf16 v[66:69], v[156:159], v[188:191], v[66:69]
	v_mfma_f32_16x16x32_bf16 v[118:121], v[152:155], v[168:171], v[118:121]
	v_mfma_f32_16x16x32_bf16 v[114:117], v[160:163], v[168:171], v[114:117]
	v_mfma_f32_16x16x32_bf16 v[102:105], v[152:155], v[176:179], v[102:105]
	v_mfma_f32_16x16x32_bf16 v[98:101], v[160:163], v[176:179], v[98:101]
	v_mfma_f32_16x16x32_bf16 v[86:89], v[152:155], v[184:187], v[86:89]
	v_mfma_f32_16x16x32_bf16 v[82:85], v[160:163], v[184:187], v[82:85]
	v_mfma_f32_16x16x32_bf16 v[70:73], v[152:155], v[192:195], v[70:73]
	v_mfma_f32_16x16x32_bf16 v[66:69], v[160:163], v[192:195], v[66:69]
	s_barrier
	s_setprio 0
	s_add_i32 s29, s29, s42
	s_mov_b32 m0, s29
	ds_read_b128 v[164:167], v244 offset:16384
	ds_read_b128 v[168:171], v244 offset:17408
	ds_read_b128 v[172:175], v244 offset:18432
	ds_read_b128 v[176:179], v244 offset:19456
	ds_read_b128 v[180:183], v244 offset:20480
	ds_read_b128 v[184:187], v244 offset:21504
	ds_read_b128 v[188:191], v244 offset:22528
	ds_read_b128 v[192:195], v244 offset:23552
	global_load_lds_dwordx4 v0, s[20:21]
	s_add_i32 m0, s29, 0x2000
	s_add_u32 s52, s20, 0x20000
	s_addc_u32 s53, s21, 0
	s_add_i32 s29, s30, s42
	global_load_lds_dwordx4 v208, s[20:21]
	s_mov_b32 m0, s29
	s_nop 0
	global_load_lds_dwordx4 v0, s[52:53]
	s_add_i32 m0, s29, 0x2000
	s_nop 0
	global_load_lds_dwordx4 v208, s[52:53]
	s_mov_b32 m0, s93
	s_nop 0
	global_load_lds_dwordx4 v204, s[72:73]
	s_mov_b32 m0, s44
	s_nop 0
	global_load_lds_dwordx4 v206, s[72:73]
	s_waitcnt vmcnt(8)
	s_waitcnt lgkmcnt(0)
	s_setprio 1
	s_barrier
	v_mfma_f32_16x16x32_bf16 v[62:65], v[132:135], v[164:167], v[62:65]
	v_mfma_f32_16x16x32_bf16 v[58:61], v[140:143], v[164:167], v[58:61]
	v_mfma_f32_16x16x32_bf16 v[46:49], v[132:135], v[172:175], v[46:49]
	v_mfma_f32_16x16x32_bf16 v[42:45], v[140:143], v[172:175], v[42:45]
	v_mfma_f32_16x16x32_bf16 v[30:33], v[132:135], v[180:183], v[30:33]
	v_mfma_f32_16x16x32_bf16 v[26:29], v[140:143], v[180:183], v[26:29]
	v_mfma_f32_16x16x32_bf16 v[14:17], v[132:135], v[188:191], v[14:17]
	v_mfma_f32_16x16x32_bf16 v[10:13], v[140:143], v[188:191], v[10:13]
	v_mfma_f32_16x16x32_bf16 v[62:65], v[136:139], v[168:171], v[62:65]
	v_mfma_f32_16x16x32_bf16 v[58:61], v[144:147], v[168:171], v[58:61]
	v_mfma_f32_16x16x32_bf16 v[46:49], v[136:139], v[176:179], v[46:49]
	v_mfma_f32_16x16x32_bf16 v[42:45], v[144:147], v[176:179], v[42:45]
	v_mfma_f32_16x16x32_bf16 v[30:33], v[136:139], v[184:187], v[30:33]
	v_mfma_f32_16x16x32_bf16 v[26:29], v[144:147], v[184:187], v[26:29]
	v_mfma_f32_16x16x32_bf16 v[14:17], v[136:139], v[192:195], v[14:17]
	v_mfma_f32_16x16x32_bf16 v[10:13], v[144:147], v[192:195], v[10:13]
	s_setprio 0
	s_setprio 1
	v_mfma_f32_16x16x32_bf16 v[54:57], v[148:151], v[164:167], v[54:57]
	v_mfma_f32_16x16x32_bf16 v[50:53], v[156:159], v[164:167], v[50:53]
	v_mfma_f32_16x16x32_bf16 v[38:41], v[148:151], v[172:175], v[38:41]
	v_mfma_f32_16x16x32_bf16 v[34:37], v[156:159], v[172:175], v[34:37]
	v_mfma_f32_16x16x32_bf16 v[22:25], v[148:151], v[180:183], v[22:25]
	v_mfma_f32_16x16x32_bf16 v[18:21], v[156:159], v[180:183], v[18:21]
	v_mfma_f32_16x16x32_bf16 v[6:9], v[148:151], v[188:191], v[6:9]
	v_mfma_f32_16x16x32_bf16 v[2:5], v[156:159], v[188:191], v[2:5]
	v_mfma_f32_16x16x32_bf16 v[54:57], v[152:155], v[168:171], v[54:57]
	v_mfma_f32_16x16x32_bf16 v[50:53], v[160:163], v[168:171], v[50:53]
	v_mfma_f32_16x16x32_bf16 v[38:41], v[152:155], v[176:179], v[38:41]
	v_mfma_f32_16x16x32_bf16 v[34:37], v[160:163], v[176:179], v[34:37]
	v_mfma_f32_16x16x32_bf16 v[22:25], v[152:155], v[184:187], v[22:25]
	v_mfma_f32_16x16x32_bf16 v[18:21], v[160:163], v[184:187], v[18:21]
	v_mfma_f32_16x16x32_bf16 v[6:9], v[152:155], v[192:195], v[6:9]
	v_mfma_f32_16x16x32_bf16 v[2:5], v[160:163], v[192:195], v[2:5]
	s_barrier
; #define PG8_STAGE(bufoff, gbase, voff) do { _Pragma("unroll") for (int _i = 0; _i < 2; ++_i) \
;         __builtin_amdgcn_global_load_lds((const gunsigned*)((const gchar*)(gbase) + (voff)[_i]), (LAS unsigned*)(lds + (bufoff) + ldsw + _i * 8192), 16, 0, 0); } while (0)
; #define PG8_LDA(dst, b, h) do { _Pragma("unroll") for (int m = 0; m < 4; ++m) _Pragma("unroll") for (int k = 0; k < 2; ++k) dst[m][k] = *(const LAS bf16x8*)(lds + PG8_SA(b, h) + aoff + m * 2048 + k * 1024); } while (0)
; #define PG8_LDB(dst, b, h) do { _Pragma("unroll") for (int n = 0; n < 2; ++n) _Pragma("unroll") for (int k = 0; k < 2; ++k) dst[n][k] = *(const LAS bf16x8*)(lds + PG8_SB(b, h) + boff + n * 2048 + k * 1024); } while (0)
; #define PG8_MMA(ai, bj, At, Bt) do { __builtin_amdgcn_s_setprio(1); _Pragma("unroll") for (int m = 0; m < 4; ++m) _Pragma("unroll") for (int n = 0; n < 2; ++n) _Pragma("unroll") for (int k = 0; k < 2; ++k) \
;         acc[ai][bj][m][n] = __builtin_amdgcn_mfma_f32_16x16x32_bf16(Bt[n][k], At[m][k], acc[ai][bj][m][n], 0, 0, 0); __builtin_amdgcn_s_setprio(0); } while (0)
; #define PG8_WAIT_V(n) asm volatile("s_waitcnt vmcnt(" #n ")" ::: "memory")
; #define PG8_WAIT_L(n) asm volatile("s_waitcnt lgkmcnt(" #n ")" ::: "memory")
; #define PG8_BAR __builtin_amdgcn_s_barrier()
; #define PG8_SCHED __builtin_amdgcn_sched_barrier(0)
; template <class Epi, class Sched>
; __device__ __forceinline__ void gemm_phase(LAS unsigned char* lds, const int tid, const Gemm g, const Sched& S, const Epi& E) {
;     ...
;             PG8_LDB(B0, 1, 0); PG8_LDB(B1, 1, 1); PG8_SCHED; PG8_LDA(At, 1, 0); PG8_STAGE(PG8_SA(0, 1), a2 + hstep, voffA);
;             PG8_WAIT_V(8); PG8_WAIT_L(0); PG8_BAR; PG8_MMA(0, 0, At, B0); PG8_MMA(0, 1, At, B1); PG8_BAR; PG8_SCHED;
;             PG8_LDA(At, 1, 1); PG8_STAGE(PG8_SB(1, 0), b3, voffB); PG8_STAGE(PG8_SB(1, 1), b3 + hstep, voffB); PG8_STAGE(PG8_SA(1, 0), a3, voffA);
;             PG8_WAIT_V(8); PG8_WAIT_L(0); PG8_BAR; PG8_MMA(1, 0, At, B0); PG8_MMA(1, 1, At, B1); PG8_BAR; PG8_SCHED;
;         }
;         if (wr == 0) PG8_BAR;
	s_setprio 0
	s_add_i32 s29, 0, 0x18000
	v_add_u32_e32 v126, s29, v242
	s_add_i32 s30, 0, 0x1c000
	ds_read_b128 v[132:135], v126
	ds_read_b128 v[136:139], v126 offset:1024
	ds_read_b128 v[140:143], v126 offset:2048
	ds_read_b128 v[144:147], v126 offset:3072
	v_add_u32_e32 v126, s30, v242
	ds_read_b128 v[148:151], v126
	ds_read_b128 v[152:155], v126 offset:1024
	ds_read_b128 v[156:159], v126 offset:2048
	ds_read_b128 v[160:163], v126 offset:3072
	s_add_u32 s52, s72, 0x20000
	s_addc_u32 s53, s73, 0
	s_mov_b32 m0, s45
	ds_read_b128 v[164:167], v244 offset:32768
	ds_read_b128 v[168:171], v244 offset:33792
	ds_read_b128 v[172:175], v244 offset:34816
	ds_read_b128 v[176:179], v244 offset:35840
	ds_read_b128 v[180:183], v244 offset:36864
	ds_read_b128 v[184:187], v244 offset:37888
	ds_read_b128 v[188:191], v244 offset:38912
	ds_read_b128 v[192:195], v244 offset:39936
	global_load_lds_dwordx4 v204, s[52:53]
	s_mov_b32 m0, s46
	s_nop 0
	global_load_lds_dwordx4 v206, s[52:53]
	s_waitcnt vmcnt(8)
	s_waitcnt lgkmcnt(0)
	s_setprio 1
	s_barrier
	v_mfma_f32_16x16x32_bf16 v[126:129], v[132:135], v[164:167], v[128:131]
	v_mfma_f32_16x16x32_bf16 v[122:125], v[140:143], v[164:167], v[122:125]
	v_mfma_f32_16x16x32_bf16 v[110:113], v[132:135], v[172:175], v[110:113]
	v_mfma_f32_16x16x32_bf16 v[106:109], v[140:143], v[172:175], v[106:109]
	v_mfma_f32_16x16x32_bf16 v[94:97], v[132:135], v[180:183], v[94:97]
	v_mfma_f32_16x16x32_bf16 v[90:93], v[140:143], v[180:183], v[90:93]
	v_mfma_f32_16x16x32_bf16 v[78:81], v[132:135], v[188:191], v[78:81]
	v_mfma_f32_16x16x32_bf16 v[74:77], v[140:143], v[188:191], v[74:77]
	v_mfma_f32_16x16x32_bf16 v[128:131], v[136:139], v[168:171], v[126:129]
	v_mfma_f32_16x16x32_bf16 v[124:127], v[144:147], v[168:171], v[122:125]
	v_mfma_f32_16x16x32_bf16 v[110:113], v[136:139], v[176:179], v[110:113]
	v_mfma_f32_16x16x32_bf16 v[106:109], v[144:147], v[176:179], v[106:109]
	v_mfma_f32_16x16x32_bf16 v[94:97], v[136:139], v[184:187], v[94:97]
	v_mfma_f32_16x16x32_bf16 v[90:93], v[144:147], v[184:187], v[90:93]
	v_mfma_f32_16x16x32_bf16 v[78:81], v[136:139], v[192:195], v[78:81]
	v_mfma_f32_16x16x32_bf16 v[74:77], v[144:147], v[192:195], v[74:77]
	s_setprio 0
	s_setprio 1
	v_mfma_f32_16x16x32_bf16 v[118:121], v[148:151], v[164:167], v[118:121]
	v_mfma_f32_16x16x32_bf16 v[114:117], v[156:159], v[164:167], v[114:117]
	v_mfma_f32_16x16x32_bf16 v[102:105], v[148:151], v[172:175], v[102:105]
	v_mfma_f32_16x16x32_bf16 v[98:101], v[156:159], v[172:175], v[98:101]
	v_mfma_f32_16x16x32_bf16 v[86:89], v[148:151], v[180:183], v[86:89]
	v_mfma_f32_16x16x32_bf16 v[82:85], v[156:159], v[180:183], v[82:85]
	v_mfma_f32_16x16x32_bf16 v[70:73], v[148:151], v[188:191], v[70:73]
	v_mfma_f32_16x16x32_bf16 v[66:69], v[156:159], v[188:191], v[66:69]
	v_mfma_f32_16x16x32_bf16 v[118:121], v[152:155], v[168:171], v[118:121]
	v_mfma_f32_16x16x32_bf16 v[114:117], v[160:163], v[168:171], v[114:117]
	v_mfma_f32_16x16x32_bf16 v[102:105], v[152:155], v[176:179], v[102:105]
	v_mfma_f32_16x16x32_bf16 v[98:101], v[160:163], v[176:179], v[98:101]
	v_mfma_f32_16x16x32_bf16 v[86:89], v[152:155], v[184:187], v[86:89]
	v_mfma_f32_16x16x32_bf16 v[82:85], v[160:163], v[184:187], v[82:85]
	v_mfma_f32_16x16x32_bf16 v[70:73], v[152:155], v[192:195], v[70:73]
	v_mfma_f32_16x16x32_bf16 v[66:69], v[160:163], v[192:195], v[66:69]
	s_barrier
	s_setprio 0
	s_add_i32 s29, s29, s42
	s_mov_b32 m0, s29
	ds_read_b128 v[164:167], v244 offset:49152
	ds_read_b128 v[168:171], v244 offset:50176
	ds_read_b128 v[172:175], v244 offset:51200
	ds_read_b128 v[176:179], v244 offset:52224
	ds_read_b128 v[180:183], v244 offset:53248
	ds_read_b128 v[184:187], v244 offset:54272
	ds_read_b128 v[188:191], v244 offset:55296
	ds_read_b128 v[192:195], v244 offset:56320
	global_load_lds_dwordx4 v201, s[20:21]
	s_add_i32 m0, s29, 0x2000
	s_add_i32 s29, s30, s42
	global_load_lds_dwordx4 v215, s[20:21]
	s_add_u32 s20, s20, 0x20080
	s_addc_u32 s21, s21, 0
	s_mov_b32 m0, s29
	s_nop 0
	global_load_lds_dwordx4 v0, s[20:21]
	s_add_i32 m0, s29, 0x2000
	s_nop 0
	global_load_lds_dwordx4 v208, s[20:21]
	s_mov_b32 m0, s47
	s_nop 0
	global_load_lds_dwordx4 v217, s[72:73]
	s_mov_b32 m0, s48
	s_nop 0
	global_load_lds_dwordx4 v219, s[72:73]
	s_waitcnt vmcnt(8)
	s_waitcnt lgkmcnt(0)
	s_setprio 1
	s_barrier
	v_mfma_f32_16x16x32_bf16 v[62:65], v[132:135], v[164:167], v[62:65]
	v_mfma_f32_16x16x32_bf16 v[58:61], v[140:143], v[164:167], v[58:61]
	v_mfma_f32_16x16x32_bf16 v[46:49], v[132:135], v[172:175], v[46:49]
	v_mfma_f32_16x16x32_bf16 v[42:45], v[140:143], v[172:175], v[42:45]
	v_mfma_f32_16x16x32_bf16 v[30:33], v[132:135], v[180:183], v[30:33]
	v_mfma_f32_16x16x32_bf16 v[26:29], v[140:143], v[180:183], v[26:29]
	v_mfma_f32_16x16x32_bf16 v[14:17], v[132:135], v[188:191], v[14:17]
	v_mfma_f32_16x16x32_bf16 v[10:13], v[140:143], v[188:191], v[10:13]
	v_mfma_f32_16x16x32_bf16 v[62:65], v[136:139], v[168:171], v[62:65]
	v_mfma_f32_16x16x32_bf16 v[58:61], v[144:147], v[168:171], v[58:61]
	v_mfma_f32_16x16x32_bf16 v[46:49], v[136:139], v[176:179], v[46:49]
	v_mfma_f32_16x16x32_bf16 v[42:45], v[144:147], v[176:179], v[42:45]
	v_mfma_f32_16x16x32_bf16 v[30:33], v[136:139], v[184:187], v[30:33]
	v_mfma_f32_16x16x32_bf16 v[26:29], v[144:147], v[184:187], v[26:29]
	v_mfma_f32_16x16x32_bf16 v[14:17], v[136:139], v[192:195], v[14:17]
	v_mfma_f32_16x16x32_bf16 v[10:13], v[144:147], v[192:195], v[10:13]
	s_setprio 0
	s_setprio 1
	v_mfma_f32_16x16x32_bf16 v[54:57], v[148:151], v[164:167], v[54:57]
	v_mfma_f32_16x16x32_bf16 v[50:53], v[156:159], v[164:167], v[50:53]
	v_mfma_f32_16x16x32_bf16 v[38:41], v[148:151], v[172:175], v[38:41]
	v_mfma_f32_16x16x32_bf16 v[34:37], v[156:159], v[172:175], v[34:37]
	v_mfma_f32_16x16x32_bf16 v[22:25], v[148:151], v[180:183], v[22:25]
	v_mfma_f32_16x16x32_bf16 v[18:21], v[156:159], v[180:183], v[18:21]
	v_mfma_f32_16x16x32_bf16 v[6:9], v[148:151], v[188:191], v[6:9]
	v_mfma_f32_16x16x32_bf16 v[2:5], v[156:159], v[188:191], v[2:5]
	v_mfma_f32_16x16x32_bf16 v[54:57], v[152:155], v[168:171], v[54:57]
	v_mfma_f32_16x16x32_bf16 v[50:53], v[160:163], v[168:171], v[50:53]
	v_mfma_f32_16x16x32_bf16 v[38:41], v[152:155], v[176:179], v[38:41]
	v_mfma_f32_16x16x32_bf16 v[34:37], v[160:163], v[176:179], v[34:37]
	v_mfma_f32_16x16x32_bf16 v[22:25], v[152:155], v[184:187], v[22:25]
	v_mfma_f32_16x16x32_bf16 v[18:21], v[160:163], v[184:187], v[18:21]
	v_mfma_f32_16x16x32_bf16 v[6:9], v[152:155], v[192:195], v[6:9]
	v_mfma_f32_16x16x32_bf16 v[2:5], v[160:163], v[192:195], v[2:5]
	s_barrier
	s_setprio 0
	s_add_i32 s51, s51, 2
	s_add_u32 s24, s24, 0x100
	s_addc_u32 s31, s31, 0
	s_add_u32 s16, s16, 0x100
	s_addc_u32 s17, s17, 0
	s_cmp_gt_u32 s51, 5
	s_cbranch_scc0 .LBB0_444
	s_and_b64 vcc, exec, s[10:11]
	s_cbranch_vccz .LBB0_447
	s_barrier

; __device__ __forceinline__ unsigned pk2(float lo, float hi) { f32x2 v = {lo, hi}; bf16x2_t b = __builtin_convertvector(v, bf16x2_t); return __builtin_bit_cast(unsigned, b); }
; __device__ __forceinline__ float bflo(unsigned w) { return __uint_as_float(w << 16); }
; __device__ __forceinline__ float bfhi(unsigned w) { return __uint_as_float(w & 0xffff0000u); }
; __device__ __forceinline__ float sigmoidf_(float x) { return __builtin_amdgcn_rcpf(1.0f + __builtin_amdgcn_exp2f(-x * LOG2E)); }
;     __device__ __forceinline__ void operator()(const f32x4 (&acc)[2][2][4][2], const Unit& u, int wr, int wc, int fr, int fq, LAS unsigned char* lds, int tid) const {
;     ...
;             for (int m = 0; m < 4; ++m) { const size_t row = (size_t)(row0 + ai * HALF + m * 16);
; #pragma unroll
;                 for (int bj = 0; bj < 2; ++bj) { const int col = col0 + bj * HALF; const u32x4 gw = gv[m][bj], pw = pv[m][bj];
;                     f32x4 z0, z1;
;                     z0[0] = sigmoidf_(bflo(gw.x)); z0[1] = sigmoidf_(bfhi(gw.x)); z0[2] = sigmoidf_(bflo(gw.y)); z0[3] = sigmoidf_(bfhi(gw.y));
;                     z1[0] = sigmoidf_(bflo(gw.z)); z1[1] = sigmoidf_(bfhi(gw.z)); z1[2] = sigmoidf_(bflo(gw.w)); z1[3] = sigmoidf_(bfhi(gw.w));
;                     const f32x4 q0 = {bflo(pw.x), bfhi(pw.x), bflo(pw.y), bfhi(pw.y)}, q1 = {bflo(pw.z), bfhi(pw.z), bflo(pw.w), bfhi(pw.w)};
;                     z0 = z0 * acc[ai][bj][m][0] + q0; z1 = z1 * acc[ai][bj][m][1] + q1;
;                     u32x4 w; w.x = pk2(z0[0], z0[1]); w.y = pk2(z0[2], z0[3]); w.z = pk2(z1[0], z1[1]); w.w = pk2(z1[2], z1[3]);
;                     *(gu32x4*)(dst + row * DM + col) = w; } }
.LBB0_481:
	s_waitcnt vmcnt(7)
	v_lshlrev_b32_e32 v140, 16, v126
	v_and_b32_e32 v126, 0xffff0000, v126
	v_mul_f32_e32 v140, 0xbfb8aa3b, v140
	v_mul_f32_e32 v126, 0xbfb8aa3b, v126
	v_exp_f32_e32 v140, v140
	v_exp_f32_e32 v141, v126
	v_and_b32_e32 v145, 0xffff0000, v122
	v_lshlrev_b32_e32 v146, 16, v124
	v_add_f32_e32 v126, 1.0, v140
	v_add_f32_e32 v140, 1.0, v141
	v_lshlrev_b32_e32 v141, 16, v127
	v_and_b32_e32 v127, 0xffff0000, v127
	v_mul_f32_e32 v141, 0xbfb8aa3b, v141
	v_mul_f32_e32 v127, 0xbfb8aa3b, v127
	v_exp_f32_e32 v141, v141
	v_exp_f32_e32 v142, v127
	v_rcp_f32_e32 v127, v140
	v_and_b32_e32 v147, 0xffff0000, v124
	v_add_f32_e32 v140, 1.0, v141
	v_add_f32_e32 v141, 1.0, v142
	v_lshlrev_b32_e32 v142, 16, v128
	v_and_b32_e32 v128, 0xffff0000, v128
	v_mul_f32_e32 v142, 0xbfb8aa3b, v142
	v_mul_f32_e32 v128, 0xbfb8aa3b, v128
	v_exp_f32_e32 v142, v142
	v_exp_f32_e32 v143, v128
	v_rcp_f32_e32 v140, v140
	v_rcp_f32_e32 v141, v141
	v_add_f32_e32 v128, 1.0, v142
	v_add_f32_e32 v142, 1.0, v143
	v_lshlrev_b32_e32 v143, 16, v129
	v_and_b32_e32 v129, 0xffff0000, v129
	v_mul_f32_e32 v143, 0xbfb8aa3b, v143
	v_mul_f32_e32 v129, 0xbfb8aa3b, v129
	v_exp_f32_e32 v143, v143
	v_exp_f32_e32 v144, v129
	v_rcp_f32_e32 v129, v142
	v_rcp_f32_e32 v128, v128
	v_add_f32_e32 v142, 1.0, v143
	v_add_f32_e32 v143, 1.0, v144
	v_rcp_f32_e32 v142, v142
	v_rcp_f32_e32 v143, v143
	v_lshlrev_b32_e32 v144, 16, v122
	v_lshlrev_b32_e32 v122, 16, v123
	v_and_b32_e32 v123, 0xffff0000, v123
	v_lshlrev_b32_e32 v124, 16, v125
	v_and_b32_e32 v125, 0xffff0000, v125
	v_pk_fma_f32 v[64:65], v[64:65], v[140:141], v[122:123]
	v_rcp_f32_e32 v126, v126
	v_pk_fma_f32 v[122:123], v[60:61], v[142:143], v[124:125]
	v_pk_fma_f32 v[60:61], v[58:59], v[128:129], v[146:147]
	v_cvt_pk_bf16_f32 v59, v64, v65
	s_waitcnt vmcnt(6)
	v_lshlrev_b32_e32 v64, 16, v118
	v_and_b32_e32 v65, 0xffff0000, v118
	v_mul_f32_e32 v64, 0xbfb8aa3b, v64
	v_mul_f32_e32 v65, 0xbfb8aa3b, v65
	v_exp_f32_e32 v64, v64
	v_exp_f32_e32 v65, v65
	v_lshl_add_u64 v[138:139], s[0:1], 0, v[138:139]
	v_pk_fma_f32 v[62:63], v[62:63], v[126:127], v[144:145]
	v_cvt_pk_bf16_f32 v60, v60, v61
	v_cvt_pk_bf16_f32 v58, v62, v63
	v_cvt_pk_bf16_f32 v61, v122, v123
	v_lshl_add_u64 v[62:63], v[138:139], 0, v[130:131]
	global_store_dwordx4 v[62:63], v[58:61], off
	v_lshlrev_b32_e32 v118, 16, v121
	v_mul_f32_e32 v118, 0xbfb8aa3b, v118
	v_add_f32_e32 v58, 1.0, v64
	v_add_f32_e32 v59, 1.0, v65
	v_lshlrev_b32_e32 v60, 16, v119
	v_and_b32_e32 v61, 0xffff0000, v119
	v_lshlrev_b32_e32 v64, 16, v120
	v_and_b32_e32 v65, 0xffff0000, v120
	v_and_b32_e32 v119, 0xffff0000, v121
	v_mul_f32_e32 v60, 0xbfb8aa3b, v60
	v_mul_f32_e32 v61, 0xbfb8aa3b, v61
	v_mul_f32_e32 v64, 0xbfb8aa3b, v64
	v_mul_f32_e32 v65, 0xbfb8aa3b, v65
	v_mul_f32_e32 v119, 0xbfb8aa3b, v119
	v_exp_f32_e32 v60, v60
	v_exp_f32_e32 v61, v61
	v_exp_f32_e32 v64, v64
	v_exp_f32_e32 v65, v65
	v_exp_f32_e32 v118, v118
	v_exp_f32_e32 v119, v119
	v_add_f32_e32 v60, 1.0, v60
	v_add_f32_e32 v61, 1.0, v61
	v_add_f32_e32 v64, 1.0, v64
	v_add_f32_e32 v65, 1.0, v65
	v_add_f32_e32 v118, 1.0, v118
	v_add_f32_e32 v119, 1.0, v119
	v_rcp_f32_e32 v58, v58
	v_rcp_f32_e32 v59, v59
	v_rcp_f32_e32 v60, v60
	v_rcp_f32_e32 v61, v61
	v_rcp_f32_e32 v64, v64
	v_rcp_f32_e32 v65, v65
	v_rcp_f32_e32 v118, v118
	v_rcp_f32_e32 v119, v119
	v_lshlrev_b32_e32 v120, 16, v114
	v_and_b32_e32 v121, 0xffff0000, v114
	v_lshlrev_b32_e32 v114, 16, v115
	v_and_b32_e32 v115, 0xffff0000, v115
	v_lshlrev_b32_e32 v122, 16, v116
	v_and_b32_e32 v123, 0xffff0000, v116
	v_lshlrev_b32_e32 v116, 16, v117
	v_and_b32_e32 v117, 0xffff0000, v117
	v_pk_fma_f32 v[56:57], v[56:57], v[60:61], v[114:115]
	v_pk_fma_f32 v[54:55], v[54:55], v[58:59], v[120:121]
	v_pk_fma_f32 v[58:59], v[52:53], v[118:119], v[116:117]
	v_pk_fma_f32 v[52:53], v[50:51], v[64:65], v[122:123]
	v_cvt_pk_bf16_f32 v50, v54, v55
	v_cvt_pk_bf16_f32 v51, v56, v57
	v_cvt_pk_bf16_f32 v52, v52, v53
	v_cvt_pk_bf16_f32 v53, v58, v59
	global_store_dwordx4 v[62:63], v[50:53], off offset:256
	s_waitcnt vmcnt(7)
	v_lshlrev_b32_e32 v54, 16, v111
	v_and_b32_e32 v55, 0xffff0000, v111
	v_lshlrev_b32_e32 v50, 16, v110
	v_mul_f32_e32 v50, 0xbfb8aa3b, v50
	v_exp_f32_e32 v52, v50
	v_and_b32_e32 v50, 0xffff0000, v110
	v_mul_f32_e32 v54, 0xbfb8aa3b, v54
	v_mul_f32_e32 v55, 0xbfb8aa3b, v55
	v_lshlrev_b32_e32 v56, 16, v112
	v_and_b32_e32 v57, 0xffff0000, v112
	v_lshlrev_b32_e32 v58, 16, v113
	v_and_b32_e32 v59, 0xffff0000, v113
	v_mul_f32_e32 v50, 0xbfb8aa3b, v50
	v_exp_f32_e32 v54, v54
	v_exp_f32_e32 v55, v55
	v_mul_f32_e32 v56, 0xbfb8aa3b, v56
	v_mul_f32_e32 v57, 0xbfb8aa3b, v57
	v_mul_f32_e32 v58, 0xbfb8aa3b, v58
	v_mul_f32_e32 v59, 0xbfb8aa3b, v59
	v_exp_f32_e32 v53, v50
	v_exp_f32_e32 v56, v56
	v_exp_f32_e32 v57, v57
	v_exp_f32_e32 v58, v58
	v_exp_f32_e32 v59, v59
	v_add_f32_e32 v54, 1.0, v54
	v_add_f32_e32 v55, 1.0, v55
	v_add_f32_e32 v52, 1.0, v52
	v_add_f32_e32 v53, 1.0, v53
	v_rcp_f32_e32 v54, v54
	v_rcp_f32_e32 v55, v55
	v_add_f32_e32 v56, 1.0, v56
	v_add_f32_e32 v57, 1.0, v57
	v_add_f32_e32 v58, 1.0, v58
	v_add_f32_e32 v59, 1.0, v59
	v_rcp_f32_e32 v52, v52
	v_rcp_f32_e32 v53, v53
	v_rcp_f32_e32 v56, v56
	v_rcp_f32_e32 v57, v57
	v_rcp_f32_e32 v58, v58
	v_rcp_f32_e32 v59, v59
	v_lshlrev_b32_e32 v62, 16, v107
	v_and_b32_e32 v63, 0xffff0000, v107
	v_lshlrev_b32_e32 v60, 16, v106
	v_and_b32_e32 v61, 0xffff0000, v106
	v_lshlrev_b32_e32 v64, 16, v108
	v_and_b32_e32 v65, 0xffff0000, v108
	v_lshlrev_b32_e32 v106, 16, v109
	v_and_b32_e32 v107, 0xffff0000, v109
	v_pk_fma_f32 v[48:49], v[48:49], v[54:55], v[62:63]
	v_pk_fma_f32 v[46:47], v[46:47], v[52:53], v[60:61]
	v_pk_fma_f32 v[52:53], v[44:45], v[58:59], v[106:107]
	v_pk_fma_f32 v[44:45], v[42:43], v[56:57], v[64:65]
	v_cvt_pk_bf16_f32 v43, v48, v49
	s_waitcnt vmcnt(6)
; __device__ __forceinline__ unsigned pk2(float lo, float hi) { f32x2 v = {lo, hi}; bf16x2_t b = __builtin_convertvector(v, bf16x2_t); return __builtin_bit_cast(unsigned, b); }
; __device__ __forceinline__ float bflo(unsigned w) { return __uint_as_float(w << 16); }
; __device__ __forceinline__ float bfhi(unsigned w) { return __uint_as_float(w & 0xffff0000u); }
; __device__ __forceinline__ float sigmoidf_(float x) { return __builtin_amdgcn_rcpf(1.0f + __builtin_amdgcn_exp2f(-x * LOG2E)); }
;     __device__ __forceinline__ void operator()(const f32x4 (&acc)[2][2][4][2], const Unit& u, int wr, int wc, int fr, int fq, LAS unsigned char* lds, int tid) const {
;     ...
;             for (int m = 0; m < 4; ++m) { const size_t row = (size_t)(row0 + ai * HALF + m * 16);
; #pragma unroll
;                 for (int bj = 0; bj < 2; ++bj) { const int col = col0 + bj * HALF; const u32x4 gw = gv[m][bj], pw = pv[m][bj];
;                     f32x4 z0, z1;
;                     z0[0] = sigmoidf_(bflo(gw.x)); z0[1] = sigmoidf_(bfhi(gw.x)); z0[2] = sigmoidf_(bflo(gw.y)); z0[3] = sigmoidf_(bfhi(gw.y));
;                     z1[0] = sigmoidf_(bflo(gw.z)); z1[1] = sigmoidf_(bfhi(gw.z)); z1[2] = sigmoidf_(bflo(gw.w)); z1[3] = sigmoidf_(bfhi(gw.w));
;                     const f32x4 q0 = {bflo(pw.x), bfhi(pw.x), bflo(pw.y), bfhi(pw.y)}, q1 = {bflo(pw.z), bfhi(pw.z), bflo(pw.w), bfhi(pw.w)};
;                     z0 = z0 * acc[ai][bj][m][0] + q0; z1 = z1 * acc[ai][bj][m][1] + q1;
;                     u32x4 w; w.x = pk2(z0[0], z0[1]); w.y = pk2(z0[2], z0[3]); w.z = pk2(z1[0], z1[1]); w.w = pk2(z1[2], z1[3]);
;                     *(gu32x4*)(dst + row * DM + col) = w; } }
	v_lshlrev_b32_e32 v48, 16, v102
	v_and_b32_e32 v49, 0xffff0000, v102
	v_mul_f32_e32 v48, 0xbfb8aa3b, v48
	v_mul_f32_e32 v49, 0xbfb8aa3b, v49
	v_exp_f32_e32 v48, v48
	v_exp_f32_e32 v49, v49
	v_lshl_add_u64 v[50:51], s[0:1], 0, v[136:137]
	v_cvt_pk_bf16_f32 v42, v46, v47
	v_cvt_pk_bf16_f32 v44, v44, v45
	v_cvt_pk_bf16_f32 v45, v52, v53
	v_lshl_add_u64 v[46:47], v[50:51], 0, v[130:131]
	global_store_dwordx4 v[46:47], v[42:45], off
	v_lshlrev_b32_e32 v50, 16, v105
	v_and_b32_e32 v51, 0xffff0000, v105
	v_add_f32_e32 v42, 1.0, v48
	v_add_f32_e32 v43, 1.0, v49
	v_lshlrev_b32_e32 v44, 16, v103
	v_and_b32_e32 v45, 0xffff0000, v103
	v_lshlrev_b32_e32 v48, 16, v104
	v_and_b32_e32 v49, 0xffff0000, v104
	v_mul_f32_e32 v44, 0xbfb8aa3b, v44
	v_mul_f32_e32 v45, 0xbfb8aa3b, v45
	v_mul_f32_e32 v48, 0xbfb8aa3b, v48
	v_mul_f32_e32 v49, 0xbfb8aa3b, v49
	v_mul_f32_e32 v50, 0xbfb8aa3b, v50
	v_mul_f32_e32 v51, 0xbfb8aa3b, v51
	v_exp_f32_e32 v44, v44
	v_exp_f32_e32 v45, v45
	v_exp_f32_e32 v48, v48
	v_exp_f32_e32 v49, v49
	v_exp_f32_e32 v50, v50
	v_exp_f32_e32 v51, v51
	v_add_f32_e32 v44, 1.0, v44
	v_add_f32_e32 v45, 1.0, v45
	v_add_f32_e32 v48, 1.0, v48
	v_add_f32_e32 v49, 1.0, v49
	v_add_f32_e32 v50, 1.0, v50
	v_add_f32_e32 v51, 1.0, v51
	v_rcp_f32_e32 v42, v42
	v_rcp_f32_e32 v43, v43
	v_rcp_f32_e32 v44, v44
	v_rcp_f32_e32 v45, v45
	v_rcp_f32_e32 v48, v48
	v_rcp_f32_e32 v49, v49
	v_rcp_f32_e32 v50, v50
	v_rcp_f32_e32 v51, v51
	v_lshlrev_b32_e32 v52, 16, v98
	v_and_b32_e32 v53, 0xffff0000, v98
	v_lshlrev_b32_e32 v54, 16, v99
	v_and_b32_e32 v55, 0xffff0000, v99
	v_lshlrev_b32_e32 v56, 16, v100
	v_and_b32_e32 v57, 0xffff0000, v100
	v_lshlrev_b32_e32 v58, 16, v101
	v_and_b32_e32 v59, 0xffff0000, v101
	v_pk_fma_f32 v[40:41], v[40:41], v[44:45], v[54:55]
	v_pk_fma_f32 v[38:39], v[38:39], v[42:43], v[52:53]
	v_pk_fma_f32 v[42:43], v[36:37], v[50:51], v[58:59]
	v_pk_fma_f32 v[36:37], v[34:35], v[48:49], v[56:57]
	v_cvt_pk_bf16_f32 v34, v38, v39
	v_cvt_pk_bf16_f32 v35, v40, v41
	v_cvt_pk_bf16_f32 v36, v36, v37
	v_cvt_pk_bf16_f32 v37, v42, v43
	global_store_dwordx4 v[46:47], v[34:37], off offset:256
	s_waitcnt vmcnt(7)
	v_lshlrev_b32_e32 v38, 16, v95
	v_and_b32_e32 v39, 0xffff0000, v95
	v_lshlrev_b32_e32 v34, 16, v94
	v_mul_f32_e32 v34, 0xbfb8aa3b, v34
	v_exp_f32_e32 v36, v34
	v_and_b32_e32 v34, 0xffff0000, v94
	v_mul_f32_e32 v38, 0xbfb8aa3b, v38
	v_mul_f32_e32 v39, 0xbfb8aa3b, v39
	v_lshlrev_b32_e32 v40, 16, v96
	v_and_b32_e32 v41, 0xffff0000, v96
	v_lshlrev_b32_e32 v42, 16, v97
	v_and_b32_e32 v43, 0xffff0000, v97
	v_mul_f32_e32 v34, 0xbfb8aa3b, v34
	v_exp_f32_e32 v38, v38
	v_exp_f32_e32 v39, v39
	v_mul_f32_e32 v40, 0xbfb8aa3b, v40
	v_mul_f32_e32 v41, 0xbfb8aa3b, v41
	v_mul_f32_e32 v42, 0xbfb8aa3b, v42
	v_mul_f32_e32 v43, 0xbfb8aa3b, v43
	v_exp_f32_e32 v37, v34
	v_exp_f32_e32 v40, v40
	v_exp_f32_e32 v41, v41
	v_exp_f32_e32 v42, v42
	v_exp_f32_e32 v43, v43
	v_add_f32_e32 v38, 1.0, v38
	v_add_f32_e32 v39, 1.0, v39
	v_add_f32_e32 v36, 1.0, v36
	v_add_f32_e32 v37, 1.0, v37
	v_rcp_f32_e32 v38, v38
	v_rcp_f32_e32 v39, v39
	v_add_f32_e32 v40, 1.0, v40
	v_add_f32_e32 v41, 1.0, v41
	v_add_f32_e32 v42, 1.0, v42
	v_add_f32_e32 v43, 1.0, v43
	v_rcp_f32_e32 v36, v36
	v_rcp_f32_e32 v37, v37
	v_rcp_f32_e32 v40, v40
	v_rcp_f32_e32 v41, v41
	v_rcp_f32_e32 v42, v42
	v_rcp_f32_e32 v43, v43
	v_lshlrev_b32_e32 v46, 16, v91
	v_and_b32_e32 v47, 0xffff0000, v91
	v_lshlrev_b32_e32 v44, 16, v90
	v_and_b32_e32 v45, 0xffff0000, v90
	v_lshlrev_b32_e32 v48, 16, v92
	v_and_b32_e32 v49, 0xffff0000, v92
	v_lshlrev_b32_e32 v50, 16, v93
	v_and_b32_e32 v51, 0xffff0000, v93
	v_pk_fma_f32 v[32:33], v[32:33], v[38:39], v[46:47]
	v_pk_fma_f32 v[30:31], v[30:31], v[36:37], v[44:45]
	v_pk_fma_f32 v[36:37], v[28:29], v[42:43], v[50:51]
	v_pk_fma_f32 v[28:29], v[26:27], v[40:41], v[48:49]
	v_cvt_pk_bf16_f32 v27, v32, v33
	s_waitcnt vmcnt(6)
	v_lshlrev_b32_e32 v32, 16, v86
	v_and_b32_e32 v33, 0xffff0000, v86
	v_mul_f32_e32 v32, 0xbfb8aa3b, v32
	v_mul_f32_e32 v33, 0xbfb8aa3b, v33
	v_exp_f32_e32 v32, v32
	v_exp_f32_e32 v33, v33
	v_lshl_add_u64 v[34:35], s[0:1], 0, v[134:135]
	v_cvt_pk_bf16_f32 v26, v30, v31
	v_cvt_pk_bf16_f32 v28, v28, v29
	v_cvt_pk_bf16_f32 v29, v36, v37
	v_lshl_add_u64 v[30:31], v[34:35], 0, v[130:131]
	global_store_dwordx4 v[30:31], v[26:29], off
	v_lshlrev_b32_e32 v34, 16, v89
	v_and_b32_e32 v35, 0xffff0000, v89
	v_add_f32_e32 v26, 1.0, v32
	v_add_f32_e32 v27, 1.0, v33
	v_lshlrev_b32_e32 v28, 16, v87
	v_and_b32_e32 v29, 0xffff0000, v87
	v_lshlrev_b32_e32 v32, 16, v88
	v_and_b32_e32 v33, 0xffff0000, v88
	v_mul_f32_e32 v28, 0xbfb8aa3b, v28
	v_mul_f32_e32 v29, 0xbfb8aa3b, v29
	v_mul_f32_e32 v32, 0xbfb8aa3b, v32
	v_mul_f32_e32 v33, 0xbfb8aa3b, v33
	v_mul_f32_e32 v34, 0xbfb8aa3b, v34
	v_mul_f32_e32 v35, 0xbfb8aa3b, v35
	v_exp_f32_e32 v28, v28
	v_exp_f32_e32 v29, v29
	v_exp_f32_e32 v32, v32
	v_exp_f32_e32 v33, v33
	v_exp_f32_e32 v34, v34
	v_exp_f32_e32 v35, v35
	v_add_f32_e32 v28, 1.0, v28
	v_add_f32_e32 v29, 1.0, v29
	v_add_f32_e32 v32, 1.0, v32
	v_add_f32_e32 v33, 1.0, v33
	v_add_f32_e32 v34, 1.0, v34
	v_add_f32_e32 v35, 1.0, v35
	v_rcp_f32_e32 v26, v26
	v_rcp_f32_e32 v27, v27
	v_rcp_f32_e32 v28, v28
	v_rcp_f32_e32 v29, v29
	v_rcp_f32_e32 v32, v32
	v_rcp_f32_e32 v33, v33
	v_rcp_f32_e32 v34, v34
	v_rcp_f32_e32 v35, v35
	v_lshlrev_b32_e32 v36, 16, v82
	v_and_b32_e32 v37, 0xffff0000, v82
	v_lshlrev_b32_e32 v38, 16, v83
	v_and_b32_e32 v39, 0xffff0000, v83
	v_lshlrev_b32_e32 v40, 16, v84
	v_and_b32_e32 v41, 0xffff0000, v84
	v_lshlrev_b32_e32 v42, 16, v85
	v_and_b32_e32 v43, 0xffff0000, v85
	v_pk_fma_f32 v[24:25], v[24:25], v[28:29], v[38:39]
	v_pk_fma_f32 v[22:23], v[22:23], v[26:27], v[36:37]
	v_pk_fma_f32 v[26:27], v[20:21], v[34:35], v[42:43]
	v_pk_fma_f32 v[20:21], v[18:19], v[32:33], v[40:41]
	v_cvt_pk_bf16_f32 v18, v22, v23
	v_cvt_pk_bf16_f32 v19, v24, v25
	v_cvt_pk_bf16_f32 v20, v20, v21
	v_cvt_pk_bf16_f32 v21, v26, v27
	global_store_dwordx4 v[30:31], v[18:21], off offset:256
	s_waitcnt vmcnt(7)
; __device__ __forceinline__ unsigned pk2(float lo, float hi) { f32x2 v = {lo, hi}; bf16x2_t b = __builtin_convertvector(v, bf16x2_t); return __builtin_bit_cast(unsigned, b); }
; __device__ __forceinline__ float bflo(unsigned w) { return __uint_as_float(w << 16); }
; __device__ __forceinline__ float bfhi(unsigned w) { return __uint_as_float(w & 0xffff0000u); }
; __device__ __forceinline__ float sigmoidf_(float x) { return __builtin_amdgcn_rcpf(1.0f + __builtin_amdgcn_exp2f(-x * LOG2E)); }
; #define PG8_BAR __builtin_amdgcn_s_barrier()
;     __device__ __forceinline__ void operator()(const f32x4 (&acc)[2][2][4][2], const Unit& u, int wr, int wc, int fr, int fq, LAS unsigned char* lds, int tid) const {
;     ...
;             for (int m = 0; m < 4; ++m) { const size_t row = (size_t)(row0 + ai * HALF + m * 16);
; #pragma unroll
;                 for (int bj = 0; bj < 2; ++bj) { const int col = col0 + bj * HALF; const u32x4 gw = gv[m][bj], pw = pv[m][bj];
;                     f32x4 z0, z1;
;                     z0[0] = sigmoidf_(bflo(gw.x)); z0[1] = sigmoidf_(bfhi(gw.x)); z0[2] = sigmoidf_(bflo(gw.y)); z0[3] = sigmoidf_(bfhi(gw.y));
;                     z1[0] = sigmoidf_(bflo(gw.z)); z1[1] = sigmoidf_(bfhi(gw.z)); z1[2] = sigmoidf_(bflo(gw.w)); z1[3] = sigmoidf_(bfhi(gw.w));
;                     const f32x4 q0 = {bflo(pw.x), bfhi(pw.x), bflo(pw.y), bfhi(pw.y)}, q1 = {bflo(pw.z), bfhi(pw.z), bflo(pw.w), bfhi(pw.w)};
;                     z0 = z0 * acc[ai][bj][m][0] + q0; z1 = z1 * acc[ai][bj][m][1] + q1;
;                     u32x4 w; w.x = pk2(z0[0], z0[1]); w.y = pk2(z0[2], z0[3]); w.z = pk2(z1[0], z1[1]); w.w = pk2(z1[2], z1[3]);
;                     *(gu32x4*)(dst + row * DM + col) = w; } }
; template <class Epi, class Sched>
; __device__ __forceinline__ void gemm_phase(LAS unsigned char* lds, const int tid, const Gemm g, const Sched& S, const Epi& E) {
;     ...
;         if (!has_next) break;
; #pragma unroll
;         for (int a = 0; a < 2; ++a)
; #pragma unroll
;             for (int b = 0; b < 2; ++b)
; #pragma unroll
;                 for (int m = 0; m < 4; ++m)
; #pragma unroll
;                     for (int n = 0; n < 2; ++n) acc[a][b][m][n] = (f32x4){0.f, 0.f, 0.f, 0.f};
;         cur = nxt; cA = nA; cB = nB; ++ui;
;         if (wr == 1) PG8_BAR;
	v_lshlrev_b32_e32 v22, 16, v79
	v_and_b32_e32 v23, 0xffff0000, v79
	v_lshlrev_b32_e32 v18, 16, v78
	v_mul_f32_e32 v18, 0xbfb8aa3b, v18
	v_exp_f32_e32 v20, v18
	v_and_b32_e32 v18, 0xffff0000, v78
	v_mul_f32_e32 v22, 0xbfb8aa3b, v22
	v_mul_f32_e32 v23, 0xbfb8aa3b, v23
	v_lshlrev_b32_e32 v24, 16, v80
	v_and_b32_e32 v25, 0xffff0000, v80
	v_lshlrev_b32_e32 v26, 16, v81
	v_and_b32_e32 v27, 0xffff0000, v81
	v_mul_f32_e32 v18, 0xbfb8aa3b, v18
	v_exp_f32_e32 v22, v22
	v_exp_f32_e32 v23, v23
	v_mul_f32_e32 v24, 0xbfb8aa3b, v24
	v_mul_f32_e32 v25, 0xbfb8aa3b, v25
	v_mul_f32_e32 v26, 0xbfb8aa3b, v26
	v_mul_f32_e32 v27, 0xbfb8aa3b, v27
	v_exp_f32_e32 v21, v18
	v_exp_f32_e32 v24, v24
	v_exp_f32_e32 v25, v25
	v_exp_f32_e32 v26, v26
	v_exp_f32_e32 v27, v27
	v_add_f32_e32 v22, 1.0, v22
	v_add_f32_e32 v23, 1.0, v23
	v_add_f32_e32 v20, 1.0, v20
	v_add_f32_e32 v21, 1.0, v21
	v_rcp_f32_e32 v22, v22
	v_rcp_f32_e32 v23, v23
	v_add_f32_e32 v24, 1.0, v24
	v_add_f32_e32 v25, 1.0, v25
	v_add_f32_e32 v26, 1.0, v26
	v_add_f32_e32 v27, 1.0, v27
	v_rcp_f32_e32 v20, v20
	v_rcp_f32_e32 v21, v21
	v_rcp_f32_e32 v24, v24
	v_rcp_f32_e32 v25, v25
	v_rcp_f32_e32 v26, v26
	v_rcp_f32_e32 v27, v27
	v_lshlrev_b32_e32 v30, 16, v75
	v_and_b32_e32 v31, 0xffff0000, v75
	v_lshlrev_b32_e32 v28, 16, v74
	v_and_b32_e32 v29, 0xffff0000, v74
	v_lshlrev_b32_e32 v32, 16, v76
	v_and_b32_e32 v33, 0xffff0000, v76
	v_lshlrev_b32_e32 v34, 16, v77
	v_and_b32_e32 v35, 0xffff0000, v77
	v_pk_fma_f32 v[16:17], v[16:17], v[22:23], v[30:31]
	v_pk_fma_f32 v[14:15], v[14:15], v[20:21], v[28:29]
	v_pk_fma_f32 v[20:21], v[12:13], v[26:27], v[34:35]
	v_pk_fma_f32 v[12:13], v[10:11], v[24:25], v[32:33]
	v_cvt_pk_bf16_f32 v11, v16, v17
	s_waitcnt vmcnt(6)
	v_lshlrev_b32_e32 v16, 16, v70
	v_and_b32_e32 v17, 0xffff0000, v70
	v_mul_f32_e32 v16, 0xbfb8aa3b, v16
	v_mul_f32_e32 v17, 0xbfb8aa3b, v17
	v_exp_f32_e32 v16, v16
	v_exp_f32_e32 v17, v17
	v_lshl_add_u64 v[18:19], s[0:1], 0, v[132:133]
	v_cvt_pk_bf16_f32 v10, v14, v15
	v_cvt_pk_bf16_f32 v12, v12, v13
	v_cvt_pk_bf16_f32 v13, v20, v21
	v_lshl_add_u64 v[14:15], v[18:19], 0, v[130:131]
	global_store_dwordx4 v[14:15], v[10:13], off
	v_lshlrev_b32_e32 v18, 16, v73
	v_and_b32_e32 v19, 0xffff0000, v73
	v_add_f32_e32 v10, 1.0, v16
	v_add_f32_e32 v11, 1.0, v17
	v_lshlrev_b32_e32 v12, 16, v71
	v_and_b32_e32 v13, 0xffff0000, v71
	v_lshlrev_b32_e32 v16, 16, v72
	v_and_b32_e32 v17, 0xffff0000, v72
	v_mul_f32_e32 v12, 0xbfb8aa3b, v12
	v_mul_f32_e32 v13, 0xbfb8aa3b, v13
	v_mul_f32_e32 v16, 0xbfb8aa3b, v16
	v_mul_f32_e32 v17, 0xbfb8aa3b, v17
	v_mul_f32_e32 v18, 0xbfb8aa3b, v18
	v_mul_f32_e32 v19, 0xbfb8aa3b, v19
	v_exp_f32_e32 v12, v12
	v_exp_f32_e32 v13, v13
	v_exp_f32_e32 v16, v16
	v_exp_f32_e32 v17, v17
	v_exp_f32_e32 v18, v18
	v_exp_f32_e32 v19, v19
	v_add_f32_e32 v12, 1.0, v12
	v_add_f32_e32 v13, 1.0, v13
	v_add_f32_e32 v16, 1.0, v16
	v_add_f32_e32 v17, 1.0, v17
	v_add_f32_e32 v18, 1.0, v18
	v_add_f32_e32 v19, 1.0, v19
	v_rcp_f32_e32 v10, v10
	v_rcp_f32_e32 v11, v11
	v_rcp_f32_e32 v12, v12
	v_rcp_f32_e32 v13, v13
	v_rcp_f32_e32 v16, v16
	v_rcp_f32_e32 v17, v17
	v_rcp_f32_e32 v18, v18
	v_rcp_f32_e32 v19, v19
	v_lshlrev_b32_e32 v20, 16, v66
	v_and_b32_e32 v21, 0xffff0000, v66
	v_lshlrev_b32_e32 v22, 16, v67
	v_and_b32_e32 v23, 0xffff0000, v67
	v_lshlrev_b32_e32 v24, 16, v68
	v_and_b32_e32 v25, 0xffff0000, v68
	v_lshlrev_b32_e32 v26, 16, v69
	v_and_b32_e32 v27, 0xffff0000, v69
	v_pk_fma_f32 v[8:9], v[8:9], v[12:13], v[22:23]
	v_pk_fma_f32 v[6:7], v[6:7], v[10:11], v[20:21]
	v_pk_fma_f32 v[10:11], v[4:5], v[18:19], v[26:27]
	v_pk_fma_f32 v[4:5], v[2:3], v[16:17], v[24:25]
	v_cvt_pk_bf16_f32 v2, v6, v7
	v_cvt_pk_bf16_f32 v3, v8, v9
	v_cvt_pk_bf16_f32 v4, v4, v5
	v_cvt_pk_bf16_f32 v5, v10, v11
	global_store_dwordx4 v[14:15], v[2:5], off offset:256
	s_andn2_b64 vcc, exec, s[2:3]
	s_mov_b64 s[0:1], -1
	s_cbranch_vccnz .LBB0_436
	s_andn2_b64 vcc, exec, s[6:7]
	s_cbranch_vccnz .LBB0_435
	s_mov_b32 vcc_lo, 1
	s_nop 0
	v_writelane_b32 v255, vcc_lo, 21
	s_branch .LBB0_435

; #define PG8_STAGE(bufoff, gbase, voff) do { _Pragma("unroll") for (int _i = 0; _i < 2; ++_i) \
;         __builtin_amdgcn_global_load_lds((const gunsigned*)((const gchar*)(gbase) + (voff)[_i]), (LAS unsigned*)(lds + (bufoff) + ldsw + _i * 8192), 16, 0, 0); } while (0)
; #define PG8_LDA(dst, b, h) do { _Pragma("unroll") for (int m = 0; m < 4; ++m) _Pragma("unroll") for (int k = 0; k < 2; ++k) dst[m][k] = *(const LAS bf16x8*)(lds + PG8_SA(b, h) + aoff + m * 2048 + k * 1024); } while (0)
; #define PG8_LDB(dst, b, h) do { _Pragma("unroll") for (int n = 0; n < 2; ++n) _Pragma("unroll") for (int k = 0; k < 2; ++k) dst[n][k] = *(const LAS bf16x8*)(lds + PG8_SB(b, h) + boff + n * 2048 + k * 1024); } while (0)
; #define PG8_WAIT_V(n) asm volatile("s_waitcnt vmcnt(" #n ")" ::: "memory")
; #define PG8_WAIT_L(n) asm volatile("s_waitcnt lgkmcnt(" #n ")" ::: "memory")
; #define PG8_BAR __builtin_amdgcn_s_barrier()
; #define PG8_SCHED __builtin_amdgcn_sched_barrier(0)
; template <class Epi, class Sched>
; __device__ __forceinline__ void gemm_phase(LAS unsigned char* lds, const int tid, const Gemm g, const Sched& S, const Epi& E) {
;     ...
;         const gchar* nA = has_next ? (const gchar*)g.A + (size_t)nxt.pm * tstep + (size_t)nxt.pz * g.zA : cA;
;         const gchar* nB = has_next ? (const gchar*)g.Bt + (size_t)nxt.pn * tstep + (size_t)nxt.pz * g.zB : cB;
;         for (int t = 0; t < nt; t += 2) {
;             const bool last = (t == nt - 2);
;             const gchar* a1 = cA + (size_t)(t + 1) * kstep;
;             const gchar* a2 = last ? nA : cA + (size_t)(t + 2) * kstep; const gchar* b2 = last ? nB : cB + (size_t)(t + 2) * kstep;
;             const gchar* a3 = a2 + kstep; const gchar* b3 = b2 + kstep;
;             PG8_LDB(B0, 0, 0); PG8_LDB(B1, 0, 1); PG8_SCHED; PG8_LDA(At, 0, 0); PG8_STAGE(PG8_SA(1, 1), a1 + hstep, voffA);
;             PG8_WAIT_V(8); PG8_WAIT_L(0); PG8_BAR; PG8_MMA(0, 0, At, B0); PG8_MMA(0, 1, At, B1); PG8_BAR; PG8_SCHED;
;     ...
; #pragma unroll
;         for (int a = 0; a < 2; ++a)
; #pragma unroll
;             for (int b = 0; b < 2; ++b)
; #pragma unroll
;                 for (int m = 0; m < 4; ++m)
; #pragma unroll
;                     for (int n = 0; n < 2; ++n) acc[a][b][m][n] = (f32x4){0.f, 0.f, 0.f, 0.f};
;         cur = nxt; cA = nA; cB = nB; ++ui;
;         if (wr == 1) PG8_BAR;
.LBB0_558:
	s_ashr_i32 s9, s8, 31
	s_lshl_b64 s[16:17], s[8:9], 19
	s_add_u32 s16, s86, s16
	s_addc_u32 s17, s87, s17
	s_and_b64 s[42:43], s[2:3], exec
	s_cselect_b32 s9, s17, s61
	s_cselect_b32 s42, s16, s60
	s_ashr_i32 s7, s6, 31
	s_lshl_b64 s[44:45], s[6:7], 19
	s_add_u32 s56, s15, s44
	s_addc_u32 s57, s23, s45
	s_and_b64 s[44:45], s[2:3], exec
	s_cselect_b32 s7, s57, s21
	s_cselect_b32 s43, s56, s20
	s_add_u32 s44, s20, 0x100
	s_addc_u32 s45, s21, 0
	s_add_u32 s60, s60, 0x40080
	v_mov_b32_e32 v2, 0
	s_addc_u32 s61, s61, 0
	s_mov_b32 s46, -2
	v_mov_b32_e32 v3, v2
	v_mov_b32_e32 v4, v2
	v_mov_b32_e32 v5, v2
	v_mov_b32_e32 v6, v2
	v_mov_b32_e32 v7, v2
	v_mov_b32_e32 v8, v2
	v_mov_b32_e32 v9, v2
	v_mov_b32_e32 v10, v2
	v_mov_b32_e32 v11, v2
	v_mov_b32_e32 v12, v2
	v_mov_b32_e32 v13, v2
	v_mov_b32_e32 v18, v2
	v_mov_b32_e32 v19, v2
	v_mov_b32_e32 v20, v2
	v_mov_b32_e32 v21, v2
	v_mov_b32_e32 v26, v2
	v_mov_b32_e32 v27, v2
	v_mov_b32_e32 v28, v2
	v_mov_b32_e32 v29, v2
	v_mov_b32_e32 v34, v2
	v_mov_b32_e32 v35, v2
	v_mov_b32_e32 v36, v2
	v_mov_b32_e32 v37, v2
	v_mov_b32_e32 v42, v2
	v_mov_b32_e32 v43, v2
	v_mov_b32_e32 v44, v2
	v_mov_b32_e32 v45, v2
	v_mov_b32_e32 v50, v2
	v_mov_b32_e32 v51, v2
	v_mov_b32_e32 v52, v2
	v_mov_b32_e32 v53, v2
	v_mov_b32_e32 v14, v2
	v_mov_b32_e32 v15, v2
	v_mov_b32_e32 v16, v2
	v_mov_b32_e32 v17, v2
	v_mov_b32_e32 v22, v2
	v_mov_b32_e32 v23, v2
	v_mov_b32_e32 v24, v2
	v_mov_b32_e32 v25, v2
	v_mov_b32_e32 v30, v2
	v_mov_b32_e32 v31, v2
	v_mov_b32_e32 v32, v2
	v_mov_b32_e32 v33, v2
	v_mov_b32_e32 v38, v2
	v_mov_b32_e32 v39, v2
	v_mov_b32_e32 v40, v2
	v_mov_b32_e32 v41, v2
	v_mov_b32_e32 v46, v2
	v_mov_b32_e32 v47, v2
	v_mov_b32_e32 v48, v2
	v_mov_b32_e32 v49, v2
	v_mov_b32_e32 v54, v2
	v_mov_b32_e32 v55, v2
	v_mov_b32_e32 v56, v2
	v_mov_b32_e32 v57, v2
	v_mov_b32_e32 v58, v2
	v_mov_b32_e32 v59, v2
	v_mov_b32_e32 v60, v2
	v_mov_b32_e32 v61, v2
	v_mov_b32_e32 v62, v2
	v_mov_b32_e32 v63, v2
	v_mov_b32_e32 v64, v2
	v_mov_b32_e32 v65, v2
	v_mov_b32_e32 v66, v2
	v_mov_b32_e32 v67, v2
	v_mov_b32_e32 v68, v2
	v_mov_b32_e32 v69, v2
	v_mov_b32_e32 v70, v2
	v_mov_b32_e32 v71, v2
	v_mov_b32_e32 v72, v2
	v_mov_b32_e32 v73, v2
	v_mov_b32_e32 v74, v2
	v_mov_b32_e32 v75, v2
	v_mov_b32_e32 v76, v2
	v_mov_b32_e32 v77, v2
	s_waitcnt vmcnt(0)
	v_mov_b32_e32 v82, v2
	v_mov_b32_e32 v83, v2
	v_mov_b32_e32 v84, v2
	v_mov_b32_e32 v85, v2
	v_mov_b32_e32 v90, v2
	v_mov_b32_e32 v91, v2
	v_mov_b32_e32 v92, v2
	v_mov_b32_e32 v93, v2
	v_mov_b32_e32 v98, v2
	v_mov_b32_e32 v99, v2
	v_mov_b32_e32 v100, v2
	v_mov_b32_e32 v101, v2
	v_mov_b32_e32 v106, v2
	v_mov_b32_e32 v107, v2
	v_mov_b32_e32 v108, v2
	v_mov_b32_e32 v109, v2
	v_mov_b32_e32 v114, v2
	v_mov_b32_e32 v115, v2
	v_mov_b32_e32 v116, v2
	v_mov_b32_e32 v117, v2
	v_mov_b32_e32 v78, v2
	v_mov_b32_e32 v79, v2
	v_mov_b32_e32 v80, v2
	v_mov_b32_e32 v81, v2
	v_mov_b32_e32 v86, v2
	v_mov_b32_e32 v87, v2
	v_mov_b32_e32 v88, v2
	v_mov_b32_e32 v89, v2
	v_mov_b32_e32 v94, v2
	v_mov_b32_e32 v95, v2
	v_mov_b32_e32 v96, v2
	v_mov_b32_e32 v97, v2
	v_mov_b32_e32 v102, v2
	v_mov_b32_e32 v103, v2
	v_mov_b32_e32 v104, v2
	v_mov_b32_e32 v105, v2
	v_mov_b32_e32 v110, v2
	v_mov_b32_e32 v111, v2
	v_mov_b32_e32 v112, v2
	v_mov_b32_e32 v113, v2
	v_mov_b32_e32 v118, v2
	v_mov_b32_e32 v119, v2
	v_mov_b32_e32 v120, v2
	v_mov_b32_e32 v121, v2
	v_mov_b32_e32 v122, v2
	v_mov_b32_e32 v123, v2
	v_mov_b32_e32 v124, v2
	v_mov_b32_e32 v125, v2
	v_mov_b32_e32 v126, v2
	v_mov_b32_e32 v127, v2
	v_mov_b32_e32 v128, v2
	v_mov_b32_e32 v129, v2
	v_add_u32_e32 v161, 0x80, v0
	v_add_u32_e32 v195, 0x80, v134
	v_add_u32_e32 v201, 0x80, v138
	v_add_u32_e32 v227, 0x80, v136
	v_readlane_b32 vcc_lo, v255, 21
	s_nop 3
	s_cmp_eq_u32 vcc_lo, 1
	s_cbranch_scc0 .Lnb_559
	s_barrier
	s_mov_b32 vcc_lo, 0
	s_nop 0
	v_writelane_b32 v255, vcc_lo, 21
.Lnb_559:
.LBB0_559:
	s_add_u32 s20, s60, 0xfffc0080
	s_addc_u32 s21, s61, -1
	s_add_i32 s29, 0, 0x10000
	s_cmp_eq_u32 s46, 12
	s_cselect_b32 s63, s9, s21
	s_cselect_b32 s62, s42, s20
	s_cselect_b32 s21, s7, s45
	s_cselect_b32 s20, s43, s44
	s_add_i32 s30, 0, 0x14000
	v_add_u32_e32 v152, s29, v165
	v_add_u32_e32 v160, s30, v165
	ds_read_b128 v[130:133], v152
	ds_read_b128 v[144:147], v152 offset:1024
	ds_read_b128 v[148:151], v152 offset:2048
	ds_read_b128 v[152:155], v152 offset:3072
	ds_read_b128 v[156:159], v160
	ds_read_b128 v[170:173], v160 offset:1024
	ds_read_b128 v[174:177], v160 offset:2048
	ds_read_b128 v[178:181], v160 offset:3072
	s_add_i32 m0, s34, 0xc000
	ds_read_b128 v[182:185], v169
	ds_read_b128 v[186:189], v169 offset:1024
	ds_read_b128 v[190:193], v169 offset:2048
	ds_read_b128 v[204:207], v169 offset:3072
	ds_read_b128 v[210:213], v169 offset:4096
	ds_read_b128 v[214:217], v169 offset:5120
	ds_read_b128 v[218:221], v169 offset:6144
	ds_read_b128 v[222:225], v169 offset:7168
	global_load_lds_dwordx4 v142, s[60:61]
	s_add_i32 m0, s34, 0xe000
	s_nop 0
	global_load_lds_dwordx4 v140, s[60:61]
	s_waitcnt vmcnt(8)
	s_waitcnt lgkmcnt(0)
	s_setprio 1
	s_barrier
; #define PG8_STAGE(bufoff, gbase, voff) do { _Pragma("unroll") for (int _i = 0; _i < 2; ++_i) \
;         __builtin_amdgcn_global_load_lds((const gunsigned*)((const gchar*)(gbase) + (voff)[_i]), (LAS unsigned*)(lds + (bufoff) + ldsw + _i * 8192), 16, 0, 0); } while (0)
; #define PG8_LDA(dst, b, h) do { _Pragma("unroll") for (int m = 0; m < 4; ++m) _Pragma("unroll") for (int k = 0; k < 2; ++k) dst[m][k] = *(const LAS bf16x8*)(lds + PG8_SA(b, h) + aoff + m * 2048 + k * 1024); } while (0)
; #define PG8_LDB(dst, b, h) do { _Pragma("unroll") for (int n = 0; n < 2; ++n) _Pragma("unroll") for (int k = 0; k < 2; ++k) dst[n][k] = *(const LAS bf16x8*)(lds + PG8_SB(b, h) + boff + n * 2048 + k * 1024); } while (0)
; #define PG8_MMA(ai, bj, At, Bt) do { __builtin_amdgcn_s_setprio(1); _Pragma("unroll") for (int m = 0; m < 4; ++m) _Pragma("unroll") for (int n = 0; n < 2; ++n) _Pragma("unroll") for (int k = 0; k < 2; ++k) \
;         acc[ai][bj][m][n] = __builtin_amdgcn_mfma_f32_16x16x32_bf16(Bt[n][k], At[m][k], acc[ai][bj][m][n], 0, 0, 0); __builtin_amdgcn_s_setprio(0); } while (0)
; #define PG8_WAIT_V(n) asm volatile("s_waitcnt vmcnt(" #n ")" ::: "memory")
; #define PG8_WAIT_L(n) asm volatile("s_waitcnt lgkmcnt(" #n ")" ::: "memory")
; #define PG8_BAR __builtin_amdgcn_s_barrier()
; #define PG8_SCHED __builtin_amdgcn_sched_barrier(0)
; template <class Epi, class Sched>
; __device__ __forceinline__ void gemm_phase(LAS unsigned char* lds, const int tid, const Gemm g, const Sched& S, const Epi& E) {
;     ...
;             PG8_LDB(B0, 0, 0); PG8_LDB(B1, 0, 1); PG8_SCHED; PG8_LDA(At, 0, 0); PG8_STAGE(PG8_SA(1, 1), a1 + hstep, voffA);
;             PG8_WAIT_V(8); PG8_WAIT_L(0); PG8_BAR; PG8_MMA(0, 0, At, B0); PG8_MMA(0, 1, At, B1); PG8_BAR; PG8_SCHED;
;             PG8_LDA(At, 0, 1); PG8_STAGE(PG8_SB(0, 0), b2, voffB); PG8_STAGE(PG8_SB(0, 1), b2 + hstep, voffB); PG8_STAGE(PG8_SA(0, 0), a2, voffA);
;             PG8_WAIT_V(8); PG8_WAIT_L(0); PG8_BAR; PG8_MMA(1, 0, At, B0); PG8_MMA(1, 1, At, B1); PG8_BAR; PG8_SCHED;
;             PG8_LDB(B0, 1, 0); PG8_LDB(B1, 1, 1); PG8_SCHED; PG8_LDA(At, 1, 0); PG8_STAGE(PG8_SA(0, 1), a2 + hstep, voffA);
;             PG8_WAIT_V(8); PG8_WAIT_L(0); PG8_BAR; PG8_MMA(0, 0, At, B0); PG8_MMA(0, 1, At, B1); PG8_BAR; PG8_SCHED;
	v_mfma_f32_16x16x32_bf16 v[126:129], v[130:133], v[182:185], v[126:129]
	v_mfma_f32_16x16x32_bf16 v[122:125], v[148:151], v[182:185], v[122:125]
	v_mfma_f32_16x16x32_bf16 v[118:121], v[130:133], v[190:193], v[118:121]
	v_mfma_f32_16x16x32_bf16 v[110:113], v[148:151], v[190:193], v[110:113]
	v_mfma_f32_16x16x32_bf16 v[102:105], v[130:133], v[210:213], v[102:105]
	v_mfma_f32_16x16x32_bf16 v[94:97], v[148:151], v[210:213], v[94:97]
	v_mfma_f32_16x16x32_bf16 v[86:89], v[130:133], v[218:221], v[86:89]
	v_mfma_f32_16x16x32_bf16 v[78:81], v[148:151], v[218:221], v[78:81]
	v_mfma_f32_16x16x32_bf16 v[126:129], v[144:147], v[186:189], v[126:129]
	v_mfma_f32_16x16x32_bf16 v[122:125], v[152:155], v[186:189], v[122:125]
	v_mfma_f32_16x16x32_bf16 v[118:121], v[144:147], v[204:207], v[118:121]
	v_mfma_f32_16x16x32_bf16 v[110:113], v[152:155], v[204:207], v[110:113]
	v_mfma_f32_16x16x32_bf16 v[102:105], v[144:147], v[214:217], v[102:105]
	v_mfma_f32_16x16x32_bf16 v[94:97], v[152:155], v[214:217], v[94:97]
	v_mfma_f32_16x16x32_bf16 v[86:89], v[144:147], v[222:225], v[86:89]
	v_mfma_f32_16x16x32_bf16 v[78:81], v[152:155], v[222:225], v[78:81]
	s_setprio 0
	s_setprio 1
	v_mfma_f32_16x16x32_bf16 v[114:117], v[156:159], v[182:185], v[114:117]
	v_mfma_f32_16x16x32_bf16 v[106:109], v[174:177], v[182:185], v[106:109]
	v_mfma_f32_16x16x32_bf16 v[98:101], v[156:159], v[190:193], v[98:101]
	v_mfma_f32_16x16x32_bf16 v[90:93], v[174:177], v[190:193], v[90:93]
	v_mfma_f32_16x16x32_bf16 v[82:85], v[156:159], v[210:213], v[82:85]
	v_mfma_f32_16x16x32_bf16 v[74:77], v[174:177], v[210:213], v[74:77]
	v_mfma_f32_16x16x32_bf16 v[70:73], v[156:159], v[218:221], v[70:73]
	v_mfma_f32_16x16x32_bf16 v[66:69], v[174:177], v[218:221], v[66:69]
	v_mfma_f32_16x16x32_bf16 v[114:117], v[170:173], v[186:189], v[114:117]
	v_mfma_f32_16x16x32_bf16 v[106:109], v[178:181], v[186:189], v[106:109]
	v_mfma_f32_16x16x32_bf16 v[98:101], v[170:173], v[204:207], v[98:101]
	v_mfma_f32_16x16x32_bf16 v[90:93], v[178:181], v[204:207], v[90:93]
	v_mfma_f32_16x16x32_bf16 v[82:85], v[170:173], v[214:217], v[82:85]
	v_mfma_f32_16x16x32_bf16 v[74:77], v[178:181], v[214:217], v[74:77]
	v_mfma_f32_16x16x32_bf16 v[70:73], v[170:173], v[222:225], v[70:73]
	v_mfma_f32_16x16x32_bf16 v[66:69], v[178:181], v[222:225], v[66:69]
	s_barrier
	s_setprio 0
	s_add_i32 s29, s29, s12
	s_mov_b32 m0, s29
	ds_read_b128 v[182:185], v169 offset:16384
	ds_read_b128 v[186:189], v169 offset:17408
	ds_read_b128 v[190:193], v169 offset:18432
	ds_read_b128 v[204:207], v169 offset:19456
	ds_read_b128 v[210:213], v169 offset:20480
	ds_read_b128 v[214:217], v169 offset:21504
	ds_read_b128 v[218:221], v169 offset:22528
	ds_read_b128 v[222:225], v169 offset:23552
	global_load_lds_dwordx4 v0, s[20:21]
	s_add_i32 m0, s29, 0x2000
	s_add_u32 s48, s20, 0x40000
	s_addc_u32 s49, s21, 0
	s_add_i32 s29, s30, s12
	global_load_lds_dwordx4 v134, s[20:21]
	s_mov_b32 m0, s29
	s_nop 0
	global_load_lds_dwordx4 v0, s[48:49]
	s_add_i32 m0, s29, 0x2000
	s_nop 0
	global_load_lds_dwordx4 v134, s[48:49]
	s_mov_b32 m0, s34
	s_nop 0
	global_load_lds_dwordx4 v138, s[62:63]
	s_mov_b32 m0, s35
	s_nop 0
	global_load_lds_dwordx4 v136, s[62:63]
	s_waitcnt vmcnt(8)
	s_waitcnt lgkmcnt(0)
	s_setprio 1
	s_barrier
	v_mfma_f32_16x16x32_bf16 v[62:65], v[130:133], v[182:185], v[62:65]
	v_mfma_f32_16x16x32_bf16 v[58:61], v[148:151], v[182:185], v[58:61]
	v_mfma_f32_16x16x32_bf16 v[54:57], v[130:133], v[190:193], v[54:57]
	v_mfma_f32_16x16x32_bf16 v[46:49], v[148:151], v[190:193], v[46:49]
	v_mfma_f32_16x16x32_bf16 v[38:41], v[130:133], v[210:213], v[38:41]
	v_mfma_f32_16x16x32_bf16 v[30:33], v[148:151], v[210:213], v[30:33]
	v_mfma_f32_16x16x32_bf16 v[22:25], v[130:133], v[218:221], v[22:25]
	v_mfma_f32_16x16x32_bf16 v[14:17], v[148:151], v[218:221], v[14:17]
	v_mfma_f32_16x16x32_bf16 v[62:65], v[144:147], v[186:189], v[62:65]
	v_mfma_f32_16x16x32_bf16 v[58:61], v[152:155], v[186:189], v[58:61]
	v_mfma_f32_16x16x32_bf16 v[54:57], v[144:147], v[204:207], v[54:57]
	v_mfma_f32_16x16x32_bf16 v[46:49], v[152:155], v[204:207], v[46:49]
	v_mfma_f32_16x16x32_bf16 v[38:41], v[144:147], v[214:217], v[38:41]
	v_mfma_f32_16x16x32_bf16 v[30:33], v[152:155], v[214:217], v[30:33]
	v_mfma_f32_16x16x32_bf16 v[22:25], v[144:147], v[222:225], v[22:25]
	v_mfma_f32_16x16x32_bf16 v[14:17], v[152:155], v[222:225], v[14:17]
	s_setprio 0
	s_setprio 1
	v_mfma_f32_16x16x32_bf16 v[50:53], v[156:159], v[182:185], v[50:53]
	v_mfma_f32_16x16x32_bf16 v[42:45], v[174:177], v[182:185], v[42:45]
	v_mfma_f32_16x16x32_bf16 v[34:37], v[156:159], v[190:193], v[34:37]
	v_mfma_f32_16x16x32_bf16 v[26:29], v[174:177], v[190:193], v[26:29]
	v_mfma_f32_16x16x32_bf16 v[18:21], v[156:159], v[210:213], v[18:21]
	v_mfma_f32_16x16x32_bf16 v[10:13], v[174:177], v[210:213], v[10:13]
	v_mfma_f32_16x16x32_bf16 v[6:9], v[156:159], v[218:221], v[6:9]
	v_mfma_f32_16x16x32_bf16 v[2:5], v[174:177], v[218:221], v[2:5]
	v_mfma_f32_16x16x32_bf16 v[50:53], v[170:173], v[186:189], v[50:53]
	v_mfma_f32_16x16x32_bf16 v[42:45], v[178:181], v[186:189], v[42:45]
	v_mfma_f32_16x16x32_bf16 v[34:37], v[170:173], v[204:207], v[34:37]
	v_mfma_f32_16x16x32_bf16 v[26:29], v[178:181], v[204:207], v[26:29]
	v_mfma_f32_16x16x32_bf16 v[18:21], v[170:173], v[214:217], v[18:21]
	v_mfma_f32_16x16x32_bf16 v[10:13], v[178:181], v[214:217], v[10:13]
	v_mfma_f32_16x16x32_bf16 v[6:9], v[170:173], v[222:225], v[6:9]
	v_mfma_f32_16x16x32_bf16 v[2:5], v[178:181], v[222:225], v[2:5]
	s_barrier
; #define PG8_STAGE(bufoff, gbase, voff) do { _Pragma("unroll") for (int _i = 0; _i < 2; ++_i) \
;         __builtin_amdgcn_global_load_lds((const gunsigned*)((const gchar*)(gbase) + (voff)[_i]), (LAS unsigned*)(lds + (bufoff) + ldsw + _i * 8192), 16, 0, 0); } while (0)
; #define PG8_LDA(dst, b, h) do { _Pragma("unroll") for (int m = 0; m < 4; ++m) _Pragma("unroll") for (int k = 0; k < 2; ++k) dst[m][k] = *(const LAS bf16x8*)(lds + PG8_SA(b, h) + aoff + m * 2048 + k * 1024); } while (0)
; #define PG8_LDB(dst, b, h) do { _Pragma("unroll") for (int n = 0; n < 2; ++n) _Pragma("unroll") for (int k = 0; k < 2; ++k) dst[n][k] = *(const LAS bf16x8*)(lds + PG8_SB(b, h) + boff + n * 2048 + k * 1024); } while (0)
; #define PG8_MMA(ai, bj, At, Bt) do { __builtin_amdgcn_s_setprio(1); _Pragma("unroll") for (int m = 0; m < 4; ++m) _Pragma("unroll") for (int n = 0; n < 2; ++n) _Pragma("unroll") for (int k = 0; k < 2; ++k) \
;         acc[ai][bj][m][n] = __builtin_amdgcn_mfma_f32_16x16x32_bf16(Bt[n][k], At[m][k], acc[ai][bj][m][n], 0, 0, 0); __builtin_amdgcn_s_setprio(0); } while (0)
; #define PG8_WAIT_V(n) asm volatile("s_waitcnt vmcnt(" #n ")" ::: "memory")
; #define PG8_WAIT_L(n) asm volatile("s_waitcnt lgkmcnt(" #n ")" ::: "memory")
; #define PG8_BAR __builtin_amdgcn_s_barrier()
; #define PG8_SCHED __builtin_amdgcn_sched_barrier(0)
; template <class Epi, class Sched>
; __device__ __forceinline__ void gemm_phase(LAS unsigned char* lds, const int tid, const Gemm g, const Sched& S, const Epi& E) {
;     ...
;             PG8_LDB(B0, 1, 0); PG8_LDB(B1, 1, 1); PG8_SCHED; PG8_LDA(At, 1, 0); PG8_STAGE(PG8_SA(0, 1), a2 + hstep, voffA);
;             PG8_WAIT_V(8); PG8_WAIT_L(0); PG8_BAR; PG8_MMA(0, 0, At, B0); PG8_MMA(0, 1, At, B1); PG8_BAR; PG8_SCHED;
;             PG8_LDA(At, 1, 1); PG8_STAGE(PG8_SB(1, 0), b3, voffB); PG8_STAGE(PG8_SB(1, 1), b3 + hstep, voffB); PG8_STAGE(PG8_SA(1, 0), a3, voffA);
;             PG8_WAIT_V(8); PG8_WAIT_L(0); PG8_BAR; PG8_MMA(1, 0, At, B0); PG8_MMA(1, 1, At, B1); PG8_BAR; PG8_SCHED;
;         }
;         if (wr == 0) PG8_BAR;
	s_setprio 0
	s_add_i32 s29, 0, 0x18000
	s_add_i32 s30, 0, 0x1c000
	v_add_u32_e32 v152, s29, v165
	v_add_u32_e32 v162, s30, v165
	ds_read_b128 v[130:133], v152
	ds_read_b128 v[144:147], v152 offset:1024
	ds_read_b128 v[148:151], v152 offset:2048
	ds_read_b128 v[152:155], v152 offset:3072
	ds_read_b128 v[156:159], v162
	ds_read_b128 v[170:173], v162 offset:1024
	ds_read_b128 v[174:177], v162 offset:2048
	ds_read_b128 v[178:181], v162 offset:3072
	s_add_u32 s48, s62, 0x40000
	s_addc_u32 s49, s63, 0
	s_mov_b32 m0, s36
	ds_read_b128 v[182:185], v169 offset:32768
	ds_read_b128 v[186:189], v169 offset:33792
	ds_read_b128 v[190:193], v169 offset:34816
	ds_read_b128 v[204:207], v169 offset:35840
	ds_read_b128 v[210:213], v169 offset:36864
	ds_read_b128 v[214:217], v169 offset:37888
	ds_read_b128 v[218:221], v169 offset:38912
	ds_read_b128 v[222:225], v169 offset:39936
	global_load_lds_dwordx4 v138, s[48:49]
	s_mov_b32 m0, s37
	s_nop 0
	global_load_lds_dwordx4 v136, s[48:49]
	s_waitcnt vmcnt(8)
	s_waitcnt lgkmcnt(0)
	s_setprio 1
	s_barrier
	v_mfma_f32_16x16x32_bf16 v[126:129], v[130:133], v[182:185], v[126:129]
	v_mfma_f32_16x16x32_bf16 v[122:125], v[148:151], v[182:185], v[122:125]
	v_mfma_f32_16x16x32_bf16 v[118:121], v[130:133], v[190:193], v[118:121]
	v_mfma_f32_16x16x32_bf16 v[110:113], v[148:151], v[190:193], v[110:113]
	v_mfma_f32_16x16x32_bf16 v[102:105], v[130:133], v[210:213], v[102:105]
	v_mfma_f32_16x16x32_bf16 v[94:97], v[148:151], v[210:213], v[94:97]
	v_mfma_f32_16x16x32_bf16 v[86:89], v[130:133], v[218:221], v[86:89]
	v_mfma_f32_16x16x32_bf16 v[78:81], v[148:151], v[218:221], v[78:81]
	v_mfma_f32_16x16x32_bf16 v[126:129], v[144:147], v[186:189], v[126:129]
	v_mfma_f32_16x16x32_bf16 v[122:125], v[152:155], v[186:189], v[122:125]
	v_mfma_f32_16x16x32_bf16 v[118:121], v[144:147], v[204:207], v[118:121]
	v_mfma_f32_16x16x32_bf16 v[110:113], v[152:155], v[204:207], v[110:113]
	v_mfma_f32_16x16x32_bf16 v[102:105], v[144:147], v[214:217], v[102:105]
	v_mfma_f32_16x16x32_bf16 v[94:97], v[152:155], v[214:217], v[94:97]
	v_mfma_f32_16x16x32_bf16 v[86:89], v[144:147], v[222:225], v[86:89]
	v_mfma_f32_16x16x32_bf16 v[78:81], v[152:155], v[222:225], v[78:81]
	s_setprio 0
	s_setprio 1
	v_mfma_f32_16x16x32_bf16 v[114:117], v[156:159], v[182:185], v[114:117]
	v_mfma_f32_16x16x32_bf16 v[106:109], v[174:177], v[182:185], v[106:109]
	v_mfma_f32_16x16x32_bf16 v[98:101], v[156:159], v[190:193], v[98:101]
	v_mfma_f32_16x16x32_bf16 v[90:93], v[174:177], v[190:193], v[90:93]
	v_mfma_f32_16x16x32_bf16 v[82:85], v[156:159], v[210:213], v[82:85]
	v_mfma_f32_16x16x32_bf16 v[74:77], v[174:177], v[210:213], v[74:77]
	v_mfma_f32_16x16x32_bf16 v[70:73], v[156:159], v[218:221], v[70:73]
	v_mfma_f32_16x16x32_bf16 v[66:69], v[174:177], v[218:221], v[66:69]
	v_mfma_f32_16x16x32_bf16 v[114:117], v[170:173], v[186:189], v[114:117]
	v_mfma_f32_16x16x32_bf16 v[106:109], v[178:181], v[186:189], v[106:109]
	v_mfma_f32_16x16x32_bf16 v[98:101], v[170:173], v[204:207], v[98:101]
	v_mfma_f32_16x16x32_bf16 v[90:93], v[178:181], v[204:207], v[90:93]
	v_mfma_f32_16x16x32_bf16 v[82:85], v[170:173], v[214:217], v[82:85]
	v_mfma_f32_16x16x32_bf16 v[74:77], v[178:181], v[214:217], v[74:77]
	v_mfma_f32_16x16x32_bf16 v[70:73], v[170:173], v[222:225], v[70:73]
	v_mfma_f32_16x16x32_bf16 v[66:69], v[178:181], v[222:225], v[66:69]
	s_barrier
	s_setprio 0
	s_add_i32 s29, s29, s12
	s_mov_b32 m0, s29
	ds_read_b128 v[182:185], v169 offset:49152
	ds_read_b128 v[186:189], v169 offset:50176
	ds_read_b128 v[190:193], v169 offset:51200
	ds_read_b128 v[204:207], v169 offset:52224
	ds_read_b128 v[210:213], v169 offset:53248
	ds_read_b128 v[214:217], v169 offset:54272
	ds_read_b128 v[218:221], v169 offset:55296
	ds_read_b128 v[222:225], v169 offset:56320
	global_load_lds_dwordx4 v161, s[20:21]
	s_add_i32 m0, s29, 0x2000
	s_add_i32 s29, s30, s12
	global_load_lds_dwordx4 v195, s[20:21]
	s_add_u32 s20, s20, 0x40080
	s_addc_u32 s21, s21, 0
	s_mov_b32 m0, s29
	s_nop 0
	global_load_lds_dwordx4 v0, s[20:21]
	s_add_i32 m0, s29, 0x2000
	s_nop 0
	global_load_lds_dwordx4 v134, s[20:21]
	s_mov_b32 m0, s38
	s_nop 0
	global_load_lds_dwordx4 v201, s[62:63]
	s_mov_b32 m0, s39
	s_nop 0
	global_load_lds_dwordx4 v227, s[62:63]
	s_waitcnt vmcnt(8)
	s_waitcnt lgkmcnt(0)
	s_setprio 1
	s_barrier
	v_mfma_f32_16x16x32_bf16 v[62:65], v[130:133], v[182:185], v[62:65]
	v_mfma_f32_16x16x32_bf16 v[58:61], v[148:151], v[182:185], v[58:61]
	v_mfma_f32_16x16x32_bf16 v[54:57], v[130:133], v[190:193], v[54:57]
	v_mfma_f32_16x16x32_bf16 v[46:49], v[148:151], v[190:193], v[46:49]
	v_mfma_f32_16x16x32_bf16 v[38:41], v[130:133], v[210:213], v[38:41]
	v_mfma_f32_16x16x32_bf16 v[30:33], v[148:151], v[210:213], v[30:33]
	v_mfma_f32_16x16x32_bf16 v[22:25], v[130:133], v[218:221], v[22:25]
	v_mfma_f32_16x16x32_bf16 v[14:17], v[148:151], v[218:221], v[14:17]
	v_mfma_f32_16x16x32_bf16 v[62:65], v[144:147], v[186:189], v[62:65]
	v_mfma_f32_16x16x32_bf16 v[58:61], v[152:155], v[186:189], v[58:61]
	v_mfma_f32_16x16x32_bf16 v[54:57], v[144:147], v[204:207], v[54:57]
	v_mfma_f32_16x16x32_bf16 v[46:49], v[152:155], v[204:207], v[46:49]
	v_mfma_f32_16x16x32_bf16 v[38:41], v[144:147], v[214:217], v[38:41]
	v_mfma_f32_16x16x32_bf16 v[30:33], v[152:155], v[214:217], v[30:33]
	v_mfma_f32_16x16x32_bf16 v[22:25], v[144:147], v[222:225], v[22:25]
	v_mfma_f32_16x16x32_bf16 v[14:17], v[152:155], v[222:225], v[14:17]
	s_setprio 0
	s_setprio 1
	v_mfma_f32_16x16x32_bf16 v[50:53], v[156:159], v[182:185], v[50:53]
	v_mfma_f32_16x16x32_bf16 v[42:45], v[174:177], v[182:185], v[42:45]
	v_mfma_f32_16x16x32_bf16 v[34:37], v[156:159], v[190:193], v[34:37]
	v_mfma_f32_16x16x32_bf16 v[26:29], v[174:177], v[190:193], v[26:29]
	v_mfma_f32_16x16x32_bf16 v[18:21], v[156:159], v[210:213], v[18:21]
	v_mfma_f32_16x16x32_bf16 v[10:13], v[174:177], v[210:213], v[10:13]
	v_mfma_f32_16x16x32_bf16 v[6:9], v[156:159], v[218:221], v[6:9]
	v_mfma_f32_16x16x32_bf16 v[2:5], v[174:177], v[218:221], v[2:5]
	v_mfma_f32_16x16x32_bf16 v[50:53], v[170:173], v[186:189], v[50:53]
	v_mfma_f32_16x16x32_bf16 v[42:45], v[178:181], v[186:189], v[42:45]
	v_mfma_f32_16x16x32_bf16 v[34:37], v[170:173], v[204:207], v[34:37]
	v_mfma_f32_16x16x32_bf16 v[26:29], v[178:181], v[204:207], v[26:29]
	v_mfma_f32_16x16x32_bf16 v[18:21], v[170:173], v[214:217], v[18:21]
	v_mfma_f32_16x16x32_bf16 v[10:13], v[178:181], v[214:217], v[10:13]
	v_mfma_f32_16x16x32_bf16 v[6:9], v[170:173], v[222:225], v[6:9]
	v_mfma_f32_16x16x32_bf16 v[2:5], v[178:181], v[222:225], v[2:5]
	s_barrier
	s_setprio 0
	s_add_i32 s46, s46, 2
	s_add_u32 s44, s44, 0x100
	s_addc_u32 s45, s45, 0
	s_add_u32 s60, s60, 0x100
	s_addc_u32 s61, s61, 0
	s_cmp_gt_u32 s46, 13
	s_cbranch_scc0 .LBB0_559
	s_and_b64 vcc, exec, s[4:5]
	s_cbranch_vccz .LBB0_562
	s_barrier

; __device__ __forceinline__ unsigned pk2(float lo, float hi) { f32x2 v = {lo, hi}; bf16x2_t b = __builtin_convertvector(v, bf16x2_t); return __builtin_bit_cast(unsigned, b); }
;     __device__ __forceinline__ void operator()(const f32x4 (&acc)[2][2][4][2], const Unit& u, int wr, int wc, int fr, int fq, LAS unsigned char* lds, int tid) const {
;     ...
;         for (int ai = 0; ai < 2; ++ai)
; #pragma unroll
;             for (int m = 0; m < 4; ++m) { const size_t row = (size_t)(row0 + ai * HALF + m * 16); const float rs = rsv[ai][m]; gbf16* rowp = O + row * ldc + col0;
; #pragma unroll
;                 for (int bj = 0; bj < 2; ++bj) { const f32x4 v0 = acc[ai][bj][m][0] * rs, v1 = acc[ai][bj][m][1] * rs;
;                     u32x4 w; w.x = pk2(v0[0], v0[1]); w.y = pk2(v0[2], v0[3]); w.z = pk2(v1[0], v1[1]); w.w = pk2(v1[2], v1[3]);
;                     *(gu32x4*)(rowp + bj * HALF) = w; } }
.Lk3_rs_hit:
	s_andn2_b64 vcc, exec, s[2:3]
	v_mul_f32_e32 v174, v159, v226
	v_mul_f32_e32 v172, v159, v236
	v_mul_f32_e32 v170, v159, v237
	v_mul_f32_e32 v168, v159, v244
	v_mul_f32_e32 v166, v159, v245
	v_mul_f32_e32 v164, v159, v246
	v_mul_f32_e32 v162, v159, v247
	v_mul_f32_e32 v130, v159, v248
	v_mov_b64_e32 v[132:133], s[96:97]
	v_mad_i64_i32 v[160:161], s[20:21], v160, s33, v[132:133]
	v_ashrrev_i32_e32 v159, 31, v158
	v_lshlrev_b64 v[158:159], 1, v[158:159]
	v_pk_mul_f32 v[128:129], v[128:129], v[174:175] op_sel_hi:[1,0]
	v_pk_mul_f32 v[126:127], v[126:127], v[174:175] op_sel_hi:[1,0]
	v_pk_mul_f32 v[176:177], v[124:125], v[174:175] op_sel_hi:[1,0]
	v_pk_mul_f32 v[124:125], v[122:123], v[174:175] op_sel_hi:[1,0]
	v_lshl_add_u64 v[160:161], v[160:161], 0, v[158:159]
	v_cvt_pk_bf16_f32 v122, v126, v127
	v_cvt_pk_bf16_f32 v123, v128, v129
	v_cvt_pk_bf16_f32 v124, v124, v125
	v_cvt_pk_bf16_f32 v125, v176, v177
	global_store_dwordx4 v[160:161], v[122:125], off
	v_pk_mul_f32 v[116:117], v[116:117], v[174:175] op_sel_hi:[1,0]
	v_pk_mul_f32 v[114:115], v[114:115], v[174:175] op_sel_hi:[1,0]
	v_pk_mul_f32 v[122:123], v[108:109], v[174:175] op_sel_hi:[1,0]
	v_pk_mul_f32 v[108:109], v[106:107], v[174:175] op_sel_hi:[1,0]
	v_cvt_pk_bf16_f32 v106, v114, v115
	v_cvt_pk_bf16_f32 v107, v116, v117
	v_cvt_pk_bf16_f32 v108, v108, v109
	v_cvt_pk_bf16_f32 v109, v122, v123
	global_store_dwordx4 v[160:161], v[106:109], off offset:256
	v_pk_mul_f32 v[112:113], v[112:113], v[172:173] op_sel_hi:[1,0]
	v_pk_mul_f32 v[110:111], v[110:111], v[172:173] op_sel_hi:[1,0]
	v_mad_i64_i32 v[106:107], s[20:21], v156, s33, v[132:133]
	v_lshl_add_u64 v[114:115], v[106:107], 0, v[158:159]
	v_pk_mul_f32 v[108:109], v[120:121], v[172:173] op_sel_hi:[1,0]
	v_pk_mul_f32 v[106:107], v[118:119], v[172:173] op_sel_hi:[1,0]
	v_pk_mul_f32 v[100:101], v[100:101], v[172:173] op_sel_hi:[1,0]
	v_cvt_pk_bf16_f32 v106, v106, v107
	v_cvt_pk_bf16_f32 v107, v108, v109
	v_cvt_pk_bf16_f32 v108, v110, v111
	v_cvt_pk_bf16_f32 v109, v112, v113
	global_store_dwordx4 v[114:115], v[106:109], off
	v_pk_mul_f32 v[98:99], v[98:99], v[172:173] op_sel_hi:[1,0]
	v_pk_mul_f32 v[96:97], v[96:97], v[170:171] op_sel_hi:[1,0]
	v_pk_mul_f32 v[106:107], v[92:93], v[172:173] op_sel_hi:[1,0]
	v_pk_mul_f32 v[92:93], v[90:91], v[172:173] op_sel_hi:[1,0]
	v_cvt_pk_bf16_f32 v90, v98, v99
	v_cvt_pk_bf16_f32 v91, v100, v101
	v_cvt_pk_bf16_f32 v92, v92, v93
	v_cvt_pk_bf16_f32 v93, v106, v107
	global_store_dwordx4 v[114:115], v[90:93], off offset:256
	v_pk_mul_f32 v[94:95], v[94:95], v[170:171] op_sel_hi:[1,0]
	v_pk_mul_f32 v[84:85], v[84:85], v[170:171] op_sel_hi:[1,0]
	v_mad_i64_i32 v[90:91], s[20:21], v154, s33, v[132:133]
	v_lshl_add_u64 v[98:99], v[90:91], 0, v[158:159]
	v_pk_mul_f32 v[92:93], v[104:105], v[170:171] op_sel_hi:[1,0]
	v_pk_mul_f32 v[90:91], v[102:103], v[170:171] op_sel_hi:[1,0]
	v_pk_mul_f32 v[82:83], v[82:83], v[170:171] op_sel_hi:[1,0]
	v_cvt_pk_bf16_f32 v90, v90, v91
	v_cvt_pk_bf16_f32 v91, v92, v93
	v_cvt_pk_bf16_f32 v92, v94, v95
	v_cvt_pk_bf16_f32 v93, v96, v97
	global_store_dwordx4 v[98:99], v[90:93], off
	v_pk_mul_f32 v[80:81], v[80:81], v[168:169] op_sel_hi:[1,0]
	v_pk_mul_f32 v[78:79], v[78:79], v[168:169] op_sel_hi:[1,0]
	v_pk_mul_f32 v[90:91], v[76:77], v[170:171] op_sel_hi:[1,0]
	v_pk_mul_f32 v[76:77], v[74:75], v[170:171] op_sel_hi:[1,0]
	v_cvt_pk_bf16_f32 v74, v82, v83
	v_cvt_pk_bf16_f32 v75, v84, v85
	v_cvt_pk_bf16_f32 v76, v76, v77
	v_cvt_pk_bf16_f32 v77, v90, v91
	global_store_dwordx4 v[98:99], v[74:77], off offset:256
	v_pk_mul_f32 v[72:73], v[72:73], v[168:169] op_sel_hi:[1,0]
	v_pk_mul_f32 v[70:71], v[70:71], v[168:169] op_sel_hi:[1,0]
	v_mad_i64_i32 v[74:75], s[20:21], v152, s33, v[132:133]
	v_lshl_add_u64 v[82:83], v[74:75], 0, v[158:159]
	v_pk_mul_f32 v[76:77], v[88:89], v[168:169] op_sel_hi:[1,0]
	v_pk_mul_f32 v[74:75], v[86:87], v[168:169] op_sel_hi:[1,0]
	v_pk_mul_f32 v[64:65], v[64:65], v[166:167] op_sel_hi:[1,0]
	v_cvt_pk_bf16_f32 v74, v74, v75
	v_cvt_pk_bf16_f32 v75, v76, v77
	v_cvt_pk_bf16_f32 v76, v78, v79
	v_cvt_pk_bf16_f32 v77, v80, v81
	global_store_dwordx4 v[82:83], v[74:77], off
	v_pk_mul_f32 v[62:63], v[62:63], v[166:167] op_sel_hi:[1,0]
; __device__ __forceinline__ unsigned pk2(float lo, float hi) { f32x2 v = {lo, hi}; bf16x2_t b = __builtin_convertvector(v, bf16x2_t); return __builtin_bit_cast(unsigned, b); }
; #define PG8_BAR __builtin_amdgcn_s_barrier()
;     __device__ __forceinline__ void operator()(const f32x4 (&acc)[2][2][4][2], const Unit& u, int wr, int wc, int fr, int fq, LAS unsigned char* lds, int tid) const {
;     ...
;         for (int ai = 0; ai < 2; ++ai)
; #pragma unroll
;             for (int m = 0; m < 4; ++m) { const size_t row = (size_t)(row0 + ai * HALF + m * 16); const float rs = rsv[ai][m]; gbf16* rowp = O + row * ldc + col0;
; #pragma unroll
;                 for (int bj = 0; bj < 2; ++bj) { const f32x4 v0 = acc[ai][bj][m][0] * rs, v1 = acc[ai][bj][m][1] * rs;
;                     u32x4 w; w.x = pk2(v0[0], v0[1]); w.y = pk2(v0[2], v0[3]); w.z = pk2(v1[0], v1[1]); w.w = pk2(v1[2], v1[3]);
;                     *(gu32x4*)(rowp + bj * HALF) = w; } }
; template <class Epi, class Sched>
; __device__ __forceinline__ void gemm_phase(LAS unsigned char* lds, const int tid, const Gemm g, const Sched& S, const Epi& E) {
;     ...
;         if (!has_next) break;
; #pragma unroll
;         for (int a = 0; a < 2; ++a)
; #pragma unroll
;             for (int b = 0; b < 2; ++b)
; #pragma unroll
;                 for (int m = 0; m < 4; ++m)
; #pragma unroll
;                     for (int n = 0; n < 2; ++n) acc[a][b][m][n] = (f32x4){0.f, 0.f, 0.f, 0.f};
;         cur = nxt; cA = nA; cB = nB; ++ui;
;         if (wr == 1) PG8_BAR;
	v_pk_mul_f32 v[52:53], v[52:53], v[166:167] op_sel_hi:[1,0]
	v_pk_mul_f32 v[74:75], v[68:69], v[168:169] op_sel_hi:[1,0]
	v_pk_mul_f32 v[68:69], v[66:67], v[168:169] op_sel_hi:[1,0]
	v_cvt_pk_bf16_f32 v66, v70, v71
	v_cvt_pk_bf16_f32 v67, v72, v73
	v_cvt_pk_bf16_f32 v68, v68, v69
	v_cvt_pk_bf16_f32 v69, v74, v75
	global_store_dwordx4 v[82:83], v[66:69], off offset:256
	v_pk_mul_f32 v[50:51], v[50:51], v[166:167] op_sel_hi:[1,0]
	v_pk_mul_f32 v[48:49], v[48:49], v[164:165] op_sel_hi:[1,0]
	v_mad_i64_i32 v[66:67], s[20:21], v150, s33, v[132:133]
	v_pk_mul_f32 v[68:69], v[60:61], v[166:167] op_sel_hi:[1,0]
	v_pk_mul_f32 v[60:61], v[58:59], v[166:167] op_sel_hi:[1,0]
	v_lshl_add_u64 v[66:67], v[66:67], 0, v[158:159]
	v_cvt_pk_bf16_f32 v58, v62, v63
	v_cvt_pk_bf16_f32 v59, v64, v65
	v_cvt_pk_bf16_f32 v60, v60, v61
	v_cvt_pk_bf16_f32 v61, v68, v69
	global_store_dwordx4 v[66:67], v[58:61], off
	v_pk_mul_f32 v[46:47], v[46:47], v[164:165] op_sel_hi:[1,0]
	v_pk_mul_f32 v[36:37], v[36:37], v[164:165] op_sel_hi:[1,0]
	v_pk_mul_f32 v[58:59], v[44:45], v[166:167] op_sel_hi:[1,0]
	v_pk_mul_f32 v[44:45], v[42:43], v[166:167] op_sel_hi:[1,0]
	v_cvt_pk_bf16_f32 v42, v50, v51
	v_cvt_pk_bf16_f32 v43, v52, v53
	v_cvt_pk_bf16_f32 v44, v44, v45
	v_cvt_pk_bf16_f32 v45, v58, v59
	global_store_dwordx4 v[66:67], v[42:45], off offset:256
	v_pk_mul_f32 v[34:35], v[34:35], v[164:165] op_sel_hi:[1,0]
	v_pk_mul_f32 v[32:33], v[32:33], v[162:163] op_sel_hi:[1,0]
	v_mad_i64_i32 v[42:43], s[20:21], v148, s33, v[132:133]
	v_lshl_add_u64 v[50:51], v[42:43], 0, v[158:159]
	v_pk_mul_f32 v[44:45], v[56:57], v[164:165] op_sel_hi:[1,0]
	v_pk_mul_f32 v[42:43], v[54:55], v[164:165] op_sel_hi:[1,0]
	v_pk_mul_f32 v[30:31], v[30:31], v[162:163] op_sel_hi:[1,0]
	v_cvt_pk_bf16_f32 v42, v42, v43
	v_cvt_pk_bf16_f32 v43, v44, v45
	v_cvt_pk_bf16_f32 v44, v46, v47
	v_cvt_pk_bf16_f32 v45, v48, v49
	global_store_dwordx4 v[50:51], v[42:45], off
	v_pk_mul_f32 v[20:21], v[20:21], v[162:163] op_sel_hi:[1,0]
	v_pk_mul_f32 v[18:19], v[18:19], v[162:163] op_sel_hi:[1,0]
	v_pk_mul_f32 v[42:43], v[28:29], v[164:165] op_sel_hi:[1,0]
	v_pk_mul_f32 v[28:29], v[26:27], v[164:165] op_sel_hi:[1,0]
	v_cvt_pk_bf16_f32 v26, v34, v35
	v_cvt_pk_bf16_f32 v27, v36, v37
	v_cvt_pk_bf16_f32 v28, v28, v29
	v_cvt_pk_bf16_f32 v29, v42, v43
	global_store_dwordx4 v[50:51], v[26:29], off offset:256
	v_pk_mul_f32 v[16:17], v[16:17], v[130:131] op_sel_hi:[1,0]
	v_pk_mul_f32 v[14:15], v[14:15], v[130:131] op_sel_hi:[1,0]
	v_mad_i64_i32 v[26:27], s[20:21], v146, s33, v[132:133]
	v_lshl_add_u64 v[34:35], v[26:27], 0, v[158:159]
	v_pk_mul_f32 v[28:29], v[40:41], v[162:163] op_sel_hi:[1,0]
	v_pk_mul_f32 v[26:27], v[38:39], v[162:163] op_sel_hi:[1,0]
	v_pk_mul_f32 v[8:9], v[8:9], v[130:131] op_sel_hi:[1,0]
	v_cvt_pk_bf16_f32 v26, v26, v27
	v_cvt_pk_bf16_f32 v27, v28, v29
	v_cvt_pk_bf16_f32 v28, v30, v31
	v_cvt_pk_bf16_f32 v29, v32, v33
	global_store_dwordx4 v[34:35], v[26:29], off
	v_pk_mul_f32 v[6:7], v[6:7], v[130:131] op_sel_hi:[1,0]
	s_nop 0
	v_pk_mul_f32 v[26:27], v[12:13], v[162:163] op_sel_hi:[1,0]
	v_pk_mul_f32 v[12:13], v[10:11], v[162:163] op_sel_hi:[1,0]
	v_cvt_pk_bf16_f32 v10, v18, v19
	v_cvt_pk_bf16_f32 v11, v20, v21
	v_cvt_pk_bf16_f32 v12, v12, v13
	v_cvt_pk_bf16_f32 v13, v26, v27
	global_store_dwordx4 v[34:35], v[10:13], off offset:256
	s_nop 1
	v_mad_i64_i32 v[10:11], s[20:21], v144, s33, v[132:133]
	v_lshl_add_u64 v[18:19], v[10:11], 0, v[158:159]
	v_pk_mul_f32 v[12:13], v[24:25], v[130:131] op_sel_hi:[1,0]
	v_pk_mul_f32 v[10:11], v[22:23], v[130:131] op_sel_hi:[1,0]
	s_mov_b64 s[20:21], -1
	v_cvt_pk_bf16_f32 v10, v10, v11
	v_cvt_pk_bf16_f32 v11, v12, v13
	v_cvt_pk_bf16_f32 v12, v14, v15
	v_cvt_pk_bf16_f32 v13, v16, v17
	global_store_dwordx4 v[18:19], v[10:13], off
	s_nop 1
	v_pk_mul_f32 v[10:11], v[4:5], v[130:131] op_sel_hi:[1,0]
	v_pk_mul_f32 v[4:5], v[2:3], v[130:131] op_sel_hi:[1,0]
	v_cvt_pk_bf16_f32 v2, v6, v7
	v_cvt_pk_bf16_f32 v3, v8, v9
	v_cvt_pk_bf16_f32 v4, v4, v5
	v_cvt_pk_bf16_f32 v5, v10, v11
	global_store_dwordx4 v[18:19], v[2:5], off offset:256
	s_cbranch_vccnz .LBB0_555
	s_andn2_b64 vcc, exec, s[0:1]
	s_cbranch_vccnz .LBB0_554
	s_mov_b32 vcc_lo, 1
	s_nop 0
	v_writelane_b32 v255, vcc_lo, 21
	s_branch .LBB0_554

; #define PG8_STAGE(bufoff, gbase, voff) do { _Pragma("unroll") for (int _i = 0; _i < 2; ++_i) \
;         __builtin_amdgcn_global_load_lds((const gunsigned*)((const gchar*)(gbase) + (voff)[_i]), (LAS unsigned*)(lds + (bufoff) + ldsw + _i * 8192), 16, 0, 0); } while (0)
; #define PG8_LDA(dst, b, h) do { _Pragma("unroll") for (int m = 0; m < 4; ++m) _Pragma("unroll") for (int k = 0; k < 2; ++k) dst[m][k] = *(const LAS bf16x8*)(lds + PG8_SA(b, h) + aoff + m * 2048 + k * 1024); } while (0)
; #define PG8_LDB(dst, b, h) do { _Pragma("unroll") for (int n = 0; n < 2; ++n) _Pragma("unroll") for (int k = 0; k < 2; ++k) dst[n][k] = *(const LAS bf16x8*)(lds + PG8_SB(b, h) + boff + n * 2048 + k * 1024); } while (0)
; #define PG8_WAIT_V(n) asm volatile("s_waitcnt vmcnt(" #n ")" ::: "memory")
; #define PG8_WAIT_L(n) asm volatile("s_waitcnt lgkmcnt(" #n ")" ::: "memory")
; #define PG8_BAR __builtin_amdgcn_s_barrier()
; #define PG8_SCHED __builtin_amdgcn_sched_barrier(0)
; template <class Epi, class Sched>
; __device__ __forceinline__ void gemm_phase(LAS unsigned char* lds, const int tid, const Gemm g, const Sched& S, const Epi& E) {
;     ...
;         const gchar* nA = has_next ? (const gchar*)g.A + (size_t)nxt.pm * tstep + (size_t)nxt.pz * g.zA : cA;
;         const gchar* nB = has_next ? (const gchar*)g.Bt + (size_t)nxt.pn * tstep + (size_t)nxt.pz * g.zB : cB;
;         for (int t = 0; t < nt; t += 2) {
;             const bool last = (t == nt - 2);
;             const gchar* a1 = cA + (size_t)(t + 1) * kstep;
;             const gchar* a2 = last ? nA : cA + (size_t)(t + 2) * kstep; const gchar* b2 = last ? nB : cB + (size_t)(t + 2) * kstep;
;             const gchar* a3 = a2 + kstep; const gchar* b3 = b2 + kstep;
;             PG8_LDB(B0, 0, 0); PG8_LDB(B1, 0, 1); PG8_SCHED; PG8_LDA(At, 0, 0); PG8_STAGE(PG8_SA(1, 1), a1 + hstep, voffA);
;             PG8_WAIT_V(8); PG8_WAIT_L(0); PG8_BAR; PG8_MMA(0, 0, At, B0); PG8_MMA(0, 1, At, B1); PG8_BAR; PG8_SCHED;
;     ...
; #pragma unroll
;         for (int a = 0; a < 2; ++a)
; #pragma unroll
;             for (int b = 0; b < 2; ++b)
; #pragma unroll
;                 for (int m = 0; m < 4; ++m)
; #pragma unroll
;                     for (int n = 0; n < 2; ++n) acc[a][b][m][n] = (f32x4){0.f, 0.f, 0.f, 0.f};
;         cur = nxt; cA = nA; cB = nB; ++ui;
;         if (wr == 1) PG8_BAR;
.LBB0_597:
	s_add_u32 s31, s20, 0x100
	v_mov_b32_e32 v2, 0
	s_addc_u32 s44, s21, 0
	s_mov_b32 s45, -2
	s_waitcnt lgkmcnt(0)
	v_mov_b32_e32 v3, v2
	v_mov_b32_e32 v4, v2
	v_mov_b32_e32 v5, v2
	v_mov_b32_e32 v6, v2
	v_mov_b32_e32 v7, v2
	v_mov_b32_e32 v8, v2
	v_mov_b32_e32 v9, v2
	v_mov_b32_e32 v18, v2
	v_mov_b32_e32 v19, v2
	v_mov_b32_e32 v20, v2
	v_mov_b32_e32 v21, v2
	v_mov_b32_e32 v22, v2
	v_mov_b32_e32 v23, v2
	v_mov_b32_e32 v24, v2
	v_mov_b32_e32 v25, v2
	v_mov_b32_e32 v34, v2
	v_mov_b32_e32 v35, v2
	v_mov_b32_e32 v36, v2
	v_mov_b32_e32 v37, v2
	v_mov_b32_e32 v38, v2
	v_mov_b32_e32 v39, v2
	v_mov_b32_e32 v40, v2
	v_mov_b32_e32 v41, v2
	v_mov_b32_e32 v50, v2
	v_mov_b32_e32 v51, v2
	v_mov_b32_e32 v52, v2
	v_mov_b32_e32 v53, v2
	v_mov_b32_e32 v54, v2
	v_mov_b32_e32 v55, v2
	v_mov_b32_e32 v56, v2
	v_mov_b32_e32 v57, v2
	v_mov_b32_e32 v10, v2
	v_mov_b32_e32 v11, v2
	v_mov_b32_e32 v12, v2
	v_mov_b32_e32 v13, v2
	v_mov_b32_e32 v14, v2
	v_mov_b32_e32 v15, v2
	v_mov_b32_e32 v16, v2
	v_mov_b32_e32 v17, v2
	v_mov_b32_e32 v26, v2
	v_mov_b32_e32 v27, v2
	v_mov_b32_e32 v28, v2
	v_mov_b32_e32 v29, v2
	v_mov_b32_e32 v30, v2
	v_mov_b32_e32 v31, v2
	v_mov_b32_e32 v32, v2
	v_mov_b32_e32 v33, v2
	v_mov_b32_e32 v42, v2
	v_mov_b32_e32 v43, v2
	v_mov_b32_e32 v44, v2
	v_mov_b32_e32 v45, v2
	v_mov_b32_e32 v46, v2
	v_mov_b32_e32 v47, v2
	v_mov_b32_e32 v48, v2
	v_mov_b32_e32 v49, v2
	v_mov_b32_e32 v58, v2
	v_mov_b32_e32 v59, v2
	v_mov_b32_e32 v60, v2
	v_mov_b32_e32 v61, v2
	v_mov_b32_e32 v62, v2
	v_mov_b32_e32 v63, v2
	v_mov_b32_e32 v64, v2
	v_mov_b32_e32 v65, v2
	v_mov_b32_e32 v66, v2
	v_mov_b32_e32 v67, v2
	v_mov_b32_e32 v68, v2
	v_mov_b32_e32 v69, v2
	v_mov_b32_e32 v70, v2
	v_mov_b32_e32 v71, v2
	v_mov_b32_e32 v72, v2
	v_mov_b32_e32 v73, v2
	s_waitcnt vmcnt(0)
	v_mov_b32_e32 v82, v2
	v_mov_b32_e32 v83, v2
	v_mov_b32_e32 v84, v2
	v_mov_b32_e32 v85, v2
	v_mov_b32_e32 v86, v2
	v_mov_b32_e32 v87, v2
	v_mov_b32_e32 v88, v2
	v_mov_b32_e32 v89, v2
	v_mov_b32_e32 v98, v2
	v_mov_b32_e32 v99, v2
	v_mov_b32_e32 v100, v2
	v_mov_b32_e32 v101, v2
	v_mov_b32_e32 v102, v2
	v_mov_b32_e32 v103, v2
	v_mov_b32_e32 v104, v2
	v_mov_b32_e32 v105, v2
	v_mov_b32_e32 v114, v2
	v_mov_b32_e32 v115, v2
	v_mov_b32_e32 v116, v2
	v_mov_b32_e32 v117, v2
	v_mov_b32_e32 v118, v2
	v_mov_b32_e32 v119, v2
	v_mov_b32_e32 v120, v2
	v_mov_b32_e32 v121, v2
	v_mov_b32_e32 v74, v2
	v_mov_b32_e32 v75, v2
	v_mov_b32_e32 v76, v2
	v_mov_b32_e32 v77, v2
	v_mov_b32_e32 v78, v2
	v_mov_b32_e32 v79, v2
	v_mov_b32_e32 v80, v2
	v_mov_b32_e32 v81, v2
	v_mov_b32_e32 v90, v2
	v_mov_b32_e32 v91, v2
	v_mov_b32_e32 v92, v2
	v_mov_b32_e32 v93, v2
	v_mov_b32_e32 v94, v2
	v_mov_b32_e32 v95, v2
	v_mov_b32_e32 v96, v2
	v_mov_b32_e32 v97, v2
	v_mov_b32_e32 v106, v2
	v_mov_b32_e32 v107, v2
	v_mov_b32_e32 v108, v2
	v_mov_b32_e32 v109, v2
	v_mov_b32_e32 v110, v2
	v_mov_b32_e32 v111, v2
	v_mov_b32_e32 v112, v2
	v_mov_b32_e32 v113, v2
	v_mov_b32_e32 v122, v2
	v_mov_b32_e32 v123, v2
	v_mov_b32_e32 v124, v2
	v_mov_b32_e32 v125, v2
	v_mov_b32_e32 v126, v2
	v_mov_b32_e32 v127, v2
	v_mov_b32_e32 v128, v2
	v_mov_b32_e32 v129, v2
	v_add_u32_e32 v221, 0x80, v0
	v_add_u32_e32 v223, 0x80, v182
	v_add_u32_e32 v225, 0x80, v178
	v_add_u32_e32 v227, 0x80, v180
	v_readlane_b32 vcc_lo, v255, 21
	s_nop 3
	s_cmp_eq_u32 vcc_lo, 1
	s_cbranch_scc0 .Lnb_598
	s_barrier
	s_mov_b32 vcc_lo, 0
	s_nop 0
	v_writelane_b32 v255, vcc_lo, 21
.Lnb_598:
.LBB0_598:
	s_add_u32 s20, s62, 0x100
	s_addc_u32 s21, s63, 0
	s_add_i32 s29, 0, 0x10000
	s_cmp_eq_u32 s45, 40
	s_cselect_b32 s73, s9, s21
	s_cselect_b32 s72, s8, s20
	s_cselect_b32 s67, s61, s44
	s_cselect_b32 s66, s60, s31
	s_add_i32 s48, 0, 0x14000
	v_add_u32_e32 v142, s29, v210
	v_add_u32_e32 v158, s48, v210
	ds_read_b128 v[130:133], v142
	ds_read_b128 v[134:137], v142 offset:1024
	ds_read_b128 v[138:141], v142 offset:2048
	ds_read_b128 v[142:145], v142 offset:3072
	ds_read_b128 v[146:149], v158
	ds_read_b128 v[150:153], v158 offset:1024
	ds_read_b128 v[154:157], v158 offset:2048
	ds_read_b128 v[158:161], v158 offset:3072
	s_add_i32 m0, s34, 0xc000
	ds_read_b128 v[162:165], v214
	ds_read_b128 v[166:169], v214 offset:1024
	ds_read_b128 v[170:173], v214 offset:2048
	ds_read_b128 v[174:177], v214 offset:3072
	ds_read_b128 v[188:191], v214 offset:4096
	ds_read_b128 v[192:195], v214 offset:5120
	ds_read_b128 v[204:207], v214 offset:6144
	ds_read_b128 v[216:219], v214 offset:7168
	global_load_lds_dwordx4 v186, s[62:63]
	s_add_i32 m0, s34, 0xe000
	s_nop 0
	global_load_lds_dwordx4 v184, s[62:63]
	s_waitcnt vmcnt(8)
	s_waitcnt lgkmcnt(0)
	s_setprio 1
	s_barrier
; #define PG8_STAGE(bufoff, gbase, voff) do { _Pragma("unroll") for (int _i = 0; _i < 2; ++_i) \
;         __builtin_amdgcn_global_load_lds((const gunsigned*)((const gchar*)(gbase) + (voff)[_i]), (LAS unsigned*)(lds + (bufoff) + ldsw + _i * 8192), 16, 0, 0); } while (0)
; #define PG8_LDA(dst, b, h) do { _Pragma("unroll") for (int m = 0; m < 4; ++m) _Pragma("unroll") for (int k = 0; k < 2; ++k) dst[m][k] = *(const LAS bf16x8*)(lds + PG8_SA(b, h) + aoff + m * 2048 + k * 1024); } while (0)
; #define PG8_LDB(dst, b, h) do { _Pragma("unroll") for (int n = 0; n < 2; ++n) _Pragma("unroll") for (int k = 0; k < 2; ++k) dst[n][k] = *(const LAS bf16x8*)(lds + PG8_SB(b, h) + boff + n * 2048 + k * 1024); } while (0)
; #define PG8_MMA(ai, bj, At, Bt) do { __builtin_amdgcn_s_setprio(1); _Pragma("unroll") for (int m = 0; m < 4; ++m) _Pragma("unroll") for (int n = 0; n < 2; ++n) _Pragma("unroll") for (int k = 0; k < 2; ++k) \
;         acc[ai][bj][m][n] = __builtin_amdgcn_mfma_f32_16x16x32_bf16(Bt[n][k], At[m][k], acc[ai][bj][m][n], 0, 0, 0); __builtin_amdgcn_s_setprio(0); } while (0)
; #define PG8_WAIT_V(n) asm volatile("s_waitcnt vmcnt(" #n ")" ::: "memory")
; #define PG8_WAIT_L(n) asm volatile("s_waitcnt lgkmcnt(" #n ")" ::: "memory")
; #define PG8_BAR __builtin_amdgcn_s_barrier()
; #define PG8_SCHED __builtin_amdgcn_sched_barrier(0)
; template <class Epi, class Sched>
; __device__ __forceinline__ void gemm_phase(LAS unsigned char* lds, const int tid, const Gemm g, const Sched& S, const Epi& E) {
;     ...
;             PG8_LDB(B0, 0, 0); PG8_LDB(B1, 0, 1); PG8_SCHED; PG8_LDA(At, 0, 0); PG8_STAGE(PG8_SA(1, 1), a1 + hstep, voffA);
;             PG8_WAIT_V(8); PG8_WAIT_L(0); PG8_BAR; PG8_MMA(0, 0, At, B0); PG8_MMA(0, 1, At, B1); PG8_BAR; PG8_SCHED;
;             PG8_LDA(At, 0, 1); PG8_STAGE(PG8_SB(0, 0), b2, voffB); PG8_STAGE(PG8_SB(0, 1), b2 + hstep, voffB); PG8_STAGE(PG8_SA(0, 0), a2, voffA);
;             PG8_WAIT_V(8); PG8_WAIT_L(0); PG8_BAR; PG8_MMA(1, 0, At, B0); PG8_MMA(1, 1, At, B1); PG8_BAR; PG8_SCHED;
;             PG8_LDB(B0, 1, 0); PG8_LDB(B1, 1, 1); PG8_SCHED; PG8_LDA(At, 1, 0); PG8_STAGE(PG8_SA(0, 1), a2 + hstep, voffA);
;             PG8_WAIT_V(8); PG8_WAIT_L(0); PG8_BAR; PG8_MMA(0, 0, At, B0); PG8_MMA(0, 1, At, B1); PG8_BAR; PG8_SCHED;
	v_mfma_f32_16x16x32_bf16 v[126:129], v[130:133], v[162:165], v[126:129]
	v_mfma_f32_16x16x32_bf16 v[122:125], v[138:141], v[162:165], v[122:125]
	v_mfma_f32_16x16x32_bf16 v[110:113], v[130:133], v[170:173], v[110:113]
	v_mfma_f32_16x16x32_bf16 v[106:109], v[138:141], v[170:173], v[106:109]
	v_mfma_f32_16x16x32_bf16 v[94:97], v[130:133], v[188:191], v[94:97]
	v_mfma_f32_16x16x32_bf16 v[90:93], v[138:141], v[188:191], v[90:93]
	v_mfma_f32_16x16x32_bf16 v[78:81], v[130:133], v[204:207], v[78:81]
	v_mfma_f32_16x16x32_bf16 v[74:77], v[138:141], v[204:207], v[74:77]
	v_mfma_f32_16x16x32_bf16 v[126:129], v[134:137], v[166:169], v[126:129]
	v_mfma_f32_16x16x32_bf16 v[122:125], v[142:145], v[166:169], v[122:125]
	v_mfma_f32_16x16x32_bf16 v[110:113], v[134:137], v[174:177], v[110:113]
	v_mfma_f32_16x16x32_bf16 v[106:109], v[142:145], v[174:177], v[106:109]
	v_mfma_f32_16x16x32_bf16 v[94:97], v[134:137], v[192:195], v[94:97]
	v_mfma_f32_16x16x32_bf16 v[90:93], v[142:145], v[192:195], v[90:93]
	v_mfma_f32_16x16x32_bf16 v[78:81], v[134:137], v[216:219], v[78:81]
	v_mfma_f32_16x16x32_bf16 v[74:77], v[142:145], v[216:219], v[74:77]
	s_setprio 0
	s_setprio 1
	v_mfma_f32_16x16x32_bf16 v[118:121], v[146:149], v[162:165], v[118:121]
	v_mfma_f32_16x16x32_bf16 v[114:117], v[154:157], v[162:165], v[114:117]
	v_mfma_f32_16x16x32_bf16 v[102:105], v[146:149], v[170:173], v[102:105]
	v_mfma_f32_16x16x32_bf16 v[98:101], v[154:157], v[170:173], v[98:101]
	v_mfma_f32_16x16x32_bf16 v[86:89], v[146:149], v[188:191], v[86:89]
	v_mfma_f32_16x16x32_bf16 v[82:85], v[154:157], v[188:191], v[82:85]
	v_mfma_f32_16x16x32_bf16 v[70:73], v[146:149], v[204:207], v[70:73]
	v_mfma_f32_16x16x32_bf16 v[66:69], v[154:157], v[204:207], v[66:69]
	v_mfma_f32_16x16x32_bf16 v[118:121], v[150:153], v[166:169], v[118:121]
	v_mfma_f32_16x16x32_bf16 v[114:117], v[158:161], v[166:169], v[114:117]
	v_mfma_f32_16x16x32_bf16 v[102:105], v[150:153], v[174:177], v[102:105]
	v_mfma_f32_16x16x32_bf16 v[98:101], v[158:161], v[174:177], v[98:101]
	v_mfma_f32_16x16x32_bf16 v[86:89], v[150:153], v[192:195], v[86:89]
	v_mfma_f32_16x16x32_bf16 v[82:85], v[158:161], v[192:195], v[82:85]
	v_mfma_f32_16x16x32_bf16 v[70:73], v[150:153], v[216:219], v[70:73]
	v_mfma_f32_16x16x32_bf16 v[66:69], v[158:161], v[216:219], v[66:69]
	s_barrier
	s_setprio 0
	s_add_i32 s29, s29, s15
	s_mov_b32 m0, s29
	ds_read_b128 v[162:165], v214 offset:16384
	ds_read_b128 v[166:169], v214 offset:17408
	ds_read_b128 v[170:173], v214 offset:18432
	ds_read_b128 v[174:177], v214 offset:19456
	ds_read_b128 v[188:191], v214 offset:20480
	ds_read_b128 v[192:195], v214 offset:21504
	ds_read_b128 v[204:207], v214 offset:22528
	ds_read_b128 v[216:219], v214 offset:23552
	global_load_lds_dwordx4 v0, s[66:67]
	s_add_i32 m0, s29, 0x2000
	s_add_u32 s46, s66, 0xb0000
	s_addc_u32 s47, s67, 0
	s_add_i32 s29, s48, s15
	global_load_lds_dwordx4 v182, s[66:67]
	s_mov_b32 m0, s29
	s_nop 0
	global_load_lds_dwordx4 v0, s[46:47]
	s_add_i32 m0, s29, 0x2000
	s_nop 0
	global_load_lds_dwordx4 v182, s[46:47]
	s_mov_b32 m0, s34
	s_nop 0
	global_load_lds_dwordx4 v178, s[72:73]
	s_mov_b32 m0, s12
	s_nop 0
	global_load_lds_dwordx4 v180, s[72:73]
	s_waitcnt vmcnt(8)
	s_waitcnt lgkmcnt(0)
	s_setprio 1
	s_barrier
	v_mfma_f32_16x16x32_bf16 v[62:65], v[130:133], v[162:165], v[62:65]
	v_mfma_f32_16x16x32_bf16 v[58:61], v[138:141], v[162:165], v[58:61]
	v_mfma_f32_16x16x32_bf16 v[46:49], v[130:133], v[170:173], v[46:49]
	v_mfma_f32_16x16x32_bf16 v[42:45], v[138:141], v[170:173], v[42:45]
	v_mfma_f32_16x16x32_bf16 v[30:33], v[130:133], v[188:191], v[30:33]
	v_mfma_f32_16x16x32_bf16 v[26:29], v[138:141], v[188:191], v[26:29]
	v_mfma_f32_16x16x32_bf16 v[14:17], v[130:133], v[204:207], v[14:17]
	v_mfma_f32_16x16x32_bf16 v[10:13], v[138:141], v[204:207], v[10:13]
	v_mfma_f32_16x16x32_bf16 v[62:65], v[134:137], v[166:169], v[62:65]
	v_mfma_f32_16x16x32_bf16 v[58:61], v[142:145], v[166:169], v[58:61]
	v_mfma_f32_16x16x32_bf16 v[46:49], v[134:137], v[174:177], v[46:49]
	v_mfma_f32_16x16x32_bf16 v[42:45], v[142:145], v[174:177], v[42:45]
	v_mfma_f32_16x16x32_bf16 v[30:33], v[134:137], v[192:195], v[30:33]
	v_mfma_f32_16x16x32_bf16 v[26:29], v[142:145], v[192:195], v[26:29]
	v_mfma_f32_16x16x32_bf16 v[14:17], v[134:137], v[216:219], v[14:17]
	v_mfma_f32_16x16x32_bf16 v[10:13], v[142:145], v[216:219], v[10:13]
	s_setprio 0
	s_setprio 1
	v_mfma_f32_16x16x32_bf16 v[54:57], v[146:149], v[162:165], v[54:57]
	v_mfma_f32_16x16x32_bf16 v[50:53], v[154:157], v[162:165], v[50:53]
	v_mfma_f32_16x16x32_bf16 v[38:41], v[146:149], v[170:173], v[38:41]
	v_mfma_f32_16x16x32_bf16 v[34:37], v[154:157], v[170:173], v[34:37]
	v_mfma_f32_16x16x32_bf16 v[22:25], v[146:149], v[188:191], v[22:25]
	v_mfma_f32_16x16x32_bf16 v[18:21], v[154:157], v[188:191], v[18:21]
	v_mfma_f32_16x16x32_bf16 v[6:9], v[146:149], v[204:207], v[6:9]
	v_mfma_f32_16x16x32_bf16 v[2:5], v[154:157], v[204:207], v[2:5]
	v_mfma_f32_16x16x32_bf16 v[54:57], v[150:153], v[166:169], v[54:57]
	v_mfma_f32_16x16x32_bf16 v[50:53], v[158:161], v[166:169], v[50:53]
	v_mfma_f32_16x16x32_bf16 v[38:41], v[150:153], v[174:177], v[38:41]
	v_mfma_f32_16x16x32_bf16 v[34:37], v[158:161], v[174:177], v[34:37]
	v_mfma_f32_16x16x32_bf16 v[22:25], v[150:153], v[192:195], v[22:25]
	v_mfma_f32_16x16x32_bf16 v[18:21], v[158:161], v[192:195], v[18:21]
	v_mfma_f32_16x16x32_bf16 v[6:9], v[150:153], v[216:219], v[6:9]
	v_mfma_f32_16x16x32_bf16 v[2:5], v[158:161], v[216:219], v[2:5]
	s_barrier
; #define PG8_STAGE(bufoff, gbase, voff) do { _Pragma("unroll") for (int _i = 0; _i < 2; ++_i) \
;         __builtin_amdgcn_global_load_lds((const gunsigned*)((const gchar*)(gbase) + (voff)[_i]), (LAS unsigned*)(lds + (bufoff) + ldsw + _i * 8192), 16, 0, 0); } while (0)
; #define PG8_LDA(dst, b, h) do { _Pragma("unroll") for (int m = 0; m < 4; ++m) _Pragma("unroll") for (int k = 0; k < 2; ++k) dst[m][k] = *(const LAS bf16x8*)(lds + PG8_SA(b, h) + aoff + m * 2048 + k * 1024); } while (0)
; #define PG8_LDB(dst, b, h) do { _Pragma("unroll") for (int n = 0; n < 2; ++n) _Pragma("unroll") for (int k = 0; k < 2; ++k) dst[n][k] = *(const LAS bf16x8*)(lds + PG8_SB(b, h) + boff + n * 2048 + k * 1024); } while (0)
; #define PG8_MMA(ai, bj, At, Bt) do { __builtin_amdgcn_s_setprio(1); _Pragma("unroll") for (int m = 0; m < 4; ++m) _Pragma("unroll") for (int n = 0; n < 2; ++n) _Pragma("unroll") for (int k = 0; k < 2; ++k) \
;         acc[ai][bj][m][n] = __builtin_amdgcn_mfma_f32_16x16x32_bf16(Bt[n][k], At[m][k], acc[ai][bj][m][n], 0, 0, 0); __builtin_amdgcn_s_setprio(0); } while (0)
; #define PG8_WAIT_V(n) asm volatile("s_waitcnt vmcnt(" #n ")" ::: "memory")
; #define PG8_WAIT_L(n) asm volatile("s_waitcnt lgkmcnt(" #n ")" ::: "memory")
; #define PG8_BAR __builtin_amdgcn_s_barrier()
; #define PG8_SCHED __builtin_amdgcn_sched_barrier(0)
; template <class Epi, class Sched>
; __device__ __forceinline__ void gemm_phase(LAS unsigned char* lds, const int tid, const Gemm g, const Sched& S, const Epi& E) {
;     ...
;             PG8_LDB(B0, 1, 0); PG8_LDB(B1, 1, 1); PG8_SCHED; PG8_LDA(At, 1, 0); PG8_STAGE(PG8_SA(0, 1), a2 + hstep, voffA);
;             PG8_WAIT_V(8); PG8_WAIT_L(0); PG8_BAR; PG8_MMA(0, 0, At, B0); PG8_MMA(0, 1, At, B1); PG8_BAR; PG8_SCHED;
;             PG8_LDA(At, 1, 1); PG8_STAGE(PG8_SB(1, 0), b3, voffB); PG8_STAGE(PG8_SB(1, 1), b3 + hstep, voffB); PG8_STAGE(PG8_SA(1, 0), a3, voffA);
;             PG8_WAIT_V(8); PG8_WAIT_L(0); PG8_BAR; PG8_MMA(1, 0, At, B0); PG8_MMA(1, 1, At, B1); PG8_BAR; PG8_SCHED;
;         }
;         if (wr == 0) PG8_BAR;
	s_setprio 0
	s_add_i32 s29, 0, 0x18000
	s_add_i32 s48, 0, 0x1c000
	v_add_u32_e32 v142, s29, v210
	v_add_u32_e32 v158, s48, v210
	ds_read_b128 v[130:133], v142
	ds_read_b128 v[134:137], v142 offset:1024
	ds_read_b128 v[138:141], v142 offset:2048
	ds_read_b128 v[142:145], v142 offset:3072
	ds_read_b128 v[146:149], v158
	ds_read_b128 v[150:153], v158 offset:1024
	ds_read_b128 v[154:157], v158 offset:2048
	ds_read_b128 v[158:161], v158 offset:3072
	s_add_u32 s46, s72, 0xb0000
	s_addc_u32 s47, s73, 0
	s_mov_b32 m0, s35
	ds_read_b128 v[162:165], v214 offset:32768
	ds_read_b128 v[166:169], v214 offset:33792
	ds_read_b128 v[170:173], v214 offset:34816
	ds_read_b128 v[174:177], v214 offset:35840
	ds_read_b128 v[188:191], v214 offset:36864
	ds_read_b128 v[192:195], v214 offset:37888
	ds_read_b128 v[204:207], v214 offset:38912
	ds_read_b128 v[216:219], v214 offset:39936
	global_load_lds_dwordx4 v178, s[46:47]
	s_mov_b32 m0, s36
	s_nop 0
	global_load_lds_dwordx4 v180, s[46:47]
	s_waitcnt vmcnt(8)
	s_waitcnt lgkmcnt(0)
	s_setprio 1
	s_barrier
	v_mfma_f32_16x16x32_bf16 v[126:129], v[130:133], v[162:165], v[126:129]
	v_mfma_f32_16x16x32_bf16 v[122:125], v[138:141], v[162:165], v[122:125]
	v_mfma_f32_16x16x32_bf16 v[110:113], v[130:133], v[170:173], v[110:113]
	v_mfma_f32_16x16x32_bf16 v[106:109], v[138:141], v[170:173], v[106:109]
	v_mfma_f32_16x16x32_bf16 v[94:97], v[130:133], v[188:191], v[94:97]
	v_mfma_f32_16x16x32_bf16 v[90:93], v[138:141], v[188:191], v[90:93]
	v_mfma_f32_16x16x32_bf16 v[78:81], v[130:133], v[204:207], v[78:81]
	v_mfma_f32_16x16x32_bf16 v[74:77], v[138:141], v[204:207], v[74:77]
	v_mfma_f32_16x16x32_bf16 v[126:129], v[134:137], v[166:169], v[126:129]
	v_mfma_f32_16x16x32_bf16 v[122:125], v[142:145], v[166:169], v[122:125]
	v_mfma_f32_16x16x32_bf16 v[110:113], v[134:137], v[174:177], v[110:113]
	v_mfma_f32_16x16x32_bf16 v[106:109], v[142:145], v[174:177], v[106:109]
	v_mfma_f32_16x16x32_bf16 v[94:97], v[134:137], v[192:195], v[94:97]
	v_mfma_f32_16x16x32_bf16 v[90:93], v[142:145], v[192:195], v[90:93]
	v_mfma_f32_16x16x32_bf16 v[78:81], v[134:137], v[216:219], v[78:81]
	v_mfma_f32_16x16x32_bf16 v[74:77], v[142:145], v[216:219], v[74:77]
	s_setprio 0
	s_setprio 1
	v_mfma_f32_16x16x32_bf16 v[118:121], v[146:149], v[162:165], v[118:121]
	v_mfma_f32_16x16x32_bf16 v[114:117], v[154:157], v[162:165], v[114:117]
	v_mfma_f32_16x16x32_bf16 v[102:105], v[146:149], v[170:173], v[102:105]
	v_mfma_f32_16x16x32_bf16 v[98:101], v[154:157], v[170:173], v[98:101]
	v_mfma_f32_16x16x32_bf16 v[86:89], v[146:149], v[188:191], v[86:89]
	v_mfma_f32_16x16x32_bf16 v[82:85], v[154:157], v[188:191], v[82:85]
	v_mfma_f32_16x16x32_bf16 v[70:73], v[146:149], v[204:207], v[70:73]
	v_mfma_f32_16x16x32_bf16 v[66:69], v[154:157], v[204:207], v[66:69]
	v_mfma_f32_16x16x32_bf16 v[118:121], v[150:153], v[166:169], v[118:121]
	v_mfma_f32_16x16x32_bf16 v[114:117], v[158:161], v[166:169], v[114:117]
	v_mfma_f32_16x16x32_bf16 v[102:105], v[150:153], v[174:177], v[102:105]
	v_mfma_f32_16x16x32_bf16 v[98:101], v[158:161], v[174:177], v[98:101]
	v_mfma_f32_16x16x32_bf16 v[86:89], v[150:153], v[192:195], v[86:89]
	v_mfma_f32_16x16x32_bf16 v[82:85], v[158:161], v[192:195], v[82:85]
	v_mfma_f32_16x16x32_bf16 v[70:73], v[150:153], v[216:219], v[70:73]
	v_mfma_f32_16x16x32_bf16 v[66:69], v[158:161], v[216:219], v[66:69]
	s_barrier
	s_setprio 0
	s_add_i32 s29, s29, s15
	s_mov_b32 m0, s29
	ds_read_b128 v[162:165], v214 offset:49152
	ds_read_b128 v[166:169], v214 offset:50176
	ds_read_b128 v[170:173], v214 offset:51200
	ds_read_b128 v[174:177], v214 offset:52224
	ds_read_b128 v[188:191], v214 offset:53248
	ds_read_b128 v[192:195], v214 offset:54272
	ds_read_b128 v[204:207], v214 offset:55296
	ds_read_b128 v[216:219], v214 offset:56320
	global_load_lds_dwordx4 v221, s[66:67]
	s_add_i32 m0, s29, 0x2000
	s_add_u32 s46, s66, 0xb0080
	s_addc_u32 s47, s67, 0
	s_add_i32 s29, s48, s15
	global_load_lds_dwordx4 v223, s[66:67]
	s_mov_b32 m0, s29
	s_nop 0
	global_load_lds_dwordx4 v0, s[46:47]
	s_add_i32 m0, s29, 0x2000
	s_nop 0
	global_load_lds_dwordx4 v182, s[46:47]
	s_mov_b32 m0, s37
	s_nop 0
	global_load_lds_dwordx4 v225, s[72:73]
	s_mov_b32 m0, s38
	s_nop 0
	global_load_lds_dwordx4 v227, s[72:73]
	s_waitcnt vmcnt(8)
	s_waitcnt lgkmcnt(0)
	s_setprio 1
	s_barrier
	v_mfma_f32_16x16x32_bf16 v[62:65], v[130:133], v[162:165], v[62:65]
	v_mfma_f32_16x16x32_bf16 v[58:61], v[138:141], v[162:165], v[58:61]
	v_mfma_f32_16x16x32_bf16 v[46:49], v[130:133], v[170:173], v[46:49]
	v_mfma_f32_16x16x32_bf16 v[42:45], v[138:141], v[170:173], v[42:45]
	v_mfma_f32_16x16x32_bf16 v[30:33], v[130:133], v[188:191], v[30:33]
	v_mfma_f32_16x16x32_bf16 v[26:29], v[138:141], v[188:191], v[26:29]
	v_mfma_f32_16x16x32_bf16 v[14:17], v[130:133], v[204:207], v[14:17]
	v_mfma_f32_16x16x32_bf16 v[10:13], v[138:141], v[204:207], v[10:13]
	v_mfma_f32_16x16x32_bf16 v[62:65], v[134:137], v[166:169], v[62:65]
	v_mfma_f32_16x16x32_bf16 v[58:61], v[142:145], v[166:169], v[58:61]
	v_mfma_f32_16x16x32_bf16 v[46:49], v[134:137], v[174:177], v[46:49]
	v_mfma_f32_16x16x32_bf16 v[42:45], v[142:145], v[174:177], v[42:45]
	v_mfma_f32_16x16x32_bf16 v[30:33], v[134:137], v[192:195], v[30:33]
	v_mfma_f32_16x16x32_bf16 v[26:29], v[142:145], v[192:195], v[26:29]
	v_mfma_f32_16x16x32_bf16 v[14:17], v[134:137], v[216:219], v[14:17]
	v_mfma_f32_16x16x32_bf16 v[10:13], v[142:145], v[216:219], v[10:13]
	s_setprio 0
	s_setprio 1
	v_mfma_f32_16x16x32_bf16 v[54:57], v[146:149], v[162:165], v[54:57]
	v_mfma_f32_16x16x32_bf16 v[50:53], v[154:157], v[162:165], v[50:53]
	v_mfma_f32_16x16x32_bf16 v[38:41], v[146:149], v[170:173], v[38:41]
	v_mfma_f32_16x16x32_bf16 v[34:37], v[154:157], v[170:173], v[34:37]
	v_mfma_f32_16x16x32_bf16 v[22:25], v[146:149], v[188:191], v[22:25]
	v_mfma_f32_16x16x32_bf16 v[18:21], v[154:157], v[188:191], v[18:21]
	v_mfma_f32_16x16x32_bf16 v[6:9], v[146:149], v[204:207], v[6:9]
	v_mfma_f32_16x16x32_bf16 v[2:5], v[154:157], v[204:207], v[2:5]
	v_mfma_f32_16x16x32_bf16 v[54:57], v[150:153], v[166:169], v[54:57]
	v_mfma_f32_16x16x32_bf16 v[50:53], v[158:161], v[166:169], v[50:53]
	v_mfma_f32_16x16x32_bf16 v[38:41], v[150:153], v[174:177], v[38:41]
	v_mfma_f32_16x16x32_bf16 v[34:37], v[158:161], v[174:177], v[34:37]
	v_mfma_f32_16x16x32_bf16 v[22:25], v[150:153], v[192:195], v[22:25]
	v_mfma_f32_16x16x32_bf16 v[18:21], v[158:161], v[192:195], v[18:21]
	v_mfma_f32_16x16x32_bf16 v[6:9], v[150:153], v[216:219], v[6:9]
	v_mfma_f32_16x16x32_bf16 v[2:5], v[158:161], v[216:219], v[2:5]
	s_barrier
	s_setprio 0
	s_add_i32 s45, s45, 2
	s_add_u32 s31, s31, 0x100
	s_addc_u32 s44, s44, 0
	s_cmp_gt_u32 s45, 41
	s_mov_b64 s[62:63], s[20:21]
	s_cbranch_scc0 .LBB0_598
	s_and_b64 vcc, exec, s[58:59]
	s_cbranch_vccz .LBB0_601
	s_barrier

; #define PG8_BAR __builtin_amdgcn_s_barrier()
;     __device__ __forceinline__ void operator()(const f32x4 (&acc)[2][2][4][2], const Unit& u, int wr, int wc, int fr, int fq, LAS unsigned char* lds, int tid) const {
;     ...
;                 if (fq == 0) red[wc * 256 + ai * HALF + wr * 64 + m * 16 + fr] = ss; }
;             asm volatile("" ::: "memory"); }
;         asm volatile("s_waitcnt lgkmcnt(0)" ::: "memory"); __builtin_amdgcn_s_barrier(); asm volatile("" ::: "memory");
;         if (tid < 256) ssq[(size_t)(u.pm * BM + tid) * 4 + u.pn] = (red[tid] + red[256 + tid]) + (red[512 + tid] + red[768 + tid]);
; template <class Epi, class Sched>
; __device__ __forceinline__ void gemm_phase(LAS unsigned char* lds, const int tid, const Gemm g, const Sched& S, const Epi& E) {
;     ...
;         if (!has_next) break;
; #pragma unroll
;         for (int a = 0; a < 2; ++a)
; #pragma unroll
;             for (int b = 0; b < 2; ++b)
; #pragma unroll
;                 for (int m = 0; m < 4; ++m)
; #pragma unroll
;                     for (int n = 0; n < 2; ++n) acc[a][b][m][n] = (f32x4){0.f, 0.f, 0.f, 0.f};
;         cur = nxt; cA = nA; cB = nB; ++ui;
;         if (wr == 1) PG8_BAR;
.LBB0_619:
	s_or_b64 exec, exec, s[20:21]
	s_and_b64 vcc, exec, s[6:7]
	s_mov_b64 s[0:1], -1
	s_cbranch_vccnz .LBB0_586
	s_andn2_b64 vcc, exec, s[16:17]
	s_cbranch_vccnz .LBB0_585
	s_mov_b32 vcc_lo, 1
	s_nop 0
	v_writelane_b32 v255, vcc_lo, 21
	s_branch .LBB0_585

; #define PG8_STAGE(bufoff, gbase, voff) do { _Pragma("unroll") for (int _i = 0; _i < 2; ++_i) \
;         __builtin_amdgcn_global_load_lds((const gunsigned*)((const gchar*)(gbase) + (voff)[_i]), (LAS unsigned*)(lds + (bufoff) + ldsw + _i * 8192), 16, 0, 0); } while (0)
; #define PG8_LDA(dst, b, h) do { _Pragma("unroll") for (int m = 0; m < 4; ++m) _Pragma("unroll") for (int k = 0; k < 2; ++k) dst[m][k] = *(const LAS bf16x8*)(lds + PG8_SA(b, h) + aoff + m * 2048 + k * 1024); } while (0)
; #define PG8_LDB(dst, b, h) do { _Pragma("unroll") for (int n = 0; n < 2; ++n) _Pragma("unroll") for (int k = 0; k < 2; ++k) dst[n][k] = *(const LAS bf16x8*)(lds + PG8_SB(b, h) + boff + n * 2048 + k * 1024); } while (0)
; #define PG8_WAIT_V(n) asm volatile("s_waitcnt vmcnt(" #n ")" ::: "memory")
; #define PG8_WAIT_L(n) asm volatile("s_waitcnt lgkmcnt(" #n ")" ::: "memory")
; #define PG8_BAR __builtin_amdgcn_s_barrier()
; #define PG8_SCHED __builtin_amdgcn_sched_barrier(0)
; template <class Epi, class Sched>
; __device__ __forceinline__ void gemm_phase(LAS unsigned char* lds, const int tid, const Gemm g, const Sched& S, const Epi& E) {
;     ...
;         const gchar* nA = has_next ? (const gchar*)g.A + (size_t)nxt.pm * tstep + (size_t)nxt.pz * g.zA : cA;
;         const gchar* nB = has_next ? (const gchar*)g.Bt + (size_t)nxt.pn * tstep + (size_t)nxt.pz * g.zB : cB;
;         for (int t = 0; t < nt; t += 2) {
;             const bool last = (t == nt - 2);
;             const gchar* a1 = cA + (size_t)(t + 1) * kstep;
;             const gchar* a2 = last ? nA : cA + (size_t)(t + 2) * kstep; const gchar* b2 = last ? nB : cB + (size_t)(t + 2) * kstep;
;             const gchar* a3 = a2 + kstep; const gchar* b3 = b2 + kstep;
;             PG8_LDB(B0, 0, 0); PG8_LDB(B1, 0, 1); PG8_SCHED; PG8_LDA(At, 0, 0); PG8_STAGE(PG8_SA(1, 1), a1 + hstep, voffA);
;             PG8_WAIT_V(8); PG8_WAIT_L(0); PG8_BAR; PG8_MMA(0, 0, At, B0); PG8_MMA(0, 1, At, B1); PG8_BAR; PG8_SCHED;
;     ...
; #pragma unroll
;         for (int a = 0; a < 2; ++a)
; #pragma unroll
;             for (int b = 0; b < 2; ++b)
; #pragma unroll
;                 for (int m = 0; m < 4; ++m)
; #pragma unroll
;                     for (int n = 0; n < 2; ++n) acc[a][b][m][n] = (f32x4){0.f, 0.f, 0.f, 0.f};
;         cur = nxt; cA = nA; cB = nB; ++ui;
;         if (wr == 1) PG8_BAR;
.LBB0_646:
	s_ashr_i32 s9, s8, 31
	s_lshl_b64 s[10:11], s[8:9], 19
	s_add_u32 s10, s86, s10
	s_addc_u32 s11, s87, s11
	s_and_b64 s[16:17], s[2:3], exec
	s_cselect_b32 s9, s11, s59
	s_cselect_b32 s37, s10, s58
	s_ashr_i32 s7, s6, 31
	s_lshl_b64 s[16:17], s[6:7], 19
	s_add_u32 s16, s84, s16
	s_addc_u32 s17, s85, s17
	s_and_b64 s[38:39], s[2:3], exec
	s_cselect_b32 s7, s17, s21
	s_cselect_b32 s38, s16, s20
	s_add_u32 s39, s20, 0x100
	s_addc_u32 s40, s21, 0
	s_add_u32 s58, s58, 0x40080
	v_mov_b32_e32 v2, 0
	s_addc_u32 s59, s59, 0
	s_mov_b32 s41, -2
	v_mov_b32_e32 v3, v2
	v_mov_b32_e32 v4, v2
	v_mov_b32_e32 v5, v2
	v_mov_b32_e32 v6, v2
	v_mov_b32_e32 v7, v2
	v_mov_b32_e32 v8, v2
	v_mov_b32_e32 v9, v2
	v_mov_b32_e32 v18, v2
	v_mov_b32_e32 v19, v2
	v_mov_b32_e32 v20, v2
	v_mov_b32_e32 v21, v2
	v_mov_b32_e32 v22, v2
	v_mov_b32_e32 v23, v2
	v_mov_b32_e32 v24, v2
	v_mov_b32_e32 v25, v2
	v_mov_b32_e32 v34, v2
	v_mov_b32_e32 v35, v2
	v_mov_b32_e32 v36, v2
	v_mov_b32_e32 v37, v2
	v_mov_b32_e32 v38, v2
	v_mov_b32_e32 v39, v2
	v_mov_b32_e32 v40, v2
	v_mov_b32_e32 v41, v2
	v_mov_b32_e32 v50, v2
	v_mov_b32_e32 v51, v2
	v_mov_b32_e32 v52, v2
	v_mov_b32_e32 v53, v2
	v_mov_b32_e32 v54, v2
	v_mov_b32_e32 v55, v2
	v_mov_b32_e32 v56, v2
	v_mov_b32_e32 v57, v2
	v_mov_b32_e32 v10, v2
	v_mov_b32_e32 v11, v2
	v_mov_b32_e32 v12, v2
	v_mov_b32_e32 v13, v2
	v_mov_b32_e32 v14, v2
	v_mov_b32_e32 v15, v2
	v_mov_b32_e32 v16, v2
	v_mov_b32_e32 v17, v2
	v_mov_b32_e32 v26, v2
	v_mov_b32_e32 v27, v2
	v_mov_b32_e32 v28, v2
	v_mov_b32_e32 v29, v2
	v_mov_b32_e32 v30, v2
	v_mov_b32_e32 v31, v2
	v_mov_b32_e32 v32, v2
	v_mov_b32_e32 v33, v2
	v_mov_b32_e32 v42, v2
	v_mov_b32_e32 v43, v2
	v_mov_b32_e32 v44, v2
	v_mov_b32_e32 v45, v2
	v_mov_b32_e32 v46, v2
	v_mov_b32_e32 v47, v2
	v_mov_b32_e32 v48, v2
	v_mov_b32_e32 v49, v2
	v_mov_b32_e32 v58, v2
	v_mov_b32_e32 v59, v2
	v_mov_b32_e32 v60, v2
	v_mov_b32_e32 v61, v2
	v_mov_b32_e32 v62, v2
	v_mov_b32_e32 v63, v2
	v_mov_b32_e32 v64, v2
	v_mov_b32_e32 v65, v2
	v_mov_b32_e32 v66, v2
	v_mov_b32_e32 v67, v2
	v_mov_b32_e32 v68, v2
	v_mov_b32_e32 v69, v2
	v_mov_b32_e32 v70, v2
	v_mov_b32_e32 v71, v2
	v_mov_b32_e32 v72, v2
	v_mov_b32_e32 v73, v2
	v_mov_b32_e32 v82, v2
	v_mov_b32_e32 v83, v2
	v_mov_b32_e32 v84, v2
	v_mov_b32_e32 v85, v2
	v_mov_b32_e32 v86, v2
	v_mov_b32_e32 v87, v2
	v_mov_b32_e32 v88, v2
	v_mov_b32_e32 v89, v2
	v_mov_b32_e32 v98, v2
	v_mov_b32_e32 v99, v2
	v_mov_b32_e32 v100, v2
	v_mov_b32_e32 v101, v2
	v_mov_b32_e32 v102, v2
	v_mov_b32_e32 v103, v2
	v_mov_b32_e32 v104, v2
	v_mov_b32_e32 v105, v2
	v_mov_b32_e32 v114, v2
	v_mov_b32_e32 v115, v2
	v_mov_b32_e32 v116, v2
	v_mov_b32_e32 v117, v2
	v_mov_b32_e32 v118, v2
	v_mov_b32_e32 v119, v2
	v_mov_b32_e32 v120, v2
	v_mov_b32_e32 v121, v2
	v_mov_b32_e32 v74, v2
	v_mov_b32_e32 v75, v2
	v_mov_b32_e32 v76, v2
	v_mov_b32_e32 v77, v2
	v_mov_b32_e32 v78, v2
	v_mov_b32_e32 v79, v2
	v_mov_b32_e32 v80, v2
	v_mov_b32_e32 v81, v2
	v_mov_b32_e32 v90, v2
	v_mov_b32_e32 v91, v2
	v_mov_b32_e32 v92, v2
	v_mov_b32_e32 v93, v2
	v_mov_b32_e32 v94, v2
	v_mov_b32_e32 v95, v2
	v_mov_b32_e32 v96, v2
	v_mov_b32_e32 v97, v2
	v_mov_b32_e32 v106, v2
	v_mov_b32_e32 v107, v2
	v_mov_b32_e32 v108, v2
	v_mov_b32_e32 v109, v2
	v_mov_b32_e32 v110, v2
	v_mov_b32_e32 v111, v2
	v_mov_b32_e32 v112, v2
	v_mov_b32_e32 v113, v2
	v_mov_b32_e32 v122, v2
	v_mov_b32_e32 v123, v2
	v_mov_b32_e32 v124, v2
	v_mov_b32_e32 v125, v2
	v_mov_b32_e32 v126, v2
	v_mov_b32_e32 v127, v2
	v_mov_b32_e32 v128, v2
	v_mov_b32_e32 v129, v2
	v_add_u32_e32 v141, 0x80, v0
	v_add_u32_e32 v195, 0x80, v130
	v_add_u32_e32 v221, 0x80, v134
	v_add_u32_e32 v223, 0x80, v132
	v_readlane_b32 vcc_lo, v255, 21
	s_nop 3
	s_cmp_eq_u32 vcc_lo, 1
	s_cbranch_scc0 .Lnb_647
	s_barrier
	s_mov_b32 vcc_lo, 0
	s_nop 0
	v_writelane_b32 v255, vcc_lo, 21
.Lnb_647:
.LBB0_647:
	s_add_u32 s20, s58, 0xfffc0080
	s_addc_u32 s21, s59, -1
	s_add_i32 s42, 0, 0x10000
	s_cmp_eq_u32 s41, 12
	s_cselect_b32 s61, s9, s21
	s_cselect_b32 s60, s37, s20
	v_add_u32_e32 v140, s42, v143
	s_cselect_b32 s21, s7, s40
	s_cselect_b32 s20, s38, s39
	s_add_i32 s44, 0, 0x14000
	ds_read_b128 v[146:149], v140
	ds_read_b128 v[150:153], v140 offset:1024
	ds_read_b128 v[154:157], v140 offset:2048
	ds_read_b128 v[158:161], v140 offset:3072
	v_add_u32_e32 v140, s44, v143
	ds_read_b128 v[162:165], v140
	ds_read_b128 v[166:169], v140 offset:1024
	ds_read_b128 v[170:173], v140 offset:2048
	ds_read_b128 v[174:177], v140 offset:3072
	s_add_i32 m0, s23, 0xc000
	ds_read_b128 v[178:181], v145
	ds_read_b128 v[182:185], v145 offset:1024
	ds_read_b128 v[186:189], v145 offset:2048
	ds_read_b128 v[190:193], v145 offset:3072
	ds_read_b128 v[204:207], v145 offset:4096
	ds_read_b128 v[208:211], v145 offset:5120
	ds_read_b128 v[212:215], v145 offset:6144
	ds_read_b128 v[216:219], v145 offset:7168
	global_load_lds_dwordx4 v138, s[58:59]
	s_add_i32 m0, s23, 0xe000
	s_nop 0
	global_load_lds_dwordx4 v136, s[58:59]
	s_waitcnt vmcnt(8)
	s_waitcnt lgkmcnt(0)
	s_setprio 1
	s_barrier
; #define PG8_STAGE(bufoff, gbase, voff) do { _Pragma("unroll") for (int _i = 0; _i < 2; ++_i) \
;         __builtin_amdgcn_global_load_lds((const gunsigned*)((const gchar*)(gbase) + (voff)[_i]), (LAS unsigned*)(lds + (bufoff) + ldsw + _i * 8192), 16, 0, 0); } while (0)
; #define PG8_LDA(dst, b, h) do { _Pragma("unroll") for (int m = 0; m < 4; ++m) _Pragma("unroll") for (int k = 0; k < 2; ++k) dst[m][k] = *(const LAS bf16x8*)(lds + PG8_SA(b, h) + aoff + m * 2048 + k * 1024); } while (0)
; #define PG8_LDB(dst, b, h) do { _Pragma("unroll") for (int n = 0; n < 2; ++n) _Pragma("unroll") for (int k = 0; k < 2; ++k) dst[n][k] = *(const LAS bf16x8*)(lds + PG8_SB(b, h) + boff + n * 2048 + k * 1024); } while (0)
; #define PG8_MMA(ai, bj, At, Bt) do { __builtin_amdgcn_s_setprio(1); _Pragma("unroll") for (int m = 0; m < 4; ++m) _Pragma("unroll") for (int n = 0; n < 2; ++n) _Pragma("unroll") for (int k = 0; k < 2; ++k) \
;         acc[ai][bj][m][n] = __builtin_amdgcn_mfma_f32_16x16x32_bf16(Bt[n][k], At[m][k], acc[ai][bj][m][n], 0, 0, 0); __builtin_amdgcn_s_setprio(0); } while (0)
; #define PG8_WAIT_V(n) asm volatile("s_waitcnt vmcnt(" #n ")" ::: "memory")
; #define PG8_WAIT_L(n) asm volatile("s_waitcnt lgkmcnt(" #n ")" ::: "memory")
; #define PG8_BAR __builtin_amdgcn_s_barrier()
; #define PG8_SCHED __builtin_amdgcn_sched_barrier(0)
; template <class Epi, class Sched>
; __device__ __forceinline__ void gemm_phase(LAS unsigned char* lds, const int tid, const Gemm g, const Sched& S, const Epi& E) {
;     ...
;             PG8_LDB(B0, 0, 0); PG8_LDB(B1, 0, 1); PG8_SCHED; PG8_LDA(At, 0, 0); PG8_STAGE(PG8_SA(1, 1), a1 + hstep, voffA);
;             PG8_WAIT_V(8); PG8_WAIT_L(0); PG8_BAR; PG8_MMA(0, 0, At, B0); PG8_MMA(0, 1, At, B1); PG8_BAR; PG8_SCHED;
;             PG8_LDA(At, 0, 1); PG8_STAGE(PG8_SB(0, 0), b2, voffB); PG8_STAGE(PG8_SB(0, 1), b2 + hstep, voffB); PG8_STAGE(PG8_SA(0, 0), a2, voffA);
;             PG8_WAIT_V(8); PG8_WAIT_L(0); PG8_BAR; PG8_MMA(1, 0, At, B0); PG8_MMA(1, 1, At, B1); PG8_BAR; PG8_SCHED;
;             PG8_LDB(B0, 1, 0); PG8_LDB(B1, 1, 1); PG8_SCHED; PG8_LDA(At, 1, 0); PG8_STAGE(PG8_SA(0, 1), a2 + hstep, voffA);
;             PG8_WAIT_V(8); PG8_WAIT_L(0); PG8_BAR; PG8_MMA(0, 0, At, B0); PG8_MMA(0, 1, At, B1); PG8_BAR; PG8_SCHED;
	v_mfma_f32_16x16x32_bf16 v[126:129], v[146:149], v[178:181], v[126:129]
	v_mfma_f32_16x16x32_bf16 v[122:125], v[154:157], v[178:181], v[122:125]
	v_mfma_f32_16x16x32_bf16 v[110:113], v[146:149], v[186:189], v[110:113]
	v_mfma_f32_16x16x32_bf16 v[106:109], v[154:157], v[186:189], v[106:109]
	v_mfma_f32_16x16x32_bf16 v[94:97], v[146:149], v[204:207], v[94:97]
	v_mfma_f32_16x16x32_bf16 v[90:93], v[154:157], v[204:207], v[90:93]
	v_mfma_f32_16x16x32_bf16 v[78:81], v[146:149], v[212:215], v[78:81]
	v_mfma_f32_16x16x32_bf16 v[74:77], v[154:157], v[212:215], v[74:77]
	v_mfma_f32_16x16x32_bf16 v[126:129], v[150:153], v[182:185], v[126:129]
	v_mfma_f32_16x16x32_bf16 v[122:125], v[158:161], v[182:185], v[122:125]
	v_mfma_f32_16x16x32_bf16 v[110:113], v[150:153], v[190:193], v[110:113]
	v_mfma_f32_16x16x32_bf16 v[106:109], v[158:161], v[190:193], v[106:109]
	v_mfma_f32_16x16x32_bf16 v[94:97], v[150:153], v[208:211], v[94:97]
	v_mfma_f32_16x16x32_bf16 v[90:93], v[158:161], v[208:211], v[90:93]
	v_mfma_f32_16x16x32_bf16 v[78:81], v[150:153], v[216:219], v[78:81]
	v_mfma_f32_16x16x32_bf16 v[74:77], v[158:161], v[216:219], v[74:77]
	s_setprio 0
	s_setprio 1
	v_mfma_f32_16x16x32_bf16 v[118:121], v[162:165], v[178:181], v[118:121]
	v_mfma_f32_16x16x32_bf16 v[114:117], v[170:173], v[178:181], v[114:117]
	v_mfma_f32_16x16x32_bf16 v[102:105], v[162:165], v[186:189], v[102:105]
	v_mfma_f32_16x16x32_bf16 v[98:101], v[170:173], v[186:189], v[98:101]
	v_mfma_f32_16x16x32_bf16 v[86:89], v[162:165], v[204:207], v[86:89]
	v_mfma_f32_16x16x32_bf16 v[82:85], v[170:173], v[204:207], v[82:85]
	v_mfma_f32_16x16x32_bf16 v[70:73], v[162:165], v[212:215], v[70:73]
	v_mfma_f32_16x16x32_bf16 v[66:69], v[170:173], v[212:215], v[66:69]
	v_mfma_f32_16x16x32_bf16 v[118:121], v[166:169], v[182:185], v[118:121]
	v_mfma_f32_16x16x32_bf16 v[114:117], v[174:177], v[182:185], v[114:117]
	v_mfma_f32_16x16x32_bf16 v[102:105], v[166:169], v[190:193], v[102:105]
	v_mfma_f32_16x16x32_bf16 v[98:101], v[174:177], v[190:193], v[98:101]
	v_mfma_f32_16x16x32_bf16 v[86:89], v[166:169], v[208:211], v[86:89]
	v_mfma_f32_16x16x32_bf16 v[82:85], v[174:177], v[208:211], v[82:85]
	v_mfma_f32_16x16x32_bf16 v[70:73], v[166:169], v[216:219], v[70:73]
	v_mfma_f32_16x16x32_bf16 v[66:69], v[174:177], v[216:219], v[66:69]
	s_barrier
	s_setprio 0
	s_add_i32 s42, s42, s12
	s_mov_b32 m0, s42
	ds_read_b128 v[178:181], v145 offset:16384
	ds_read_b128 v[182:185], v145 offset:17408
	ds_read_b128 v[186:189], v145 offset:18432
	ds_read_b128 v[190:193], v145 offset:19456
	ds_read_b128 v[204:207], v145 offset:20480
	ds_read_b128 v[208:211], v145 offset:21504
	ds_read_b128 v[212:215], v145 offset:22528
	ds_read_b128 v[216:219], v145 offset:23552
	global_load_lds_dwordx4 v0, s[20:21]
	s_add_i32 m0, s42, 0x2000
	s_add_u32 s42, s20, 0x40000
	s_addc_u32 s43, s21, 0
	s_add_i32 s44, s44, s12
	global_load_lds_dwordx4 v130, s[20:21]
	s_mov_b32 m0, s44
	s_nop 0
	global_load_lds_dwordx4 v0, s[42:43]
	s_add_i32 m0, s44, 0x2000
	s_nop 0
	global_load_lds_dwordx4 v130, s[42:43]
	s_mov_b32 m0, s23
	s_nop 0
	global_load_lds_dwordx4 v134, s[60:61]
	s_mov_b32 m0, s24
	s_nop 0
	global_load_lds_dwordx4 v132, s[60:61]
	s_waitcnt vmcnt(8)
	s_waitcnt lgkmcnt(0)
	s_setprio 1
	s_barrier
	v_mfma_f32_16x16x32_bf16 v[62:65], v[146:149], v[178:181], v[62:65]
	v_mfma_f32_16x16x32_bf16 v[58:61], v[154:157], v[178:181], v[58:61]
	v_mfma_f32_16x16x32_bf16 v[46:49], v[146:149], v[186:189], v[46:49]
	v_mfma_f32_16x16x32_bf16 v[42:45], v[154:157], v[186:189], v[42:45]
	v_mfma_f32_16x16x32_bf16 v[30:33], v[146:149], v[204:207], v[30:33]
	v_mfma_f32_16x16x32_bf16 v[26:29], v[154:157], v[204:207], v[26:29]
	v_mfma_f32_16x16x32_bf16 v[14:17], v[146:149], v[212:215], v[14:17]
	v_mfma_f32_16x16x32_bf16 v[10:13], v[154:157], v[212:215], v[10:13]
	v_mfma_f32_16x16x32_bf16 v[62:65], v[150:153], v[182:185], v[62:65]
	v_mfma_f32_16x16x32_bf16 v[58:61], v[158:161], v[182:185], v[58:61]
	v_mfma_f32_16x16x32_bf16 v[46:49], v[150:153], v[190:193], v[46:49]
	v_mfma_f32_16x16x32_bf16 v[42:45], v[158:161], v[190:193], v[42:45]
	v_mfma_f32_16x16x32_bf16 v[30:33], v[150:153], v[208:211], v[30:33]
	v_mfma_f32_16x16x32_bf16 v[26:29], v[158:161], v[208:211], v[26:29]
	v_mfma_f32_16x16x32_bf16 v[14:17], v[150:153], v[216:219], v[14:17]
	v_mfma_f32_16x16x32_bf16 v[10:13], v[158:161], v[216:219], v[10:13]
	s_setprio 0
	s_setprio 1
	v_mfma_f32_16x16x32_bf16 v[54:57], v[162:165], v[178:181], v[54:57]
	v_mfma_f32_16x16x32_bf16 v[50:53], v[170:173], v[178:181], v[50:53]
	v_mfma_f32_16x16x32_bf16 v[38:41], v[162:165], v[186:189], v[38:41]
	v_mfma_f32_16x16x32_bf16 v[34:37], v[170:173], v[186:189], v[34:37]
	v_mfma_f32_16x16x32_bf16 v[22:25], v[162:165], v[204:207], v[22:25]
	v_mfma_f32_16x16x32_bf16 v[18:21], v[170:173], v[204:207], v[18:21]
	v_mfma_f32_16x16x32_bf16 v[6:9], v[162:165], v[212:215], v[6:9]
	v_mfma_f32_16x16x32_bf16 v[2:5], v[170:173], v[212:215], v[2:5]
	v_mfma_f32_16x16x32_bf16 v[54:57], v[166:169], v[182:185], v[54:57]
	v_mfma_f32_16x16x32_bf16 v[50:53], v[174:177], v[182:185], v[50:53]
	v_mfma_f32_16x16x32_bf16 v[38:41], v[166:169], v[190:193], v[38:41]
	v_mfma_f32_16x16x32_bf16 v[34:37], v[174:177], v[190:193], v[34:37]
	v_mfma_f32_16x16x32_bf16 v[22:25], v[166:169], v[208:211], v[22:25]
	v_mfma_f32_16x16x32_bf16 v[18:21], v[174:177], v[208:211], v[18:21]
	v_mfma_f32_16x16x32_bf16 v[6:9], v[166:169], v[216:219], v[6:9]
	v_mfma_f32_16x16x32_bf16 v[2:5], v[174:177], v[216:219], v[2:5]
	s_barrier
; #define PG8_STAGE(bufoff, gbase, voff) do { _Pragma("unroll") for (int _i = 0; _i < 2; ++_i) \
;         __builtin_amdgcn_global_load_lds((const gunsigned*)((const gchar*)(gbase) + (voff)[_i]), (LAS unsigned*)(lds + (bufoff) + ldsw + _i * 8192), 16, 0, 0); } while (0)
; #define PG8_LDA(dst, b, h) do { _Pragma("unroll") for (int m = 0; m < 4; ++m) _Pragma("unroll") for (int k = 0; k < 2; ++k) dst[m][k] = *(const LAS bf16x8*)(lds + PG8_SA(b, h) + aoff + m * 2048 + k * 1024); } while (0)
; #define PG8_LDB(dst, b, h) do { _Pragma("unroll") for (int n = 0; n < 2; ++n) _Pragma("unroll") for (int k = 0; k < 2; ++k) dst[n][k] = *(const LAS bf16x8*)(lds + PG8_SB(b, h) + boff + n * 2048 + k * 1024); } while (0)
; #define PG8_MMA(ai, bj, At, Bt) do { __builtin_amdgcn_s_setprio(1); _Pragma("unroll") for (int m = 0; m < 4; ++m) _Pragma("unroll") for (int n = 0; n < 2; ++n) _Pragma("unroll") for (int k = 0; k < 2; ++k) \
;         acc[ai][bj][m][n] = __builtin_amdgcn_mfma_f32_16x16x32_bf16(Bt[n][k], At[m][k], acc[ai][bj][m][n], 0, 0, 0); __builtin_amdgcn_s_setprio(0); } while (0)
; #define PG8_WAIT_V(n) asm volatile("s_waitcnt vmcnt(" #n ")" ::: "memory")
; #define PG8_WAIT_L(n) asm volatile("s_waitcnt lgkmcnt(" #n ")" ::: "memory")
; #define PG8_BAR __builtin_amdgcn_s_barrier()
; #define PG8_SCHED __builtin_amdgcn_sched_barrier(0)
; template <class Epi, class Sched>
; __device__ __forceinline__ void gemm_phase(LAS unsigned char* lds, const int tid, const Gemm g, const Sched& S, const Epi& E) {
;     ...
;             PG8_LDB(B0, 1, 0); PG8_LDB(B1, 1, 1); PG8_SCHED; PG8_LDA(At, 1, 0); PG8_STAGE(PG8_SA(0, 1), a2 + hstep, voffA);
;             PG8_WAIT_V(8); PG8_WAIT_L(0); PG8_BAR; PG8_MMA(0, 0, At, B0); PG8_MMA(0, 1, At, B1); PG8_BAR; PG8_SCHED;
;             PG8_LDA(At, 1, 1); PG8_STAGE(PG8_SB(1, 0), b3, voffB); PG8_STAGE(PG8_SB(1, 1), b3 + hstep, voffB); PG8_STAGE(PG8_SA(1, 0), a3, voffA);
;             PG8_WAIT_V(8); PG8_WAIT_L(0); PG8_BAR; PG8_MMA(1, 0, At, B0); PG8_MMA(1, 1, At, B1); PG8_BAR; PG8_SCHED;
;         }
;         if (wr == 0) PG8_BAR;
	s_setprio 0
	s_add_i32 s44, 0, 0x18000
	s_add_i32 s45, 0, 0x1c000
	v_add_u32_e32 v158, s44, v143
	v_add_u32_e32 v174, s45, v143
	ds_read_b128 v[146:149], v158
	ds_read_b128 v[150:153], v158 offset:1024
	ds_read_b128 v[154:157], v158 offset:2048
	ds_read_b128 v[158:161], v158 offset:3072
	ds_read_b128 v[162:165], v174
	ds_read_b128 v[166:169], v174 offset:1024
	ds_read_b128 v[170:173], v174 offset:2048
	ds_read_b128 v[174:177], v174 offset:3072
	s_add_u32 s42, s60, 0x40000
	s_addc_u32 s43, s61, 0
	s_mov_b32 m0, s29
	ds_read_b128 v[178:181], v145 offset:32768
	ds_read_b128 v[182:185], v145 offset:33792
	ds_read_b128 v[186:189], v145 offset:34816
	ds_read_b128 v[190:193], v145 offset:35840
	ds_read_b128 v[204:207], v145 offset:36864
	ds_read_b128 v[208:211], v145 offset:37888
	ds_read_b128 v[212:215], v145 offset:38912
	ds_read_b128 v[216:219], v145 offset:39936
	global_load_lds_dwordx4 v134, s[42:43]
	s_mov_b32 m0, s30
	s_nop 0
	global_load_lds_dwordx4 v132, s[42:43]
	s_waitcnt vmcnt(8)
	s_waitcnt lgkmcnt(0)
	s_setprio 1
	s_barrier
	v_mfma_f32_16x16x32_bf16 v[126:129], v[146:149], v[178:181], v[126:129]
	v_mfma_f32_16x16x32_bf16 v[122:125], v[154:157], v[178:181], v[122:125]
	v_mfma_f32_16x16x32_bf16 v[110:113], v[146:149], v[186:189], v[110:113]
	v_mfma_f32_16x16x32_bf16 v[106:109], v[154:157], v[186:189], v[106:109]
	v_mfma_f32_16x16x32_bf16 v[94:97], v[146:149], v[204:207], v[94:97]
	v_mfma_f32_16x16x32_bf16 v[90:93], v[154:157], v[204:207], v[90:93]
	v_mfma_f32_16x16x32_bf16 v[78:81], v[146:149], v[212:215], v[78:81]
	v_mfma_f32_16x16x32_bf16 v[74:77], v[154:157], v[212:215], v[74:77]
	v_mfma_f32_16x16x32_bf16 v[126:129], v[150:153], v[182:185], v[126:129]
	v_mfma_f32_16x16x32_bf16 v[122:125], v[158:161], v[182:185], v[122:125]
	v_mfma_f32_16x16x32_bf16 v[110:113], v[150:153], v[190:193], v[110:113]
	v_mfma_f32_16x16x32_bf16 v[106:109], v[158:161], v[190:193], v[106:109]
	v_mfma_f32_16x16x32_bf16 v[94:97], v[150:153], v[208:211], v[94:97]
	v_mfma_f32_16x16x32_bf16 v[90:93], v[158:161], v[208:211], v[90:93]
	v_mfma_f32_16x16x32_bf16 v[78:81], v[150:153], v[216:219], v[78:81]
	v_mfma_f32_16x16x32_bf16 v[74:77], v[158:161], v[216:219], v[74:77]
	s_setprio 0
	s_setprio 1
	v_mfma_f32_16x16x32_bf16 v[118:121], v[162:165], v[178:181], v[118:121]
	v_mfma_f32_16x16x32_bf16 v[114:117], v[170:173], v[178:181], v[114:117]
	v_mfma_f32_16x16x32_bf16 v[102:105], v[162:165], v[186:189], v[102:105]
	v_mfma_f32_16x16x32_bf16 v[98:101], v[170:173], v[186:189], v[98:101]
	v_mfma_f32_16x16x32_bf16 v[86:89], v[162:165], v[204:207], v[86:89]
	v_mfma_f32_16x16x32_bf16 v[82:85], v[170:173], v[204:207], v[82:85]
	v_mfma_f32_16x16x32_bf16 v[70:73], v[162:165], v[212:215], v[70:73]
	v_mfma_f32_16x16x32_bf16 v[66:69], v[170:173], v[212:215], v[66:69]
	v_mfma_f32_16x16x32_bf16 v[118:121], v[166:169], v[182:185], v[118:121]
	v_mfma_f32_16x16x32_bf16 v[114:117], v[174:177], v[182:185], v[114:117]
	v_mfma_f32_16x16x32_bf16 v[102:105], v[166:169], v[190:193], v[102:105]
	v_mfma_f32_16x16x32_bf16 v[98:101], v[174:177], v[190:193], v[98:101]
	v_mfma_f32_16x16x32_bf16 v[86:89], v[166:169], v[208:211], v[86:89]
	v_mfma_f32_16x16x32_bf16 v[82:85], v[174:177], v[208:211], v[82:85]
	v_mfma_f32_16x16x32_bf16 v[70:73], v[166:169], v[216:219], v[70:73]
	v_mfma_f32_16x16x32_bf16 v[66:69], v[174:177], v[216:219], v[66:69]
	s_barrier
	s_setprio 0
	s_add_i32 s42, s44, s12
	s_mov_b32 m0, s42
	ds_read_b128 v[178:181], v145 offset:49152
	ds_read_b128 v[182:185], v145 offset:50176
	ds_read_b128 v[186:189], v145 offset:51200
	ds_read_b128 v[190:193], v145 offset:52224
	ds_read_b128 v[204:207], v145 offset:53248
	ds_read_b128 v[208:211], v145 offset:54272
	ds_read_b128 v[212:215], v145 offset:55296
	ds_read_b128 v[216:219], v145 offset:56320
	global_load_lds_dwordx4 v141, s[20:21]
	s_add_i32 m0, s42, 0x2000
	s_add_i32 s42, s45, s12
	global_load_lds_dwordx4 v195, s[20:21]
	s_add_u32 s20, s20, 0x40080
	s_addc_u32 s21, s21, 0
	s_mov_b32 m0, s42
	s_nop 0
	global_load_lds_dwordx4 v0, s[20:21]
	s_add_i32 m0, s42, 0x2000
	s_nop 0
	global_load_lds_dwordx4 v130, s[20:21]
	s_mov_b32 m0, s31
	s_nop 0
	global_load_lds_dwordx4 v221, s[60:61]
	s_mov_b32 m0, s34
	s_nop 0
	global_load_lds_dwordx4 v223, s[60:61]
	s_waitcnt vmcnt(8)
	s_waitcnt lgkmcnt(0)
	s_setprio 1
	s_barrier
	v_mfma_f32_16x16x32_bf16 v[62:65], v[146:149], v[178:181], v[62:65]
	v_mfma_f32_16x16x32_bf16 v[58:61], v[154:157], v[178:181], v[58:61]
	v_mfma_f32_16x16x32_bf16 v[46:49], v[146:149], v[186:189], v[46:49]
	v_mfma_f32_16x16x32_bf16 v[42:45], v[154:157], v[186:189], v[42:45]
	v_mfma_f32_16x16x32_bf16 v[30:33], v[146:149], v[204:207], v[30:33]
	v_mfma_f32_16x16x32_bf16 v[26:29], v[154:157], v[204:207], v[26:29]
	v_mfma_f32_16x16x32_bf16 v[14:17], v[146:149], v[212:215], v[14:17]
	v_mfma_f32_16x16x32_bf16 v[10:13], v[154:157], v[212:215], v[10:13]
	v_mfma_f32_16x16x32_bf16 v[62:65], v[150:153], v[182:185], v[62:65]
	v_mfma_f32_16x16x32_bf16 v[58:61], v[158:161], v[182:185], v[58:61]
	v_mfma_f32_16x16x32_bf16 v[46:49], v[150:153], v[190:193], v[46:49]
	v_mfma_f32_16x16x32_bf16 v[42:45], v[158:161], v[190:193], v[42:45]
	v_mfma_f32_16x16x32_bf16 v[30:33], v[150:153], v[208:211], v[30:33]
	v_mfma_f32_16x16x32_bf16 v[26:29], v[158:161], v[208:211], v[26:29]
	v_mfma_f32_16x16x32_bf16 v[14:17], v[150:153], v[216:219], v[14:17]
	v_mfma_f32_16x16x32_bf16 v[10:13], v[158:161], v[216:219], v[10:13]
	s_setprio 0
	s_setprio 1
	v_mfma_f32_16x16x32_bf16 v[54:57], v[162:165], v[178:181], v[54:57]
	v_mfma_f32_16x16x32_bf16 v[50:53], v[170:173], v[178:181], v[50:53]
	v_mfma_f32_16x16x32_bf16 v[38:41], v[162:165], v[186:189], v[38:41]
	v_mfma_f32_16x16x32_bf16 v[34:37], v[170:173], v[186:189], v[34:37]
	v_mfma_f32_16x16x32_bf16 v[22:25], v[162:165], v[204:207], v[22:25]
	v_mfma_f32_16x16x32_bf16 v[18:21], v[170:173], v[204:207], v[18:21]
	v_mfma_f32_16x16x32_bf16 v[6:9], v[162:165], v[212:215], v[6:9]
	v_mfma_f32_16x16x32_bf16 v[2:5], v[170:173], v[212:215], v[2:5]
	v_mfma_f32_16x16x32_bf16 v[54:57], v[166:169], v[182:185], v[54:57]
	v_mfma_f32_16x16x32_bf16 v[50:53], v[174:177], v[182:185], v[50:53]
	v_mfma_f32_16x16x32_bf16 v[38:41], v[166:169], v[190:193], v[38:41]
	v_mfma_f32_16x16x32_bf16 v[34:37], v[174:177], v[190:193], v[34:37]
	v_mfma_f32_16x16x32_bf16 v[22:25], v[166:169], v[208:211], v[22:25]
	v_mfma_f32_16x16x32_bf16 v[18:21], v[174:177], v[208:211], v[18:21]
	v_mfma_f32_16x16x32_bf16 v[6:9], v[166:169], v[216:219], v[6:9]
	v_mfma_f32_16x16x32_bf16 v[2:5], v[174:177], v[216:219], v[2:5]
	s_barrier
	s_setprio 0
	s_add_i32 s41, s41, 2
	s_add_u32 s39, s39, 0x100
	s_addc_u32 s40, s40, 0
	s_add_u32 s58, s58, 0x100
	s_addc_u32 s59, s59, 0
	s_cmp_gt_u32 s41, 13
	s_cbranch_scc0 .LBB0_647
	s_and_b64 vcc, exec, s[4:5]
	s_cbranch_vccz .LBB0_650
	s_barrier
; __device__ __forceinline__ unsigned pk2(float lo, float hi) { f32x2 v = {lo, hi}; bf16x2_t b = __builtin_convertvector(v, bf16x2_t); return __builtin_bit_cast(unsigned, b); }
; __device__ __forceinline__ float sigmoidf_(float x) { return __builtin_amdgcn_rcpf(1.0f + __builtin_amdgcn_exp2f(-x * LOG2E)); }
;     __device__ __forceinline__ void operator()(const f32x4 (&acc)[2][2][4][2], const Unit& u, int wr, int wc, int fr, int fq, LAS unsigned char* lds, int tid) const {
;         const int row0 = u.pm * BM + wr * 64 + fr, col0 = u.pn * HALF + wc * 32 + 8 * fq;
; #pragma unroll
;         for (int ai = 0; ai < 2; ++ai)
; #pragma unroll
;             for (int m = 0; m < 4; ++m) { gbf16* rowp = O + (size_t)(row0 + ai * HALF + m * 16) * FF + col0;
;                 float h[8];
; #pragma unroll
;                 for (int n = 0; n < 2; ++n)
; #pragma unroll
;                     for (int e = 0; e < 4; ++e) { const float g = acc[ai][0][m][n][e], uu = acc[ai][1][m][n][e]; h[n * 4 + e] = g * sigmoidf_(g) * uu; }
;                 u32x4 w; w.x = pk2(h[0], h[1]); w.y = pk2(h[2], h[3]); w.z = pk2(h[4], h[5]); w.w = pk2(h[6], h[7]);
;                 *(gu32x4*)rowp = w; }
.LBB0_650:
	v_mul_f32_e32 v140, 0xbfb8aa3b, v126
	v_exp_f32_e32 v140, v140
	v_mul_f32_e32 v141, 0xbfb8aa3b, v127
	v_exp_f32_e32 v141, v141
	v_mul_f32_e32 v147, 0xbfb8aa3b, v128
	v_add_f32_e32 v140, 1.0, v140
	v_rcp_f32_e32 v150, v140
	v_add_f32_e32 v140, 1.0, v141
	v_rcp_f32_e32 v151, v140
	v_exp_f32_e32 v147, v147
	v_lshl_or_b32 v148, s36, 7, v144
	v_lshl_add_u32 v146, s56, 8, v142
	v_pk_mul_f32 v[126:127], v[126:127], v[150:151]
	v_mul_f32_e32 v150, 0xbfb8aa3b, v129
	v_exp_f32_e32 v150, v150
	v_pk_mul_f32 v[118:119], v[126:127], v[118:119]
	v_add_f32_e32 v126, 1.0, v147
	v_mul_f32_e32 v147, 0xbfb8aa3b, v122
	v_add_f32_e32 v127, 1.0, v150
	v_rcp_f32_e32 v126, v126
	v_rcp_f32_e32 v127, v127
	v_exp_f32_e32 v147, v147
	v_mul_f32_e32 v150, 0xbfb8aa3b, v123
	v_exp_f32_e32 v150, v150
	v_pk_mul_f32 v[126:127], v[128:129], v[126:127]
	v_add_f32_e32 v128, 1.0, v147
	v_mul_f32_e32 v147, 0xbfb8aa3b, v124
	v_add_f32_e32 v129, 1.0, v150
	v_exp_f32_e32 v147, v147
	v_mul_f32_e32 v150, 0xbfb8aa3b, v125
	v_exp_f32_e32 v151, v150
	v_rcp_f32_e32 v128, v128
	v_add_f32_e32 v147, 1.0, v147
	v_rcp_f32_e32 v129, v129
	v_rcp_f32_e32 v150, v147
	v_add_f32_e32 v147, 1.0, v151
	v_rcp_f32_e32 v151, v147
	v_pk_mul_f32 v[122:123], v[122:123], v[128:129]
	v_pk_mul_f32 v[120:121], v[126:127], v[120:121]
	v_pk_mul_f32 v[122:123], v[122:123], v[114:115]
	v_pk_mul_f32 v[114:115], v[124:125], v[150:151]
	v_ashrrev_i32_e32 v149, 31, v148
	v_pk_mul_f32 v[124:125], v[114:115], v[116:117]
	v_cvt_pk_bf16_f32 v117, v120, v121
	v_mul_f32_e32 v120, 0xbfb8aa3b, v110
	v_mul_f32_e32 v121, 0xbfb8aa3b, v111
	v_exp_f32_e32 v120, v120
	v_exp_f32_e32 v121, v121
	v_mov_b64_e32 v[140:141], s[88:89]
	v_mad_i64_i32 v[152:153], s[20:21], v146, s79, v[140:141]
	v_lshlrev_b64 v[114:115], 1, v[148:149]
	v_lshl_add_u64 v[126:127], v[152:153], 0, v[114:115]
	v_cvt_pk_bf16_f32 v116, v118, v119
	v_cvt_pk_bf16_f32 v118, v122, v123
	v_cvt_pk_bf16_f32 v119, v124, v125
	global_store_dwordx4 v[126:127], v[116:119], off
	s_andn2_b64 vcc, exec, s[2:3]
	s_mov_b64 s[2:3], -1
	v_add_f32_e32 v116, 1.0, v120
	v_add_f32_e32 v117, 1.0, v121
	v_rcp_f32_e32 v116, v116
	v_rcp_f32_e32 v117, v117
	v_or_b32_e32 v118, 16, v146
	v_mad_i64_i32 v[118:119], s[20:21], v118, s79, v[140:141]
	v_pk_mul_f32 v[110:111], v[110:111], v[116:117]
	v_mul_f32_e32 v116, 0xbfb8aa3b, v112
	v_mul_f32_e32 v117, 0xbfb8aa3b, v113
	v_exp_f32_e32 v116, v116
	v_exp_f32_e32 v117, v117
	v_pk_mul_f32 v[102:103], v[110:111], v[102:103]
	v_add_f32_e32 v110, 1.0, v116
	v_add_f32_e32 v111, 1.0, v117
	v_mul_f32_e32 v116, 0xbfb8aa3b, v106
	v_mul_f32_e32 v117, 0xbfb8aa3b, v107
	v_rcp_f32_e32 v110, v110
	v_rcp_f32_e32 v111, v111
	v_exp_f32_e32 v116, v116
	v_exp_f32_e32 v117, v117
	v_pk_mul_f32 v[110:111], v[112:113], v[110:111]
	v_add_f32_e32 v112, 1.0, v116
	v_add_f32_e32 v113, 1.0, v117
	v_mul_f32_e32 v116, 0xbfb8aa3b, v108
	v_mul_f32_e32 v117, 0xbfb8aa3b, v109
	v_exp_f32_e32 v116, v116
	v_exp_f32_e32 v117, v117
	v_rcp_f32_e32 v112, v112
	v_rcp_f32_e32 v113, v113
	v_add_f32_e32 v116, 1.0, v116
	v_add_f32_e32 v117, 1.0, v117
	v_rcp_f32_e32 v116, v116
	v_rcp_f32_e32 v117, v117
	v_pk_mul_f32 v[106:107], v[106:107], v[112:113]
	v_pk_mul_f32 v[104:105], v[110:111], v[104:105]
	v_pk_mul_f32 v[106:107], v[106:107], v[98:99]
	v_pk_mul_f32 v[98:99], v[108:109], v[116:117]
	v_lshl_add_u64 v[110:111], v[118:119], 0, v[114:115]
	v_pk_mul_f32 v[108:109], v[98:99], v[100:101]
	v_cvt_pk_bf16_f32 v98, v102, v103
	v_mul_f32_e32 v102, 0xbfb8aa3b, v94
	v_mul_f32_e32 v103, 0xbfb8aa3b, v95
	v_exp_f32_e32 v102, v102
	v_exp_f32_e32 v103, v103
	v_cvt_pk_bf16_f32 v99, v104, v105
	v_cvt_pk_bf16_f32 v100, v106, v107
	v_cvt_pk_bf16_f32 v101, v108, v109
	global_store_dwordx4 v[110:111], v[98:101], off
	s_nop 1
	v_add_f32_e32 v98, 1.0, v102
	v_add_f32_e32 v99, 1.0, v103
	v_rcp_f32_e32 v98, v98
	v_rcp_f32_e32 v99, v99
	v_or_b32_e32 v100, 32, v146
	v_mad_i64_i32 v[100:101], s[20:21], v100, s79, v[140:141]
	v_pk_mul_f32 v[94:95], v[94:95], v[98:99]
	v_mul_f32_e32 v98, 0xbfb8aa3b, v96
	v_mul_f32_e32 v99, 0xbfb8aa3b, v97
	v_exp_f32_e32 v98, v98
	v_exp_f32_e32 v99, v99
	v_pk_mul_f32 v[86:87], v[94:95], v[86:87]
	v_add_f32_e32 v94, 1.0, v98
	v_add_f32_e32 v95, 1.0, v99
	v_mul_f32_e32 v98, 0xbfb8aa3b, v90
	v_mul_f32_e32 v99, 0xbfb8aa3b, v91
	v_rcp_f32_e32 v94, v94
	v_rcp_f32_e32 v95, v95
	v_exp_f32_e32 v98, v98
	v_exp_f32_e32 v99, v99
	v_pk_mul_f32 v[94:95], v[96:97], v[94:95]
	v_add_f32_e32 v96, 1.0, v98
	v_add_f32_e32 v97, 1.0, v99
	v_mul_f32_e32 v98, 0xbfb8aa3b, v92
	v_mul_f32_e32 v99, 0xbfb8aa3b, v93
	v_exp_f32_e32 v98, v98
	v_exp_f32_e32 v99, v99
	v_rcp_f32_e32 v96, v96
	v_rcp_f32_e32 v97, v97
	v_add_f32_e32 v98, 1.0, v98
	v_add_f32_e32 v99, 1.0, v99
	v_rcp_f32_e32 v98, v98
	v_rcp_f32_e32 v99, v99
	v_pk_mul_f32 v[90:91], v[90:91], v[96:97]
	v_pk_mul_f32 v[88:89], v[94:95], v[88:89]
	v_pk_mul_f32 v[90:91], v[90:91], v[82:83]
	v_pk_mul_f32 v[82:83], v[92:93], v[98:99]
	v_lshl_add_u64 v[94:95], v[100:101], 0, v[114:115]
	v_pk_mul_f32 v[92:93], v[82:83], v[84:85]
	v_cvt_pk_bf16_f32 v82, v86, v87
	v_mul_f32_e32 v86, 0xbfb8aa3b, v78
	v_mul_f32_e32 v87, 0xbfb8aa3b, v79
	v_exp_f32_e32 v86, v86
	v_exp_f32_e32 v87, v87
	v_cvt_pk_bf16_f32 v83, v88, v89
	v_cvt_pk_bf16_f32 v84, v90, v91
	v_cvt_pk_bf16_f32 v85, v92, v93
	global_store_dwordx4 v[94:95], v[82:85], off
	s_nop 1
	v_add_f32_e32 v82, 1.0, v86
	v_add_f32_e32 v83, 1.0, v87
	v_rcp_f32_e32 v82, v82
	v_rcp_f32_e32 v83, v83
	v_or_b32_e32 v84, 48, v146
	v_mad_i64_i32 v[84:85], s[20:21], v84, s79, v[140:141]
	v_pk_mul_f32 v[78:79], v[78:79], v[82:83]
	v_mul_f32_e32 v82, 0xbfb8aa3b, v80
	v_mul_f32_e32 v83, 0xbfb8aa3b, v81
	v_exp_f32_e32 v82, v82
; __device__ __forceinline__ unsigned pk2(float lo, float hi) { f32x2 v = {lo, hi}; bf16x2_t b = __builtin_convertvector(v, bf16x2_t); return __builtin_bit_cast(unsigned, b); }
; __device__ __forceinline__ float sigmoidf_(float x) { return __builtin_amdgcn_rcpf(1.0f + __builtin_amdgcn_exp2f(-x * LOG2E)); }
;     __device__ __forceinline__ void operator()(const f32x4 (&acc)[2][2][4][2], const Unit& u, int wr, int wc, int fr, int fq, LAS unsigned char* lds, int tid) const {
;         const int row0 = u.pm * BM + wr * 64 + fr, col0 = u.pn * HALF + wc * 32 + 8 * fq;
; #pragma unroll
;         for (int ai = 0; ai < 2; ++ai)
; #pragma unroll
;             for (int m = 0; m < 4; ++m) { gbf16* rowp = O + (size_t)(row0 + ai * HALF + m * 16) * FF + col0;
;                 float h[8];
; #pragma unroll
;                 for (int n = 0; n < 2; ++n)
; #pragma unroll
;                     for (int e = 0; e < 4; ++e) { const float g = acc[ai][0][m][n][e], uu = acc[ai][1][m][n][e]; h[n * 4 + e] = g * sigmoidf_(g) * uu; }
;                 u32x4 w; w.x = pk2(h[0], h[1]); w.y = pk2(h[2], h[3]); w.z = pk2(h[4], h[5]); w.w = pk2(h[6], h[7]);
;                 *(gu32x4*)rowp = w; }
	v_exp_f32_e32 v83, v83
	v_pk_mul_f32 v[70:71], v[78:79], v[70:71]
	v_add_f32_e32 v78, 1.0, v82
	v_add_f32_e32 v79, 1.0, v83
	v_mul_f32_e32 v82, 0xbfb8aa3b, v74
	v_mul_f32_e32 v83, 0xbfb8aa3b, v75
	v_rcp_f32_e32 v78, v78
	v_rcp_f32_e32 v79, v79
	v_exp_f32_e32 v82, v82
	v_exp_f32_e32 v83, v83
	v_pk_mul_f32 v[78:79], v[80:81], v[78:79]
	v_add_f32_e32 v80, 1.0, v82
	v_add_f32_e32 v81, 1.0, v83
	v_mul_f32_e32 v82, 0xbfb8aa3b, v76
	v_mul_f32_e32 v83, 0xbfb8aa3b, v77
	v_exp_f32_e32 v82, v82
	v_exp_f32_e32 v83, v83
	v_rcp_f32_e32 v80, v80
	v_rcp_f32_e32 v81, v81
	v_add_f32_e32 v82, 1.0, v82
	v_add_f32_e32 v83, 1.0, v83
	v_rcp_f32_e32 v82, v82
	v_rcp_f32_e32 v83, v83
	v_pk_mul_f32 v[74:75], v[74:75], v[80:81]
	v_pk_mul_f32 v[72:73], v[78:79], v[72:73]
	v_pk_mul_f32 v[74:75], v[74:75], v[66:67]
	v_pk_mul_f32 v[66:67], v[76:77], v[82:83]
	v_lshl_add_u64 v[78:79], v[84:85], 0, v[114:115]
	v_pk_mul_f32 v[76:77], v[66:67], v[68:69]
	v_cvt_pk_bf16_f32 v66, v70, v71
	v_mul_f32_e32 v70, 0xbfb8aa3b, v62
	v_mul_f32_e32 v71, 0xbfb8aa3b, v63
	v_exp_f32_e32 v70, v70
	v_exp_f32_e32 v71, v71
	v_cvt_pk_bf16_f32 v67, v72, v73
	v_cvt_pk_bf16_f32 v68, v74, v75
	v_cvt_pk_bf16_f32 v69, v76, v77
	global_store_dwordx4 v[78:79], v[66:69], off
	s_nop 1
	v_add_f32_e32 v66, 1.0, v70
	v_add_f32_e32 v67, 1.0, v71
	v_rcp_f32_e32 v66, v66
	v_rcp_f32_e32 v67, v67
	v_add_u32_e32 v68, 0x80, v146
	v_mad_i64_i32 v[68:69], s[20:21], v68, s79, v[140:141]
	v_pk_mul_f32 v[62:63], v[62:63], v[66:67]
	v_mul_f32_e32 v66, 0xbfb8aa3b, v64
	v_mul_f32_e32 v67, 0xbfb8aa3b, v65
	v_exp_f32_e32 v66, v66
	v_exp_f32_e32 v67, v67
	v_pk_mul_f32 v[54:55], v[62:63], v[54:55]
	v_add_f32_e32 v62, 1.0, v66
	v_add_f32_e32 v63, 1.0, v67
	v_mul_f32_e32 v66, 0xbfb8aa3b, v58
	v_mul_f32_e32 v67, 0xbfb8aa3b, v59
	v_rcp_f32_e32 v62, v62
	v_rcp_f32_e32 v63, v63
	v_exp_f32_e32 v66, v66
	v_exp_f32_e32 v67, v67
	v_pk_mul_f32 v[62:63], v[64:65], v[62:63]
	v_add_f32_e32 v64, 1.0, v66
	v_add_f32_e32 v65, 1.0, v67
	v_mul_f32_e32 v66, 0xbfb8aa3b, v60
	v_mul_f32_e32 v67, 0xbfb8aa3b, v61
	v_exp_f32_e32 v66, v66
	v_exp_f32_e32 v67, v67
	v_rcp_f32_e32 v64, v64
	v_rcp_f32_e32 v65, v65
	v_add_f32_e32 v66, 1.0, v66
	v_add_f32_e32 v67, 1.0, v67
	v_rcp_f32_e32 v66, v66
	v_rcp_f32_e32 v67, v67
	v_pk_mul_f32 v[58:59], v[58:59], v[64:65]
	v_pk_mul_f32 v[56:57], v[62:63], v[56:57]
	v_pk_mul_f32 v[58:59], v[58:59], v[50:51]
	v_pk_mul_f32 v[50:51], v[60:61], v[66:67]
	v_lshl_add_u64 v[62:63], v[68:69], 0, v[114:115]
	v_pk_mul_f32 v[60:61], v[50:51], v[52:53]
	v_cvt_pk_bf16_f32 v50, v54, v55
	v_mul_f32_e32 v54, 0xbfb8aa3b, v46
	v_mul_f32_e32 v55, 0xbfb8aa3b, v47
	v_exp_f32_e32 v54, v54
	v_exp_f32_e32 v55, v55
	v_cvt_pk_bf16_f32 v51, v56, v57
	v_cvt_pk_bf16_f32 v52, v58, v59
	v_cvt_pk_bf16_f32 v53, v60, v61
	global_store_dwordx4 v[62:63], v[50:53], off
	s_nop 1
	v_add_f32_e32 v50, 1.0, v54
	v_add_f32_e32 v51, 1.0, v55
	v_rcp_f32_e32 v50, v50
	v_rcp_f32_e32 v51, v51
	v_add_u32_e32 v52, 0x90, v146
	v_mad_i64_i32 v[52:53], s[20:21], v52, s79, v[140:141]
	v_pk_mul_f32 v[46:47], v[46:47], v[50:51]
	v_mul_f32_e32 v50, 0xbfb8aa3b, v48
	v_mul_f32_e32 v51, 0xbfb8aa3b, v49
	v_exp_f32_e32 v50, v50
	v_exp_f32_e32 v51, v51
	v_pk_mul_f32 v[38:39], v[46:47], v[38:39]
	v_add_f32_e32 v46, 1.0, v50
	v_add_f32_e32 v47, 1.0, v51
	v_mul_f32_e32 v50, 0xbfb8aa3b, v42
	v_mul_f32_e32 v51, 0xbfb8aa3b, v43
	v_rcp_f32_e32 v46, v46
	v_rcp_f32_e32 v47, v47
	v_exp_f32_e32 v50, v50
	v_exp_f32_e32 v51, v51
	v_pk_mul_f32 v[46:47], v[48:49], v[46:47]
	v_add_f32_e32 v48, 1.0, v50
	v_add_f32_e32 v49, 1.0, v51
	v_mul_f32_e32 v50, 0xbfb8aa3b, v44
	v_mul_f32_e32 v51, 0xbfb8aa3b, v45
	v_exp_f32_e32 v50, v50
	v_exp_f32_e32 v51, v51
	v_rcp_f32_e32 v48, v48
	v_rcp_f32_e32 v49, v49
	v_add_f32_e32 v50, 1.0, v50
	v_add_f32_e32 v51, 1.0, v51
; __device__ __forceinline__ unsigned pk2(float lo, float hi) { f32x2 v = {lo, hi}; bf16x2_t b = __builtin_convertvector(v, bf16x2_t); return __builtin_bit_cast(unsigned, b); }
; __device__ __forceinline__ float sigmoidf_(float x) { return __builtin_amdgcn_rcpf(1.0f + __builtin_amdgcn_exp2f(-x * LOG2E)); }
; #define PG8_BAR __builtin_amdgcn_s_barrier()
;     __device__ __forceinline__ void operator()(const f32x4 (&acc)[2][2][4][2], const Unit& u, int wr, int wc, int fr, int fq, LAS unsigned char* lds, int tid) const {
;     ...
;             for (int m = 0; m < 4; ++m) { gbf16* rowp = O + (size_t)(row0 + ai * HALF + m * 16) * FF + col0;
;                 float h[8];
; #pragma unroll
;                 for (int n = 0; n < 2; ++n)
; #pragma unroll
;                     for (int e = 0; e < 4; ++e) { const float g = acc[ai][0][m][n][e], uu = acc[ai][1][m][n][e]; h[n * 4 + e] = g * sigmoidf_(g) * uu; }
;                 u32x4 w; w.x = pk2(h[0], h[1]); w.y = pk2(h[2], h[3]); w.z = pk2(h[4], h[5]); w.w = pk2(h[6], h[7]);
;                 *(gu32x4*)rowp = w; }
; template <class Epi, class Sched>
; __device__ __forceinline__ void gemm_phase(LAS unsigned char* lds, const int tid, const Gemm g, const Sched& S, const Epi& E) {
;     ...
;         if (wr == 1) PG8_BAR;
	v_rcp_f32_e32 v50, v50
	v_rcp_f32_e32 v51, v51
	v_pk_mul_f32 v[42:43], v[42:43], v[48:49]
	v_pk_mul_f32 v[40:41], v[46:47], v[40:41]
	v_pk_mul_f32 v[42:43], v[42:43], v[34:35]
	v_pk_mul_f32 v[34:35], v[44:45], v[50:51]
	v_lshl_add_u64 v[46:47], v[52:53], 0, v[114:115]
	v_pk_mul_f32 v[44:45], v[34:35], v[36:37]
	v_cvt_pk_bf16_f32 v34, v38, v39
	v_mul_f32_e32 v38, 0xbfb8aa3b, v30
	v_mul_f32_e32 v39, 0xbfb8aa3b, v31
	v_exp_f32_e32 v38, v38
	v_exp_f32_e32 v39, v39
	v_cvt_pk_bf16_f32 v35, v40, v41
	v_cvt_pk_bf16_f32 v36, v42, v43
	v_cvt_pk_bf16_f32 v37, v44, v45
	global_store_dwordx4 v[46:47], v[34:37], off
	s_nop 1
	v_add_f32_e32 v34, 1.0, v38
	v_add_f32_e32 v35, 1.0, v39
	v_rcp_f32_e32 v34, v34
	v_rcp_f32_e32 v35, v35
	v_add_u32_e32 v36, 0xa0, v146
	v_mad_i64_i32 v[36:37], s[20:21], v36, s79, v[140:141]
	v_pk_mul_f32 v[30:31], v[30:31], v[34:35]
	v_mul_f32_e32 v34, 0xbfb8aa3b, v32
	v_mul_f32_e32 v35, 0xbfb8aa3b, v33
	v_exp_f32_e32 v34, v34
	v_exp_f32_e32 v35, v35
	v_pk_mul_f32 v[22:23], v[30:31], v[22:23]
	v_add_f32_e32 v30, 1.0, v34
	v_add_f32_e32 v31, 1.0, v35
	v_mul_f32_e32 v34, 0xbfb8aa3b, v26
	v_mul_f32_e32 v35, 0xbfb8aa3b, v27
	v_rcp_f32_e32 v30, v30
	v_rcp_f32_e32 v31, v31
	v_exp_f32_e32 v34, v34
	v_exp_f32_e32 v35, v35
	v_pk_mul_f32 v[30:31], v[32:33], v[30:31]
	v_add_f32_e32 v32, 1.0, v34
	v_add_f32_e32 v33, 1.0, v35
	v_mul_f32_e32 v34, 0xbfb8aa3b, v28
	v_mul_f32_e32 v35, 0xbfb8aa3b, v29
	v_exp_f32_e32 v34, v34
	v_exp_f32_e32 v35, v35
	v_rcp_f32_e32 v32, v32
	v_rcp_f32_e32 v33, v33
	v_add_f32_e32 v34, 1.0, v34
	v_add_f32_e32 v35, 1.0, v35
	v_rcp_f32_e32 v34, v34
	v_rcp_f32_e32 v35, v35
	v_pk_mul_f32 v[26:27], v[26:27], v[32:33]
	v_pk_mul_f32 v[24:25], v[30:31], v[24:25]
	v_pk_mul_f32 v[26:27], v[26:27], v[18:19]
	v_pk_mul_f32 v[18:19], v[28:29], v[34:35]
	v_lshl_add_u64 v[30:31], v[36:37], 0, v[114:115]
	v_pk_mul_f32 v[28:29], v[18:19], v[20:21]
	v_cvt_pk_bf16_f32 v18, v22, v23
	v_mul_f32_e32 v22, 0xbfb8aa3b, v14
	v_mul_f32_e32 v23, 0xbfb8aa3b, v15
	v_exp_f32_e32 v22, v22
	v_exp_f32_e32 v23, v23
	v_cvt_pk_bf16_f32 v19, v24, v25
	v_cvt_pk_bf16_f32 v20, v26, v27
	v_cvt_pk_bf16_f32 v21, v28, v29
	global_store_dwordx4 v[30:31], v[18:21], off
	s_nop 1
	v_add_f32_e32 v18, 1.0, v22
	v_add_f32_e32 v19, 1.0, v23
	v_rcp_f32_e32 v18, v18
	v_rcp_f32_e32 v19, v19
	v_add_u32_e32 v20, 0xb0, v146
	v_mad_i64_i32 v[20:21], s[20:21], v20, s79, v[140:141]
	v_pk_mul_f32 v[14:15], v[14:15], v[18:19]
	v_mul_f32_e32 v18, 0xbfb8aa3b, v16
	v_mul_f32_e32 v19, 0xbfb8aa3b, v17
	v_exp_f32_e32 v18, v18
	v_exp_f32_e32 v19, v19
	v_pk_mul_f32 v[6:7], v[14:15], v[6:7]
	v_add_f32_e32 v14, 1.0, v18
	v_add_f32_e32 v15, 1.0, v19
	v_mul_f32_e32 v18, 0xbfb8aa3b, v10
	v_mul_f32_e32 v19, 0xbfb8aa3b, v11
	v_rcp_f32_e32 v14, v14
	v_rcp_f32_e32 v15, v15
	v_exp_f32_e32 v18, v18
	v_exp_f32_e32 v19, v19
	v_pk_mul_f32 v[14:15], v[16:17], v[14:15]
	v_add_f32_e32 v16, 1.0, v18
	v_add_f32_e32 v17, 1.0, v19
	v_mul_f32_e32 v18, 0xbfb8aa3b, v12
	v_mul_f32_e32 v19, 0xbfb8aa3b, v13
	v_exp_f32_e32 v18, v18
	v_exp_f32_e32 v19, v19
	v_rcp_f32_e32 v16, v16
	v_rcp_f32_e32 v17, v17
	v_add_f32_e32 v18, 1.0, v18
	v_add_f32_e32 v19, 1.0, v19
	v_rcp_f32_e32 v18, v18
	v_rcp_f32_e32 v19, v19
	v_pk_mul_f32 v[10:11], v[10:11], v[16:17]
	v_pk_mul_f32 v[8:9], v[14:15], v[8:9]
	v_pk_mul_f32 v[10:11], v[10:11], v[2:3]
	v_pk_mul_f32 v[2:3], v[12:13], v[18:19]
	v_lshl_add_u64 v[14:15], v[20:21], 0, v[114:115]
	v_pk_mul_f32 v[12:13], v[2:3], v[4:5]
	v_cvt_pk_bf16_f32 v2, v6, v7
	v_cvt_pk_bf16_f32 v3, v8, v9
	v_cvt_pk_bf16_f32 v4, v10, v11
	v_cvt_pk_bf16_f32 v5, v12, v13
	global_store_dwordx4 v[14:15], v[2:5], off
	s_cbranch_vccnz .LBB0_643
	s_andn2_b64 vcc, exec, s[0:1]
	s_cbranch_vccnz .LBB0_642
	s_mov_b32 vcc_lo, 1
	s_nop 0
	v_writelane_b32 v255, vcc_lo, 21
	s_branch .LBB0_642
